# v28 with the burst-tail priority (2) kept through the issue part of the following load phase
# baseline (speedup 1.0000x reference)
.LBB0_379:
	v_add_u32_e32 v14, s56, v140
	v_add_u32_e32 v30, s57, v140
	ds_read_b128 v[2:5], v14
	ds_read_b128 v[6:9], v14 offset:1024
	ds_read_b128 v[10:13], v14 offset:2048
	ds_read_b128 v[14:17], v14 offset:3072
	ds_read_b128 v[18:21], v30
	ds_read_b128 v[22:25], v30 offset:1024
	ds_read_b128 v[26:29], v30 offset:2048
	ds_read_b128 v[30:33], v30 offset:3072
	v_add_u32_e32 v141, 0, v1
	ds_read_b128 v[34:37], v141
	ds_read_b128 v[38:41], v141 offset:1024
	ds_read_b128 v[42:45], v141 offset:2048
	ds_read_b128 v[46:49], v141 offset:3072
	ds_read_b128 v[50:53], v141 offset:4096
	ds_read_b128 v[54:57], v141 offset:5120
	ds_read_b128 v[58:61], v141 offset:6144
	ds_read_b128 v[62:65], v141 offset:7168
	s_waitcnt vmcnt(8)
	s_waitcnt lgkmcnt(0)
	s_barrier
	s_setprio 1
	s_waitcnt lgkmcnt(0)
	v_mfma_f32_16x16x32_bf16 v[66:69], v[2:5], v[34:37], 0
	v_mfma_f32_16x16x32_bf16 v[66:69], v[6:9], v[38:41], v[66:69]
	v_mfma_f32_16x16x32_bf16 v[70:73], v[10:13], v[34:37], 0
	v_mfma_f32_16x16x32_bf16 v[70:73], v[14:17], v[38:41], v[70:73]
	v_mfma_f32_16x16x32_bf16 v[78:81], v[10:13], v[42:45], 0
	v_mfma_f32_16x16x32_bf16 v[78:81], v[14:17], v[46:49], v[78:81]
	v_mfma_f32_16x16x32_bf16 v[74:77], v[2:5], v[42:45], 0
	v_mfma_f32_16x16x32_bf16 v[74:77], v[6:9], v[46:49], v[74:77]
	v_mfma_f32_16x16x32_bf16 v[82:85], v[2:5], v[50:53], 0
	v_mfma_f32_16x16x32_bf16 v[82:85], v[6:9], v[54:57], v[82:85]
	v_mfma_f32_16x16x32_bf16 v[86:89], v[10:13], v[50:53], 0
	v_mfma_f32_16x16x32_bf16 v[86:89], v[14:17], v[54:57], v[86:89]
	v_mfma_f32_16x16x32_bf16 v[94:97], v[10:13], v[58:61], 0
	v_mfma_f32_16x16x32_bf16 v[94:97], v[14:17], v[62:65], v[94:97]
	v_mfma_f32_16x16x32_bf16 v[90:93], v[2:5], v[58:61], 0
	v_mfma_f32_16x16x32_bf16 v[90:93], v[6:9], v[62:65], v[90:93]
	s_setprio 0
	s_setprio 1
	v_mfma_f32_16x16x32_bf16 v[98:101], v[18:21], v[34:37], 0
	v_mfma_f32_16x16x32_bf16 v[34:37], v[26:29], v[34:37], 0
	v_mfma_f32_16x16x32_bf16 v[102:105], v[18:21], v[42:45], 0
	v_mfma_f32_16x16x32_bf16 v[42:45], v[26:29], v[42:45], 0
	v_mfma_f32_16x16x32_bf16 v[106:109], v[18:21], v[50:53], 0
	v_mfma_f32_16x16x32_bf16 v[50:53], v[26:29], v[50:53], 0
	v_mfma_f32_16x16x32_bf16 v[110:113], v[18:21], v[58:61], 0
	v_mfma_f32_16x16x32_bf16 v[58:61], v[26:29], v[58:61], 0
	v_mfma_f32_16x16x32_bf16 v[98:101], v[22:25], v[38:41], v[98:101]
	v_mfma_f32_16x16x32_bf16 v[38:41], v[30:33], v[38:41], v[34:37]
	v_mfma_f32_16x16x32_bf16 v[102:105], v[22:25], v[46:49], v[102:105]
	v_mfma_f32_16x16x32_bf16 v[46:49], v[30:33], v[46:49], v[42:45]
	v_mfma_f32_16x16x32_bf16 v[106:109], v[22:25], v[54:57], v[106:109]
	v_mfma_f32_16x16x32_bf16 v[54:57], v[30:33], v[54:57], v[50:53]
	s_setprio 2
	s_barrier
	v_mfma_f32_16x16x32_bf16 v[110:113], v[22:25], v[62:65], v[110:113]
	v_mfma_f32_16x16x32_bf16 v[62:65], v[30:33], v[62:65], v[58:61]
	v_lshl_add_u64 v[136:137], s[38:39], 0, v[130:131]
	s_add_i32 s60, s56, s21
	v_mov_b32_e32 v135, v131
	v_lshl_add_u64 v[142:143], v[136:137], 0, s[10:11]
	s_mov_b32 m0, s60
	v_lshl_add_u64 v[244:245], s[38:39], 0, v[134:135]
	ds_read_b128 v[34:37], v141 offset:16384
	ds_read_b128 v[42:45], v141 offset:17408
	ds_read_b128 v[50:53], v141 offset:18432
	ds_read_b128 v[58:61], v141 offset:19456
	ds_read_b128 v[114:117], v141 offset:20480
	ds_read_b128 v[118:121], v141 offset:21504
	ds_read_b128 v[122:125], v141 offset:22528
	ds_read_b128 v[126:129], v141 offset:23552
	global_load_lds_dwordx4 v[142:143], off
	v_lshl_add_u64 v[142:143], v[244:245], 0, s[10:11]
	s_add_i32 m0, s60, 0x2000
	s_add_i32 s60, s57, s21
	global_load_lds_dwordx4 v[142:143], off
	s_mov_b32 m0, s60
	v_mov_b32_e32 v139, v131
	global_load_lds_dwordx4 v130, s[40:41]
	s_add_i32 m0, s60, 0x2000
	v_lshl_add_u64 v[246:247], s[36:37], 0, v[138:139]
	v_mov_b32_e32 v133, v131
	global_load_lds_dwordx4 v134, s[40:41]
	v_lshl_add_u64 v[142:143], v[246:247], 0, s[10:11]
	s_mov_b32 m0, s33
	v_lshl_add_u64 v[248:249], s[36:37], 0, v[132:133]
	global_load_lds_dwordx4 v[142:143], off
	v_lshl_add_u64 v[142:143], v[248:249], 0, s[10:11]
	s_mov_b32 m0, s46
	s_nop 0
	global_load_lds_dwordx4 v[142:143], off
	s_setprio 0
	s_waitcnt vmcnt(8)
	s_waitcnt lgkmcnt(0)
	s_barrier
	s_setprio 1
	s_waitcnt lgkmcnt(0)
	v_mfma_f32_16x16x32_bf16 v[142:145], v[2:5], v[34:37], 0
	v_mfma_f32_16x16x32_bf16 v[148:151], v[10:13], v[34:37], 0
	v_mfma_f32_16x16x32_bf16 v[152:155], v[2:5], v[50:53], 0
	v_mfma_f32_16x16x32_bf16 v[156:159], v[10:13], v[50:53], 0
	v_mfma_f32_16x16x32_bf16 v[160:163], v[2:5], v[114:117], 0
	v_mfma_f32_16x16x32_bf16 v[164:167], v[10:13], v[114:117], 0
	v_mfma_f32_16x16x32_bf16 v[2:5], v[2:5], v[122:125], 0
	v_mfma_f32_16x16x32_bf16 v[10:13], v[10:13], v[122:125], 0
	v_mfma_f32_16x16x32_bf16 v[142:145], v[6:9], v[42:45], v[142:145]
	v_mfma_f32_16x16x32_bf16 v[148:151], v[14:17], v[42:45], v[148:151]
	v_mfma_f32_16x16x32_bf16 v[152:155], v[6:9], v[58:61], v[152:155]
	v_mfma_f32_16x16x32_bf16 v[156:159], v[14:17], v[58:61], v[156:159]
	v_mfma_f32_16x16x32_bf16 v[160:163], v[6:9], v[118:121], v[160:163]
	v_mfma_f32_16x16x32_bf16 v[164:167], v[14:17], v[118:121], v[164:167]
	v_mfma_f32_16x16x32_bf16 v[168:171], v[6:9], v[126:129], v[2:5]
	v_mfma_f32_16x16x32_bf16 v[172:175], v[14:17], v[126:129], v[10:13]
	s_setprio 0
	s_setprio 1
	v_mfma_f32_16x16x32_bf16 v[2:5], v[18:21], v[34:37], 0
	v_mfma_f32_16x16x32_bf16 v[6:9], v[26:29], v[34:37], 0
	v_mfma_f32_16x16x32_bf16 v[10:13], v[18:21], v[50:53], 0
	v_mfma_f32_16x16x32_bf16 v[14:17], v[26:29], v[50:53], 0
	v_mfma_f32_16x16x32_bf16 v[34:37], v[18:21], v[114:117], 0
	v_mfma_f32_16x16x32_bf16 v[50:53], v[26:29], v[114:117], 0
	v_mfma_f32_16x16x32_bf16 v[18:21], v[18:21], v[122:125], 0
	v_mfma_f32_16x16x32_bf16 v[26:29], v[26:29], v[122:125], 0
	v_mfma_f32_16x16x32_bf16 v[114:117], v[22:25], v[42:45], v[2:5]
	v_mfma_f32_16x16x32_bf16 v[188:191], v[22:25], v[118:121], v[34:37]
	v_mfma_f32_16x16x32_bf16 v[118:121], v[30:33], v[118:121], v[50:53]
	v_mfma_f32_16x16x32_bf16 v[176:179], v[30:33], v[42:45], v[6:9]
	v_mfma_f32_16x16x32_bf16 v[180:183], v[22:25], v[58:61], v[10:13]
	v_mfma_f32_16x16x32_bf16 v[184:187], v[30:33], v[58:61], v[14:17]
	s_setprio 2
	s_barrier
	v_mfma_f32_16x16x32_bf16 v[192:195], v[22:25], v[126:129], v[18:21]
	v_mfma_f32_16x16x32_bf16 v[196:199], v[30:33], v[126:129], v[26:29]
	s_add_i32 s60, 0, 0x18000
	v_add_u32_e32 v2, s60, v140
	s_add_i32 s61, 0, 0x1c000
	ds_read_b128 v[200:203], v2
	ds_read_b128 v[204:207], v2 offset:1024
	ds_read_b128 v[208:211], v2 offset:2048
	ds_read_b128 v[212:215], v2 offset:3072
	v_add_u32_e32 v2, s61, v140
	ds_read_b128 v[216:219], v2
	ds_read_b128 v[220:223], v2 offset:1024
	ds_read_b128 v[224:227], v2 offset:2048
	ds_read_b128 v[228:231], v2 offset:3072
	s_mov_b32 m0, s47
	ds_read_b128 v[42:45], v141 offset:32768
	ds_read_b128 v[50:53], v141 offset:33792
	ds_read_b128 v[58:61], v141 offset:34816
	ds_read_b128 v[122:125], v141 offset:35840
	ds_read_b128 v[126:129], v141 offset:36864
	ds_read_b128 v[232:235], v141 offset:37888
	ds_read_b128 v[236:239], v141 offset:38912
	ds_read_b128 v[240:243], v141 offset:39936
	global_load_lds_dwordx4 v138, s[42:43]
	s_mov_b32 m0, s48
	s_nop 0
	global_load_lds_dwordx4 v132, s[42:43]
	s_setprio 0
	s_waitcnt vmcnt(8)
	s_waitcnt lgkmcnt(0)
	s_barrier
	s_setprio 1
	s_waitcnt lgkmcnt(0)
	v_mfma_f32_16x16x32_bf16 v[2:5], v[200:203], v[42:45], v[66:69]
	v_mfma_f32_16x16x32_bf16 v[6:9], v[208:211], v[42:45], v[70:73]
	v_mfma_f32_16x16x32_bf16 v[10:13], v[200:203], v[58:61], v[74:77]
	v_mfma_f32_16x16x32_bf16 v[14:17], v[208:211], v[58:61], v[78:81]
	v_mfma_f32_16x16x32_bf16 v[18:21], v[200:203], v[126:129], v[82:85]
	v_mfma_f32_16x16x32_bf16 v[22:25], v[208:211], v[126:129], v[86:89]
	v_mfma_f32_16x16x32_bf16 v[26:29], v[200:203], v[236:239], v[90:93]
	v_mfma_f32_16x16x32_bf16 v[30:33], v[208:211], v[236:239], v[94:97]
	v_mfma_f32_16x16x32_bf16 v[2:5], v[204:207], v[50:53], v[2:5]
	v_mfma_f32_16x16x32_bf16 v[6:9], v[212:215], v[50:53], v[6:9]
	v_mfma_f32_16x16x32_bf16 v[10:13], v[204:207], v[122:125], v[10:13]
	v_mfma_f32_16x16x32_bf16 v[14:17], v[212:215], v[122:125], v[14:17]
	v_mfma_f32_16x16x32_bf16 v[18:21], v[204:207], v[232:235], v[18:21]
	v_mfma_f32_16x16x32_bf16 v[22:25], v[212:215], v[232:235], v[22:25]
	v_mfma_f32_16x16x32_bf16 v[26:29], v[204:207], v[240:243], v[26:29]
	v_mfma_f32_16x16x32_bf16 v[30:33], v[212:215], v[240:243], v[30:33]
	s_setprio 0
	s_setprio 1
	v_mfma_f32_16x16x32_bf16 v[34:37], v[216:219], v[42:45], v[98:101]
	v_mfma_f32_16x16x32_bf16 v[38:41], v[224:227], v[42:45], v[38:41]
	v_mfma_f32_16x16x32_bf16 v[34:37], v[220:223], v[50:53], v[34:37]
	v_mfma_f32_16x16x32_bf16 v[38:41], v[228:231], v[50:53], v[38:41]
	v_mfma_f32_16x16x32_bf16 v[42:45], v[216:219], v[58:61], v[102:105]
	v_mfma_f32_16x16x32_bf16 v[46:49], v[224:227], v[58:61], v[46:49]
	v_mfma_f32_16x16x32_bf16 v[50:53], v[216:219], v[126:129], v[106:109]
	v_mfma_f32_16x16x32_bf16 v[54:57], v[224:227], v[126:129], v[54:57]
	v_mfma_f32_16x16x32_bf16 v[58:61], v[216:219], v[236:239], v[110:113]
	v_mfma_f32_16x16x32_bf16 v[62:65], v[224:227], v[236:239], v[62:65]
	v_mfma_f32_16x16x32_bf16 v[42:45], v[220:223], v[122:125], v[42:45]
	v_mfma_f32_16x16x32_bf16 v[46:49], v[228:231], v[122:125], v[46:49]
	v_mfma_f32_16x16x32_bf16 v[50:53], v[220:223], v[232:235], v[50:53]
	v_mfma_f32_16x16x32_bf16 v[54:57], v[228:231], v[232:235], v[54:57]
	s_setprio 2
	s_barrier
	v_mfma_f32_16x16x32_bf16 v[58:61], v[220:223], v[240:243], v[58:61]
	v_mfma_f32_16x16x32_bf16 v[62:65], v[228:231], v[240:243], v[62:65]
	s_add_i32 s60, s60, s21
	v_lshl_add_u64 v[66:67], v[136:137], 0, s[12:13]
	s_mov_b32 m0, s60
	ds_read_b128 v[94:97], v141 offset:49152
	ds_read_b128 v[98:101], v141 offset:50176
	ds_read_b128 v[102:105], v141 offset:51200
	ds_read_b128 v[106:109], v141 offset:52224
	ds_read_b128 v[110:113], v141 offset:53248
	ds_read_b128 v[232:235], v141 offset:54272
	ds_read_b128 v[236:239], v141 offset:55296
	ds_read_b128 v[240:243], v141 offset:56320
	global_load_lds_dwordx4 v[66:67], off
	v_lshl_add_u64 v[66:67], v[244:245], 0, s[12:13]
	s_add_i32 m0, s60, 0x2000
	s_add_i32 s60, s61, s21
	global_load_lds_dwordx4 v[66:67], off
	s_mov_b32 m0, s60
	v_lshl_add_u64 v[66:67], v[246:247], 0, s[12:13]
	global_load_lds_dwordx4 v130, s[44:45]
	s_add_i32 m0, s60, 0x2000
	s_nop 0
	global_load_lds_dwordx4 v134, s[44:45]
	s_mov_b32 m0, s52
	s_nop 0
	global_load_lds_dwordx4 v[66:67], off
	v_lshl_add_u64 v[66:67], v[248:249], 0, s[12:13]
	s_mov_b32 m0, s53
	s_nop 0
	global_load_lds_dwordx4 v[66:67], off
	s_setprio 0
	s_waitcnt vmcnt(8)
	s_waitcnt lgkmcnt(0)
	s_barrier
	s_setprio 1
	s_waitcnt lgkmcnt(0)
	v_mfma_f32_16x16x32_bf16 v[66:69], v[200:203], v[94:97], v[142:145]
	v_mfma_f32_16x16x32_bf16 v[122:125], v[204:207], v[98:101], v[66:69]
	v_mfma_f32_16x16x32_bf16 v[66:69], v[208:211], v[94:97], v[148:151]
	v_mfma_f32_16x16x32_bf16 v[126:129], v[212:215], v[98:101], v[66:69]
	v_mfma_f32_16x16x32_bf16 v[66:69], v[200:203], v[102:105], v[152:155]
	v_mfma_f32_16x16x32_bf16 v[70:73], v[208:211], v[102:105], v[156:159]
	v_mfma_f32_16x16x32_bf16 v[74:77], v[200:203], v[110:113], v[160:163]
	v_mfma_f32_16x16x32_bf16 v[78:81], v[208:211], v[110:113], v[164:167]
	v_mfma_f32_16x16x32_bf16 v[82:85], v[200:203], v[236:239], v[168:171]
	v_mfma_f32_16x16x32_bf16 v[86:89], v[208:211], v[236:239], v[172:175]
	v_mfma_f32_16x16x32_bf16 v[66:69], v[204:207], v[106:109], v[66:69]
	v_mfma_f32_16x16x32_bf16 v[70:73], v[212:215], v[106:109], v[70:73]
	v_mfma_f32_16x16x32_bf16 v[74:77], v[204:207], v[232:235], v[74:77]
	v_mfma_f32_16x16x32_bf16 v[78:81], v[212:215], v[232:235], v[78:81]
	v_mfma_f32_16x16x32_bf16 v[82:85], v[204:207], v[240:243], v[82:85]
	v_mfma_f32_16x16x32_bf16 v[86:89], v[212:215], v[240:243], v[86:89]
	s_setprio 0
	s_setprio 1
	v_mfma_f32_16x16x32_bf16 v[90:93], v[216:219], v[94:97], v[114:117]
	v_mfma_f32_16x16x32_bf16 v[94:97], v[224:227], v[94:97], v[176:179]
	v_mfma_f32_16x16x32_bf16 v[90:93], v[220:223], v[98:101], v[90:93]
	v_mfma_f32_16x16x32_bf16 v[94:97], v[228:231], v[98:101], v[94:97]
	v_mfma_f32_16x16x32_bf16 v[98:101], v[216:219], v[102:105], v[180:183]
	v_mfma_f32_16x16x32_bf16 v[102:105], v[224:227], v[102:105], v[184:187]
	v_mfma_f32_16x16x32_bf16 v[98:101], v[220:223], v[106:109], v[98:101]
	v_mfma_f32_16x16x32_bf16 v[102:105], v[228:231], v[106:109], v[102:105]
	v_mfma_f32_16x16x32_bf16 v[106:109], v[216:219], v[110:113], v[188:191]
	v_mfma_f32_16x16x32_bf16 v[110:113], v[224:227], v[110:113], v[118:121]
	v_mfma_f32_16x16x32_bf16 v[114:117], v[216:219], v[236:239], v[192:195]
	v_mfma_f32_16x16x32_bf16 v[118:121], v[224:227], v[236:239], v[196:199]
	v_mfma_f32_16x16x32_bf16 v[106:109], v[220:223], v[232:235], v[106:109]
	v_mfma_f32_16x16x32_bf16 v[110:113], v[228:231], v[232:235], v[110:113]
	s_setprio 2
	s_barrier
	v_mfma_f32_16x16x32_bf16 v[114:117], v[220:223], v[240:243], v[114:117]
	v_mfma_f32_16x16x32_bf16 v[118:121], v[228:231], v[240:243], v[118:121]
	s_setprio 0
	s_add_i32 s59, s59, 2
	s_cmp_ge_i32 s59, s15
	s_cbranch_scc0 .LBB0_379
	v_mov_b32_e32 v136, v130
	s_branch .LBB0_382

.LBB0_383:
	v_add_u32_e32 v133, s56, v140
	ds_read_b128 v[142:145], v133
	ds_read_b128 v[148:151], v133 offset:1024
	ds_read_b128 v[152:155], v133 offset:2048
	ds_read_b128 v[156:159], v133 offset:3072
	v_add_u32_e32 v133, s57, v140
	ds_read_b128 v[160:163], v133
	ds_read_b128 v[164:167], v133 offset:1024
	ds_read_b128 v[168:171], v133 offset:2048
	ds_read_b128 v[172:175], v133 offset:3072
	s_add_u32 s38, s36, 0xfff80080
	s_addc_u32 s39, s37, -1
	s_cmp_eq_u32 s43, 28
	s_cselect_b32 s41, s31, s39
	s_cselect_b32 s40, s30, s38
	s_cselect_b32 s39, s35, s42
	s_cselect_b32 s38, s34, s15
	s_mov_b32 m0, s54
	v_add_u32_e32 v141, 0, v1
	ds_read_b128 v[176:179], v141
	ds_read_b128 v[180:183], v141 offset:1024
	ds_read_b128 v[184:187], v141 offset:2048
	ds_read_b128 v[188:191], v141 offset:3072
	ds_read_b128 v[192:195], v141 offset:4096
	ds_read_b128 v[196:199], v141 offset:5120
	ds_read_b128 v[200:203], v141 offset:6144
	ds_read_b128 v[204:207], v141 offset:7168
	global_load_lds_dwordx4 v130, s[36:37]
	s_mov_b32 m0, s55
	v_mov_b32_e32 v133, v131
	global_load_lds_dwordx4 v132, s[36:37]
	s_waitcnt vmcnt(8)
	s_waitcnt lgkmcnt(0)
	s_barrier
	s_setprio 1
	s_waitcnt lgkmcnt(0)
	v_mfma_f32_16x16x32_bf16 v[2:5], v[142:145], v[176:179], v[2:5]
	v_mfma_f32_16x16x32_bf16 v[2:5], v[148:151], v[180:183], v[2:5]
	v_mfma_f32_16x16x32_bf16 v[6:9], v[156:159], v[180:183], v[6:9]
	v_mfma_f32_16x16x32_bf16 v[6:9], v[152:155], v[176:179], v[6:9]
	v_mfma_f32_16x16x32_bf16 v[14:17], v[152:155], v[184:187], v[14:17]
	v_mfma_f32_16x16x32_bf16 v[14:17], v[156:159], v[188:191], v[14:17]
	v_mfma_f32_16x16x32_bf16 v[10:13], v[148:151], v[188:191], v[10:13]
	v_mfma_f32_16x16x32_bf16 v[10:13], v[142:145], v[184:187], v[10:13]
	v_mfma_f32_16x16x32_bf16 v[18:21], v[142:145], v[192:195], v[18:21]
	v_mfma_f32_16x16x32_bf16 v[18:21], v[148:151], v[196:199], v[18:21]
	v_mfma_f32_16x16x32_bf16 v[22:25], v[156:159], v[196:199], v[22:25]
	v_mfma_f32_16x16x32_bf16 v[22:25], v[152:155], v[192:195], v[22:25]
	v_mfma_f32_16x16x32_bf16 v[30:33], v[152:155], v[200:203], v[30:33]
	v_mfma_f32_16x16x32_bf16 v[30:33], v[156:159], v[204:207], v[30:33]
	v_mfma_f32_16x16x32_bf16 v[26:29], v[148:151], v[204:207], v[26:29]
	v_mfma_f32_16x16x32_bf16 v[26:29], v[142:145], v[200:203], v[26:29]
	s_setprio 0
	s_setprio 1
	v_mfma_f32_16x16x32_bf16 v[34:37], v[160:163], v[176:179], v[34:37]
	v_mfma_f32_16x16x32_bf16 v[34:37], v[164:167], v[180:183], v[34:37]
	v_mfma_f32_16x16x32_bf16 v[38:41], v[172:175], v[180:183], v[38:41]
	v_mfma_f32_16x16x32_bf16 v[38:41], v[168:171], v[176:179], v[38:41]
	v_mfma_f32_16x16x32_bf16 v[46:49], v[168:171], v[184:187], v[46:49]
	v_mfma_f32_16x16x32_bf16 v[46:49], v[172:175], v[188:191], v[46:49]
	v_mfma_f32_16x16x32_bf16 v[42:45], v[164:167], v[188:191], v[42:45]
	v_mfma_f32_16x16x32_bf16 v[42:45], v[160:163], v[184:187], v[42:45]
	v_mfma_f32_16x16x32_bf16 v[50:53], v[160:163], v[192:195], v[50:53]
	v_mfma_f32_16x16x32_bf16 v[50:53], v[164:167], v[196:199], v[50:53]
	v_mfma_f32_16x16x32_bf16 v[54:57], v[172:175], v[196:199], v[54:57]
	v_mfma_f32_16x16x32_bf16 v[54:57], v[168:171], v[192:195], v[54:57]
	v_mfma_f32_16x16x32_bf16 v[62:65], v[168:171], v[200:203], v[62:65]
	v_mfma_f32_16x16x32_bf16 v[62:65], v[172:175], v[204:207], v[62:65]
	s_setprio 2
	s_barrier
	v_mfma_f32_16x16x32_bf16 v[58:61], v[164:167], v[204:207], v[58:61]
	v_mfma_f32_16x16x32_bf16 v[58:61], v[160:163], v[200:203], v[58:61]
	s_add_i32 s44, s56, s21
	s_mov_b32 m0, s44
	ds_read_b128 v[176:179], v141 offset:16384
	ds_read_b128 v[180:183], v141 offset:17408
	ds_read_b128 v[184:187], v141 offset:18432
	ds_read_b128 v[188:191], v141 offset:19456
	ds_read_b128 v[192:195], v141 offset:20480
	ds_read_b128 v[196:199], v141 offset:21504
	ds_read_b128 v[200:203], v141 offset:22528
	ds_read_b128 v[204:207], v141 offset:23552
	global_load_lds_dwordx4 v136, s[38:39]
	s_add_i32 m0, s44, 0x2000
	s_add_u32 s44, s38, 0x80000
	s_addc_u32 s45, s39, 0
	s_add_i32 s59, s57, s21
	global_load_lds_dwordx4 v134, s[38:39]
	s_mov_b32 m0, s59
	v_mov_b32_e32 v137, v131
	global_load_lds_dwordx4 v136, s[44:45]
	s_add_i32 m0, s59, 0x2000
	v_mov_b32_e32 v135, v131
	global_load_lds_dwordx4 v134, s[44:45]
	s_mov_b32 m0, s33
	v_lshl_add_u64 v[138:139], s[38:39], 0, v[136:137]
	global_load_lds_dwordx4 v130, s[40:41]
	s_mov_b32 m0, s46
	v_lshl_add_u64 v[208:209], s[38:39], 0, v[134:135]
	global_load_lds_dwordx4 v132, s[40:41]
	s_setprio 0
	s_waitcnt vmcnt(8)
	s_waitcnt lgkmcnt(0)
	v_lshl_add_u64 v[210:211], s[40:41], 0, v[130:131]
	v_lshl_add_u64 v[212:213], s[40:41], 0, v[132:133]
	s_barrier
	s_setprio 1
	s_waitcnt lgkmcnt(0)
	v_mfma_f32_16x16x32_bf16 v[122:125], v[142:145], v[176:179], v[122:125]
	v_mfma_f32_16x16x32_bf16 v[122:125], v[148:151], v[180:183], v[122:125]
	v_mfma_f32_16x16x32_bf16 v[126:129], v[156:159], v[180:183], v[126:129]
	v_mfma_f32_16x16x32_bf16 v[126:129], v[152:155], v[176:179], v[126:129]
	v_mfma_f32_16x16x32_bf16 v[70:73], v[152:155], v[184:187], v[70:73]
	v_mfma_f32_16x16x32_bf16 v[70:73], v[156:159], v[188:191], v[70:73]
	v_mfma_f32_16x16x32_bf16 v[66:69], v[148:151], v[188:191], v[66:69]
	v_mfma_f32_16x16x32_bf16 v[66:69], v[142:145], v[184:187], v[66:69]
	v_mfma_f32_16x16x32_bf16 v[74:77], v[142:145], v[192:195], v[74:77]
	v_mfma_f32_16x16x32_bf16 v[74:77], v[148:151], v[196:199], v[74:77]
	v_mfma_f32_16x16x32_bf16 v[78:81], v[156:159], v[196:199], v[78:81]
	v_mfma_f32_16x16x32_bf16 v[78:81], v[152:155], v[192:195], v[78:81]
	v_mfma_f32_16x16x32_bf16 v[86:89], v[152:155], v[200:203], v[86:89]
	v_mfma_f32_16x16x32_bf16 v[86:89], v[156:159], v[204:207], v[86:89]
	v_mfma_f32_16x16x32_bf16 v[82:85], v[148:151], v[204:207], v[82:85]
	v_mfma_f32_16x16x32_bf16 v[82:85], v[142:145], v[200:203], v[82:85]
	s_setprio 0
	s_setprio 1
	v_mfma_f32_16x16x32_bf16 v[90:93], v[160:163], v[176:179], v[90:93]
	v_mfma_f32_16x16x32_bf16 v[90:93], v[164:167], v[180:183], v[90:93]
	v_mfma_f32_16x16x32_bf16 v[94:97], v[172:175], v[180:183], v[94:97]
	v_mfma_f32_16x16x32_bf16 v[94:97], v[168:171], v[176:179], v[94:97]
	v_mfma_f32_16x16x32_bf16 v[102:105], v[168:171], v[184:187], v[102:105]
	v_mfma_f32_16x16x32_bf16 v[102:105], v[172:175], v[188:191], v[102:105]
	v_mfma_f32_16x16x32_bf16 v[98:101], v[164:167], v[188:191], v[98:101]
	v_mfma_f32_16x16x32_bf16 v[98:101], v[160:163], v[184:187], v[98:101]
	v_mfma_f32_16x16x32_bf16 v[106:109], v[160:163], v[192:195], v[106:109]
	v_mfma_f32_16x16x32_bf16 v[106:109], v[164:167], v[196:199], v[106:109]
	v_mfma_f32_16x16x32_bf16 v[110:113], v[172:175], v[196:199], v[110:113]
	v_mfma_f32_16x16x32_bf16 v[110:113], v[168:171], v[192:195], v[110:113]
	v_mfma_f32_16x16x32_bf16 v[118:121], v[168:171], v[200:203], v[118:121]
	v_mfma_f32_16x16x32_bf16 v[118:121], v[172:175], v[204:207], v[118:121]
	s_setprio 2
	s_barrier
	v_mfma_f32_16x16x32_bf16 v[114:117], v[164:167], v[204:207], v[114:117]
	v_mfma_f32_16x16x32_bf16 v[114:117], v[160:163], v[200:203], v[114:117]
	s_add_i32 s44, 0, 0x18000
	v_add_u32_e32 v135, s44, v140
	s_add_i32 s45, 0, 0x1c000
	ds_read_b128 v[142:145], v135
	ds_read_b128 v[148:151], v135 offset:1024
	ds_read_b128 v[152:155], v135 offset:2048
	ds_read_b128 v[156:159], v135 offset:3072
	v_add_u32_e32 v135, s45, v140
	ds_read_b128 v[160:163], v135
	ds_read_b128 v[164:167], v135 offset:1024
	ds_read_b128 v[168:171], v135 offset:2048
	ds_read_b128 v[172:175], v135 offset:3072
	s_add_u32 s40, s40, 0x80000
	s_addc_u32 s41, s41, 0
	s_mov_b32 m0, s47
	ds_read_b128 v[176:179], v141 offset:32768
	ds_read_b128 v[180:183], v141 offset:33792
	ds_read_b128 v[184:187], v141 offset:34816
	ds_read_b128 v[188:191], v141 offset:35840
	ds_read_b128 v[192:195], v141 offset:36864
	ds_read_b128 v[196:199], v141 offset:37888
	ds_read_b128 v[200:203], v141 offset:38912
	ds_read_b128 v[204:207], v141 offset:39936
	global_load_lds_dwordx4 v130, s[40:41]
	s_mov_b32 m0, s48
	s_nop 0
	global_load_lds_dwordx4 v132, s[40:41]
	s_setprio 0
	s_waitcnt vmcnt(8)
	s_waitcnt lgkmcnt(0)
	s_barrier
	s_setprio 1
	s_waitcnt lgkmcnt(0)
	v_mfma_f32_16x16x32_bf16 v[2:5], v[142:145], v[176:179], v[2:5]
	v_mfma_f32_16x16x32_bf16 v[2:5], v[148:151], v[180:183], v[2:5]
	v_mfma_f32_16x16x32_bf16 v[6:9], v[156:159], v[180:183], v[6:9]
	v_mfma_f32_16x16x32_bf16 v[6:9], v[152:155], v[176:179], v[6:9]
	v_mfma_f32_16x16x32_bf16 v[14:17], v[152:155], v[184:187], v[14:17]
	v_mfma_f32_16x16x32_bf16 v[14:17], v[156:159], v[188:191], v[14:17]
	v_mfma_f32_16x16x32_bf16 v[10:13], v[148:151], v[188:191], v[10:13]
	v_mfma_f32_16x16x32_bf16 v[10:13], v[142:145], v[184:187], v[10:13]
	v_mfma_f32_16x16x32_bf16 v[18:21], v[142:145], v[192:195], v[18:21]
	v_mfma_f32_16x16x32_bf16 v[18:21], v[148:151], v[196:199], v[18:21]
	v_mfma_f32_16x16x32_bf16 v[22:25], v[156:159], v[196:199], v[22:25]
	v_mfma_f32_16x16x32_bf16 v[22:25], v[152:155], v[192:195], v[22:25]
	v_mfma_f32_16x16x32_bf16 v[30:33], v[152:155], v[200:203], v[30:33]
	v_mfma_f32_16x16x32_bf16 v[30:33], v[156:159], v[204:207], v[30:33]
	v_mfma_f32_16x16x32_bf16 v[26:29], v[148:151], v[204:207], v[26:29]
	v_mfma_f32_16x16x32_bf16 v[26:29], v[142:145], v[200:203], v[26:29]
	s_setprio 0
	s_setprio 1
	v_mfma_f32_16x16x32_bf16 v[34:37], v[160:163], v[176:179], v[34:37]
	v_mfma_f32_16x16x32_bf16 v[34:37], v[164:167], v[180:183], v[34:37]
	v_mfma_f32_16x16x32_bf16 v[38:41], v[172:175], v[180:183], v[38:41]
	v_mfma_f32_16x16x32_bf16 v[38:41], v[168:171], v[176:179], v[38:41]
	v_mfma_f32_16x16x32_bf16 v[46:49], v[168:171], v[184:187], v[46:49]
	v_mfma_f32_16x16x32_bf16 v[46:49], v[172:175], v[188:191], v[46:49]
	v_mfma_f32_16x16x32_bf16 v[42:45], v[164:167], v[188:191], v[42:45]
	v_mfma_f32_16x16x32_bf16 v[42:45], v[160:163], v[184:187], v[42:45]
	v_mfma_f32_16x16x32_bf16 v[50:53], v[160:163], v[192:195], v[50:53]
	v_mfma_f32_16x16x32_bf16 v[50:53], v[164:167], v[196:199], v[50:53]
	v_mfma_f32_16x16x32_bf16 v[54:57], v[172:175], v[196:199], v[54:57]
	v_mfma_f32_16x16x32_bf16 v[54:57], v[168:171], v[192:195], v[54:57]
	v_mfma_f32_16x16x32_bf16 v[62:65], v[168:171], v[200:203], v[62:65]
	v_mfma_f32_16x16x32_bf16 v[62:65], v[172:175], v[204:207], v[62:65]
	s_setprio 2
	s_barrier
	v_mfma_f32_16x16x32_bf16 v[58:61], v[164:167], v[204:207], v[58:61]
	v_mfma_f32_16x16x32_bf16 v[58:61], v[160:163], v[200:203], v[58:61]
	s_add_i32 s40, s44, s21
	v_lshl_add_u64 v[138:139], v[138:139], 0, s[6:7]
	s_mov_b32 m0, s40
	ds_read_b128 v[176:179], v141 offset:49152
	ds_read_b128 v[180:183], v141 offset:50176
	ds_read_b128 v[184:187], v141 offset:51200
	ds_read_b128 v[188:191], v141 offset:52224
	ds_read_b128 v[192:195], v141 offset:53248
	ds_read_b128 v[196:199], v141 offset:54272
	ds_read_b128 v[200:203], v141 offset:55296
	ds_read_b128 v[204:207], v141 offset:56320
	global_load_lds_dwordx4 v[138:139], off
	s_add_i32 m0, s40, 0x2000
	s_add_u32 s38, s38, 0x80080
	v_lshl_add_u64 v[138:139], v[208:209], 0, s[6:7]
	s_addc_u32 s39, s39, 0
	s_add_i32 s40, s45, s21
	global_load_lds_dwordx4 v[138:139], off
	s_mov_b32 m0, s40
	v_lshl_add_u64 v[138:139], v[210:211], 0, s[6:7]
	global_load_lds_dwordx4 v136, s[38:39]
	s_add_i32 m0, s40, 0x2000
	s_nop 0
	global_load_lds_dwordx4 v134, s[38:39]
	s_mov_b32 m0, s52
	s_nop 0
	global_load_lds_dwordx4 v[138:139], off
	v_lshl_add_u64 v[138:139], v[212:213], 0, s[6:7]
	s_mov_b32 m0, s53
	s_nop 0
	global_load_lds_dwordx4 v[138:139], off
	s_setprio 0
	s_waitcnt vmcnt(8)
	s_waitcnt lgkmcnt(0)
	s_barrier
	s_setprio 1
	s_waitcnt lgkmcnt(0)
	v_mfma_f32_16x16x32_bf16 v[122:125], v[142:145], v[176:179], v[122:125]
	v_mfma_f32_16x16x32_bf16 v[122:125], v[148:151], v[180:183], v[122:125]
	v_mfma_f32_16x16x32_bf16 v[126:129], v[156:159], v[180:183], v[126:129]
	v_mfma_f32_16x16x32_bf16 v[126:129], v[152:155], v[176:179], v[126:129]
	v_mfma_f32_16x16x32_bf16 v[70:73], v[152:155], v[184:187], v[70:73]
	v_mfma_f32_16x16x32_bf16 v[70:73], v[156:159], v[188:191], v[70:73]
	v_mfma_f32_16x16x32_bf16 v[66:69], v[148:151], v[188:191], v[66:69]
	v_mfma_f32_16x16x32_bf16 v[66:69], v[142:145], v[184:187], v[66:69]
	v_mfma_f32_16x16x32_bf16 v[74:77], v[142:145], v[192:195], v[74:77]
	v_mfma_f32_16x16x32_bf16 v[74:77], v[148:151], v[196:199], v[74:77]
	v_mfma_f32_16x16x32_bf16 v[78:81], v[156:159], v[196:199], v[78:81]
	v_mfma_f32_16x16x32_bf16 v[78:81], v[152:155], v[192:195], v[78:81]
	v_mfma_f32_16x16x32_bf16 v[86:89], v[152:155], v[200:203], v[86:89]
	v_mfma_f32_16x16x32_bf16 v[86:89], v[156:159], v[204:207], v[86:89]
	v_mfma_f32_16x16x32_bf16 v[82:85], v[148:151], v[204:207], v[82:85]
	v_mfma_f32_16x16x32_bf16 v[82:85], v[142:145], v[200:203], v[82:85]
	s_setprio 0
	s_setprio 1
	v_mfma_f32_16x16x32_bf16 v[90:93], v[160:163], v[176:179], v[90:93]
	v_mfma_f32_16x16x32_bf16 v[90:93], v[164:167], v[180:183], v[90:93]
	v_mfma_f32_16x16x32_bf16 v[94:97], v[172:175], v[180:183], v[94:97]
	v_mfma_f32_16x16x32_bf16 v[94:97], v[168:171], v[176:179], v[94:97]
	v_mfma_f32_16x16x32_bf16 v[102:105], v[168:171], v[184:187], v[102:105]
	v_mfma_f32_16x16x32_bf16 v[102:105], v[172:175], v[188:191], v[102:105]
	v_mfma_f32_16x16x32_bf16 v[98:101], v[164:167], v[188:191], v[98:101]
	v_mfma_f32_16x16x32_bf16 v[98:101], v[160:163], v[184:187], v[98:101]
	v_mfma_f32_16x16x32_bf16 v[106:109], v[160:163], v[192:195], v[106:109]
	v_mfma_f32_16x16x32_bf16 v[106:109], v[164:167], v[196:199], v[106:109]
	v_mfma_f32_16x16x32_bf16 v[110:113], v[172:175], v[196:199], v[110:113]
	v_mfma_f32_16x16x32_bf16 v[110:113], v[168:171], v[192:195], v[110:113]
	v_mfma_f32_16x16x32_bf16 v[118:121], v[168:171], v[200:203], v[118:121]
	v_mfma_f32_16x16x32_bf16 v[118:121], v[172:175], v[204:207], v[118:121]
	s_setprio 2
	s_barrier
	v_mfma_f32_16x16x32_bf16 v[114:117], v[164:167], v[204:207], v[114:117]
	v_mfma_f32_16x16x32_bf16 v[114:117], v[160:163], v[200:203], v[114:117]
	s_setprio 0
	s_add_i32 s43, s43, 2
	s_add_u32 s36, s36, 0x100
	s_addc_u32 s37, s37, 0
	s_add_u32 s15, s15, 0x100
	s_addc_u32 s42, s42, 0
	s_cmp_gt_u32 s43, 29
	s_cbranch_scc0 .LBB0_383
	s_and_b64 vcc, exec, s[8:9]
	s_cbranch_vccz .LBB0_386
	s_barrier

.LBB0_462:
	v_add_u32_e32 v14, s54, v140
	v_add_u32_e32 v30, s55, v140
	ds_read_b128 v[2:5], v14
	ds_read_b128 v[6:9], v14 offset:1024
	ds_read_b128 v[10:13], v14 offset:2048
	ds_read_b128 v[14:17], v14 offset:3072
	ds_read_b128 v[18:21], v30
	ds_read_b128 v[22:25], v30 offset:1024
	ds_read_b128 v[26:29], v30 offset:2048
	ds_read_b128 v[30:33], v30 offset:3072
	v_add_u32_e32 v141, 0, v1
	ds_read_b128 v[34:37], v141
	ds_read_b128 v[38:41], v141 offset:1024
	ds_read_b128 v[42:45], v141 offset:2048
	ds_read_b128 v[46:49], v141 offset:3072
	ds_read_b128 v[50:53], v141 offset:4096
	ds_read_b128 v[54:57], v141 offset:5120
	ds_read_b128 v[58:61], v141 offset:6144
	ds_read_b128 v[62:65], v141 offset:7168
	s_waitcnt vmcnt(8)
	s_waitcnt lgkmcnt(0)
	s_barrier
	s_setprio 1
	s_waitcnt lgkmcnt(0)
	v_mfma_f32_16x16x32_bf16 v[66:69], v[2:5], v[34:37], 0
	v_mfma_f32_16x16x32_bf16 v[66:69], v[6:9], v[38:41], v[66:69]
	v_mfma_f32_16x16x32_bf16 v[70:73], v[10:13], v[34:37], 0
	v_mfma_f32_16x16x32_bf16 v[70:73], v[14:17], v[38:41], v[70:73]
	v_mfma_f32_16x16x32_bf16 v[78:81], v[10:13], v[42:45], 0
	v_mfma_f32_16x16x32_bf16 v[78:81], v[14:17], v[46:49], v[78:81]
	v_mfma_f32_16x16x32_bf16 v[74:77], v[2:5], v[42:45], 0
	v_mfma_f32_16x16x32_bf16 v[74:77], v[6:9], v[46:49], v[74:77]
	v_mfma_f32_16x16x32_bf16 v[82:85], v[2:5], v[50:53], 0
	v_mfma_f32_16x16x32_bf16 v[82:85], v[6:9], v[54:57], v[82:85]
	v_mfma_f32_16x16x32_bf16 v[86:89], v[10:13], v[50:53], 0
	v_mfma_f32_16x16x32_bf16 v[86:89], v[14:17], v[54:57], v[86:89]
	v_mfma_f32_16x16x32_bf16 v[94:97], v[10:13], v[58:61], 0
	v_mfma_f32_16x16x32_bf16 v[94:97], v[14:17], v[62:65], v[94:97]
	v_mfma_f32_16x16x32_bf16 v[90:93], v[2:5], v[58:61], 0
	v_mfma_f32_16x16x32_bf16 v[90:93], v[6:9], v[62:65], v[90:93]
	s_setprio 0
	s_setprio 1
	v_mfma_f32_16x16x32_bf16 v[98:101], v[18:21], v[34:37], 0
	v_mfma_f32_16x16x32_bf16 v[34:37], v[26:29], v[34:37], 0
	v_mfma_f32_16x16x32_bf16 v[102:105], v[18:21], v[42:45], 0
	v_mfma_f32_16x16x32_bf16 v[42:45], v[26:29], v[42:45], 0
	v_mfma_f32_16x16x32_bf16 v[106:109], v[18:21], v[50:53], 0
	v_mfma_f32_16x16x32_bf16 v[50:53], v[26:29], v[50:53], 0
	v_mfma_f32_16x16x32_bf16 v[110:113], v[18:21], v[58:61], 0
	v_mfma_f32_16x16x32_bf16 v[58:61], v[26:29], v[58:61], 0
	v_mfma_f32_16x16x32_bf16 v[98:101], v[22:25], v[38:41], v[98:101]
	v_mfma_f32_16x16x32_bf16 v[38:41], v[30:33], v[38:41], v[34:37]
	v_mfma_f32_16x16x32_bf16 v[102:105], v[22:25], v[46:49], v[102:105]
	v_mfma_f32_16x16x32_bf16 v[46:49], v[30:33], v[46:49], v[42:45]
	v_mfma_f32_16x16x32_bf16 v[106:109], v[22:25], v[54:57], v[106:109]
	v_mfma_f32_16x16x32_bf16 v[54:57], v[30:33], v[54:57], v[50:53]
	s_setprio 2
	s_barrier
	v_mfma_f32_16x16x32_bf16 v[110:113], v[22:25], v[62:65], v[110:113]
	v_mfma_f32_16x16x32_bf16 v[62:65], v[30:33], v[62:65], v[58:61]
	v_lshl_add_u64 v[136:137], s[36:37], 0, v[130:131]
	s_add_i32 s62, s54, s21
	v_mov_b32_e32 v135, v131
	v_lshl_add_u64 v[142:143], v[136:137], 0, s[12:13]
	s_mov_b32 m0, s62
	v_lshl_add_u64 v[244:245], s[36:37], 0, v[134:135]
	ds_read_b128 v[34:37], v141 offset:16384
	ds_read_b128 v[42:45], v141 offset:17408
	ds_read_b128 v[50:53], v141 offset:18432
	ds_read_b128 v[58:61], v141 offset:19456
	ds_read_b128 v[114:117], v141 offset:20480
	ds_read_b128 v[118:121], v141 offset:21504
	ds_read_b128 v[122:125], v141 offset:22528
	ds_read_b128 v[126:129], v141 offset:23552
	global_load_lds_dwordx4 v[142:143], off
	v_lshl_add_u64 v[142:143], v[244:245], 0, s[12:13]
	s_add_i32 m0, s62, 0x2000
	s_add_i32 s62, s55, s21
	global_load_lds_dwordx4 v[142:143], off
	s_mov_b32 m0, s62
	v_mov_b32_e32 v139, v131
	global_load_lds_dwordx4 v130, s[38:39]
	s_add_i32 m0, s62, 0x2000
	v_lshl_add_u64 v[246:247], s[34:35], 0, v[138:139]
	v_mov_b32_e32 v133, v131
	global_load_lds_dwordx4 v134, s[38:39]
	v_lshl_add_u64 v[142:143], v[246:247], 0, s[12:13]
	s_mov_b32 m0, s33
	v_lshl_add_u64 v[248:249], s[34:35], 0, v[132:133]
	global_load_lds_dwordx4 v[142:143], off
	v_lshl_add_u64 v[142:143], v[248:249], 0, s[12:13]
	s_mov_b32 m0, s44
	s_nop 0
	global_load_lds_dwordx4 v[142:143], off
	s_setprio 0
	s_waitcnt vmcnt(8)
	s_waitcnt lgkmcnt(0)
	s_barrier
	s_setprio 1
	s_waitcnt lgkmcnt(0)
	v_mfma_f32_16x16x32_bf16 v[142:145], v[2:5], v[34:37], 0
	v_mfma_f32_16x16x32_bf16 v[148:151], v[10:13], v[34:37], 0
	v_mfma_f32_16x16x32_bf16 v[152:155], v[2:5], v[50:53], 0
	v_mfma_f32_16x16x32_bf16 v[156:159], v[10:13], v[50:53], 0
	v_mfma_f32_16x16x32_bf16 v[160:163], v[2:5], v[114:117], 0
	v_mfma_f32_16x16x32_bf16 v[164:167], v[10:13], v[114:117], 0
	v_mfma_f32_16x16x32_bf16 v[2:5], v[2:5], v[122:125], 0
	v_mfma_f32_16x16x32_bf16 v[10:13], v[10:13], v[122:125], 0
	v_mfma_f32_16x16x32_bf16 v[142:145], v[6:9], v[42:45], v[142:145]
	v_mfma_f32_16x16x32_bf16 v[148:151], v[14:17], v[42:45], v[148:151]
	v_mfma_f32_16x16x32_bf16 v[152:155], v[6:9], v[58:61], v[152:155]
	v_mfma_f32_16x16x32_bf16 v[156:159], v[14:17], v[58:61], v[156:159]
	v_mfma_f32_16x16x32_bf16 v[160:163], v[6:9], v[118:121], v[160:163]
	v_mfma_f32_16x16x32_bf16 v[164:167], v[14:17], v[118:121], v[164:167]
	v_mfma_f32_16x16x32_bf16 v[168:171], v[6:9], v[126:129], v[2:5]
	v_mfma_f32_16x16x32_bf16 v[172:175], v[14:17], v[126:129], v[10:13]
	s_setprio 0
	s_setprio 1
	v_mfma_f32_16x16x32_bf16 v[2:5], v[18:21], v[34:37], 0
	v_mfma_f32_16x16x32_bf16 v[6:9], v[26:29], v[34:37], 0
	v_mfma_f32_16x16x32_bf16 v[10:13], v[18:21], v[50:53], 0
	v_mfma_f32_16x16x32_bf16 v[14:17], v[26:29], v[50:53], 0
	v_mfma_f32_16x16x32_bf16 v[34:37], v[18:21], v[114:117], 0
	v_mfma_f32_16x16x32_bf16 v[50:53], v[26:29], v[114:117], 0
	v_mfma_f32_16x16x32_bf16 v[18:21], v[18:21], v[122:125], 0
	v_mfma_f32_16x16x32_bf16 v[26:29], v[26:29], v[122:125], 0
	v_mfma_f32_16x16x32_bf16 v[114:117], v[22:25], v[42:45], v[2:5]
	v_mfma_f32_16x16x32_bf16 v[122:125], v[30:33], v[42:45], v[6:9]
	v_mfma_f32_16x16x32_bf16 v[184:187], v[22:25], v[118:121], v[34:37]
	v_mfma_f32_16x16x32_bf16 v[118:121], v[30:33], v[118:121], v[50:53]
	v_mfma_f32_16x16x32_bf16 v[188:191], v[22:25], v[126:129], v[18:21]
	v_mfma_f32_16x16x32_bf16 v[126:129], v[30:33], v[126:129], v[26:29]
	s_setprio 2
	s_barrier
	v_mfma_f32_16x16x32_bf16 v[176:179], v[22:25], v[58:61], v[10:13]
	v_mfma_f32_16x16x32_bf16 v[180:183], v[30:33], v[58:61], v[14:17]
	s_add_i32 s62, 0, 0x18000
	v_add_u32_e32 v2, s62, v140
	s_add_i32 s63, 0, 0x1c000
	ds_read_b128 v[192:195], v2
	ds_read_b128 v[196:199], v2 offset:1024
	ds_read_b128 v[200:203], v2 offset:2048
	ds_read_b128 v[204:207], v2 offset:3072
	v_add_u32_e32 v2, s63, v140
	ds_read_b128 v[208:211], v2
	ds_read_b128 v[212:215], v2 offset:1024
	ds_read_b128 v[216:219], v2 offset:2048
	ds_read_b128 v[220:223], v2 offset:3072
	s_mov_b32 m0, s45
	ds_read_b128 v[42:45], v141 offset:32768
	ds_read_b128 v[50:53], v141 offset:33792
	ds_read_b128 v[58:61], v141 offset:34816
	ds_read_b128 v[224:227], v141 offset:35840
	ds_read_b128 v[228:231], v141 offset:36864
	ds_read_b128 v[232:235], v141 offset:37888
	ds_read_b128 v[236:239], v141 offset:38912
	ds_read_b128 v[240:243], v141 offset:39936
	global_load_lds_dwordx4 v138, s[40:41]
	s_mov_b32 m0, s46
	s_nop 0
	global_load_lds_dwordx4 v132, s[40:41]
	s_setprio 0
	s_waitcnt vmcnt(8)
	s_waitcnt lgkmcnt(0)
	s_barrier
	s_setprio 1
	s_waitcnt lgkmcnt(0)
	v_mfma_f32_16x16x32_bf16 v[2:5], v[192:195], v[42:45], v[66:69]
	v_mfma_f32_16x16x32_bf16 v[6:9], v[200:203], v[42:45], v[70:73]
	v_mfma_f32_16x16x32_bf16 v[10:13], v[192:195], v[58:61], v[74:77]
	v_mfma_f32_16x16x32_bf16 v[14:17], v[200:203], v[58:61], v[78:81]
	v_mfma_f32_16x16x32_bf16 v[18:21], v[192:195], v[228:231], v[82:85]
	v_mfma_f32_16x16x32_bf16 v[22:25], v[200:203], v[228:231], v[86:89]
	v_mfma_f32_16x16x32_bf16 v[26:29], v[192:195], v[236:239], v[90:93]
	v_mfma_f32_16x16x32_bf16 v[30:33], v[200:203], v[236:239], v[94:97]
	v_mfma_f32_16x16x32_bf16 v[2:5], v[196:199], v[50:53], v[2:5]
	v_mfma_f32_16x16x32_bf16 v[6:9], v[204:207], v[50:53], v[6:9]
	v_mfma_f32_16x16x32_bf16 v[10:13], v[196:199], v[224:227], v[10:13]
	v_mfma_f32_16x16x32_bf16 v[14:17], v[204:207], v[224:227], v[14:17]
	v_mfma_f32_16x16x32_bf16 v[18:21], v[196:199], v[232:235], v[18:21]
	v_mfma_f32_16x16x32_bf16 v[22:25], v[204:207], v[232:235], v[22:25]
	v_mfma_f32_16x16x32_bf16 v[26:29], v[196:199], v[240:243], v[26:29]
	v_mfma_f32_16x16x32_bf16 v[30:33], v[204:207], v[240:243], v[30:33]
	s_setprio 0
	s_setprio 1
	v_mfma_f32_16x16x32_bf16 v[34:37], v[208:211], v[42:45], v[98:101]
	v_mfma_f32_16x16x32_bf16 v[38:41], v[216:219], v[42:45], v[38:41]
	v_mfma_f32_16x16x32_bf16 v[34:37], v[212:215], v[50:53], v[34:37]
	v_mfma_f32_16x16x32_bf16 v[38:41], v[220:223], v[50:53], v[38:41]
	v_mfma_f32_16x16x32_bf16 v[42:45], v[208:211], v[58:61], v[102:105]
	v_mfma_f32_16x16x32_bf16 v[46:49], v[216:219], v[58:61], v[46:49]
	v_mfma_f32_16x16x32_bf16 v[50:53], v[208:211], v[228:231], v[106:109]
	v_mfma_f32_16x16x32_bf16 v[54:57], v[216:219], v[228:231], v[54:57]
	v_mfma_f32_16x16x32_bf16 v[58:61], v[208:211], v[236:239], v[110:113]
	v_mfma_f32_16x16x32_bf16 v[62:65], v[216:219], v[236:239], v[62:65]
	v_mfma_f32_16x16x32_bf16 v[42:45], v[212:215], v[224:227], v[42:45]
	v_mfma_f32_16x16x32_bf16 v[46:49], v[220:223], v[224:227], v[46:49]
	v_mfma_f32_16x16x32_bf16 v[50:53], v[212:215], v[232:235], v[50:53]
	v_mfma_f32_16x16x32_bf16 v[54:57], v[220:223], v[232:235], v[54:57]
	s_setprio 2
	s_barrier
	v_mfma_f32_16x16x32_bf16 v[58:61], v[212:215], v[240:243], v[58:61]
	v_mfma_f32_16x16x32_bf16 v[62:65], v[220:223], v[240:243], v[62:65]
	s_add_i32 s62, s62, s21
	v_lshl_add_u64 v[66:67], v[136:137], 0, s[14:15]
	s_mov_b32 m0, s62
	ds_read_b128 v[102:105], v141 offset:49152
	ds_read_b128 v[106:109], v141 offset:50176
	ds_read_b128 v[110:113], v141 offset:51200
	ds_read_b128 v[224:227], v141 offset:52224
	ds_read_b128 v[228:231], v141 offset:53248
	ds_read_b128 v[232:235], v141 offset:54272
	ds_read_b128 v[236:239], v141 offset:55296
	ds_read_b128 v[240:243], v141 offset:56320
	global_load_lds_dwordx4 v[66:67], off
	v_lshl_add_u64 v[66:67], v[244:245], 0, s[14:15]
	s_add_i32 m0, s62, 0x2000
	s_add_i32 s62, s63, s21
	global_load_lds_dwordx4 v[66:67], off
	s_mov_b32 m0, s62
	v_lshl_add_u64 v[66:67], v[246:247], 0, s[14:15]
	global_load_lds_dwordx4 v130, s[42:43]
	s_add_i32 m0, s62, 0x2000
	s_nop 0
	global_load_lds_dwordx4 v134, s[42:43]
	s_mov_b32 m0, s50
	s_nop 0
	global_load_lds_dwordx4 v[66:67], off
	v_lshl_add_u64 v[66:67], v[248:249], 0, s[14:15]
	s_mov_b32 m0, s51
	s_nop 0
	global_load_lds_dwordx4 v[66:67], off
	s_setprio 0
	s_waitcnt vmcnt(8)
	s_waitcnt lgkmcnt(0)
	s_barrier
	s_setprio 1
	s_waitcnt lgkmcnt(0)
	v_mfma_f32_16x16x32_bf16 v[66:69], v[192:195], v[102:105], v[142:145]
	v_mfma_f32_16x16x32_bf16 v[70:73], v[200:203], v[102:105], v[148:151]
	v_mfma_f32_16x16x32_bf16 v[74:77], v[192:195], v[110:113], v[152:155]
	v_mfma_f32_16x16x32_bf16 v[78:81], v[200:203], v[110:113], v[156:159]
	v_mfma_f32_16x16x32_bf16 v[82:85], v[192:195], v[228:231], v[160:163]
	v_mfma_f32_16x16x32_bf16 v[86:89], v[200:203], v[228:231], v[164:167]
	v_mfma_f32_16x16x32_bf16 v[90:93], v[192:195], v[236:239], v[168:171]
	v_mfma_f32_16x16x32_bf16 v[94:97], v[200:203], v[236:239], v[172:175]
	v_mfma_f32_16x16x32_bf16 v[66:69], v[196:199], v[106:109], v[66:69]
	v_mfma_f32_16x16x32_bf16 v[70:73], v[204:207], v[106:109], v[70:73]
	v_mfma_f32_16x16x32_bf16 v[74:77], v[196:199], v[224:227], v[74:77]
	v_mfma_f32_16x16x32_bf16 v[78:81], v[204:207], v[224:227], v[78:81]
	v_mfma_f32_16x16x32_bf16 v[82:85], v[196:199], v[232:235], v[82:85]
	v_mfma_f32_16x16x32_bf16 v[86:89], v[204:207], v[232:235], v[86:89]
	v_mfma_f32_16x16x32_bf16 v[90:93], v[196:199], v[240:243], v[90:93]
	v_mfma_f32_16x16x32_bf16 v[94:97], v[204:207], v[240:243], v[94:97]
	s_setprio 0
	s_setprio 1
	v_mfma_f32_16x16x32_bf16 v[98:101], v[208:211], v[102:105], v[114:117]
	v_mfma_f32_16x16x32_bf16 v[102:105], v[216:219], v[102:105], v[122:125]
	v_mfma_f32_16x16x32_bf16 v[98:101], v[212:215], v[106:109], v[98:101]
	v_mfma_f32_16x16x32_bf16 v[102:105], v[220:223], v[106:109], v[102:105]
	v_mfma_f32_16x16x32_bf16 v[106:109], v[208:211], v[110:113], v[176:179]
	v_mfma_f32_16x16x32_bf16 v[110:113], v[216:219], v[110:113], v[180:183]
	v_mfma_f32_16x16x32_bf16 v[114:117], v[208:211], v[228:231], v[184:187]
	v_mfma_f32_16x16x32_bf16 v[118:121], v[216:219], v[228:231], v[118:121]
	v_mfma_f32_16x16x32_bf16 v[122:125], v[208:211], v[236:239], v[188:191]
	v_mfma_f32_16x16x32_bf16 v[126:129], v[216:219], v[236:239], v[126:129]
	v_mfma_f32_16x16x32_bf16 v[106:109], v[212:215], v[224:227], v[106:109]
	v_mfma_f32_16x16x32_bf16 v[110:113], v[220:223], v[224:227], v[110:113]
	v_mfma_f32_16x16x32_bf16 v[114:117], v[212:215], v[232:235], v[114:117]
	v_mfma_f32_16x16x32_bf16 v[118:121], v[220:223], v[232:235], v[118:121]
	s_setprio 2
	s_barrier
	v_mfma_f32_16x16x32_bf16 v[122:125], v[212:215], v[240:243], v[122:125]
	v_mfma_f32_16x16x32_bf16 v[126:129], v[220:223], v[240:243], v[126:129]
	s_setprio 0
	s_add_i32 s61, s61, 2
	s_cmp_ge_i32 s61, s60
	s_cbranch_scc0 .LBB0_462
	v_mov_b32_e32 v136, v130
	s_branch .LBB0_465

.LBB0_466:
	v_add_u32_e32 v133, s54, v140
	ds_read_b128 v[142:145], v133
	ds_read_b128 v[148:151], v133 offset:1024
	ds_read_b128 v[152:155], v133 offset:2048
	ds_read_b128 v[156:159], v133 offset:3072
	v_add_u32_e32 v133, s55, v140
	ds_read_b128 v[160:163], v133
	ds_read_b128 v[164:167], v133 offset:1024
	ds_read_b128 v[168:171], v133 offset:2048
	ds_read_b128 v[172:175], v133 offset:3072
	s_add_u32 s36, s34, 0xffc00080
	s_addc_u32 s37, s35, -1
	s_cmp_eq_u32 s42, 4
	s_cselect_b32 s39, s29, s37
	s_cselect_b32 s38, s28, s36
	s_cselect_b32 s37, s31, s41
	s_cselect_b32 s36, s30, s40
	s_mov_b32 m0, s52
	v_add_u32_e32 v141, 0, v1
	ds_read_b128 v[176:179], v141
	ds_read_b128 v[180:183], v141 offset:1024
	ds_read_b128 v[184:187], v141 offset:2048
	ds_read_b128 v[188:191], v141 offset:3072
	ds_read_b128 v[192:195], v141 offset:4096
	ds_read_b128 v[196:199], v141 offset:5120
	ds_read_b128 v[200:203], v141 offset:6144
	ds_read_b128 v[204:207], v141 offset:7168
	global_load_lds_dwordx4 v130, s[34:35]
	s_mov_b32 m0, s53
	v_mov_b32_e32 v133, v131
	global_load_lds_dwordx4 v132, s[34:35]
	s_waitcnt vmcnt(8)
	s_waitcnt lgkmcnt(0)
	s_barrier
	s_setprio 1
	s_waitcnt lgkmcnt(0)
	v_mfma_f32_16x16x32_bf16 v[2:5], v[142:145], v[176:179], v[2:5]
	v_mfma_f32_16x16x32_bf16 v[2:5], v[148:151], v[180:183], v[2:5]
	v_mfma_f32_16x16x32_bf16 v[6:9], v[156:159], v[180:183], v[6:9]
	v_mfma_f32_16x16x32_bf16 v[6:9], v[152:155], v[176:179], v[6:9]
	v_mfma_f32_16x16x32_bf16 v[14:17], v[152:155], v[184:187], v[14:17]
	v_mfma_f32_16x16x32_bf16 v[14:17], v[156:159], v[188:191], v[14:17]
	v_mfma_f32_16x16x32_bf16 v[10:13], v[148:151], v[188:191], v[10:13]
	v_mfma_f32_16x16x32_bf16 v[10:13], v[142:145], v[184:187], v[10:13]
	v_mfma_f32_16x16x32_bf16 v[18:21], v[142:145], v[192:195], v[18:21]
	v_mfma_f32_16x16x32_bf16 v[18:21], v[148:151], v[196:199], v[18:21]
	v_mfma_f32_16x16x32_bf16 v[22:25], v[156:159], v[196:199], v[22:25]
	v_mfma_f32_16x16x32_bf16 v[22:25], v[152:155], v[192:195], v[22:25]
	v_mfma_f32_16x16x32_bf16 v[30:33], v[152:155], v[200:203], v[30:33]
	v_mfma_f32_16x16x32_bf16 v[30:33], v[156:159], v[204:207], v[30:33]
	v_mfma_f32_16x16x32_bf16 v[26:29], v[148:151], v[204:207], v[26:29]
	v_mfma_f32_16x16x32_bf16 v[26:29], v[142:145], v[200:203], v[26:29]
	s_setprio 0
	s_setprio 1
	v_mfma_f32_16x16x32_bf16 v[34:37], v[160:163], v[176:179], v[34:37]
	v_mfma_f32_16x16x32_bf16 v[34:37], v[164:167], v[180:183], v[34:37]
	v_mfma_f32_16x16x32_bf16 v[38:41], v[172:175], v[180:183], v[38:41]
	v_mfma_f32_16x16x32_bf16 v[38:41], v[168:171], v[176:179], v[38:41]
	v_mfma_f32_16x16x32_bf16 v[46:49], v[168:171], v[184:187], v[46:49]
	v_mfma_f32_16x16x32_bf16 v[46:49], v[172:175], v[188:191], v[46:49]
	v_mfma_f32_16x16x32_bf16 v[42:45], v[164:167], v[188:191], v[42:45]
	v_mfma_f32_16x16x32_bf16 v[42:45], v[160:163], v[184:187], v[42:45]
	v_mfma_f32_16x16x32_bf16 v[50:53], v[160:163], v[192:195], v[50:53]
	v_mfma_f32_16x16x32_bf16 v[50:53], v[164:167], v[196:199], v[50:53]
	v_mfma_f32_16x16x32_bf16 v[54:57], v[172:175], v[196:199], v[54:57]
	v_mfma_f32_16x16x32_bf16 v[54:57], v[168:171], v[192:195], v[54:57]
	v_mfma_f32_16x16x32_bf16 v[62:65], v[168:171], v[200:203], v[62:65]
	v_mfma_f32_16x16x32_bf16 v[62:65], v[172:175], v[204:207], v[62:65]
	s_setprio 2
	s_barrier
	v_mfma_f32_16x16x32_bf16 v[58:61], v[164:167], v[204:207], v[58:61]
	v_mfma_f32_16x16x32_bf16 v[58:61], v[160:163], v[200:203], v[58:61]
	s_add_i32 s43, s54, s21
	s_mov_b32 m0, s43
	ds_read_b128 v[176:179], v141 offset:16384
	ds_read_b128 v[180:183], v141 offset:17408
	ds_read_b128 v[184:187], v141 offset:18432
	ds_read_b128 v[188:191], v141 offset:19456
	ds_read_b128 v[192:195], v141 offset:20480
	ds_read_b128 v[196:199], v141 offset:21504
	ds_read_b128 v[200:203], v141 offset:22528
	ds_read_b128 v[204:207], v141 offset:23552
	global_load_lds_dwordx4 v136, s[36:37]
	s_add_i32 m0, s43, 0x2000
	s_add_u32 s60, s36, 0x80000
	s_addc_u32 s61, s37, 0
	s_add_i32 s43, s55, s21
	global_load_lds_dwordx4 v134, s[36:37]
	s_mov_b32 m0, s43
	v_mov_b32_e32 v137, v131
	global_load_lds_dwordx4 v136, s[60:61]
	s_add_i32 m0, s43, 0x2000
	v_mov_b32_e32 v135, v131
	global_load_lds_dwordx4 v134, s[60:61]
	s_mov_b32 m0, s33
	v_lshl_add_u64 v[138:139], s[36:37], 0, v[136:137]
	global_load_lds_dwordx4 v130, s[38:39]
	s_mov_b32 m0, s44
	v_lshl_add_u64 v[208:209], s[36:37], 0, v[134:135]
	global_load_lds_dwordx4 v132, s[38:39]
	s_setprio 0
	s_waitcnt vmcnt(8)
	s_waitcnt lgkmcnt(0)
	v_lshl_add_u64 v[210:211], s[38:39], 0, v[130:131]
	v_lshl_add_u64 v[212:213], s[38:39], 0, v[132:133]
	s_barrier
	s_setprio 1
	s_waitcnt lgkmcnt(0)
	v_mfma_f32_16x16x32_bf16 v[66:69], v[142:145], v[176:179], v[66:69]
	v_mfma_f32_16x16x32_bf16 v[66:69], v[148:151], v[180:183], v[66:69]
	v_mfma_f32_16x16x32_bf16 v[70:73], v[156:159], v[180:183], v[70:73]
	v_mfma_f32_16x16x32_bf16 v[70:73], v[152:155], v[176:179], v[70:73]
	v_mfma_f32_16x16x32_bf16 v[78:81], v[152:155], v[184:187], v[78:81]
	v_mfma_f32_16x16x32_bf16 v[78:81], v[156:159], v[188:191], v[78:81]
	v_mfma_f32_16x16x32_bf16 v[74:77], v[148:151], v[188:191], v[74:77]
	v_mfma_f32_16x16x32_bf16 v[74:77], v[142:145], v[184:187], v[74:77]
	v_mfma_f32_16x16x32_bf16 v[82:85], v[142:145], v[192:195], v[82:85]
	v_mfma_f32_16x16x32_bf16 v[82:85], v[148:151], v[196:199], v[82:85]
	v_mfma_f32_16x16x32_bf16 v[86:89], v[156:159], v[196:199], v[86:89]
	v_mfma_f32_16x16x32_bf16 v[86:89], v[152:155], v[192:195], v[86:89]
	v_mfma_f32_16x16x32_bf16 v[94:97], v[152:155], v[200:203], v[94:97]
	v_mfma_f32_16x16x32_bf16 v[94:97], v[156:159], v[204:207], v[94:97]
	v_mfma_f32_16x16x32_bf16 v[90:93], v[148:151], v[204:207], v[90:93]
	v_mfma_f32_16x16x32_bf16 v[90:93], v[142:145], v[200:203], v[90:93]
	s_setprio 0
	s_setprio 1
	v_mfma_f32_16x16x32_bf16 v[98:101], v[160:163], v[176:179], v[98:101]
	v_mfma_f32_16x16x32_bf16 v[98:101], v[164:167], v[180:183], v[98:101]
	v_mfma_f32_16x16x32_bf16 v[102:105], v[172:175], v[180:183], v[102:105]
	v_mfma_f32_16x16x32_bf16 v[102:105], v[168:171], v[176:179], v[102:105]
	v_mfma_f32_16x16x32_bf16 v[110:113], v[168:171], v[184:187], v[110:113]
	v_mfma_f32_16x16x32_bf16 v[110:113], v[172:175], v[188:191], v[110:113]
	v_mfma_f32_16x16x32_bf16 v[106:109], v[164:167], v[188:191], v[106:109]
	v_mfma_f32_16x16x32_bf16 v[106:109], v[160:163], v[184:187], v[106:109]
	v_mfma_f32_16x16x32_bf16 v[114:117], v[160:163], v[192:195], v[114:117]
	v_mfma_f32_16x16x32_bf16 v[114:117], v[164:167], v[196:199], v[114:117]
	v_mfma_f32_16x16x32_bf16 v[118:121], v[172:175], v[196:199], v[118:121]
	v_mfma_f32_16x16x32_bf16 v[118:121], v[168:171], v[192:195], v[118:121]
	v_mfma_f32_16x16x32_bf16 v[126:129], v[168:171], v[200:203], v[126:129]
	v_mfma_f32_16x16x32_bf16 v[126:129], v[172:175], v[204:207], v[126:129]
	s_setprio 2
	s_barrier
	v_mfma_f32_16x16x32_bf16 v[122:125], v[164:167], v[204:207], v[122:125]
	v_mfma_f32_16x16x32_bf16 v[122:125], v[160:163], v[200:203], v[122:125]
	s_add_i32 s43, 0, 0x18000
	v_add_u32_e32 v135, s43, v140
	s_add_i32 s60, 0, 0x1c000
	ds_read_b128 v[142:145], v135
	ds_read_b128 v[148:151], v135 offset:1024
	ds_read_b128 v[152:155], v135 offset:2048
	ds_read_b128 v[156:159], v135 offset:3072
	v_add_u32_e32 v135, s60, v140
	ds_read_b128 v[160:163], v135
	ds_read_b128 v[164:167], v135 offset:1024
	ds_read_b128 v[168:171], v135 offset:2048
	ds_read_b128 v[172:175], v135 offset:3072
	s_add_u32 s38, s38, 0x400000
	s_addc_u32 s39, s39, 0
	s_mov_b32 m0, s45
	ds_read_b128 v[176:179], v141 offset:32768
	ds_read_b128 v[180:183], v141 offset:33792
	ds_read_b128 v[184:187], v141 offset:34816
	ds_read_b128 v[188:191], v141 offset:35840
	ds_read_b128 v[192:195], v141 offset:36864
	ds_read_b128 v[196:199], v141 offset:37888
	ds_read_b128 v[200:203], v141 offset:38912
	ds_read_b128 v[204:207], v141 offset:39936
	global_load_lds_dwordx4 v130, s[38:39]
	s_mov_b32 m0, s46
	s_nop 0
	global_load_lds_dwordx4 v132, s[38:39]
	s_setprio 0
	s_waitcnt vmcnt(8)
	s_waitcnt lgkmcnt(0)
	s_barrier
	s_setprio 1
	s_waitcnt lgkmcnt(0)
	v_mfma_f32_16x16x32_bf16 v[2:5], v[142:145], v[176:179], v[2:5]
	v_mfma_f32_16x16x32_bf16 v[2:5], v[148:151], v[180:183], v[2:5]
	v_mfma_f32_16x16x32_bf16 v[6:9], v[156:159], v[180:183], v[6:9]
	v_mfma_f32_16x16x32_bf16 v[6:9], v[152:155], v[176:179], v[6:9]
	v_mfma_f32_16x16x32_bf16 v[14:17], v[152:155], v[184:187], v[14:17]
	v_mfma_f32_16x16x32_bf16 v[14:17], v[156:159], v[188:191], v[14:17]
	v_mfma_f32_16x16x32_bf16 v[10:13], v[148:151], v[188:191], v[10:13]
	v_mfma_f32_16x16x32_bf16 v[10:13], v[142:145], v[184:187], v[10:13]
	v_mfma_f32_16x16x32_bf16 v[18:21], v[142:145], v[192:195], v[18:21]
	v_mfma_f32_16x16x32_bf16 v[18:21], v[148:151], v[196:199], v[18:21]
	v_mfma_f32_16x16x32_bf16 v[22:25], v[156:159], v[196:199], v[22:25]
	v_mfma_f32_16x16x32_bf16 v[22:25], v[152:155], v[192:195], v[22:25]
	v_mfma_f32_16x16x32_bf16 v[30:33], v[152:155], v[200:203], v[30:33]
	v_mfma_f32_16x16x32_bf16 v[30:33], v[156:159], v[204:207], v[30:33]
	v_mfma_f32_16x16x32_bf16 v[26:29], v[148:151], v[204:207], v[26:29]
	v_mfma_f32_16x16x32_bf16 v[26:29], v[142:145], v[200:203], v[26:29]
	s_setprio 0
	s_setprio 1
	v_mfma_f32_16x16x32_bf16 v[34:37], v[160:163], v[176:179], v[34:37]
	v_mfma_f32_16x16x32_bf16 v[34:37], v[164:167], v[180:183], v[34:37]
	v_mfma_f32_16x16x32_bf16 v[38:41], v[172:175], v[180:183], v[38:41]
	v_mfma_f32_16x16x32_bf16 v[38:41], v[168:171], v[176:179], v[38:41]
	v_mfma_f32_16x16x32_bf16 v[46:49], v[168:171], v[184:187], v[46:49]
	v_mfma_f32_16x16x32_bf16 v[46:49], v[172:175], v[188:191], v[46:49]
	v_mfma_f32_16x16x32_bf16 v[42:45], v[164:167], v[188:191], v[42:45]
	v_mfma_f32_16x16x32_bf16 v[42:45], v[160:163], v[184:187], v[42:45]
	v_mfma_f32_16x16x32_bf16 v[50:53], v[160:163], v[192:195], v[50:53]
	v_mfma_f32_16x16x32_bf16 v[50:53], v[164:167], v[196:199], v[50:53]
	v_mfma_f32_16x16x32_bf16 v[54:57], v[172:175], v[196:199], v[54:57]
	v_mfma_f32_16x16x32_bf16 v[54:57], v[168:171], v[192:195], v[54:57]
	v_mfma_f32_16x16x32_bf16 v[62:65], v[168:171], v[200:203], v[62:65]
	v_mfma_f32_16x16x32_bf16 v[62:65], v[172:175], v[204:207], v[62:65]
	s_setprio 2
	s_barrier
	v_mfma_f32_16x16x32_bf16 v[58:61], v[164:167], v[204:207], v[58:61]
	v_mfma_f32_16x16x32_bf16 v[58:61], v[160:163], v[200:203], v[58:61]
	s_add_i32 s38, s43, s21
	v_lshl_add_u64 v[138:139], v[138:139], 0, s[8:9]
	s_mov_b32 m0, s38
	ds_read_b128 v[176:179], v141 offset:49152
	ds_read_b128 v[180:183], v141 offset:50176
	ds_read_b128 v[184:187], v141 offset:51200
	ds_read_b128 v[188:191], v141 offset:52224
	ds_read_b128 v[192:195], v141 offset:53248
	ds_read_b128 v[196:199], v141 offset:54272
	ds_read_b128 v[200:203], v141 offset:55296
	ds_read_b128 v[204:207], v141 offset:56320
	global_load_lds_dwordx4 v[138:139], off
	s_add_i32 m0, s38, 0x2000
	s_add_u32 s36, s36, 0x80080
	v_lshl_add_u64 v[138:139], v[208:209], 0, s[8:9]
	s_addc_u32 s37, s37, 0
	s_add_i32 s38, s60, s21
	global_load_lds_dwordx4 v[138:139], off
	s_mov_b32 m0, s38
	v_lshl_add_u64 v[138:139], v[210:211], 0, s[8:9]
	global_load_lds_dwordx4 v136, s[36:37]
	s_add_i32 m0, s38, 0x2000
	s_nop 0
	global_load_lds_dwordx4 v134, s[36:37]
	s_mov_b32 m0, s50
	s_nop 0
	global_load_lds_dwordx4 v[138:139], off
	v_lshl_add_u64 v[138:139], v[212:213], 0, s[8:9]
	s_mov_b32 m0, s51
	s_nop 0
	global_load_lds_dwordx4 v[138:139], off
	s_setprio 0
	s_waitcnt vmcnt(8)
	s_waitcnt lgkmcnt(0)
	s_barrier
	s_setprio 1
	s_waitcnt lgkmcnt(0)
	v_mfma_f32_16x16x32_bf16 v[66:69], v[142:145], v[176:179], v[66:69]
	v_mfma_f32_16x16x32_bf16 v[66:69], v[148:151], v[180:183], v[66:69]
	v_mfma_f32_16x16x32_bf16 v[70:73], v[156:159], v[180:183], v[70:73]
	v_mfma_f32_16x16x32_bf16 v[70:73], v[152:155], v[176:179], v[70:73]
	v_mfma_f32_16x16x32_bf16 v[78:81], v[152:155], v[184:187], v[78:81]
	v_mfma_f32_16x16x32_bf16 v[78:81], v[156:159], v[188:191], v[78:81]
	v_mfma_f32_16x16x32_bf16 v[74:77], v[148:151], v[188:191], v[74:77]
	v_mfma_f32_16x16x32_bf16 v[74:77], v[142:145], v[184:187], v[74:77]
	v_mfma_f32_16x16x32_bf16 v[82:85], v[142:145], v[192:195], v[82:85]
	v_mfma_f32_16x16x32_bf16 v[82:85], v[148:151], v[196:199], v[82:85]
	v_mfma_f32_16x16x32_bf16 v[86:89], v[156:159], v[196:199], v[86:89]
	v_mfma_f32_16x16x32_bf16 v[86:89], v[152:155], v[192:195], v[86:89]
	v_mfma_f32_16x16x32_bf16 v[94:97], v[152:155], v[200:203], v[94:97]
	v_mfma_f32_16x16x32_bf16 v[94:97], v[156:159], v[204:207], v[94:97]
	v_mfma_f32_16x16x32_bf16 v[90:93], v[148:151], v[204:207], v[90:93]
	v_mfma_f32_16x16x32_bf16 v[90:93], v[142:145], v[200:203], v[90:93]
	s_setprio 0
	s_setprio 1
	v_mfma_f32_16x16x32_bf16 v[98:101], v[160:163], v[176:179], v[98:101]
	v_mfma_f32_16x16x32_bf16 v[98:101], v[164:167], v[180:183], v[98:101]
	v_mfma_f32_16x16x32_bf16 v[102:105], v[172:175], v[180:183], v[102:105]
	v_mfma_f32_16x16x32_bf16 v[102:105], v[168:171], v[176:179], v[102:105]
	v_mfma_f32_16x16x32_bf16 v[110:113], v[168:171], v[184:187], v[110:113]
	v_mfma_f32_16x16x32_bf16 v[110:113], v[172:175], v[188:191], v[110:113]
	v_mfma_f32_16x16x32_bf16 v[106:109], v[164:167], v[188:191], v[106:109]
	v_mfma_f32_16x16x32_bf16 v[106:109], v[160:163], v[184:187], v[106:109]
	v_mfma_f32_16x16x32_bf16 v[114:117], v[160:163], v[192:195], v[114:117]
	v_mfma_f32_16x16x32_bf16 v[114:117], v[164:167], v[196:199], v[114:117]
	v_mfma_f32_16x16x32_bf16 v[118:121], v[172:175], v[196:199], v[118:121]
	v_mfma_f32_16x16x32_bf16 v[118:121], v[168:171], v[192:195], v[118:121]
	v_mfma_f32_16x16x32_bf16 v[126:129], v[168:171], v[200:203], v[126:129]
	v_mfma_f32_16x16x32_bf16 v[126:129], v[172:175], v[204:207], v[126:129]
	s_setprio 2
	s_barrier
	v_mfma_f32_16x16x32_bf16 v[122:125], v[164:167], v[204:207], v[122:125]
	v_mfma_f32_16x16x32_bf16 v[122:125], v[160:163], v[200:203], v[122:125]
	s_setprio 0
	s_add_i32 s42, s42, 2
	s_add_u32 s34, s34, 0x100
	s_addc_u32 s35, s35, 0
	s_add_u32 s40, s40, 0x100
	s_addc_u32 s41, s41, 0
	s_cmp_gt_u32 s42, 5
	s_cbranch_scc0 .LBB0_466
	s_and_b64 vcc, exec, s[10:11]
	s_cbranch_vccz .LBB0_469
	s_barrier

.LBB0_495:
	v_add_u32_e32 v14, s58, v140
	v_add_u32_e32 v30, s59, v140
	ds_read_b128 v[2:5], v14
	ds_read_b128 v[6:9], v14 offset:1024
	ds_read_b128 v[10:13], v14 offset:2048
	ds_read_b128 v[14:17], v14 offset:3072
	ds_read_b128 v[18:21], v30
	ds_read_b128 v[22:25], v30 offset:1024
	ds_read_b128 v[26:29], v30 offset:2048
	ds_read_b128 v[30:33], v30 offset:3072
	v_add_u32_e32 v141, 0, v1
	ds_read_b128 v[34:37], v141
	ds_read_b128 v[38:41], v141 offset:1024
	ds_read_b128 v[42:45], v141 offset:2048
	ds_read_b128 v[46:49], v141 offset:3072
	ds_read_b128 v[50:53], v141 offset:4096
	ds_read_b128 v[54:57], v141 offset:5120
	ds_read_b128 v[58:61], v141 offset:6144
	ds_read_b128 v[62:65], v141 offset:7168
	s_waitcnt vmcnt(8)
	s_waitcnt lgkmcnt(0)
	s_barrier
	s_setprio 1
	s_waitcnt lgkmcnt(0)
	v_mfma_f32_16x16x32_bf16 v[66:69], v[2:5], v[34:37], 0
	v_mfma_f32_16x16x32_bf16 v[66:69], v[6:9], v[38:41], v[66:69]
	v_mfma_f32_16x16x32_bf16 v[70:73], v[10:13], v[34:37], 0
	v_mfma_f32_16x16x32_bf16 v[70:73], v[14:17], v[38:41], v[70:73]
	v_mfma_f32_16x16x32_bf16 v[78:81], v[10:13], v[42:45], 0
	v_mfma_f32_16x16x32_bf16 v[78:81], v[14:17], v[46:49], v[78:81]
	v_mfma_f32_16x16x32_bf16 v[74:77], v[2:5], v[42:45], 0
	v_mfma_f32_16x16x32_bf16 v[74:77], v[6:9], v[46:49], v[74:77]
	v_mfma_f32_16x16x32_bf16 v[82:85], v[2:5], v[50:53], 0
	v_mfma_f32_16x16x32_bf16 v[82:85], v[6:9], v[54:57], v[82:85]
	v_mfma_f32_16x16x32_bf16 v[86:89], v[10:13], v[50:53], 0
	v_mfma_f32_16x16x32_bf16 v[86:89], v[14:17], v[54:57], v[86:89]
	v_mfma_f32_16x16x32_bf16 v[94:97], v[10:13], v[58:61], 0
	v_mfma_f32_16x16x32_bf16 v[94:97], v[14:17], v[62:65], v[94:97]
	v_mfma_f32_16x16x32_bf16 v[90:93], v[2:5], v[58:61], 0
	v_mfma_f32_16x16x32_bf16 v[90:93], v[6:9], v[62:65], v[90:93]
	s_setprio 0
	s_setprio 1
	v_mfma_f32_16x16x32_bf16 v[98:101], v[18:21], v[34:37], 0
	v_mfma_f32_16x16x32_bf16 v[34:37], v[26:29], v[34:37], 0
	v_mfma_f32_16x16x32_bf16 v[102:105], v[18:21], v[42:45], 0
	v_mfma_f32_16x16x32_bf16 v[42:45], v[26:29], v[42:45], 0
	v_mfma_f32_16x16x32_bf16 v[106:109], v[18:21], v[50:53], 0
	v_mfma_f32_16x16x32_bf16 v[50:53], v[26:29], v[50:53], 0
	v_mfma_f32_16x16x32_bf16 v[110:113], v[18:21], v[58:61], 0
	v_mfma_f32_16x16x32_bf16 v[58:61], v[26:29], v[58:61], 0
	v_mfma_f32_16x16x32_bf16 v[98:101], v[22:25], v[38:41], v[98:101]
	v_mfma_f32_16x16x32_bf16 v[38:41], v[30:33], v[38:41], v[34:37]
	v_mfma_f32_16x16x32_bf16 v[102:105], v[22:25], v[46:49], v[102:105]
	v_mfma_f32_16x16x32_bf16 v[46:49], v[30:33], v[46:49], v[42:45]
	v_mfma_f32_16x16x32_bf16 v[106:109], v[22:25], v[54:57], v[106:109]
	v_mfma_f32_16x16x32_bf16 v[54:57], v[30:33], v[54:57], v[50:53]
	s_setprio 2
	s_barrier
	v_mfma_f32_16x16x32_bf16 v[110:113], v[22:25], v[62:65], v[110:113]
	v_mfma_f32_16x16x32_bf16 v[62:65], v[30:33], v[62:65], v[58:61]
	v_lshl_add_u64 v[136:137], s[38:39], 0, v[130:131]
	s_add_i32 s62, s58, s46
	v_mov_b32_e32 v135, v131
	v_lshl_add_u64 v[142:143], v[136:137], 0, s[10:11]
	s_mov_b32 m0, s62
	v_lshl_add_u64 v[244:245], s[38:39], 0, v[134:135]
	ds_read_b128 v[34:37], v141 offset:16384
	ds_read_b128 v[42:45], v141 offset:17408
	ds_read_b128 v[50:53], v141 offset:18432
	ds_read_b128 v[58:61], v141 offset:19456
	ds_read_b128 v[114:117], v141 offset:20480
	ds_read_b128 v[118:121], v141 offset:21504
	ds_read_b128 v[122:125], v141 offset:22528
	ds_read_b128 v[126:129], v141 offset:23552
	global_load_lds_dwordx4 v[142:143], off
	v_lshl_add_u64 v[142:143], v[244:245], 0, s[10:11]
	s_add_i32 m0, s62, 0x2000
	s_add_i32 s62, s59, s46
	global_load_lds_dwordx4 v[142:143], off
	s_mov_b32 m0, s62
	v_mov_b32_e32 v139, v131
	global_load_lds_dwordx4 v130, s[40:41]
	s_add_i32 m0, s62, 0x2000
	v_lshl_add_u64 v[246:247], s[36:37], 0, v[138:139]
	v_mov_b32_e32 v133, v131
	global_load_lds_dwordx4 v134, s[40:41]
	v_lshl_add_u64 v[142:143], v[246:247], 0, s[10:11]
	s_mov_b32 m0, s47
	v_lshl_add_u64 v[248:249], s[36:37], 0, v[132:133]
	global_load_lds_dwordx4 v[142:143], off
	v_lshl_add_u64 v[142:143], v[248:249], 0, s[10:11]
	s_mov_b32 m0, s48
	s_nop 0
	global_load_lds_dwordx4 v[142:143], off
	s_setprio 0
	s_waitcnt vmcnt(8)
	s_waitcnt lgkmcnt(0)
	s_barrier
	s_setprio 1
	s_waitcnt lgkmcnt(0)
	v_mfma_f32_16x16x32_bf16 v[142:145], v[2:5], v[34:37], 0
	v_mfma_f32_16x16x32_bf16 v[148:151], v[10:13], v[34:37], 0
	v_mfma_f32_16x16x32_bf16 v[152:155], v[2:5], v[50:53], 0
	v_mfma_f32_16x16x32_bf16 v[156:159], v[10:13], v[50:53], 0
	v_mfma_f32_16x16x32_bf16 v[160:163], v[2:5], v[114:117], 0
	v_mfma_f32_16x16x32_bf16 v[164:167], v[10:13], v[114:117], 0
	v_mfma_f32_16x16x32_bf16 v[2:5], v[2:5], v[122:125], 0
	v_mfma_f32_16x16x32_bf16 v[10:13], v[10:13], v[122:125], 0
	v_mfma_f32_16x16x32_bf16 v[142:145], v[6:9], v[42:45], v[142:145]
	v_mfma_f32_16x16x32_bf16 v[148:151], v[14:17], v[42:45], v[148:151]
	v_mfma_f32_16x16x32_bf16 v[152:155], v[6:9], v[58:61], v[152:155]
	v_mfma_f32_16x16x32_bf16 v[156:159], v[14:17], v[58:61], v[156:159]
	v_mfma_f32_16x16x32_bf16 v[160:163], v[6:9], v[118:121], v[160:163]
	v_mfma_f32_16x16x32_bf16 v[164:167], v[14:17], v[118:121], v[164:167]
	v_mfma_f32_16x16x32_bf16 v[168:171], v[6:9], v[126:129], v[2:5]
	v_mfma_f32_16x16x32_bf16 v[172:175], v[14:17], v[126:129], v[10:13]
	s_setprio 0
	s_setprio 1
	v_mfma_f32_16x16x32_bf16 v[2:5], v[18:21], v[34:37], 0
	v_mfma_f32_16x16x32_bf16 v[6:9], v[26:29], v[34:37], 0
	v_mfma_f32_16x16x32_bf16 v[10:13], v[18:21], v[50:53], 0
	v_mfma_f32_16x16x32_bf16 v[14:17], v[26:29], v[50:53], 0
	v_mfma_f32_16x16x32_bf16 v[34:37], v[18:21], v[114:117], 0
	v_mfma_f32_16x16x32_bf16 v[50:53], v[26:29], v[114:117], 0
	v_mfma_f32_16x16x32_bf16 v[18:21], v[18:21], v[122:125], 0
	v_mfma_f32_16x16x32_bf16 v[26:29], v[26:29], v[122:125], 0
	v_mfma_f32_16x16x32_bf16 v[114:117], v[22:25], v[42:45], v[2:5]
	v_mfma_f32_16x16x32_bf16 v[122:125], v[30:33], v[42:45], v[6:9]
	v_mfma_f32_16x16x32_bf16 v[184:187], v[22:25], v[118:121], v[34:37]
	v_mfma_f32_16x16x32_bf16 v[118:121], v[30:33], v[118:121], v[50:53]
	v_mfma_f32_16x16x32_bf16 v[188:191], v[22:25], v[126:129], v[18:21]
	v_mfma_f32_16x16x32_bf16 v[126:129], v[30:33], v[126:129], v[26:29]
	s_setprio 2
	s_barrier
	v_mfma_f32_16x16x32_bf16 v[176:179], v[22:25], v[58:61], v[10:13]
	v_mfma_f32_16x16x32_bf16 v[180:183], v[30:33], v[58:61], v[14:17]
	s_add_i32 s62, 0, 0x18000
	v_add_u32_e32 v2, s62, v140
	s_add_i32 s63, 0, 0x1c000
	ds_read_b128 v[192:195], v2
	ds_read_b128 v[196:199], v2 offset:1024
	ds_read_b128 v[200:203], v2 offset:2048
	ds_read_b128 v[204:207], v2 offset:3072
	v_add_u32_e32 v2, s63, v140
	ds_read_b128 v[208:211], v2
	ds_read_b128 v[212:215], v2 offset:1024
	ds_read_b128 v[216:219], v2 offset:2048
	ds_read_b128 v[220:223], v2 offset:3072
	s_mov_b32 m0, s49
	ds_read_b128 v[42:45], v141 offset:32768
	ds_read_b128 v[50:53], v141 offset:33792
	ds_read_b128 v[58:61], v141 offset:34816
	ds_read_b128 v[224:227], v141 offset:35840
	ds_read_b128 v[228:231], v141 offset:36864
	ds_read_b128 v[232:235], v141 offset:37888
	ds_read_b128 v[236:239], v141 offset:38912
	ds_read_b128 v[240:243], v141 offset:39936
	global_load_lds_dwordx4 v138, s[42:43]
	s_mov_b32 m0, s50
	s_nop 0
	global_load_lds_dwordx4 v132, s[42:43]
	s_setprio 0
	s_waitcnt vmcnt(8)
	s_waitcnt lgkmcnt(0)
	s_barrier
	s_setprio 1
	s_waitcnt lgkmcnt(0)
	v_mfma_f32_16x16x32_bf16 v[2:5], v[192:195], v[42:45], v[66:69]
	v_mfma_f32_16x16x32_bf16 v[6:9], v[200:203], v[42:45], v[70:73]
	v_mfma_f32_16x16x32_bf16 v[10:13], v[192:195], v[58:61], v[74:77]
	v_mfma_f32_16x16x32_bf16 v[14:17], v[200:203], v[58:61], v[78:81]
	v_mfma_f32_16x16x32_bf16 v[18:21], v[192:195], v[228:231], v[82:85]
	v_mfma_f32_16x16x32_bf16 v[22:25], v[200:203], v[228:231], v[86:89]
	v_mfma_f32_16x16x32_bf16 v[26:29], v[192:195], v[236:239], v[90:93]
	v_mfma_f32_16x16x32_bf16 v[30:33], v[200:203], v[236:239], v[94:97]
	v_mfma_f32_16x16x32_bf16 v[2:5], v[196:199], v[50:53], v[2:5]
	v_mfma_f32_16x16x32_bf16 v[6:9], v[204:207], v[50:53], v[6:9]
	v_mfma_f32_16x16x32_bf16 v[10:13], v[196:199], v[224:227], v[10:13]
	v_mfma_f32_16x16x32_bf16 v[14:17], v[204:207], v[224:227], v[14:17]
	v_mfma_f32_16x16x32_bf16 v[18:21], v[196:199], v[232:235], v[18:21]
	v_mfma_f32_16x16x32_bf16 v[22:25], v[204:207], v[232:235], v[22:25]
	v_mfma_f32_16x16x32_bf16 v[26:29], v[196:199], v[240:243], v[26:29]
	v_mfma_f32_16x16x32_bf16 v[30:33], v[204:207], v[240:243], v[30:33]
	s_setprio 0
	s_setprio 1
	v_mfma_f32_16x16x32_bf16 v[34:37], v[208:211], v[42:45], v[98:101]
	v_mfma_f32_16x16x32_bf16 v[38:41], v[216:219], v[42:45], v[38:41]
	v_mfma_f32_16x16x32_bf16 v[34:37], v[212:215], v[50:53], v[34:37]
	v_mfma_f32_16x16x32_bf16 v[38:41], v[220:223], v[50:53], v[38:41]
	v_mfma_f32_16x16x32_bf16 v[42:45], v[208:211], v[58:61], v[102:105]
	v_mfma_f32_16x16x32_bf16 v[46:49], v[216:219], v[58:61], v[46:49]
	v_mfma_f32_16x16x32_bf16 v[50:53], v[208:211], v[228:231], v[106:109]
	v_mfma_f32_16x16x32_bf16 v[54:57], v[216:219], v[228:231], v[54:57]
	v_mfma_f32_16x16x32_bf16 v[58:61], v[208:211], v[236:239], v[110:113]
	v_mfma_f32_16x16x32_bf16 v[62:65], v[216:219], v[236:239], v[62:65]
	v_mfma_f32_16x16x32_bf16 v[42:45], v[212:215], v[224:227], v[42:45]
	v_mfma_f32_16x16x32_bf16 v[46:49], v[220:223], v[224:227], v[46:49]
	v_mfma_f32_16x16x32_bf16 v[50:53], v[212:215], v[232:235], v[50:53]
	v_mfma_f32_16x16x32_bf16 v[54:57], v[220:223], v[232:235], v[54:57]
	s_setprio 2
	s_barrier
	v_mfma_f32_16x16x32_bf16 v[58:61], v[212:215], v[240:243], v[58:61]
	v_mfma_f32_16x16x32_bf16 v[62:65], v[220:223], v[240:243], v[62:65]
	s_add_i32 s62, s62, s46
	v_lshl_add_u64 v[66:67], v[136:137], 0, s[12:13]
	s_mov_b32 m0, s62
	ds_read_b128 v[102:105], v141 offset:49152
	ds_read_b128 v[106:109], v141 offset:50176
	ds_read_b128 v[110:113], v141 offset:51200
	ds_read_b128 v[224:227], v141 offset:52224
	ds_read_b128 v[228:231], v141 offset:53248
	ds_read_b128 v[232:235], v141 offset:54272
	ds_read_b128 v[236:239], v141 offset:55296
	ds_read_b128 v[240:243], v141 offset:56320
	global_load_lds_dwordx4 v[66:67], off
	v_lshl_add_u64 v[66:67], v[244:245], 0, s[12:13]
	s_add_i32 m0, s62, 0x2000
	s_add_i32 s62, s63, s46
	global_load_lds_dwordx4 v[66:67], off
	s_mov_b32 m0, s62
	v_lshl_add_u64 v[66:67], v[246:247], 0, s[12:13]
	global_load_lds_dwordx4 v130, s[44:45]
	s_add_i32 m0, s62, 0x2000
	s_nop 0
	global_load_lds_dwordx4 v134, s[44:45]
	s_mov_b32 m0, s54
	s_nop 0
	global_load_lds_dwordx4 v[66:67], off
	v_lshl_add_u64 v[66:67], v[248:249], 0, s[12:13]
	s_mov_b32 m0, s55
	s_nop 0
	global_load_lds_dwordx4 v[66:67], off
	s_setprio 0
	s_waitcnt vmcnt(8)
	s_waitcnt lgkmcnt(0)
	s_barrier
	s_setprio 1
	s_waitcnt lgkmcnt(0)
	v_mfma_f32_16x16x32_bf16 v[66:69], v[192:195], v[102:105], v[142:145]
	v_mfma_f32_16x16x32_bf16 v[70:73], v[200:203], v[102:105], v[148:151]
	v_mfma_f32_16x16x32_bf16 v[74:77], v[192:195], v[110:113], v[152:155]
	v_mfma_f32_16x16x32_bf16 v[78:81], v[200:203], v[110:113], v[156:159]
	v_mfma_f32_16x16x32_bf16 v[82:85], v[192:195], v[228:231], v[160:163]
	v_mfma_f32_16x16x32_bf16 v[86:89], v[200:203], v[228:231], v[164:167]
	v_mfma_f32_16x16x32_bf16 v[90:93], v[192:195], v[236:239], v[168:171]
	v_mfma_f32_16x16x32_bf16 v[94:97], v[200:203], v[236:239], v[172:175]
	v_mfma_f32_16x16x32_bf16 v[66:69], v[196:199], v[106:109], v[66:69]
	v_mfma_f32_16x16x32_bf16 v[70:73], v[204:207], v[106:109], v[70:73]
	v_mfma_f32_16x16x32_bf16 v[74:77], v[196:199], v[224:227], v[74:77]
	v_mfma_f32_16x16x32_bf16 v[78:81], v[204:207], v[224:227], v[78:81]
	v_mfma_f32_16x16x32_bf16 v[82:85], v[196:199], v[232:235], v[82:85]
	v_mfma_f32_16x16x32_bf16 v[86:89], v[204:207], v[232:235], v[86:89]
	v_mfma_f32_16x16x32_bf16 v[90:93], v[196:199], v[240:243], v[90:93]
	v_mfma_f32_16x16x32_bf16 v[94:97], v[204:207], v[240:243], v[94:97]
	s_setprio 0
	s_setprio 1
	v_mfma_f32_16x16x32_bf16 v[98:101], v[208:211], v[102:105], v[114:117]
	v_mfma_f32_16x16x32_bf16 v[102:105], v[216:219], v[102:105], v[122:125]
	v_mfma_f32_16x16x32_bf16 v[98:101], v[212:215], v[106:109], v[98:101]
	v_mfma_f32_16x16x32_bf16 v[102:105], v[220:223], v[106:109], v[102:105]
	v_mfma_f32_16x16x32_bf16 v[106:109], v[208:211], v[110:113], v[176:179]
	v_mfma_f32_16x16x32_bf16 v[110:113], v[216:219], v[110:113], v[180:183]
	v_mfma_f32_16x16x32_bf16 v[114:117], v[208:211], v[228:231], v[184:187]
	v_mfma_f32_16x16x32_bf16 v[118:121], v[216:219], v[228:231], v[118:121]
	v_mfma_f32_16x16x32_bf16 v[122:125], v[208:211], v[236:239], v[188:191]
	v_mfma_f32_16x16x32_bf16 v[126:129], v[216:219], v[236:239], v[126:129]
	v_mfma_f32_16x16x32_bf16 v[106:109], v[212:215], v[224:227], v[106:109]
	v_mfma_f32_16x16x32_bf16 v[110:113], v[220:223], v[224:227], v[110:113]
	v_mfma_f32_16x16x32_bf16 v[114:117], v[212:215], v[232:235], v[114:117]
	v_mfma_f32_16x16x32_bf16 v[118:121], v[220:223], v[232:235], v[118:121]
	s_setprio 2
	s_barrier
	v_mfma_f32_16x16x32_bf16 v[122:125], v[212:215], v[240:243], v[122:125]
	v_mfma_f32_16x16x32_bf16 v[126:129], v[220:223], v[240:243], v[126:129]
	s_setprio 0
	s_add_i32 s27, s27, 2
	s_cmp_ge_i32 s27, s15
	s_cbranch_scc0 .LBB0_495
	v_mov_b32_e32 v136, v130
	s_branch .LBB0_498

.LBB0_499:
	v_add_u32_e32 v133, s58, v140
	ds_read_b128 v[142:145], v133
	ds_read_b128 v[148:151], v133 offset:1024
	ds_read_b128 v[152:155], v133 offset:2048
	ds_read_b128 v[156:159], v133 offset:3072
	v_add_u32_e32 v133, s59, v140
	ds_read_b128 v[160:163], v133
	ds_read_b128 v[164:167], v133 offset:1024
	ds_read_b128 v[168:171], v133 offset:2048
	ds_read_b128 v[172:175], v133 offset:3072
	s_add_u32 s38, s36, 0xfff80080
	s_addc_u32 s39, s37, -1
	s_cmp_eq_u32 s42, 4
	s_cselect_b32 s41, s31, s39
	s_cselect_b32 s40, s30, s38
	s_cselect_b32 s39, s35, s27
	s_cselect_b32 s38, s34, s15
	s_mov_b32 m0, s56
	v_add_u32_e32 v141, 0, v1
	ds_read_b128 v[176:179], v141
	ds_read_b128 v[180:183], v141 offset:1024
	ds_read_b128 v[184:187], v141 offset:2048
	ds_read_b128 v[188:191], v141 offset:3072
	ds_read_b128 v[192:195], v141 offset:4096
	ds_read_b128 v[196:199], v141 offset:5120
	ds_read_b128 v[200:203], v141 offset:6144
	ds_read_b128 v[204:207], v141 offset:7168
	global_load_lds_dwordx4 v130, s[36:37]
	s_mov_b32 m0, s57
	v_mov_b32_e32 v133, v131
	global_load_lds_dwordx4 v132, s[36:37]
	s_waitcnt vmcnt(8)
	s_waitcnt lgkmcnt(0)
	s_barrier
	s_setprio 1
	s_waitcnt lgkmcnt(0)
	v_mfma_f32_16x16x32_bf16 v[2:5], v[142:145], v[176:179], v[2:5]
	v_mfma_f32_16x16x32_bf16 v[2:5], v[148:151], v[180:183], v[2:5]
	v_mfma_f32_16x16x32_bf16 v[6:9], v[156:159], v[180:183], v[6:9]
	v_mfma_f32_16x16x32_bf16 v[6:9], v[152:155], v[176:179], v[6:9]
	v_mfma_f32_16x16x32_bf16 v[14:17], v[152:155], v[184:187], v[14:17]
	v_mfma_f32_16x16x32_bf16 v[14:17], v[156:159], v[188:191], v[14:17]
	v_mfma_f32_16x16x32_bf16 v[10:13], v[148:151], v[188:191], v[10:13]
	v_mfma_f32_16x16x32_bf16 v[10:13], v[142:145], v[184:187], v[10:13]
	v_mfma_f32_16x16x32_bf16 v[18:21], v[142:145], v[192:195], v[18:21]
	v_mfma_f32_16x16x32_bf16 v[18:21], v[148:151], v[196:199], v[18:21]
	v_mfma_f32_16x16x32_bf16 v[22:25], v[156:159], v[196:199], v[22:25]
	v_mfma_f32_16x16x32_bf16 v[22:25], v[152:155], v[192:195], v[22:25]
	v_mfma_f32_16x16x32_bf16 v[30:33], v[152:155], v[200:203], v[30:33]
	v_mfma_f32_16x16x32_bf16 v[30:33], v[156:159], v[204:207], v[30:33]
	v_mfma_f32_16x16x32_bf16 v[26:29], v[148:151], v[204:207], v[26:29]
	v_mfma_f32_16x16x32_bf16 v[26:29], v[142:145], v[200:203], v[26:29]
	s_setprio 0
	s_setprio 1
	v_mfma_f32_16x16x32_bf16 v[34:37], v[160:163], v[176:179], v[34:37]
	v_mfma_f32_16x16x32_bf16 v[34:37], v[164:167], v[180:183], v[34:37]
	v_mfma_f32_16x16x32_bf16 v[38:41], v[172:175], v[180:183], v[38:41]
	v_mfma_f32_16x16x32_bf16 v[38:41], v[168:171], v[176:179], v[38:41]
	v_mfma_f32_16x16x32_bf16 v[46:49], v[168:171], v[184:187], v[46:49]
	v_mfma_f32_16x16x32_bf16 v[46:49], v[172:175], v[188:191], v[46:49]
	v_mfma_f32_16x16x32_bf16 v[42:45], v[164:167], v[188:191], v[42:45]
	v_mfma_f32_16x16x32_bf16 v[42:45], v[160:163], v[184:187], v[42:45]
	v_mfma_f32_16x16x32_bf16 v[50:53], v[160:163], v[192:195], v[50:53]
	v_mfma_f32_16x16x32_bf16 v[50:53], v[164:167], v[196:199], v[50:53]
	v_mfma_f32_16x16x32_bf16 v[54:57], v[172:175], v[196:199], v[54:57]
	v_mfma_f32_16x16x32_bf16 v[54:57], v[168:171], v[192:195], v[54:57]
	v_mfma_f32_16x16x32_bf16 v[62:65], v[168:171], v[200:203], v[62:65]
	v_mfma_f32_16x16x32_bf16 v[62:65], v[172:175], v[204:207], v[62:65]
	s_setprio 2
	s_barrier
	v_mfma_f32_16x16x32_bf16 v[58:61], v[164:167], v[204:207], v[58:61]
	v_mfma_f32_16x16x32_bf16 v[58:61], v[160:163], v[200:203], v[58:61]
	s_add_i32 s43, s58, s46
	s_mov_b32 m0, s43
	ds_read_b128 v[176:179], v141 offset:16384
	ds_read_b128 v[180:183], v141 offset:17408
	ds_read_b128 v[184:187], v141 offset:18432
	ds_read_b128 v[188:191], v141 offset:19456
	ds_read_b128 v[192:195], v141 offset:20480
	ds_read_b128 v[196:199], v141 offset:21504
	ds_read_b128 v[200:203], v141 offset:22528
	ds_read_b128 v[204:207], v141 offset:23552
	global_load_lds_dwordx4 v136, s[38:39]
	s_add_i32 m0, s43, 0x2000
	s_add_u32 s44, s38, 0x400000
	s_addc_u32 s45, s39, 0
	s_add_i32 s43, s59, s46
	global_load_lds_dwordx4 v134, s[38:39]
	s_mov_b32 m0, s43
	v_mov_b32_e32 v137, v131
	global_load_lds_dwordx4 v136, s[44:45]
	s_add_i32 m0, s43, 0x2000
	v_mov_b32_e32 v135, v131
	global_load_lds_dwordx4 v134, s[44:45]
	s_mov_b32 m0, s47
	v_lshl_add_u64 v[138:139], s[38:39], 0, v[136:137]
	global_load_lds_dwordx4 v130, s[40:41]
	s_mov_b32 m0, s48
	v_lshl_add_u64 v[208:209], s[38:39], 0, v[134:135]
	global_load_lds_dwordx4 v132, s[40:41]
	s_setprio 0
	s_waitcnt vmcnt(8)
	s_waitcnt lgkmcnt(0)
	v_lshl_add_u64 v[210:211], s[40:41], 0, v[130:131]
	v_lshl_add_u64 v[212:213], s[40:41], 0, v[132:133]
	s_barrier
	s_setprio 1
	s_waitcnt lgkmcnt(0)
	v_mfma_f32_16x16x32_bf16 v[66:69], v[142:145], v[176:179], v[66:69]
	v_mfma_f32_16x16x32_bf16 v[66:69], v[148:151], v[180:183], v[66:69]
	v_mfma_f32_16x16x32_bf16 v[70:73], v[156:159], v[180:183], v[70:73]
	v_mfma_f32_16x16x32_bf16 v[70:73], v[152:155], v[176:179], v[70:73]
	v_mfma_f32_16x16x32_bf16 v[78:81], v[152:155], v[184:187], v[78:81]
	v_mfma_f32_16x16x32_bf16 v[78:81], v[156:159], v[188:191], v[78:81]
	v_mfma_f32_16x16x32_bf16 v[74:77], v[148:151], v[188:191], v[74:77]
	v_mfma_f32_16x16x32_bf16 v[74:77], v[142:145], v[184:187], v[74:77]
	v_mfma_f32_16x16x32_bf16 v[82:85], v[142:145], v[192:195], v[82:85]
	v_mfma_f32_16x16x32_bf16 v[82:85], v[148:151], v[196:199], v[82:85]
	v_mfma_f32_16x16x32_bf16 v[86:89], v[156:159], v[196:199], v[86:89]
	v_mfma_f32_16x16x32_bf16 v[86:89], v[152:155], v[192:195], v[86:89]
	v_mfma_f32_16x16x32_bf16 v[94:97], v[152:155], v[200:203], v[94:97]
	v_mfma_f32_16x16x32_bf16 v[94:97], v[156:159], v[204:207], v[94:97]
	v_mfma_f32_16x16x32_bf16 v[90:93], v[148:151], v[204:207], v[90:93]
	v_mfma_f32_16x16x32_bf16 v[90:93], v[142:145], v[200:203], v[90:93]
	s_setprio 0
	s_setprio 1
	v_mfma_f32_16x16x32_bf16 v[98:101], v[160:163], v[176:179], v[98:101]
	v_mfma_f32_16x16x32_bf16 v[98:101], v[164:167], v[180:183], v[98:101]
	v_mfma_f32_16x16x32_bf16 v[102:105], v[172:175], v[180:183], v[102:105]
	v_mfma_f32_16x16x32_bf16 v[102:105], v[168:171], v[176:179], v[102:105]
	v_mfma_f32_16x16x32_bf16 v[110:113], v[168:171], v[184:187], v[110:113]
	v_mfma_f32_16x16x32_bf16 v[110:113], v[172:175], v[188:191], v[110:113]
	v_mfma_f32_16x16x32_bf16 v[106:109], v[164:167], v[188:191], v[106:109]
	v_mfma_f32_16x16x32_bf16 v[106:109], v[160:163], v[184:187], v[106:109]
	v_mfma_f32_16x16x32_bf16 v[114:117], v[160:163], v[192:195], v[114:117]
	v_mfma_f32_16x16x32_bf16 v[114:117], v[164:167], v[196:199], v[114:117]
	v_mfma_f32_16x16x32_bf16 v[118:121], v[172:175], v[196:199], v[118:121]
	v_mfma_f32_16x16x32_bf16 v[118:121], v[168:171], v[192:195], v[118:121]
	v_mfma_f32_16x16x32_bf16 v[126:129], v[168:171], v[200:203], v[126:129]
	v_mfma_f32_16x16x32_bf16 v[126:129], v[172:175], v[204:207], v[126:129]
	s_setprio 2
	s_barrier
	v_mfma_f32_16x16x32_bf16 v[122:125], v[164:167], v[204:207], v[122:125]
	v_mfma_f32_16x16x32_bf16 v[122:125], v[160:163], v[200:203], v[122:125]
	s_add_i32 s43, 0, 0x18000
	v_add_u32_e32 v135, s43, v140
	s_add_i32 s44, 0, 0x1c000
	ds_read_b128 v[142:145], v135
	ds_read_b128 v[148:151], v135 offset:1024
	ds_read_b128 v[152:155], v135 offset:2048
	ds_read_b128 v[156:159], v135 offset:3072
	v_add_u32_e32 v135, s44, v140
	ds_read_b128 v[160:163], v135
	ds_read_b128 v[164:167], v135 offset:1024
	ds_read_b128 v[168:171], v135 offset:2048
	ds_read_b128 v[172:175], v135 offset:3072
	s_add_u32 s40, s40, 0x80000
	s_addc_u32 s41, s41, 0
	s_mov_b32 m0, s49
	ds_read_b128 v[176:179], v141 offset:32768
	ds_read_b128 v[180:183], v141 offset:33792
	ds_read_b128 v[184:187], v141 offset:34816
	ds_read_b128 v[188:191], v141 offset:35840
	ds_read_b128 v[192:195], v141 offset:36864
	ds_read_b128 v[196:199], v141 offset:37888
	ds_read_b128 v[200:203], v141 offset:38912
	ds_read_b128 v[204:207], v141 offset:39936
	global_load_lds_dwordx4 v130, s[40:41]
	s_mov_b32 m0, s50
	s_nop 0
	global_load_lds_dwordx4 v132, s[40:41]
	s_setprio 0
	s_waitcnt vmcnt(8)
	s_waitcnt lgkmcnt(0)
	s_barrier
	s_setprio 1
	s_waitcnt lgkmcnt(0)
	v_mfma_f32_16x16x32_bf16 v[2:5], v[142:145], v[176:179], v[2:5]
	v_mfma_f32_16x16x32_bf16 v[2:5], v[148:151], v[180:183], v[2:5]
	v_mfma_f32_16x16x32_bf16 v[6:9], v[156:159], v[180:183], v[6:9]
	v_mfma_f32_16x16x32_bf16 v[6:9], v[152:155], v[176:179], v[6:9]
	v_mfma_f32_16x16x32_bf16 v[14:17], v[152:155], v[184:187], v[14:17]
	v_mfma_f32_16x16x32_bf16 v[14:17], v[156:159], v[188:191], v[14:17]
	v_mfma_f32_16x16x32_bf16 v[10:13], v[148:151], v[188:191], v[10:13]
	v_mfma_f32_16x16x32_bf16 v[10:13], v[142:145], v[184:187], v[10:13]
	v_mfma_f32_16x16x32_bf16 v[18:21], v[142:145], v[192:195], v[18:21]
	v_mfma_f32_16x16x32_bf16 v[18:21], v[148:151], v[196:199], v[18:21]
	v_mfma_f32_16x16x32_bf16 v[22:25], v[156:159], v[196:199], v[22:25]
	v_mfma_f32_16x16x32_bf16 v[22:25], v[152:155], v[192:195], v[22:25]
	v_mfma_f32_16x16x32_bf16 v[30:33], v[152:155], v[200:203], v[30:33]
	v_mfma_f32_16x16x32_bf16 v[30:33], v[156:159], v[204:207], v[30:33]
	v_mfma_f32_16x16x32_bf16 v[26:29], v[148:151], v[204:207], v[26:29]
	v_mfma_f32_16x16x32_bf16 v[26:29], v[142:145], v[200:203], v[26:29]
	s_setprio 0
	s_setprio 1
	v_mfma_f32_16x16x32_bf16 v[34:37], v[160:163], v[176:179], v[34:37]
	v_mfma_f32_16x16x32_bf16 v[34:37], v[164:167], v[180:183], v[34:37]
	v_mfma_f32_16x16x32_bf16 v[38:41], v[172:175], v[180:183], v[38:41]
	v_mfma_f32_16x16x32_bf16 v[38:41], v[168:171], v[176:179], v[38:41]
	v_mfma_f32_16x16x32_bf16 v[46:49], v[168:171], v[184:187], v[46:49]
	v_mfma_f32_16x16x32_bf16 v[46:49], v[172:175], v[188:191], v[46:49]
	v_mfma_f32_16x16x32_bf16 v[42:45], v[164:167], v[188:191], v[42:45]
	v_mfma_f32_16x16x32_bf16 v[42:45], v[160:163], v[184:187], v[42:45]
	v_mfma_f32_16x16x32_bf16 v[50:53], v[160:163], v[192:195], v[50:53]
	v_mfma_f32_16x16x32_bf16 v[50:53], v[164:167], v[196:199], v[50:53]
	v_mfma_f32_16x16x32_bf16 v[54:57], v[172:175], v[196:199], v[54:57]
	v_mfma_f32_16x16x32_bf16 v[54:57], v[168:171], v[192:195], v[54:57]
	v_mfma_f32_16x16x32_bf16 v[62:65], v[168:171], v[200:203], v[62:65]
	v_mfma_f32_16x16x32_bf16 v[62:65], v[172:175], v[204:207], v[62:65]
	s_setprio 2
	s_barrier
	v_mfma_f32_16x16x32_bf16 v[58:61], v[164:167], v[204:207], v[58:61]
	v_mfma_f32_16x16x32_bf16 v[58:61], v[160:163], v[200:203], v[58:61]
	s_add_i32 s40, s43, s46
	v_lshl_add_u64 v[138:139], v[138:139], 0, s[6:7]
	s_mov_b32 m0, s40
	ds_read_b128 v[176:179], v141 offset:49152
	ds_read_b128 v[180:183], v141 offset:50176
	ds_read_b128 v[184:187], v141 offset:51200
	ds_read_b128 v[188:191], v141 offset:52224
	ds_read_b128 v[192:195], v141 offset:53248
	ds_read_b128 v[196:199], v141 offset:54272
	ds_read_b128 v[200:203], v141 offset:55296
	ds_read_b128 v[204:207], v141 offset:56320
	global_load_lds_dwordx4 v[138:139], off
	s_add_i32 m0, s40, 0x2000
	s_add_u32 s38, s38, 0x400080
	v_lshl_add_u64 v[138:139], v[208:209], 0, s[6:7]
	s_addc_u32 s39, s39, 0
	s_add_i32 s40, s44, s46
	global_load_lds_dwordx4 v[138:139], off
	s_mov_b32 m0, s40
	v_lshl_add_u64 v[138:139], v[210:211], 0, s[6:7]
	global_load_lds_dwordx4 v136, s[38:39]
	s_add_i32 m0, s40, 0x2000
	s_nop 0
	global_load_lds_dwordx4 v134, s[38:39]
	s_mov_b32 m0, s54
	s_nop 0
	global_load_lds_dwordx4 v[138:139], off
	v_lshl_add_u64 v[138:139], v[212:213], 0, s[6:7]
	s_mov_b32 m0, s55
	s_nop 0
	global_load_lds_dwordx4 v[138:139], off
	s_setprio 0
	s_waitcnt vmcnt(8)
	s_waitcnt lgkmcnt(0)
	s_barrier
	s_setprio 1
	s_waitcnt lgkmcnt(0)
	v_mfma_f32_16x16x32_bf16 v[66:69], v[142:145], v[176:179], v[66:69]
	v_mfma_f32_16x16x32_bf16 v[66:69], v[148:151], v[180:183], v[66:69]
	v_mfma_f32_16x16x32_bf16 v[70:73], v[156:159], v[180:183], v[70:73]
	v_mfma_f32_16x16x32_bf16 v[70:73], v[152:155], v[176:179], v[70:73]
	v_mfma_f32_16x16x32_bf16 v[78:81], v[152:155], v[184:187], v[78:81]
	v_mfma_f32_16x16x32_bf16 v[78:81], v[156:159], v[188:191], v[78:81]
	v_mfma_f32_16x16x32_bf16 v[74:77], v[148:151], v[188:191], v[74:77]
	v_mfma_f32_16x16x32_bf16 v[74:77], v[142:145], v[184:187], v[74:77]
	v_mfma_f32_16x16x32_bf16 v[82:85], v[142:145], v[192:195], v[82:85]
	v_mfma_f32_16x16x32_bf16 v[82:85], v[148:151], v[196:199], v[82:85]
	v_mfma_f32_16x16x32_bf16 v[86:89], v[156:159], v[196:199], v[86:89]
	v_mfma_f32_16x16x32_bf16 v[86:89], v[152:155], v[192:195], v[86:89]
	v_mfma_f32_16x16x32_bf16 v[94:97], v[152:155], v[200:203], v[94:97]
	v_mfma_f32_16x16x32_bf16 v[94:97], v[156:159], v[204:207], v[94:97]
	v_mfma_f32_16x16x32_bf16 v[90:93], v[148:151], v[204:207], v[90:93]
	v_mfma_f32_16x16x32_bf16 v[90:93], v[142:145], v[200:203], v[90:93]
	s_setprio 0
	s_setprio 1
	v_mfma_f32_16x16x32_bf16 v[98:101], v[160:163], v[176:179], v[98:101]
	v_mfma_f32_16x16x32_bf16 v[98:101], v[164:167], v[180:183], v[98:101]
	v_mfma_f32_16x16x32_bf16 v[102:105], v[172:175], v[180:183], v[102:105]
	v_mfma_f32_16x16x32_bf16 v[102:105], v[168:171], v[176:179], v[102:105]
	v_mfma_f32_16x16x32_bf16 v[110:113], v[168:171], v[184:187], v[110:113]
	v_mfma_f32_16x16x32_bf16 v[110:113], v[172:175], v[188:191], v[110:113]
	v_mfma_f32_16x16x32_bf16 v[106:109], v[164:167], v[188:191], v[106:109]
	v_mfma_f32_16x16x32_bf16 v[106:109], v[160:163], v[184:187], v[106:109]
	v_mfma_f32_16x16x32_bf16 v[114:117], v[160:163], v[192:195], v[114:117]
	v_mfma_f32_16x16x32_bf16 v[114:117], v[164:167], v[196:199], v[114:117]
	v_mfma_f32_16x16x32_bf16 v[118:121], v[172:175], v[196:199], v[118:121]
	v_mfma_f32_16x16x32_bf16 v[118:121], v[168:171], v[192:195], v[118:121]
	v_mfma_f32_16x16x32_bf16 v[126:129], v[168:171], v[200:203], v[126:129]
	v_mfma_f32_16x16x32_bf16 v[126:129], v[172:175], v[204:207], v[126:129]
	s_setprio 2
	s_barrier
	v_mfma_f32_16x16x32_bf16 v[122:125], v[164:167], v[204:207], v[122:125]
	v_mfma_f32_16x16x32_bf16 v[122:125], v[160:163], v[200:203], v[122:125]
	s_setprio 0
	s_add_i32 s42, s42, 2
	s_add_u32 s36, s36, 0x100
	s_addc_u32 s37, s37, 0
	s_add_u32 s15, s15, 0x100
	s_addc_u32 s27, s27, 0
	s_cmp_gt_u32 s42, 5
	s_cbranch_scc0 .LBB0_499
	s_and_b64 vcc, exec, s[8:9]
	s_cbranch_vccz .LBB0_502
	s_barrier

.LBB0_528:
	s_add_i32 s53, 0, 0x10000
	s_add_i32 s72, 0, 0x14000
	v_add_u32_e32 v16, s53, v147
	v_add_u32_e32 v32, s72, v147
	ds_read_b128 v[4:7], v16
	ds_read_b128 v[8:11], v16 offset:1024
	ds_read_b128 v[12:15], v16 offset:2048
	ds_read_b128 v[16:19], v16 offset:3072
	ds_read_b128 v[20:23], v32
	ds_read_b128 v[24:27], v32 offset:1024
	ds_read_b128 v[28:31], v32 offset:2048
	ds_read_b128 v[32:35], v32 offset:3072
	v_add_u32_e32 v231, 0, v146
	ds_read_b128 v[36:39], v231
	ds_read_b128 v[40:43], v231 offset:1024
	ds_read_b128 v[44:47], v231 offset:2048
	ds_read_b128 v[48:51], v231 offset:3072
	ds_read_b128 v[52:55], v231 offset:4096
	ds_read_b128 v[56:59], v231 offset:5120
	ds_read_b128 v[60:63], v231 offset:6144
	ds_read_b128 v[64:67], v231 offset:7168
	s_waitcnt vmcnt(8)
	s_waitcnt lgkmcnt(0)
	s_barrier
	s_setprio 1
	s_waitcnt lgkmcnt(0)
	v_mfma_f32_16x16x32_f16 v[68:71], v[4:7], v[36:39], 0
	v_mfma_f32_16x16x32_f16 v[68:71], v[8:11], v[40:43], v[68:71]
	v_mfma_f32_16x16x32_f16 v[72:75], v[12:15], v[36:39], 0
	v_mfma_f32_16x16x32_f16 v[72:75], v[16:19], v[40:43], v[72:75]
	v_mfma_f32_16x16x32_f16 v[80:83], v[12:15], v[44:47], 0
	v_mfma_f32_16x16x32_f16 v[80:83], v[16:19], v[48:51], v[80:83]
	v_mfma_f32_16x16x32_f16 v[76:79], v[4:7], v[44:47], 0
	v_mfma_f32_16x16x32_f16 v[76:79], v[8:11], v[48:51], v[76:79]
	v_mfma_f32_16x16x32_f16 v[84:87], v[4:7], v[52:55], 0
	v_mfma_f32_16x16x32_f16 v[84:87], v[8:11], v[56:59], v[84:87]
	v_mfma_f32_16x16x32_f16 v[88:91], v[12:15], v[52:55], 0
	v_mfma_f32_16x16x32_f16 v[88:91], v[16:19], v[56:59], v[88:91]
	v_mfma_f32_16x16x32_f16 v[96:99], v[12:15], v[60:63], 0
	v_mfma_f32_16x16x32_f16 v[96:99], v[16:19], v[64:67], v[96:99]
	v_mfma_f32_16x16x32_f16 v[92:95], v[4:7], v[60:63], 0
	v_mfma_f32_16x16x32_f16 v[92:95], v[8:11], v[64:67], v[92:95]
	s_setprio 0
	s_setprio 1
	v_mfma_f32_16x16x32_f16 v[100:103], v[20:23], v[36:39], 0
	v_mfma_f32_16x16x32_f16 v[36:39], v[28:31], v[36:39], 0
	v_mfma_f32_16x16x32_f16 v[104:107], v[20:23], v[44:47], 0
	v_mfma_f32_16x16x32_f16 v[44:47], v[28:31], v[44:47], 0
	v_mfma_f32_16x16x32_f16 v[108:111], v[20:23], v[52:55], 0
	v_mfma_f32_16x16x32_f16 v[52:55], v[28:31], v[52:55], 0
	v_mfma_f32_16x16x32_f16 v[112:115], v[20:23], v[60:63], 0
	v_mfma_f32_16x16x32_f16 v[60:63], v[28:31], v[60:63], 0
	v_mfma_f32_16x16x32_f16 v[100:103], v[24:27], v[40:43], v[100:103]
	v_mfma_f32_16x16x32_f16 v[40:43], v[32:35], v[40:43], v[36:39]
	v_mfma_f32_16x16x32_f16 v[104:107], v[24:27], v[48:51], v[104:107]
	v_mfma_f32_16x16x32_f16 v[48:51], v[32:35], v[48:51], v[44:47]
	v_mfma_f32_16x16x32_f16 v[108:111], v[24:27], v[56:59], v[108:111]
	v_mfma_f32_16x16x32_f16 v[56:59], v[32:35], v[56:59], v[52:55]
	s_setprio 2
	s_barrier
	v_mfma_f32_16x16x32_f16 v[112:115], v[24:27], v[64:67], v[112:115]
	v_mfma_f32_16x16x32_f16 v[64:67], v[32:35], v[64:67], v[60:63]
	v_lshl_add_u64 v[136:137], s[6:7], 0, v[2:3]
	s_add_i32 s53, s53, s38
	v_mov_b32_e32 v135, v3
	v_lshl_add_u64 v[140:141], v[136:137], 0, s[74:75]
	s_mov_b32 m0, s53
	v_lshl_add_u64 v[144:145], s[6:7], 0, v[134:135]
	ds_read_b128 v[36:39], v231 offset:16384
	ds_read_b128 v[44:47], v231 offset:17408
	ds_read_b128 v[52:55], v231 offset:18432
	ds_read_b128 v[60:63], v231 offset:19456
	ds_read_b128 v[116:119], v231 offset:20480
	ds_read_b128 v[120:123], v231 offset:21504
	ds_read_b128 v[124:127], v231 offset:22528
	ds_read_b128 v[128:131], v231 offset:23552
	global_load_lds_dwordx4 v[140:141], off
	v_lshl_add_u64 v[140:141], v[144:145], 0, s[74:75]
	s_add_i32 m0, s53, 0x2000
	s_add_i32 s53, s72, s38
	global_load_lds_dwordx4 v[140:141], off
	s_mov_b32 m0, s53
	v_mov_b32_e32 v139, v3
	global_load_lds_dwordx4 v2, s[16:17]
	s_add_i32 m0, s53, 0x2000
	v_lshl_add_u64 v[248:249], s[8:9], 0, v[138:139]
	v_mov_b32_e32 v133, v3
	global_load_lds_dwordx4 v134, s[16:17]
	v_lshl_add_u64 v[140:141], v[248:249], 0, s[74:75]
	s_mov_b32 m0, s58
	v_lshl_add_u64 v[250:251], s[8:9], 0, v[132:133]
	global_load_lds_dwordx4 v[140:141], off
	v_lshl_add_u64 v[140:141], v[250:251], 0, s[74:75]
	s_mov_b32 m0, s59
	s_nop 0
	global_load_lds_dwordx4 v[140:141], off
	s_setprio 0
	s_waitcnt vmcnt(8)
	s_waitcnt lgkmcnt(0)
	s_barrier
	s_setprio 1
	s_waitcnt lgkmcnt(0)
	v_mfma_f32_16x16x32_f16 v[140:143], v[4:7], v[36:39], 0
	v_mfma_f32_16x16x32_f16 v[148:151], v[12:15], v[36:39], 0
	v_mfma_f32_16x16x32_f16 v[152:155], v[4:7], v[52:55], 0
	v_mfma_f32_16x16x32_f16 v[156:159], v[12:15], v[52:55], 0
	v_mfma_f32_16x16x32_f16 v[160:163], v[4:7], v[116:119], 0
	v_mfma_f32_16x16x32_f16 v[164:167], v[12:15], v[116:119], 0
	v_mfma_f32_16x16x32_f16 v[4:7], v[4:7], v[124:127], 0
	v_mfma_f32_16x16x32_f16 v[12:15], v[12:15], v[124:127], 0
	v_mfma_f32_16x16x32_f16 v[140:143], v[8:11], v[44:47], v[140:143]
	v_mfma_f32_16x16x32_f16 v[148:151], v[16:19], v[44:47], v[148:151]
	v_mfma_f32_16x16x32_f16 v[152:155], v[8:11], v[60:63], v[152:155]
	v_mfma_f32_16x16x32_f16 v[156:159], v[16:19], v[60:63], v[156:159]
	v_mfma_f32_16x16x32_f16 v[160:163], v[8:11], v[120:123], v[160:163]
	v_mfma_f32_16x16x32_f16 v[164:167], v[16:19], v[120:123], v[164:167]
	v_mfma_f32_16x16x32_f16 v[168:171], v[8:11], v[128:131], v[4:7]
	v_mfma_f32_16x16x32_f16 v[172:175], v[16:19], v[128:131], v[12:15]
	s_setprio 0
	s_setprio 1
	v_mfma_f32_16x16x32_f16 v[4:7], v[20:23], v[36:39], 0
	v_mfma_f32_16x16x32_f16 v[8:11], v[28:31], v[36:39], 0
	v_mfma_f32_16x16x32_f16 v[12:15], v[20:23], v[52:55], 0
	v_mfma_f32_16x16x32_f16 v[16:19], v[28:31], v[52:55], 0
	v_mfma_f32_16x16x32_f16 v[36:39], v[20:23], v[116:119], 0
	v_mfma_f32_16x16x32_f16 v[52:55], v[28:31], v[116:119], 0
	v_mfma_f32_16x16x32_f16 v[20:23], v[20:23], v[124:127], 0
	v_mfma_f32_16x16x32_f16 v[28:31], v[28:31], v[124:127], 0
	v_mfma_f32_16x16x32_f16 v[116:119], v[24:27], v[44:47], v[4:7]
	v_mfma_f32_16x16x32_f16 v[124:127], v[32:35], v[44:47], v[8:11]
	v_mfma_f32_16x16x32_f16 v[184:187], v[24:27], v[120:123], v[36:39]
	v_mfma_f32_16x16x32_f16 v[120:123], v[32:35], v[120:123], v[52:55]
	v_mfma_f32_16x16x32_f16 v[188:191], v[24:27], v[128:131], v[20:23]
	v_mfma_f32_16x16x32_f16 v[128:131], v[32:35], v[128:131], v[28:31]
	s_setprio 2
	s_barrier
	v_mfma_f32_16x16x32_f16 v[176:179], v[24:27], v[60:63], v[12:15]
	v_mfma_f32_16x16x32_f16 v[180:183], v[32:35], v[60:63], v[16:19]
	s_add_i32 s53, 0, 0x18000
	v_add_u32_e32 v4, s53, v147
	s_add_i32 s72, 0, 0x1c000
	ds_read_b128 v[192:195], v4
	ds_read_b128 v[196:199], v4 offset:1024
	ds_read_b128 v[200:203], v4 offset:2048
	ds_read_b128 v[204:207], v4 offset:3072
	v_add_u32_e32 v4, s72, v147
	ds_read_b128 v[208:211], v4
	ds_read_b128 v[212:215], v4 offset:1024
	ds_read_b128 v[216:219], v4 offset:2048
	ds_read_b128 v[220:223], v4 offset:3072
	s_mov_b32 m0, s60
	ds_read_b128 v[44:47], v231 offset:32768
	ds_read_b128 v[52:55], v231 offset:33792
	ds_read_b128 v[60:63], v231 offset:34816
	ds_read_b128 v[224:227], v231 offset:35840
	ds_read_b128 v[232:235], v231 offset:36864
	ds_read_b128 v[236:239], v231 offset:37888
	ds_read_b128 v[240:243], v231 offset:38912
	ds_read_b128 v[244:247], v231 offset:39936
	global_load_lds_dwordx4 v138, s[26:27]
	s_mov_b32 m0, s61
	s_nop 0
	global_load_lds_dwordx4 v132, s[26:27]
	s_setprio 0
	s_waitcnt vmcnt(8)
	s_waitcnt lgkmcnt(0)
	s_barrier
	s_setprio 1
	s_waitcnt lgkmcnt(0)
	v_mfma_f32_16x16x32_f16 v[4:7], v[192:195], v[44:47], v[68:71]
	v_mfma_f32_16x16x32_f16 v[8:11], v[200:203], v[44:47], v[72:75]
	v_mfma_f32_16x16x32_f16 v[12:15], v[192:195], v[60:63], v[76:79]
	v_mfma_f32_16x16x32_f16 v[16:19], v[200:203], v[60:63], v[80:83]
	v_mfma_f32_16x16x32_f16 v[20:23], v[192:195], v[232:235], v[84:87]
	v_mfma_f32_16x16x32_f16 v[24:27], v[200:203], v[232:235], v[88:91]
	v_mfma_f32_16x16x32_f16 v[28:31], v[192:195], v[240:243], v[92:95]
	v_mfma_f32_16x16x32_f16 v[32:35], v[200:203], v[240:243], v[96:99]
	v_mfma_f32_16x16x32_f16 v[4:7], v[196:199], v[52:55], v[4:7]
	v_mfma_f32_16x16x32_f16 v[8:11], v[204:207], v[52:55], v[8:11]
	v_mfma_f32_16x16x32_f16 v[12:15], v[196:199], v[224:227], v[12:15]
	v_mfma_f32_16x16x32_f16 v[16:19], v[204:207], v[224:227], v[16:19]
	v_mfma_f32_16x16x32_f16 v[20:23], v[196:199], v[236:239], v[20:23]
	v_mfma_f32_16x16x32_f16 v[24:27], v[204:207], v[236:239], v[24:27]
	v_mfma_f32_16x16x32_f16 v[28:31], v[196:199], v[244:247], v[28:31]
	v_mfma_f32_16x16x32_f16 v[32:35], v[204:207], v[244:247], v[32:35]
	s_setprio 0
	s_setprio 1
	v_mfma_f32_16x16x32_f16 v[36:39], v[208:211], v[44:47], v[100:103]
	v_mfma_f32_16x16x32_f16 v[40:43], v[216:219], v[44:47], v[40:43]
	v_mfma_f32_16x16x32_f16 v[36:39], v[212:215], v[52:55], v[36:39]
	v_mfma_f32_16x16x32_f16 v[40:43], v[220:223], v[52:55], v[40:43]
	v_mfma_f32_16x16x32_f16 v[44:47], v[208:211], v[60:63], v[104:107]
	v_mfma_f32_16x16x32_f16 v[48:51], v[216:219], v[60:63], v[48:51]
	v_mfma_f32_16x16x32_f16 v[52:55], v[208:211], v[232:235], v[108:111]
	v_mfma_f32_16x16x32_f16 v[56:59], v[216:219], v[232:235], v[56:59]
	v_mfma_f32_16x16x32_f16 v[60:63], v[208:211], v[240:243], v[112:115]
	v_mfma_f32_16x16x32_f16 v[64:67], v[216:219], v[240:243], v[64:67]
	v_mfma_f32_16x16x32_f16 v[44:47], v[212:215], v[224:227], v[44:47]
	v_mfma_f32_16x16x32_f16 v[48:51], v[220:223], v[224:227], v[48:51]
	v_mfma_f32_16x16x32_f16 v[52:55], v[212:215], v[236:239], v[52:55]
	v_mfma_f32_16x16x32_f16 v[56:59], v[220:223], v[236:239], v[56:59]
	s_setprio 2
	s_barrier
	v_mfma_f32_16x16x32_f16 v[60:63], v[212:215], v[244:247], v[60:63]
	v_mfma_f32_16x16x32_f16 v[64:67], v[220:223], v[244:247], v[64:67]
	s_add_i32 s53, s53, s38
	v_lshl_add_u64 v[68:69], v[136:137], 0, s[24:25]
	s_mov_b32 m0, s53
	ds_read_b128 v[104:107], v231 offset:49152
	ds_read_b128 v[108:111], v231 offset:50176
	ds_read_b128 v[112:115], v231 offset:51200
	ds_read_b128 v[224:227], v231 offset:52224
	ds_read_b128 v[232:235], v231 offset:53248
	ds_read_b128 v[236:239], v231 offset:54272
	ds_read_b128 v[240:243], v231 offset:55296
	ds_read_b128 v[244:247], v231 offset:56320
	global_load_lds_dwordx4 v[68:69], off
	v_lshl_add_u64 v[68:69], v[144:145], 0, s[24:25]
	s_add_i32 m0, s53, 0x2000
	s_add_i32 s53, s72, s38
	global_load_lds_dwordx4 v[68:69], off
	s_mov_b32 m0, s53
	v_lshl_add_u64 v[68:69], v[248:249], 0, s[24:25]
	global_load_lds_dwordx4 v2, s[28:29]
	s_add_i32 m0, s53, 0x2000
	s_nop 0
	global_load_lds_dwordx4 v134, s[28:29]
	s_mov_b32 m0, s64
	s_nop 0
	global_load_lds_dwordx4 v[68:69], off
	v_lshl_add_u64 v[68:69], v[250:251], 0, s[24:25]
	s_mov_b32 m0, s65
	s_nop 0
	global_load_lds_dwordx4 v[68:69], off
	s_setprio 0
	s_waitcnt vmcnt(8)
	s_waitcnt lgkmcnt(0)
	s_barrier
	s_setprio 1
	s_waitcnt lgkmcnt(0)
	v_mfma_f32_16x16x32_f16 v[68:71], v[192:195], v[104:107], v[140:143]
	v_mfma_f32_16x16x32_f16 v[72:75], v[200:203], v[104:107], v[148:151]
	v_mfma_f32_16x16x32_f16 v[76:79], v[192:195], v[112:115], v[152:155]
	v_mfma_f32_16x16x32_f16 v[80:83], v[200:203], v[112:115], v[156:159]
	v_mfma_f32_16x16x32_f16 v[84:87], v[192:195], v[232:235], v[160:163]
	v_mfma_f32_16x16x32_f16 v[88:91], v[200:203], v[232:235], v[164:167]
	v_mfma_f32_16x16x32_f16 v[92:95], v[192:195], v[240:243], v[168:171]
	v_mfma_f32_16x16x32_f16 v[96:99], v[200:203], v[240:243], v[172:175]
	v_mfma_f32_16x16x32_f16 v[68:71], v[196:199], v[108:111], v[68:71]
	v_mfma_f32_16x16x32_f16 v[72:75], v[204:207], v[108:111], v[72:75]
	v_mfma_f32_16x16x32_f16 v[76:79], v[196:199], v[224:227], v[76:79]
	v_mfma_f32_16x16x32_f16 v[80:83], v[204:207], v[224:227], v[80:83]
	v_mfma_f32_16x16x32_f16 v[84:87], v[196:199], v[236:239], v[84:87]
	v_mfma_f32_16x16x32_f16 v[88:91], v[204:207], v[236:239], v[88:91]
	v_mfma_f32_16x16x32_f16 v[92:95], v[196:199], v[244:247], v[92:95]
	v_mfma_f32_16x16x32_f16 v[96:99], v[204:207], v[244:247], v[96:99]
	s_setprio 0
	s_setprio 1
	v_mfma_f32_16x16x32_f16 v[100:103], v[208:211], v[104:107], v[116:119]
	v_mfma_f32_16x16x32_f16 v[104:107], v[216:219], v[104:107], v[124:127]
	v_mfma_f32_16x16x32_f16 v[100:103], v[212:215], v[108:111], v[100:103]
	v_mfma_f32_16x16x32_f16 v[104:107], v[220:223], v[108:111], v[104:107]
	v_mfma_f32_16x16x32_f16 v[108:111], v[208:211], v[112:115], v[176:179]
	v_mfma_f32_16x16x32_f16 v[112:115], v[216:219], v[112:115], v[180:183]
	v_mfma_f32_16x16x32_f16 v[116:119], v[208:211], v[232:235], v[184:187]
	v_mfma_f32_16x16x32_f16 v[120:123], v[216:219], v[232:235], v[120:123]
	v_mfma_f32_16x16x32_f16 v[124:127], v[208:211], v[240:243], v[188:191]
	v_mfma_f32_16x16x32_f16 v[128:131], v[216:219], v[240:243], v[128:131]
	v_mfma_f32_16x16x32_f16 v[108:111], v[212:215], v[224:227], v[108:111]
	v_mfma_f32_16x16x32_f16 v[112:115], v[220:223], v[224:227], v[112:115]
	v_mfma_f32_16x16x32_f16 v[116:119], v[212:215], v[236:239], v[116:119]
	v_mfma_f32_16x16x32_f16 v[120:123], v[220:223], v[236:239], v[120:123]
	s_setprio 2
	s_barrier
	v_mfma_f32_16x16x32_f16 v[124:127], v[212:215], v[244:247], v[124:127]
	v_mfma_f32_16x16x32_f16 v[128:131], v[220:223], v[244:247], v[128:131]
	s_setprio 0
	s_add_i32 s41, s41, 2
	s_cmp_ge_i32 s41, s40
	s_cbranch_scc0 .LBB0_528
	v_mov_b32_e32 v136, v2
	s_branch .LBB0_531

.LBB0_532:
	s_add_u32 s6, s8, 0xfff80080
	s_addc_u32 s7, s9, -1
	s_add_i32 s29, 0, 0x10000
	s_cmp_eq_u32 s28, 28
	s_cselect_b32 s17, s13, s7
	s_cselect_b32 s16, s12, s6
	v_add_u32_e32 v133, s29, v147
	s_cselect_b32 s7, s15, s27
	s_cselect_b32 s6, s14, s26
	s_add_i32 s53, 0, 0x14000
	ds_read_b128 v[138:141], v133
	ds_read_b128 v[142:145], v133 offset:1024
	ds_read_b128 v[148:151], v133 offset:2048
	ds_read_b128 v[152:155], v133 offset:3072
	v_add_u32_e32 v133, s53, v147
	ds_read_b128 v[156:159], v133
	ds_read_b128 v[160:163], v133 offset:1024
	ds_read_b128 v[164:167], v133 offset:2048
	ds_read_b128 v[168:171], v133 offset:3072
	s_mov_b32 m0, s66
	v_add_u32_e32 v212, 0, v146
	ds_read_b128 v[172:175], v212
	ds_read_b128 v[176:179], v212 offset:1024
	ds_read_b128 v[180:183], v212 offset:2048
	ds_read_b128 v[184:187], v212 offset:3072
	ds_read_b128 v[188:191], v212 offset:4096
	ds_read_b128 v[192:195], v212 offset:5120
	ds_read_b128 v[196:199], v212 offset:6144
	ds_read_b128 v[200:203], v212 offset:7168
	global_load_lds_dwordx4 v2, s[8:9]
	s_mov_b32 m0, s67
	v_mov_b32_e32 v133, v3
	global_load_lds_dwordx4 v132, s[8:9]
	s_waitcnt vmcnt(8)
	s_waitcnt lgkmcnt(0)
	s_barrier
	s_setprio 1
	s_waitcnt lgkmcnt(0)
	v_mfma_f32_16x16x32_f16 v[4:7], v[138:141], v[172:175], v[4:7]
	v_mfma_f32_16x16x32_f16 v[4:7], v[142:145], v[176:179], v[4:7]
	v_mfma_f32_16x16x32_f16 v[8:11], v[152:155], v[176:179], v[8:11]
	v_mfma_f32_16x16x32_f16 v[8:11], v[148:151], v[172:175], v[8:11]
	v_mfma_f32_16x16x32_f16 v[16:19], v[148:151], v[180:183], v[16:19]
	v_mfma_f32_16x16x32_f16 v[16:19], v[152:155], v[184:187], v[16:19]
	v_mfma_f32_16x16x32_f16 v[12:15], v[142:145], v[184:187], v[12:15]
	v_mfma_f32_16x16x32_f16 v[12:15], v[138:141], v[180:183], v[12:15]
	v_mfma_f32_16x16x32_f16 v[20:23], v[138:141], v[188:191], v[20:23]
	v_mfma_f32_16x16x32_f16 v[20:23], v[142:145], v[192:195], v[20:23]
	v_mfma_f32_16x16x32_f16 v[24:27], v[152:155], v[192:195], v[24:27]
	v_mfma_f32_16x16x32_f16 v[24:27], v[148:151], v[188:191], v[24:27]
	v_mfma_f32_16x16x32_f16 v[32:35], v[148:151], v[196:199], v[32:35]
	v_mfma_f32_16x16x32_f16 v[32:35], v[152:155], v[200:203], v[32:35]
	v_mfma_f32_16x16x32_f16 v[28:31], v[142:145], v[200:203], v[28:31]
	v_mfma_f32_16x16x32_f16 v[28:31], v[138:141], v[196:199], v[28:31]
	s_setprio 0
	s_setprio 1
	v_mfma_f32_16x16x32_f16 v[36:39], v[156:159], v[172:175], v[36:39]
	v_mfma_f32_16x16x32_f16 v[36:39], v[160:163], v[176:179], v[36:39]
	v_mfma_f32_16x16x32_f16 v[40:43], v[168:171], v[176:179], v[40:43]
	v_mfma_f32_16x16x32_f16 v[40:43], v[164:167], v[172:175], v[40:43]
	v_mfma_f32_16x16x32_f16 v[48:51], v[164:167], v[180:183], v[48:51]
	v_mfma_f32_16x16x32_f16 v[48:51], v[168:171], v[184:187], v[48:51]
	v_mfma_f32_16x16x32_f16 v[44:47], v[160:163], v[184:187], v[44:47]
	v_mfma_f32_16x16x32_f16 v[44:47], v[156:159], v[180:183], v[44:47]
	v_mfma_f32_16x16x32_f16 v[52:55], v[156:159], v[188:191], v[52:55]
	v_mfma_f32_16x16x32_f16 v[52:55], v[160:163], v[192:195], v[52:55]
	v_mfma_f32_16x16x32_f16 v[56:59], v[168:171], v[192:195], v[56:59]
	v_mfma_f32_16x16x32_f16 v[56:59], v[164:167], v[188:191], v[56:59]
	v_mfma_f32_16x16x32_f16 v[64:67], v[164:167], v[196:199], v[64:67]
	v_mfma_f32_16x16x32_f16 v[64:67], v[168:171], v[200:203], v[64:67]
	s_setprio 2
	s_barrier
	v_mfma_f32_16x16x32_f16 v[60:63], v[160:163], v[200:203], v[60:63]
	v_mfma_f32_16x16x32_f16 v[60:63], v[156:159], v[196:199], v[60:63]
	s_add_i32 s29, s29, s38
	s_mov_b32 m0, s29
	ds_read_b128 v[172:175], v212 offset:16384
	ds_read_b128 v[176:179], v212 offset:17408
	ds_read_b128 v[180:183], v212 offset:18432
	ds_read_b128 v[184:187], v212 offset:19456
	ds_read_b128 v[188:191], v212 offset:20480
	ds_read_b128 v[192:195], v212 offset:21504
	ds_read_b128 v[196:199], v212 offset:22528
	ds_read_b128 v[200:203], v212 offset:23552
	global_load_lds_dwordx4 v136, s[6:7]
	s_add_i32 m0, s29, 0x2000
	s_add_u32 s40, s6, 0x80000
	s_addc_u32 s41, s7, 0
	s_add_i32 s29, s53, s38
	global_load_lds_dwordx4 v134, s[6:7]
	s_mov_b32 m0, s29
	v_mov_b32_e32 v137, v3
	global_load_lds_dwordx4 v136, s[40:41]
	s_add_i32 m0, s29, 0x2000
	v_mov_b32_e32 v135, v3
	global_load_lds_dwordx4 v134, s[40:41]
	s_mov_b32 m0, s58
	v_lshl_add_u64 v[204:205], s[6:7], 0, v[136:137]
	global_load_lds_dwordx4 v2, s[16:17]
	s_mov_b32 m0, s59
	v_lshl_add_u64 v[206:207], s[6:7], 0, v[134:135]
	global_load_lds_dwordx4 v132, s[16:17]
	s_setprio 0
	s_waitcnt vmcnt(8)
	s_waitcnt lgkmcnt(0)
	v_lshl_add_u64 v[208:209], s[16:17], 0, v[2:3]
	v_lshl_add_u64 v[210:211], s[16:17], 0, v[132:133]
	s_barrier
	s_setprio 1
	s_waitcnt lgkmcnt(0)
	v_mfma_f32_16x16x32_f16 v[68:71], v[138:141], v[172:175], v[68:71]
	v_mfma_f32_16x16x32_f16 v[68:71], v[142:145], v[176:179], v[68:71]
	v_mfma_f32_16x16x32_f16 v[72:75], v[152:155], v[176:179], v[72:75]
	v_mfma_f32_16x16x32_f16 v[72:75], v[148:151], v[172:175], v[72:75]
	v_mfma_f32_16x16x32_f16 v[80:83], v[148:151], v[180:183], v[80:83]
	v_mfma_f32_16x16x32_f16 v[80:83], v[152:155], v[184:187], v[80:83]
	v_mfma_f32_16x16x32_f16 v[76:79], v[142:145], v[184:187], v[76:79]
	v_mfma_f32_16x16x32_f16 v[76:79], v[138:141], v[180:183], v[76:79]
	v_mfma_f32_16x16x32_f16 v[84:87], v[138:141], v[188:191], v[84:87]
	v_mfma_f32_16x16x32_f16 v[84:87], v[142:145], v[192:195], v[84:87]
	v_mfma_f32_16x16x32_f16 v[88:91], v[152:155], v[192:195], v[88:91]
	v_mfma_f32_16x16x32_f16 v[88:91], v[148:151], v[188:191], v[88:91]
	v_mfma_f32_16x16x32_f16 v[96:99], v[148:151], v[196:199], v[96:99]
	v_mfma_f32_16x16x32_f16 v[96:99], v[152:155], v[200:203], v[96:99]
	v_mfma_f32_16x16x32_f16 v[92:95], v[142:145], v[200:203], v[92:95]
	v_mfma_f32_16x16x32_f16 v[92:95], v[138:141], v[196:199], v[92:95]
	s_setprio 0
	s_setprio 1
	v_mfma_f32_16x16x32_f16 v[100:103], v[156:159], v[172:175], v[100:103]
	v_mfma_f32_16x16x32_f16 v[100:103], v[160:163], v[176:179], v[100:103]
	v_mfma_f32_16x16x32_f16 v[104:107], v[168:171], v[176:179], v[104:107]
	v_mfma_f32_16x16x32_f16 v[104:107], v[164:167], v[172:175], v[104:107]
	v_mfma_f32_16x16x32_f16 v[112:115], v[164:167], v[180:183], v[112:115]
	v_mfma_f32_16x16x32_f16 v[112:115], v[168:171], v[184:187], v[112:115]
	v_mfma_f32_16x16x32_f16 v[108:111], v[160:163], v[184:187], v[108:111]
	v_mfma_f32_16x16x32_f16 v[108:111], v[156:159], v[180:183], v[108:111]
	v_mfma_f32_16x16x32_f16 v[116:119], v[156:159], v[188:191], v[116:119]
	v_mfma_f32_16x16x32_f16 v[116:119], v[160:163], v[192:195], v[116:119]
	v_mfma_f32_16x16x32_f16 v[120:123], v[168:171], v[192:195], v[120:123]
	v_mfma_f32_16x16x32_f16 v[120:123], v[164:167], v[188:191], v[120:123]
	v_mfma_f32_16x16x32_f16 v[128:131], v[164:167], v[196:199], v[128:131]
	v_mfma_f32_16x16x32_f16 v[128:131], v[168:171], v[200:203], v[128:131]
	s_setprio 2
	s_barrier
	v_mfma_f32_16x16x32_f16 v[124:127], v[160:163], v[200:203], v[124:127]
	v_mfma_f32_16x16x32_f16 v[124:127], v[156:159], v[196:199], v[124:127]
	s_add_i32 s29, 0, 0x18000
	v_add_u32_e32 v135, s29, v147
	s_add_i32 s40, 0, 0x1c000
	ds_read_b128 v[138:141], v135
	ds_read_b128 v[142:145], v135 offset:1024
	ds_read_b128 v[148:151], v135 offset:2048
	ds_read_b128 v[152:155], v135 offset:3072
	v_add_u32_e32 v135, s40, v147
	ds_read_b128 v[156:159], v135
	ds_read_b128 v[160:163], v135 offset:1024
	ds_read_b128 v[164:167], v135 offset:2048
	ds_read_b128 v[168:171], v135 offset:3072
	s_add_u32 s16, s16, 0x80000
	s_addc_u32 s17, s17, 0
	s_mov_b32 m0, s60
	ds_read_b128 v[172:175], v212 offset:32768
	ds_read_b128 v[176:179], v212 offset:33792
	ds_read_b128 v[180:183], v212 offset:34816
	ds_read_b128 v[184:187], v212 offset:35840
	ds_read_b128 v[188:191], v212 offset:36864
	ds_read_b128 v[192:195], v212 offset:37888
	ds_read_b128 v[196:199], v212 offset:38912
	ds_read_b128 v[200:203], v212 offset:39936
	global_load_lds_dwordx4 v2, s[16:17]
	s_mov_b32 m0, s61
	s_nop 0
	global_load_lds_dwordx4 v132, s[16:17]
	s_setprio 0
	s_waitcnt vmcnt(8)
	s_waitcnt lgkmcnt(0)
	s_barrier
	s_setprio 1
	s_waitcnt lgkmcnt(0)
	v_mfma_f32_16x16x32_f16 v[4:7], v[138:141], v[172:175], v[4:7]
	v_mfma_f32_16x16x32_f16 v[4:7], v[142:145], v[176:179], v[4:7]
	v_mfma_f32_16x16x32_f16 v[8:11], v[152:155], v[176:179], v[8:11]
	v_mfma_f32_16x16x32_f16 v[8:11], v[148:151], v[172:175], v[8:11]
	v_mfma_f32_16x16x32_f16 v[16:19], v[148:151], v[180:183], v[16:19]
	v_mfma_f32_16x16x32_f16 v[16:19], v[152:155], v[184:187], v[16:19]
	v_mfma_f32_16x16x32_f16 v[12:15], v[142:145], v[184:187], v[12:15]
	v_mfma_f32_16x16x32_f16 v[12:15], v[138:141], v[180:183], v[12:15]
	v_mfma_f32_16x16x32_f16 v[20:23], v[138:141], v[188:191], v[20:23]
	v_mfma_f32_16x16x32_f16 v[20:23], v[142:145], v[192:195], v[20:23]
	v_mfma_f32_16x16x32_f16 v[24:27], v[152:155], v[192:195], v[24:27]
	v_mfma_f32_16x16x32_f16 v[24:27], v[148:151], v[188:191], v[24:27]
	v_mfma_f32_16x16x32_f16 v[32:35], v[148:151], v[196:199], v[32:35]
	v_mfma_f32_16x16x32_f16 v[32:35], v[152:155], v[200:203], v[32:35]
	v_mfma_f32_16x16x32_f16 v[28:31], v[142:145], v[200:203], v[28:31]
	v_mfma_f32_16x16x32_f16 v[28:31], v[138:141], v[196:199], v[28:31]
	s_setprio 0
	s_setprio 1
	v_mfma_f32_16x16x32_f16 v[36:39], v[156:159], v[172:175], v[36:39]
	v_mfma_f32_16x16x32_f16 v[36:39], v[160:163], v[176:179], v[36:39]
	v_mfma_f32_16x16x32_f16 v[40:43], v[168:171], v[176:179], v[40:43]
	v_mfma_f32_16x16x32_f16 v[40:43], v[164:167], v[172:175], v[40:43]
	v_mfma_f32_16x16x32_f16 v[48:51], v[164:167], v[180:183], v[48:51]
	v_mfma_f32_16x16x32_f16 v[48:51], v[168:171], v[184:187], v[48:51]
	v_mfma_f32_16x16x32_f16 v[44:47], v[160:163], v[184:187], v[44:47]
	v_mfma_f32_16x16x32_f16 v[44:47], v[156:159], v[180:183], v[44:47]
	v_mfma_f32_16x16x32_f16 v[52:55], v[156:159], v[188:191], v[52:55]
	v_mfma_f32_16x16x32_f16 v[52:55], v[160:163], v[192:195], v[52:55]
	v_mfma_f32_16x16x32_f16 v[56:59], v[168:171], v[192:195], v[56:59]
	v_mfma_f32_16x16x32_f16 v[56:59], v[164:167], v[188:191], v[56:59]
	v_mfma_f32_16x16x32_f16 v[64:67], v[164:167], v[196:199], v[64:67]
	v_mfma_f32_16x16x32_f16 v[64:67], v[168:171], v[200:203], v[64:67]
	s_setprio 2
	s_barrier
	v_mfma_f32_16x16x32_f16 v[60:63], v[160:163], v[200:203], v[60:63]
	v_mfma_f32_16x16x32_f16 v[60:63], v[156:159], v[196:199], v[60:63]
	s_add_i32 s16, s29, s38
	v_lshl_add_u64 v[204:205], v[204:205], 0, s[86:87]
	s_mov_b32 m0, s16
	ds_read_b128 v[172:175], v212 offset:49152
	ds_read_b128 v[176:179], v212 offset:50176
	ds_read_b128 v[180:183], v212 offset:51200
	ds_read_b128 v[184:187], v212 offset:52224
	ds_read_b128 v[188:191], v212 offset:53248
	ds_read_b128 v[192:195], v212 offset:54272
	ds_read_b128 v[196:199], v212 offset:55296
	ds_read_b128 v[200:203], v212 offset:56320
	global_load_lds_dwordx4 v[204:205], off
	s_add_i32 m0, s16, 0x2000
	s_add_u32 s6, s6, 0x80080
	v_lshl_add_u64 v[204:205], v[206:207], 0, s[86:87]
	s_addc_u32 s7, s7, 0
	s_add_i32 s16, s40, s38
	global_load_lds_dwordx4 v[204:205], off
	s_mov_b32 m0, s16
	v_lshl_add_u64 v[204:205], v[208:209], 0, s[86:87]
	global_load_lds_dwordx4 v136, s[6:7]
	s_add_i32 m0, s16, 0x2000
	s_nop 0
	global_load_lds_dwordx4 v134, s[6:7]
	s_mov_b32 m0, s64
	s_nop 0
	global_load_lds_dwordx4 v[204:205], off
	v_lshl_add_u64 v[204:205], v[210:211], 0, s[86:87]
	s_mov_b32 m0, s65
	s_nop 0
	global_load_lds_dwordx4 v[204:205], off
	s_setprio 0
	s_waitcnt vmcnt(8)
	s_waitcnt lgkmcnt(0)
	s_barrier
	s_setprio 1
	s_waitcnt lgkmcnt(0)
	v_mfma_f32_16x16x32_f16 v[68:71], v[138:141], v[172:175], v[68:71]
	v_mfma_f32_16x16x32_f16 v[68:71], v[142:145], v[176:179], v[68:71]
	v_mfma_f32_16x16x32_f16 v[72:75], v[152:155], v[176:179], v[72:75]
	v_mfma_f32_16x16x32_f16 v[72:75], v[148:151], v[172:175], v[72:75]
	v_mfma_f32_16x16x32_f16 v[80:83], v[148:151], v[180:183], v[80:83]
	v_mfma_f32_16x16x32_f16 v[80:83], v[152:155], v[184:187], v[80:83]
	v_mfma_f32_16x16x32_f16 v[76:79], v[142:145], v[184:187], v[76:79]
	v_mfma_f32_16x16x32_f16 v[76:79], v[138:141], v[180:183], v[76:79]
	v_mfma_f32_16x16x32_f16 v[84:87], v[138:141], v[188:191], v[84:87]
	v_mfma_f32_16x16x32_f16 v[84:87], v[142:145], v[192:195], v[84:87]
	v_mfma_f32_16x16x32_f16 v[88:91], v[152:155], v[192:195], v[88:91]
	v_mfma_f32_16x16x32_f16 v[88:91], v[148:151], v[188:191], v[88:91]
	v_mfma_f32_16x16x32_f16 v[96:99], v[148:151], v[196:199], v[96:99]
	v_mfma_f32_16x16x32_f16 v[96:99], v[152:155], v[200:203], v[96:99]
	v_mfma_f32_16x16x32_f16 v[92:95], v[142:145], v[200:203], v[92:95]
	v_mfma_f32_16x16x32_f16 v[92:95], v[138:141], v[196:199], v[92:95]
	s_setprio 0
	s_setprio 1
	v_mfma_f32_16x16x32_f16 v[100:103], v[156:159], v[172:175], v[100:103]
	v_mfma_f32_16x16x32_f16 v[100:103], v[160:163], v[176:179], v[100:103]
	v_mfma_f32_16x16x32_f16 v[104:107], v[168:171], v[176:179], v[104:107]
	v_mfma_f32_16x16x32_f16 v[104:107], v[164:167], v[172:175], v[104:107]
	v_mfma_f32_16x16x32_f16 v[112:115], v[164:167], v[180:183], v[112:115]
	v_mfma_f32_16x16x32_f16 v[112:115], v[168:171], v[184:187], v[112:115]
	v_mfma_f32_16x16x32_f16 v[108:111], v[160:163], v[184:187], v[108:111]
	v_mfma_f32_16x16x32_f16 v[108:111], v[156:159], v[180:183], v[108:111]
	v_mfma_f32_16x16x32_f16 v[116:119], v[156:159], v[188:191], v[116:119]
	v_mfma_f32_16x16x32_f16 v[116:119], v[160:163], v[192:195], v[116:119]
	v_mfma_f32_16x16x32_f16 v[120:123], v[168:171], v[192:195], v[120:123]
	v_mfma_f32_16x16x32_f16 v[120:123], v[164:167], v[188:191], v[120:123]
	v_mfma_f32_16x16x32_f16 v[128:131], v[164:167], v[196:199], v[128:131]
	v_mfma_f32_16x16x32_f16 v[128:131], v[168:171], v[200:203], v[128:131]
	s_setprio 2
	s_barrier
	v_mfma_f32_16x16x32_f16 v[124:127], v[160:163], v[200:203], v[124:127]
	v_mfma_f32_16x16x32_f16 v[124:127], v[156:159], v[196:199], v[124:127]
	s_setprio 0
	s_add_i32 s28, s28, 2
	s_add_u32 s8, s8, 0x100
	s_addc_u32 s9, s9, 0
	s_add_u32 s26, s26, 0x100
	s_addc_u32 s27, s27, 0
	s_cmp_gt_u32 s28, 29
	s_cbranch_scc0 .LBB0_532
	s_and_b64 vcc, exec, s[50:51]
	s_cbranch_vccz .LBB0_535
	s_barrier

.LBB0_641:
	s_add_i32 s43, 0, 0x10000
	s_add_i32 s71, 0, 0x14000
	v_add_u32_e32 v16, s43, v232
	v_add_u32_e32 v32, s71, v232
	ds_read_b128 v[4:7], v16
	ds_read_b128 v[8:11], v16 offset:1024
	ds_read_b128 v[12:15], v16 offset:2048
	ds_read_b128 v[16:19], v16 offset:3072
	ds_read_b128 v[20:23], v32
	ds_read_b128 v[24:27], v32 offset:1024
	ds_read_b128 v[28:31], v32 offset:2048
	ds_read_b128 v[32:35], v32 offset:3072
	v_add_u32_e32 v233, 0, v231
	ds_read_b128 v[36:39], v233
	ds_read_b128 v[40:43], v233 offset:1024
	ds_read_b128 v[44:47], v233 offset:2048
	ds_read_b128 v[48:51], v233 offset:3072
	ds_read_b128 v[52:55], v233 offset:4096
	ds_read_b128 v[56:59], v233 offset:5120
	ds_read_b128 v[60:63], v233 offset:6144
	ds_read_b128 v[64:67], v233 offset:7168
	s_waitcnt vmcnt(8)
	s_waitcnt lgkmcnt(0)
	s_barrier
	s_setprio 1
	s_waitcnt lgkmcnt(0)
	v_mfma_f32_16x16x32_bf16 v[68:71], v[4:7], v[36:39], 0
	v_mfma_f32_16x16x32_bf16 v[68:71], v[8:11], v[40:43], v[68:71]
	v_mfma_f32_16x16x32_bf16 v[72:75], v[12:15], v[36:39], 0
	v_mfma_f32_16x16x32_bf16 v[72:75], v[16:19], v[40:43], v[72:75]
	v_mfma_f32_16x16x32_bf16 v[80:83], v[12:15], v[44:47], 0
	v_mfma_f32_16x16x32_bf16 v[80:83], v[16:19], v[48:51], v[80:83]
	v_mfma_f32_16x16x32_bf16 v[76:79], v[4:7], v[44:47], 0
	v_mfma_f32_16x16x32_bf16 v[76:79], v[8:11], v[48:51], v[76:79]
	v_mfma_f32_16x16x32_bf16 v[84:87], v[4:7], v[52:55], 0
	v_mfma_f32_16x16x32_bf16 v[84:87], v[8:11], v[56:59], v[84:87]
	v_mfma_f32_16x16x32_bf16 v[88:91], v[12:15], v[52:55], 0
	v_mfma_f32_16x16x32_bf16 v[88:91], v[16:19], v[56:59], v[88:91]
	v_mfma_f32_16x16x32_bf16 v[96:99], v[12:15], v[60:63], 0
	v_mfma_f32_16x16x32_bf16 v[96:99], v[16:19], v[64:67], v[96:99]
	v_mfma_f32_16x16x32_bf16 v[92:95], v[4:7], v[60:63], 0
	v_mfma_f32_16x16x32_bf16 v[92:95], v[8:11], v[64:67], v[92:95]
	s_setprio 0
	s_setprio 1
	v_mfma_f32_16x16x32_bf16 v[100:103], v[20:23], v[36:39], 0
	v_mfma_f32_16x16x32_bf16 v[36:39], v[28:31], v[36:39], 0
	v_mfma_f32_16x16x32_bf16 v[104:107], v[20:23], v[44:47], 0
	v_mfma_f32_16x16x32_bf16 v[44:47], v[28:31], v[44:47], 0
	v_mfma_f32_16x16x32_bf16 v[108:111], v[20:23], v[52:55], 0
	v_mfma_f32_16x16x32_bf16 v[52:55], v[28:31], v[52:55], 0
	v_mfma_f32_16x16x32_bf16 v[112:115], v[20:23], v[60:63], 0
	v_mfma_f32_16x16x32_bf16 v[60:63], v[28:31], v[60:63], 0
	v_mfma_f32_16x16x32_bf16 v[100:103], v[24:27], v[40:43], v[100:103]
	v_mfma_f32_16x16x32_bf16 v[40:43], v[32:35], v[40:43], v[36:39]
	v_mfma_f32_16x16x32_bf16 v[104:107], v[24:27], v[48:51], v[104:107]
	v_mfma_f32_16x16x32_bf16 v[48:51], v[32:35], v[48:51], v[44:47]
	v_mfma_f32_16x16x32_bf16 v[108:111], v[24:27], v[56:59], v[108:111]
	v_mfma_f32_16x16x32_bf16 v[56:59], v[32:35], v[56:59], v[52:55]
	s_setprio 2
	s_barrier
	v_mfma_f32_16x16x32_bf16 v[112:115], v[24:27], v[64:67], v[112:115]
	v_mfma_f32_16x16x32_bf16 v[64:67], v[32:35], v[64:67], v[60:63]
	v_lshl_add_u64 v[186:187], s[8:9], 0, v[2:3]
	s_add_i32 s43, s43, s54
	v_mov_b32_e32 v191, v3
	v_lshl_add_u64 v[134:135], v[186:187], 0, s[80:81]
	s_mov_b32 m0, s43
	v_lshl_add_u64 v[246:247], s[8:9], 0, v[190:191]
	ds_read_b128 v[36:39], v233 offset:16384
	ds_read_b128 v[44:47], v233 offset:17408
	ds_read_b128 v[52:55], v233 offset:18432
	ds_read_b128 v[60:63], v233 offset:19456
	ds_read_b128 v[116:119], v233 offset:20480
	ds_read_b128 v[120:123], v233 offset:21504
	ds_read_b128 v[124:127], v233 offset:22528
	ds_read_b128 v[128:131], v233 offset:23552
	global_load_lds_dwordx4 v[134:135], off
	v_lshl_add_u64 v[134:135], v[246:247], 0, s[80:81]
	s_add_i32 m0, s43, 0x2000
	s_add_i32 s43, s71, s54
	global_load_lds_dwordx4 v[134:135], off
	s_mov_b32 m0, s43
	v_mov_b32_e32 v133, v3
	global_load_lds_dwordx4 v2, s[16:17]
	s_add_i32 m0, s43, 0x2000
	v_lshl_add_u64 v[248:249], s[6:7], 0, v[132:133]
	v_mov_b32_e32 v189, v3
	global_load_lds_dwordx4 v190, s[16:17]
	v_lshl_add_u64 v[134:135], v[248:249], 0, s[80:81]
	s_mov_b32 m0, s55
	v_lshl_add_u64 v[250:251], s[6:7], 0, v[188:189]
	global_load_lds_dwordx4 v[134:135], off
	v_lshl_add_u64 v[134:135], v[250:251], 0, s[80:81]
	s_mov_b32 m0, s56
	s_nop 0
	global_load_lds_dwordx4 v[134:135], off
	s_setprio 0
	s_waitcnt vmcnt(8)
	s_waitcnt lgkmcnt(0)
	s_barrier
	s_setprio 1
	s_waitcnt lgkmcnt(0)
	v_mfma_f32_16x16x32_bf16 v[134:137], v[4:7], v[36:39], 0
	v_mfma_f32_16x16x32_bf16 v[138:141], v[12:15], v[36:39], 0
	v_mfma_f32_16x16x32_bf16 v[142:145], v[4:7], v[52:55], 0
	v_mfma_f32_16x16x32_bf16 v[146:149], v[12:15], v[52:55], 0
	v_mfma_f32_16x16x32_bf16 v[150:153], v[4:7], v[116:119], 0
	v_mfma_f32_16x16x32_bf16 v[154:157], v[12:15], v[116:119], 0
	v_mfma_f32_16x16x32_bf16 v[4:7], v[4:7], v[124:127], 0
	v_mfma_f32_16x16x32_bf16 v[12:15], v[12:15], v[124:127], 0
	v_mfma_f32_16x16x32_bf16 v[134:137], v[8:11], v[44:47], v[134:137]
	v_mfma_f32_16x16x32_bf16 v[138:141], v[16:19], v[44:47], v[138:141]
	v_mfma_f32_16x16x32_bf16 v[142:145], v[8:11], v[60:63], v[142:145]
	v_mfma_f32_16x16x32_bf16 v[146:149], v[16:19], v[60:63], v[146:149]
	v_mfma_f32_16x16x32_bf16 v[150:153], v[8:11], v[120:123], v[150:153]
	v_mfma_f32_16x16x32_bf16 v[154:157], v[16:19], v[120:123], v[154:157]
	v_mfma_f32_16x16x32_bf16 v[158:161], v[8:11], v[128:131], v[4:7]
	v_mfma_f32_16x16x32_bf16 v[162:165], v[16:19], v[128:131], v[12:15]
	s_setprio 0
	s_setprio 1
	v_mfma_f32_16x16x32_bf16 v[4:7], v[20:23], v[36:39], 0
	v_mfma_f32_16x16x32_bf16 v[8:11], v[28:31], v[36:39], 0
	v_mfma_f32_16x16x32_bf16 v[12:15], v[20:23], v[52:55], 0
	v_mfma_f32_16x16x32_bf16 v[16:19], v[28:31], v[52:55], 0
	v_mfma_f32_16x16x32_bf16 v[36:39], v[20:23], v[116:119], 0
	v_mfma_f32_16x16x32_bf16 v[52:55], v[28:31], v[116:119], 0
	v_mfma_f32_16x16x32_bf16 v[20:23], v[20:23], v[124:127], 0
	v_mfma_f32_16x16x32_bf16 v[28:31], v[28:31], v[124:127], 0
	v_mfma_f32_16x16x32_bf16 v[116:119], v[24:27], v[44:47], v[4:7]
	v_mfma_f32_16x16x32_bf16 v[124:127], v[32:35], v[44:47], v[8:11]
	v_mfma_f32_16x16x32_bf16 v[174:177], v[24:27], v[120:123], v[36:39]
	v_mfma_f32_16x16x32_bf16 v[120:123], v[32:35], v[120:123], v[52:55]
	v_mfma_f32_16x16x32_bf16 v[178:181], v[24:27], v[128:131], v[20:23]
	v_mfma_f32_16x16x32_bf16 v[128:131], v[32:35], v[128:131], v[28:31]
	s_setprio 2
	s_barrier
	v_mfma_f32_16x16x32_bf16 v[166:169], v[24:27], v[60:63], v[12:15]
	v_mfma_f32_16x16x32_bf16 v[170:173], v[32:35], v[60:63], v[16:19]
	s_add_i32 s43, 0, 0x18000
	v_add_u32_e32 v4, s43, v232
	s_add_i32 s71, 0, 0x1c000
	ds_read_b128 v[182:185], v4
	ds_read_b128 v[192:195], v4 offset:1024
	ds_read_b128 v[196:199], v4 offset:2048
	ds_read_b128 v[200:203], v4 offset:3072
	v_add_u32_e32 v4, s71, v232
	ds_read_b128 v[204:207], v4
	ds_read_b128 v[208:211], v4 offset:1024
	ds_read_b128 v[212:215], v4 offset:2048
	ds_read_b128 v[216:219], v4 offset:3072
	s_mov_b32 m0, s57
	ds_read_b128 v[44:47], v233 offset:32768
	ds_read_b128 v[52:55], v233 offset:33792
	ds_read_b128 v[60:63], v233 offset:34816
	ds_read_b128 v[220:223], v233 offset:35840
	ds_read_b128 v[224:227], v233 offset:36864
	ds_read_b128 v[234:237], v233 offset:37888
	ds_read_b128 v[238:241], v233 offset:38912
	ds_read_b128 v[242:245], v233 offset:39936
	global_load_lds_dwordx4 v132, s[26:27]
	s_mov_b32 m0, s58
	s_nop 0
	global_load_lds_dwordx4 v188, s[26:27]
	s_setprio 0
	s_waitcnt vmcnt(8)
	s_waitcnt lgkmcnt(0)
	s_barrier
	s_setprio 1
	s_waitcnt lgkmcnt(0)
	v_mfma_f32_16x16x32_bf16 v[4:7], v[182:185], v[44:47], v[68:71]
	v_mfma_f32_16x16x32_bf16 v[8:11], v[196:199], v[44:47], v[72:75]
	v_mfma_f32_16x16x32_bf16 v[12:15], v[182:185], v[60:63], v[76:79]
	v_mfma_f32_16x16x32_bf16 v[16:19], v[196:199], v[60:63], v[80:83]
	v_mfma_f32_16x16x32_bf16 v[20:23], v[182:185], v[224:227], v[84:87]
	v_mfma_f32_16x16x32_bf16 v[24:27], v[196:199], v[224:227], v[88:91]
	v_mfma_f32_16x16x32_bf16 v[28:31], v[182:185], v[238:241], v[92:95]
	v_mfma_f32_16x16x32_bf16 v[32:35], v[196:199], v[238:241], v[96:99]
	v_mfma_f32_16x16x32_bf16 v[4:7], v[192:195], v[52:55], v[4:7]
	v_mfma_f32_16x16x32_bf16 v[8:11], v[200:203], v[52:55], v[8:11]
	v_mfma_f32_16x16x32_bf16 v[12:15], v[192:195], v[220:223], v[12:15]
	v_mfma_f32_16x16x32_bf16 v[16:19], v[200:203], v[220:223], v[16:19]
	v_mfma_f32_16x16x32_bf16 v[20:23], v[192:195], v[234:237], v[20:23]
	v_mfma_f32_16x16x32_bf16 v[24:27], v[200:203], v[234:237], v[24:27]
	v_mfma_f32_16x16x32_bf16 v[28:31], v[192:195], v[242:245], v[28:31]
	v_mfma_f32_16x16x32_bf16 v[32:35], v[200:203], v[242:245], v[32:35]
	s_setprio 0
	s_setprio 1
	v_mfma_f32_16x16x32_bf16 v[36:39], v[204:207], v[44:47], v[100:103]
	v_mfma_f32_16x16x32_bf16 v[40:43], v[212:215], v[44:47], v[40:43]
	v_mfma_f32_16x16x32_bf16 v[36:39], v[208:211], v[52:55], v[36:39]
	v_mfma_f32_16x16x32_bf16 v[40:43], v[216:219], v[52:55], v[40:43]
	v_mfma_f32_16x16x32_bf16 v[44:47], v[204:207], v[60:63], v[104:107]
	v_mfma_f32_16x16x32_bf16 v[48:51], v[212:215], v[60:63], v[48:51]
	v_mfma_f32_16x16x32_bf16 v[52:55], v[204:207], v[224:227], v[108:111]
	v_mfma_f32_16x16x32_bf16 v[56:59], v[212:215], v[224:227], v[56:59]
	v_mfma_f32_16x16x32_bf16 v[60:63], v[204:207], v[238:241], v[112:115]
	v_mfma_f32_16x16x32_bf16 v[64:67], v[212:215], v[238:241], v[64:67]
	v_mfma_f32_16x16x32_bf16 v[44:47], v[208:211], v[220:223], v[44:47]
	v_mfma_f32_16x16x32_bf16 v[48:51], v[216:219], v[220:223], v[48:51]
	v_mfma_f32_16x16x32_bf16 v[52:55], v[208:211], v[234:237], v[52:55]
	v_mfma_f32_16x16x32_bf16 v[56:59], v[216:219], v[234:237], v[56:59]
	s_setprio 2
	s_barrier
	v_mfma_f32_16x16x32_bf16 v[60:63], v[208:211], v[242:245], v[60:63]
	v_mfma_f32_16x16x32_bf16 v[64:67], v[216:219], v[242:245], v[64:67]
	s_add_i32 s43, s43, s54
	v_lshl_add_u64 v[68:69], v[186:187], 0, s[0:1]
	s_mov_b32 m0, s43
	ds_read_b128 v[104:107], v233 offset:49152
	ds_read_b128 v[108:111], v233 offset:50176
	ds_read_b128 v[112:115], v233 offset:51200
	ds_read_b128 v[220:223], v233 offset:52224
	ds_read_b128 v[224:227], v233 offset:53248
	ds_read_b128 v[234:237], v233 offset:54272
	ds_read_b128 v[238:241], v233 offset:55296
	ds_read_b128 v[242:245], v233 offset:56320
	global_load_lds_dwordx4 v[68:69], off
	v_lshl_add_u64 v[68:69], v[246:247], 0, s[0:1]
	s_add_i32 m0, s43, 0x2000
	s_add_i32 s43, s71, s54
	global_load_lds_dwordx4 v[68:69], off
	s_mov_b32 m0, s43
	v_lshl_add_u64 v[68:69], v[248:249], 0, s[0:1]
	global_load_lds_dwordx4 v2, s[28:29]
	s_add_i32 m0, s43, 0x2000
	s_nop 0
	global_load_lds_dwordx4 v190, s[28:29]
	s_mov_b32 m0, s62
	s_nop 0
	global_load_lds_dwordx4 v[68:69], off
	v_lshl_add_u64 v[68:69], v[250:251], 0, s[0:1]
	s_mov_b32 m0, s63
	s_nop 0
	global_load_lds_dwordx4 v[68:69], off
	s_setprio 0
	s_waitcnt vmcnt(8)
	s_waitcnt lgkmcnt(0)
	s_barrier
	s_setprio 1
	s_waitcnt lgkmcnt(0)
	v_mfma_f32_16x16x32_bf16 v[68:71], v[182:185], v[104:107], v[134:137]
	v_mfma_f32_16x16x32_bf16 v[72:75], v[196:199], v[104:107], v[138:141]
	v_mfma_f32_16x16x32_bf16 v[76:79], v[182:185], v[112:115], v[142:145]
	v_mfma_f32_16x16x32_bf16 v[80:83], v[196:199], v[112:115], v[146:149]
	v_mfma_f32_16x16x32_bf16 v[84:87], v[182:185], v[224:227], v[150:153]
	v_mfma_f32_16x16x32_bf16 v[88:91], v[196:199], v[224:227], v[154:157]
	v_mfma_f32_16x16x32_bf16 v[92:95], v[182:185], v[238:241], v[158:161]
	v_mfma_f32_16x16x32_bf16 v[96:99], v[196:199], v[238:241], v[162:165]
	v_mfma_f32_16x16x32_bf16 v[68:71], v[192:195], v[108:111], v[68:71]
	v_mfma_f32_16x16x32_bf16 v[72:75], v[200:203], v[108:111], v[72:75]
	v_mfma_f32_16x16x32_bf16 v[76:79], v[192:195], v[220:223], v[76:79]
	v_mfma_f32_16x16x32_bf16 v[80:83], v[200:203], v[220:223], v[80:83]
	v_mfma_f32_16x16x32_bf16 v[84:87], v[192:195], v[234:237], v[84:87]
	v_mfma_f32_16x16x32_bf16 v[88:91], v[200:203], v[234:237], v[88:91]
	v_mfma_f32_16x16x32_bf16 v[92:95], v[192:195], v[242:245], v[92:95]
	v_mfma_f32_16x16x32_bf16 v[96:99], v[200:203], v[242:245], v[96:99]
	s_setprio 0
	s_setprio 1
	v_mfma_f32_16x16x32_bf16 v[100:103], v[204:207], v[104:107], v[116:119]
	v_mfma_f32_16x16x32_bf16 v[104:107], v[212:215], v[104:107], v[124:127]
	v_mfma_f32_16x16x32_bf16 v[100:103], v[208:211], v[108:111], v[100:103]
	v_mfma_f32_16x16x32_bf16 v[104:107], v[216:219], v[108:111], v[104:107]
	v_mfma_f32_16x16x32_bf16 v[108:111], v[204:207], v[112:115], v[166:169]
	v_mfma_f32_16x16x32_bf16 v[112:115], v[212:215], v[112:115], v[170:173]
	v_mfma_f32_16x16x32_bf16 v[116:119], v[204:207], v[224:227], v[174:177]
	v_mfma_f32_16x16x32_bf16 v[120:123], v[212:215], v[224:227], v[120:123]
	v_mfma_f32_16x16x32_bf16 v[124:127], v[204:207], v[238:241], v[178:181]
	v_mfma_f32_16x16x32_bf16 v[128:131], v[212:215], v[238:241], v[128:131]
	v_mfma_f32_16x16x32_bf16 v[108:111], v[208:211], v[220:223], v[108:111]
	v_mfma_f32_16x16x32_bf16 v[112:115], v[216:219], v[220:223], v[112:115]
	v_mfma_f32_16x16x32_bf16 v[116:119], v[208:211], v[234:237], v[116:119]
	v_mfma_f32_16x16x32_bf16 v[120:123], v[216:219], v[234:237], v[120:123]
	s_setprio 2
	s_barrier
	v_mfma_f32_16x16x32_bf16 v[124:127], v[208:211], v[242:245], v[124:127]
	v_mfma_f32_16x16x32_bf16 v[128:131], v[216:219], v[242:245], v[128:131]
	s_setprio 0
	s_add_i32 s42, s42, 2
	s_cmp_ge_i32 s42, s38
	s_cbranch_scc0 .LBB0_641
	v_mov_b32_e32 v192, v2
	s_branch .LBB0_644

.LBB0_649:
	s_or_b32 s38, s28, 1
	s_lshl_b64 s[42:43], s[38:39], 7
	s_sub_u32 s38, 0, s42
	s_subb_u32 s42, 0, s43
	s_add_u32 s38, s6, s38
	s_addc_u32 s43, s7, s42
	s_add_i32 s71, 0, 0x10000
	s_add_i32 s72, 0, 0x14000
	v_add_u32_e32 v144, s71, v232
	v_add_u32_e32 v160, s72, v232
	s_waitcnt lgkmcnt(0)
	ds_read_b128 v[132:135], v144
	ds_read_b128 v[136:139], v144 offset:1024
	ds_read_b128 v[140:143], v144 offset:2048
	ds_read_b128 v[144:147], v144 offset:3072
	ds_read_b128 v[148:151], v160
	ds_read_b128 v[152:155], v160 offset:1024
	ds_read_b128 v[156:159], v160 offset:2048
	ds_read_b128 v[160:163], v160 offset:3072
	s_add_u32 s42, s38, 0x160000
	s_mov_b32 m0, s64
	v_add_u32_e32 v210, 0, v231
	s_addc_u32 s43, s43, 0
	ds_read_b128 v[164:167], v210
	ds_read_b128 v[168:171], v210 offset:1024
	ds_read_b128 v[172:175], v210 offset:2048
	ds_read_b128 v[176:179], v210 offset:3072
	ds_read_b128 v[180:183], v210 offset:4096
	ds_read_b128 v[184:187], v210 offset:5120
	ds_read_b128 v[194:197], v210 offset:6144
	ds_read_b128 v[198:201], v210 offset:7168
	global_load_lds_dwordx4 v2, s[42:43]
	s_mov_b32 m0, s65
	v_mov_b32_e32 v189, v3
	global_load_lds_dwordx4 v188, s[42:43]
	s_waitcnt vmcnt(8)
	s_waitcnt lgkmcnt(0)
	s_barrier
	s_setprio 1
	s_waitcnt lgkmcnt(0)
	v_mfma_f32_16x16x32_bf16 v[4:7], v[132:135], v[164:167], v[4:7]
	v_mfma_f32_16x16x32_bf16 v[4:7], v[136:139], v[168:171], v[4:7]
	v_mfma_f32_16x16x32_bf16 v[8:11], v[144:147], v[168:171], v[8:11]
	v_mfma_f32_16x16x32_bf16 v[8:11], v[140:143], v[164:167], v[8:11]
	v_mfma_f32_16x16x32_bf16 v[16:19], v[140:143], v[172:175], v[16:19]
	v_mfma_f32_16x16x32_bf16 v[16:19], v[144:147], v[176:179], v[16:19]
	v_mfma_f32_16x16x32_bf16 v[12:15], v[136:139], v[176:179], v[12:15]
	v_mfma_f32_16x16x32_bf16 v[12:15], v[132:135], v[172:175], v[12:15]
	v_mfma_f32_16x16x32_bf16 v[20:23], v[132:135], v[180:183], v[20:23]
	v_mfma_f32_16x16x32_bf16 v[20:23], v[136:139], v[184:187], v[20:23]
	v_mfma_f32_16x16x32_bf16 v[24:27], v[144:147], v[184:187], v[24:27]
	v_mfma_f32_16x16x32_bf16 v[24:27], v[140:143], v[180:183], v[24:27]
	v_mfma_f32_16x16x32_bf16 v[32:35], v[140:143], v[194:197], v[32:35]
	v_mfma_f32_16x16x32_bf16 v[32:35], v[144:147], v[198:201], v[32:35]
	v_mfma_f32_16x16x32_bf16 v[28:31], v[136:139], v[198:201], v[28:31]
	v_mfma_f32_16x16x32_bf16 v[28:31], v[132:135], v[194:197], v[28:31]
	s_setprio 0
	s_setprio 1
	v_mfma_f32_16x16x32_bf16 v[36:39], v[148:151], v[164:167], v[36:39]
	v_mfma_f32_16x16x32_bf16 v[36:39], v[152:155], v[168:171], v[36:39]
	v_mfma_f32_16x16x32_bf16 v[40:43], v[160:163], v[168:171], v[40:43]
	v_mfma_f32_16x16x32_bf16 v[40:43], v[156:159], v[164:167], v[40:43]
	v_mfma_f32_16x16x32_bf16 v[48:51], v[156:159], v[172:175], v[48:51]
	v_mfma_f32_16x16x32_bf16 v[48:51], v[160:163], v[176:179], v[48:51]
	v_mfma_f32_16x16x32_bf16 v[44:47], v[152:155], v[176:179], v[44:47]
	v_mfma_f32_16x16x32_bf16 v[44:47], v[148:151], v[172:175], v[44:47]
	v_mfma_f32_16x16x32_bf16 v[52:55], v[148:151], v[180:183], v[52:55]
	v_mfma_f32_16x16x32_bf16 v[52:55], v[152:155], v[184:187], v[52:55]
	v_mfma_f32_16x16x32_bf16 v[56:59], v[160:163], v[184:187], v[56:59]
	v_mfma_f32_16x16x32_bf16 v[56:59], v[156:159], v[180:183], v[56:59]
	v_mfma_f32_16x16x32_bf16 v[64:67], v[156:159], v[194:197], v[64:67]
	v_mfma_f32_16x16x32_bf16 v[64:67], v[160:163], v[198:201], v[64:67]
	s_setprio 2
	s_barrier
	v_mfma_f32_16x16x32_bf16 v[60:63], v[152:155], v[198:201], v[60:63]
	v_mfma_f32_16x16x32_bf16 v[60:63], v[148:151], v[194:197], v[60:63]
	s_add_i32 s38, s71, s54
	s_mov_b32 m0, s38
	ds_read_b128 v[164:167], v210 offset:16384
	ds_read_b128 v[168:171], v210 offset:17408
	ds_read_b128 v[172:175], v210 offset:18432
	ds_read_b128 v[176:179], v210 offset:19456
	ds_read_b128 v[180:183], v210 offset:20480
	ds_read_b128 v[184:187], v210 offset:21504
	ds_read_b128 v[194:197], v210 offset:22528
	ds_read_b128 v[198:201], v210 offset:23552
	global_load_lds_dwordx4 v192, s[16:17]
	s_add_i32 m0, s38, 0x2000
	s_add_u32 s42, s16, 0x160000
	s_addc_u32 s43, s17, 0
	s_add_i32 s38, s72, s54
	global_load_lds_dwordx4 v190, s[16:17]
	s_mov_b32 m0, s38
	v_mov_b32_e32 v193, v3
	global_load_lds_dwordx4 v192, s[42:43]
	s_add_i32 m0, s38, 0x2000
	v_mov_b32_e32 v191, v3
	global_load_lds_dwordx4 v190, s[42:43]
	s_mov_b32 m0, s55
	v_lshl_add_u64 v[202:203], s[16:17], 0, v[192:193]
	global_load_lds_dwordx4 v2, s[26:27]
	s_mov_b32 m0, s56
	v_lshl_add_u64 v[204:205], s[16:17], 0, v[190:191]
	global_load_lds_dwordx4 v188, s[26:27]
	s_setprio 0
	s_waitcnt vmcnt(8)
	s_waitcnt lgkmcnt(0)
	v_lshl_add_u64 v[206:207], s[26:27], 0, v[2:3]
	v_lshl_add_u64 v[208:209], s[26:27], 0, v[188:189]
	s_barrier
	s_setprio 1
	s_waitcnt lgkmcnt(0)
	v_mfma_f32_16x16x32_bf16 v[68:71], v[132:135], v[164:167], v[68:71]
	v_mfma_f32_16x16x32_bf16 v[68:71], v[136:139], v[168:171], v[68:71]
	v_mfma_f32_16x16x32_bf16 v[72:75], v[144:147], v[168:171], v[72:75]
	v_mfma_f32_16x16x32_bf16 v[72:75], v[140:143], v[164:167], v[72:75]
	v_mfma_f32_16x16x32_bf16 v[80:83], v[140:143], v[172:175], v[80:83]
	v_mfma_f32_16x16x32_bf16 v[80:83], v[144:147], v[176:179], v[80:83]
	v_mfma_f32_16x16x32_bf16 v[76:79], v[136:139], v[176:179], v[76:79]
	v_mfma_f32_16x16x32_bf16 v[76:79], v[132:135], v[172:175], v[76:79]
	v_mfma_f32_16x16x32_bf16 v[84:87], v[132:135], v[180:183], v[84:87]
	v_mfma_f32_16x16x32_bf16 v[84:87], v[136:139], v[184:187], v[84:87]
	v_mfma_f32_16x16x32_bf16 v[88:91], v[144:147], v[184:187], v[88:91]
	v_mfma_f32_16x16x32_bf16 v[88:91], v[140:143], v[180:183], v[88:91]
	v_mfma_f32_16x16x32_bf16 v[96:99], v[140:143], v[194:197], v[96:99]
	v_mfma_f32_16x16x32_bf16 v[96:99], v[144:147], v[198:201], v[96:99]
	v_mfma_f32_16x16x32_bf16 v[92:95], v[136:139], v[198:201], v[92:95]
	v_mfma_f32_16x16x32_bf16 v[92:95], v[132:135], v[194:197], v[92:95]
	s_setprio 0
	s_setprio 1
	v_mfma_f32_16x16x32_bf16 v[100:103], v[148:151], v[164:167], v[100:103]
	v_mfma_f32_16x16x32_bf16 v[100:103], v[152:155], v[168:171], v[100:103]
	v_mfma_f32_16x16x32_bf16 v[104:107], v[160:163], v[168:171], v[104:107]
	v_mfma_f32_16x16x32_bf16 v[104:107], v[156:159], v[164:167], v[104:107]
	v_mfma_f32_16x16x32_bf16 v[112:115], v[156:159], v[172:175], v[112:115]
	v_mfma_f32_16x16x32_bf16 v[112:115], v[160:163], v[176:179], v[112:115]
	v_mfma_f32_16x16x32_bf16 v[108:111], v[152:155], v[176:179], v[108:111]
	v_mfma_f32_16x16x32_bf16 v[108:111], v[148:151], v[172:175], v[108:111]
	v_mfma_f32_16x16x32_bf16 v[116:119], v[148:151], v[180:183], v[116:119]
	v_mfma_f32_16x16x32_bf16 v[116:119], v[152:155], v[184:187], v[116:119]
	v_mfma_f32_16x16x32_bf16 v[120:123], v[160:163], v[184:187], v[120:123]
	v_mfma_f32_16x16x32_bf16 v[120:123], v[156:159], v[180:183], v[120:123]
	v_mfma_f32_16x16x32_bf16 v[128:131], v[156:159], v[194:197], v[128:131]
	v_mfma_f32_16x16x32_bf16 v[128:131], v[160:163], v[198:201], v[128:131]
	s_setprio 2
	s_barrier
	v_mfma_f32_16x16x32_bf16 v[124:127], v[152:155], v[198:201], v[124:127]
	v_mfma_f32_16x16x32_bf16 v[124:127], v[148:151], v[194:197], v[124:127]
	s_add_i32 s38, 0, 0x18000
	s_add_i32 s42, 0, 0x1c000
	v_add_u32_e32 v144, s38, v232
	v_add_u32_e32 v160, s42, v232
	ds_read_b128 v[132:135], v144
	ds_read_b128 v[136:139], v144 offset:1024
	ds_read_b128 v[140:143], v144 offset:2048
	ds_read_b128 v[144:147], v144 offset:3072
	ds_read_b128 v[148:151], v160
	ds_read_b128 v[152:155], v160 offset:1024
	ds_read_b128 v[156:159], v160 offset:2048
	ds_read_b128 v[160:163], v160 offset:3072
	s_add_u32 s26, s26, 0x160000
	s_addc_u32 s27, s27, 0
	s_mov_b32 m0, s57
	ds_read_b128 v[164:167], v210 offset:32768
	ds_read_b128 v[168:171], v210 offset:33792
	ds_read_b128 v[172:175], v210 offset:34816
	ds_read_b128 v[176:179], v210 offset:35840
	ds_read_b128 v[180:183], v210 offset:36864
	ds_read_b128 v[184:187], v210 offset:37888
	ds_read_b128 v[194:197], v210 offset:38912
	ds_read_b128 v[198:201], v210 offset:39936
	global_load_lds_dwordx4 v2, s[26:27]
	s_mov_b32 m0, s58
	s_nop 0
	global_load_lds_dwordx4 v188, s[26:27]
	s_setprio 0
	s_waitcnt vmcnt(8)
	s_waitcnt lgkmcnt(0)
	s_barrier
	s_setprio 1
	s_waitcnt lgkmcnt(0)
	v_mfma_f32_16x16x32_bf16 v[4:7], v[132:135], v[164:167], v[4:7]
	v_mfma_f32_16x16x32_bf16 v[4:7], v[136:139], v[168:171], v[4:7]
	v_mfma_f32_16x16x32_bf16 v[8:11], v[144:147], v[168:171], v[8:11]
	v_mfma_f32_16x16x32_bf16 v[8:11], v[140:143], v[164:167], v[8:11]
	v_mfma_f32_16x16x32_bf16 v[16:19], v[140:143], v[172:175], v[16:19]
	v_mfma_f32_16x16x32_bf16 v[16:19], v[144:147], v[176:179], v[16:19]
	v_mfma_f32_16x16x32_bf16 v[12:15], v[136:139], v[176:179], v[12:15]
	v_mfma_f32_16x16x32_bf16 v[12:15], v[132:135], v[172:175], v[12:15]
	v_mfma_f32_16x16x32_bf16 v[20:23], v[132:135], v[180:183], v[20:23]
	v_mfma_f32_16x16x32_bf16 v[20:23], v[136:139], v[184:187], v[20:23]
	v_mfma_f32_16x16x32_bf16 v[24:27], v[144:147], v[184:187], v[24:27]
	v_mfma_f32_16x16x32_bf16 v[24:27], v[140:143], v[180:183], v[24:27]
	v_mfma_f32_16x16x32_bf16 v[32:35], v[140:143], v[194:197], v[32:35]
	v_mfma_f32_16x16x32_bf16 v[32:35], v[144:147], v[198:201], v[32:35]
	v_mfma_f32_16x16x32_bf16 v[28:31], v[136:139], v[198:201], v[28:31]
	v_mfma_f32_16x16x32_bf16 v[28:31], v[132:135], v[194:197], v[28:31]
	s_setprio 0
	s_setprio 1
	v_mfma_f32_16x16x32_bf16 v[36:39], v[148:151], v[164:167], v[36:39]
	v_mfma_f32_16x16x32_bf16 v[36:39], v[152:155], v[168:171], v[36:39]
	v_mfma_f32_16x16x32_bf16 v[40:43], v[160:163], v[168:171], v[40:43]
	v_mfma_f32_16x16x32_bf16 v[40:43], v[156:159], v[164:167], v[40:43]
	v_mfma_f32_16x16x32_bf16 v[48:51], v[156:159], v[172:175], v[48:51]
	v_mfma_f32_16x16x32_bf16 v[48:51], v[160:163], v[176:179], v[48:51]
	v_mfma_f32_16x16x32_bf16 v[44:47], v[152:155], v[176:179], v[44:47]
	v_mfma_f32_16x16x32_bf16 v[44:47], v[148:151], v[172:175], v[44:47]
	v_mfma_f32_16x16x32_bf16 v[52:55], v[148:151], v[180:183], v[52:55]
	v_mfma_f32_16x16x32_bf16 v[52:55], v[152:155], v[184:187], v[52:55]
	v_mfma_f32_16x16x32_bf16 v[56:59], v[160:163], v[184:187], v[56:59]
	v_mfma_f32_16x16x32_bf16 v[56:59], v[156:159], v[180:183], v[56:59]
	v_mfma_f32_16x16x32_bf16 v[64:67], v[156:159], v[194:197], v[64:67]
	v_mfma_f32_16x16x32_bf16 v[64:67], v[160:163], v[198:201], v[64:67]
	s_setprio 2
	s_barrier
	v_mfma_f32_16x16x32_bf16 v[60:63], v[152:155], v[198:201], v[60:63]
	v_mfma_f32_16x16x32_bf16 v[60:63], v[148:151], v[194:197], v[60:63]
	s_add_i32 s26, s38, s54
	v_lshl_add_u64 v[202:203], v[202:203], 0, s[4:5]
	s_mov_b32 m0, s26
	ds_read_b128 v[164:167], v210 offset:49152
	ds_read_b128 v[168:171], v210 offset:50176
	ds_read_b128 v[172:175], v210 offset:51200
	ds_read_b128 v[176:179], v210 offset:52224
	ds_read_b128 v[180:183], v210 offset:53248
	ds_read_b128 v[184:187], v210 offset:54272
	ds_read_b128 v[194:197], v210 offset:55296
	ds_read_b128 v[198:201], v210 offset:56320
	global_load_lds_dwordx4 v[202:203], off
	s_add_i32 m0, s26, 0x2000
	s_add_u32 s16, s16, 0x15ff80
	v_lshl_add_u64 v[202:203], v[204:205], 0, s[4:5]
	s_addc_u32 s17, s17, 0
	s_add_i32 s26, s42, s54
	global_load_lds_dwordx4 v[202:203], off
	s_mov_b32 m0, s26
	v_lshl_add_u64 v[202:203], v[206:207], 0, s[4:5]
	global_load_lds_dwordx4 v192, s[16:17]
	s_add_i32 m0, s26, 0x2000
	s_nop 0
	global_load_lds_dwordx4 v190, s[16:17]
	s_mov_b32 m0, s62
	s_nop 0
	global_load_lds_dwordx4 v[202:203], off
	v_lshl_add_u64 v[202:203], v[208:209], 0, s[4:5]
	s_mov_b32 m0, s63
	s_nop 0
	global_load_lds_dwordx4 v[202:203], off
	s_setprio 0
	s_waitcnt vmcnt(8)
	s_waitcnt lgkmcnt(0)
	s_barrier
	s_setprio 1
	s_waitcnt lgkmcnt(0)
	v_mfma_f32_16x16x32_bf16 v[68:71], v[132:135], v[164:167], v[68:71]
	v_mfma_f32_16x16x32_bf16 v[68:71], v[136:139], v[168:171], v[68:71]
	v_mfma_f32_16x16x32_bf16 v[72:75], v[144:147], v[168:171], v[72:75]
	v_mfma_f32_16x16x32_bf16 v[72:75], v[140:143], v[164:167], v[72:75]
	v_mfma_f32_16x16x32_bf16 v[80:83], v[140:143], v[172:175], v[80:83]
	v_mfma_f32_16x16x32_bf16 v[80:83], v[144:147], v[176:179], v[80:83]
	v_mfma_f32_16x16x32_bf16 v[76:79], v[136:139], v[176:179], v[76:79]
	v_mfma_f32_16x16x32_bf16 v[76:79], v[132:135], v[172:175], v[76:79]
	v_mfma_f32_16x16x32_bf16 v[84:87], v[132:135], v[180:183], v[84:87]
	v_mfma_f32_16x16x32_bf16 v[84:87], v[136:139], v[184:187], v[84:87]
	v_mfma_f32_16x16x32_bf16 v[88:91], v[144:147], v[184:187], v[88:91]
	v_mfma_f32_16x16x32_bf16 v[88:91], v[140:143], v[180:183], v[88:91]
	v_mfma_f32_16x16x32_bf16 v[96:99], v[140:143], v[194:197], v[96:99]
	v_mfma_f32_16x16x32_bf16 v[96:99], v[144:147], v[198:201], v[96:99]
	v_mfma_f32_16x16x32_bf16 v[92:95], v[136:139], v[198:201], v[92:95]
	v_mfma_f32_16x16x32_bf16 v[92:95], v[132:135], v[194:197], v[92:95]
	s_setprio 0
	s_setprio 1
	v_mfma_f32_16x16x32_bf16 v[100:103], v[148:151], v[164:167], v[100:103]
	v_mfma_f32_16x16x32_bf16 v[100:103], v[152:155], v[168:171], v[100:103]
	v_mfma_f32_16x16x32_bf16 v[104:107], v[160:163], v[168:171], v[104:107]
	v_mfma_f32_16x16x32_bf16 v[104:107], v[156:159], v[164:167], v[104:107]
	v_mfma_f32_16x16x32_bf16 v[112:115], v[156:159], v[172:175], v[112:115]
	v_mfma_f32_16x16x32_bf16 v[112:115], v[160:163], v[176:179], v[112:115]
	v_mfma_f32_16x16x32_bf16 v[108:111], v[152:155], v[176:179], v[108:111]
	v_mfma_f32_16x16x32_bf16 v[108:111], v[148:151], v[172:175], v[108:111]
	v_mfma_f32_16x16x32_bf16 v[116:119], v[148:151], v[180:183], v[116:119]
	v_mfma_f32_16x16x32_bf16 v[116:119], v[152:155], v[184:187], v[116:119]
	v_mfma_f32_16x16x32_bf16 v[120:123], v[160:163], v[184:187], v[120:123]
	v_mfma_f32_16x16x32_bf16 v[120:123], v[156:159], v[180:183], v[120:123]
	v_mfma_f32_16x16x32_bf16 v[128:131], v[156:159], v[194:197], v[128:131]
	v_mfma_f32_16x16x32_bf16 v[128:131], v[160:163], v[198:201], v[128:131]
	s_setprio 2
	s_barrier
	v_mfma_f32_16x16x32_bf16 v[124:127], v[152:155], v[198:201], v[124:127]
	v_mfma_f32_16x16x32_bf16 v[124:127], v[148:151], v[194:197], v[124:127]
	s_setprio 0
	s_cmpk_gt_u32 s28, 0x55
	s_cbranch_scc1 .LBB0_651
	s_mov_b32 s28, s29
	s_branch .LBB0_645

.LBB0_749:
	s_add_i32 s47, 0, 0x10000
	s_add_i32 s49, 0, 0x14000
	v_add_u32_e32 v16, s47, v147
	v_add_u32_e32 v32, s49, v147
	ds_read_b128 v[4:7], v16
	ds_read_b128 v[8:11], v16 offset:1024
	ds_read_b128 v[12:15], v16 offset:2048
	ds_read_b128 v[16:19], v16 offset:3072
	ds_read_b128 v[20:23], v32
	ds_read_b128 v[24:27], v32 offset:1024
	ds_read_b128 v[28:31], v32 offset:2048
	ds_read_b128 v[32:35], v32 offset:3072
	v_add_u32_e32 v231, 0, v146
	ds_read_b128 v[36:39], v231
	ds_read_b128 v[40:43], v231 offset:1024
	ds_read_b128 v[44:47], v231 offset:2048
	ds_read_b128 v[48:51], v231 offset:3072
	ds_read_b128 v[52:55], v231 offset:4096
	ds_read_b128 v[56:59], v231 offset:5120
	ds_read_b128 v[60:63], v231 offset:6144
	ds_read_b128 v[64:67], v231 offset:7168
	s_waitcnt vmcnt(8)
	s_waitcnt lgkmcnt(0)
	s_barrier
	s_setprio 1
	s_waitcnt lgkmcnt(0)
	v_mfma_f32_16x16x32_f16 v[68:71], v[4:7], v[36:39], 0
	v_mfma_f32_16x16x32_f16 v[68:71], v[8:11], v[40:43], v[68:71]
	v_mfma_f32_16x16x32_f16 v[72:75], v[12:15], v[36:39], 0
	v_mfma_f32_16x16x32_f16 v[72:75], v[16:19], v[40:43], v[72:75]
	v_mfma_f32_16x16x32_f16 v[80:83], v[12:15], v[44:47], 0
	v_mfma_f32_16x16x32_f16 v[80:83], v[16:19], v[48:51], v[80:83]
	v_mfma_f32_16x16x32_f16 v[76:79], v[4:7], v[44:47], 0
	v_mfma_f32_16x16x32_f16 v[76:79], v[8:11], v[48:51], v[76:79]
	v_mfma_f32_16x16x32_f16 v[84:87], v[4:7], v[52:55], 0
	v_mfma_f32_16x16x32_f16 v[84:87], v[8:11], v[56:59], v[84:87]
	v_mfma_f32_16x16x32_f16 v[88:91], v[12:15], v[52:55], 0
	v_mfma_f32_16x16x32_f16 v[88:91], v[16:19], v[56:59], v[88:91]
	v_mfma_f32_16x16x32_f16 v[96:99], v[12:15], v[60:63], 0
	v_mfma_f32_16x16x32_f16 v[96:99], v[16:19], v[64:67], v[96:99]
	v_mfma_f32_16x16x32_f16 v[92:95], v[4:7], v[60:63], 0
	v_mfma_f32_16x16x32_f16 v[92:95], v[8:11], v[64:67], v[92:95]
	s_setprio 0
	s_setprio 1
	v_mfma_f32_16x16x32_f16 v[100:103], v[20:23], v[36:39], 0
	v_mfma_f32_16x16x32_f16 v[36:39], v[28:31], v[36:39], 0
	v_mfma_f32_16x16x32_f16 v[104:107], v[20:23], v[44:47], 0
	v_mfma_f32_16x16x32_f16 v[44:47], v[28:31], v[44:47], 0
	v_mfma_f32_16x16x32_f16 v[108:111], v[20:23], v[52:55], 0
	v_mfma_f32_16x16x32_f16 v[52:55], v[28:31], v[52:55], 0
	v_mfma_f32_16x16x32_f16 v[112:115], v[20:23], v[60:63], 0
	v_mfma_f32_16x16x32_f16 v[60:63], v[28:31], v[60:63], 0
	v_mfma_f32_16x16x32_f16 v[100:103], v[24:27], v[40:43], v[100:103]
	v_mfma_f32_16x16x32_f16 v[40:43], v[32:35], v[40:43], v[36:39]
	v_mfma_f32_16x16x32_f16 v[104:107], v[24:27], v[48:51], v[104:107]
	v_mfma_f32_16x16x32_f16 v[48:51], v[32:35], v[48:51], v[44:47]
	v_mfma_f32_16x16x32_f16 v[108:111], v[24:27], v[56:59], v[108:111]
	v_mfma_f32_16x16x32_f16 v[56:59], v[32:35], v[56:59], v[52:55]
	s_setprio 2
	s_barrier
	v_mfma_f32_16x16x32_f16 v[112:115], v[24:27], v[64:67], v[112:115]
	v_mfma_f32_16x16x32_f16 v[64:67], v[32:35], v[64:67], v[60:63]
	v_lshl_add_u64 v[136:137], s[6:7], 0, v[2:3]
	s_add_i32 s47, s47, s62
	v_mov_b32_e32 v135, v3
	v_lshl_add_u64 v[140:141], v[136:137], 0, s[74:75]
	s_mov_b32 m0, s47
	v_lshl_add_u64 v[144:145], s[6:7], 0, v[134:135]
	ds_read_b128 v[36:39], v231 offset:16384
	ds_read_b128 v[44:47], v231 offset:17408
	ds_read_b128 v[52:55], v231 offset:18432
	ds_read_b128 v[60:63], v231 offset:19456
	ds_read_b128 v[116:119], v231 offset:20480
	ds_read_b128 v[120:123], v231 offset:21504
	ds_read_b128 v[124:127], v231 offset:22528
	ds_read_b128 v[128:131], v231 offset:23552
	global_load_lds_dwordx4 v[140:141], off
	v_lshl_add_u64 v[140:141], v[144:145], 0, s[74:75]
	s_add_i32 m0, s47, 0x2000
	s_add_i32 s47, s49, s62
	global_load_lds_dwordx4 v[140:141], off
	s_mov_b32 m0, s47
	v_mov_b32_e32 v139, v3
	global_load_lds_dwordx4 v2, s[16:17]
	s_add_i32 m0, s47, 0x2000
	v_lshl_add_u64 v[248:249], s[8:9], 0, v[138:139]
	v_mov_b32_e32 v133, v3
	global_load_lds_dwordx4 v134, s[16:17]
	v_lshl_add_u64 v[140:141], v[248:249], 0, s[74:75]
	s_mov_b32 m0, s63
	v_lshl_add_u64 v[250:251], s[8:9], 0, v[132:133]
	global_load_lds_dwordx4 v[140:141], off
	v_lshl_add_u64 v[140:141], v[250:251], 0, s[74:75]
	s_mov_b32 m0, s64
	s_nop 0
	global_load_lds_dwordx4 v[140:141], off
	s_setprio 0
	s_waitcnt vmcnt(8)
	s_waitcnt lgkmcnt(0)
	s_barrier
	s_setprio 1
	s_waitcnt lgkmcnt(0)
	v_mfma_f32_16x16x32_f16 v[140:143], v[4:7], v[36:39], 0
	v_mfma_f32_16x16x32_f16 v[148:151], v[12:15], v[36:39], 0
	v_mfma_f32_16x16x32_f16 v[152:155], v[4:7], v[52:55], 0
	v_mfma_f32_16x16x32_f16 v[156:159], v[12:15], v[52:55], 0
	v_mfma_f32_16x16x32_f16 v[160:163], v[4:7], v[116:119], 0
	v_mfma_f32_16x16x32_f16 v[164:167], v[12:15], v[116:119], 0
	v_mfma_f32_16x16x32_f16 v[4:7], v[4:7], v[124:127], 0
	v_mfma_f32_16x16x32_f16 v[12:15], v[12:15], v[124:127], 0
	v_mfma_f32_16x16x32_f16 v[140:143], v[8:11], v[44:47], v[140:143]
	v_mfma_f32_16x16x32_f16 v[148:151], v[16:19], v[44:47], v[148:151]
	v_mfma_f32_16x16x32_f16 v[152:155], v[8:11], v[60:63], v[152:155]
	v_mfma_f32_16x16x32_f16 v[156:159], v[16:19], v[60:63], v[156:159]
	v_mfma_f32_16x16x32_f16 v[160:163], v[8:11], v[120:123], v[160:163]
	v_mfma_f32_16x16x32_f16 v[164:167], v[16:19], v[120:123], v[164:167]
	v_mfma_f32_16x16x32_f16 v[168:171], v[8:11], v[128:131], v[4:7]
	v_mfma_f32_16x16x32_f16 v[172:175], v[16:19], v[128:131], v[12:15]
	s_setprio 0
	s_setprio 1
	v_mfma_f32_16x16x32_f16 v[4:7], v[20:23], v[36:39], 0
	v_mfma_f32_16x16x32_f16 v[8:11], v[28:31], v[36:39], 0
	v_mfma_f32_16x16x32_f16 v[12:15], v[20:23], v[52:55], 0
	v_mfma_f32_16x16x32_f16 v[16:19], v[28:31], v[52:55], 0
	v_mfma_f32_16x16x32_f16 v[36:39], v[20:23], v[116:119], 0
	v_mfma_f32_16x16x32_f16 v[52:55], v[28:31], v[116:119], 0
	v_mfma_f32_16x16x32_f16 v[20:23], v[20:23], v[124:127], 0
	v_mfma_f32_16x16x32_f16 v[28:31], v[28:31], v[124:127], 0
	v_mfma_f32_16x16x32_f16 v[116:119], v[24:27], v[44:47], v[4:7]
	v_mfma_f32_16x16x32_f16 v[124:127], v[32:35], v[44:47], v[8:11]
	v_mfma_f32_16x16x32_f16 v[184:187], v[24:27], v[120:123], v[36:39]
	v_mfma_f32_16x16x32_f16 v[120:123], v[32:35], v[120:123], v[52:55]
	v_mfma_f32_16x16x32_f16 v[188:191], v[24:27], v[128:131], v[20:23]
	v_mfma_f32_16x16x32_f16 v[128:131], v[32:35], v[128:131], v[28:31]
	s_setprio 2
	s_barrier
	v_mfma_f32_16x16x32_f16 v[176:179], v[24:27], v[60:63], v[12:15]
	v_mfma_f32_16x16x32_f16 v[180:183], v[32:35], v[60:63], v[16:19]
	s_add_i32 s47, 0, 0x18000
	v_add_u32_e32 v4, s47, v147
	s_add_i32 s49, 0, 0x1c000
	ds_read_b128 v[192:195], v4
	ds_read_b128 v[196:199], v4 offset:1024
	ds_read_b128 v[200:203], v4 offset:2048
	ds_read_b128 v[204:207], v4 offset:3072
	v_add_u32_e32 v4, s49, v147
	ds_read_b128 v[208:211], v4
	ds_read_b128 v[212:215], v4 offset:1024
	ds_read_b128 v[216:219], v4 offset:2048
	ds_read_b128 v[220:223], v4 offset:3072
	s_mov_b32 m0, s65
	ds_read_b128 v[44:47], v231 offset:32768
	ds_read_b128 v[52:55], v231 offset:33792
	ds_read_b128 v[60:63], v231 offset:34816
	ds_read_b128 v[224:227], v231 offset:35840
	ds_read_b128 v[232:235], v231 offset:36864
	ds_read_b128 v[236:239], v231 offset:37888
	ds_read_b128 v[240:243], v231 offset:38912
	ds_read_b128 v[244:247], v231 offset:39936
	global_load_lds_dwordx4 v138, s[26:27]
	s_mov_b32 m0, s66
	s_nop 0
	global_load_lds_dwordx4 v132, s[26:27]
	s_setprio 0
	s_waitcnt vmcnt(8)
	s_waitcnt lgkmcnt(0)
	s_barrier
	s_setprio 1
	s_waitcnt lgkmcnt(0)
	v_mfma_f32_16x16x32_f16 v[4:7], v[192:195], v[44:47], v[68:71]
	v_mfma_f32_16x16x32_f16 v[8:11], v[200:203], v[44:47], v[72:75]
	v_mfma_f32_16x16x32_f16 v[12:15], v[192:195], v[60:63], v[76:79]
	v_mfma_f32_16x16x32_f16 v[16:19], v[200:203], v[60:63], v[80:83]
	v_mfma_f32_16x16x32_f16 v[20:23], v[192:195], v[232:235], v[84:87]
	v_mfma_f32_16x16x32_f16 v[24:27], v[200:203], v[232:235], v[88:91]
	v_mfma_f32_16x16x32_f16 v[28:31], v[192:195], v[240:243], v[92:95]
	v_mfma_f32_16x16x32_f16 v[32:35], v[200:203], v[240:243], v[96:99]
	v_mfma_f32_16x16x32_f16 v[4:7], v[196:199], v[52:55], v[4:7]
	v_mfma_f32_16x16x32_f16 v[8:11], v[204:207], v[52:55], v[8:11]
	v_mfma_f32_16x16x32_f16 v[12:15], v[196:199], v[224:227], v[12:15]
	v_mfma_f32_16x16x32_f16 v[16:19], v[204:207], v[224:227], v[16:19]
	v_mfma_f32_16x16x32_f16 v[20:23], v[196:199], v[236:239], v[20:23]
	v_mfma_f32_16x16x32_f16 v[24:27], v[204:207], v[236:239], v[24:27]
	v_mfma_f32_16x16x32_f16 v[28:31], v[196:199], v[244:247], v[28:31]
	v_mfma_f32_16x16x32_f16 v[32:35], v[204:207], v[244:247], v[32:35]
	s_setprio 0
	s_setprio 1
	v_mfma_f32_16x16x32_f16 v[36:39], v[208:211], v[44:47], v[100:103]
	v_mfma_f32_16x16x32_f16 v[40:43], v[216:219], v[44:47], v[40:43]
	v_mfma_f32_16x16x32_f16 v[36:39], v[212:215], v[52:55], v[36:39]
	v_mfma_f32_16x16x32_f16 v[40:43], v[220:223], v[52:55], v[40:43]
	v_mfma_f32_16x16x32_f16 v[44:47], v[208:211], v[60:63], v[104:107]
	v_mfma_f32_16x16x32_f16 v[48:51], v[216:219], v[60:63], v[48:51]
	v_mfma_f32_16x16x32_f16 v[52:55], v[208:211], v[232:235], v[108:111]
	v_mfma_f32_16x16x32_f16 v[56:59], v[216:219], v[232:235], v[56:59]
	v_mfma_f32_16x16x32_f16 v[60:63], v[208:211], v[240:243], v[112:115]
	v_mfma_f32_16x16x32_f16 v[64:67], v[216:219], v[240:243], v[64:67]
	v_mfma_f32_16x16x32_f16 v[44:47], v[212:215], v[224:227], v[44:47]
	v_mfma_f32_16x16x32_f16 v[48:51], v[220:223], v[224:227], v[48:51]
	v_mfma_f32_16x16x32_f16 v[52:55], v[212:215], v[236:239], v[52:55]
	v_mfma_f32_16x16x32_f16 v[56:59], v[220:223], v[236:239], v[56:59]
	s_setprio 2
	s_barrier
	v_mfma_f32_16x16x32_f16 v[60:63], v[212:215], v[244:247], v[60:63]
	v_mfma_f32_16x16x32_f16 v[64:67], v[220:223], v[244:247], v[64:67]
	s_add_i32 s47, s47, s62
	v_lshl_add_u64 v[68:69], v[136:137], 0, s[24:25]
	s_mov_b32 m0, s47
	ds_read_b128 v[104:107], v231 offset:49152
	ds_read_b128 v[108:111], v231 offset:50176
	ds_read_b128 v[112:115], v231 offset:51200
	ds_read_b128 v[224:227], v231 offset:52224
	ds_read_b128 v[232:235], v231 offset:53248
	ds_read_b128 v[236:239], v231 offset:54272
	ds_read_b128 v[240:243], v231 offset:55296
	ds_read_b128 v[244:247], v231 offset:56320
	global_load_lds_dwordx4 v[68:69], off
	v_lshl_add_u64 v[68:69], v[144:145], 0, s[24:25]
	s_add_i32 m0, s47, 0x2000
	s_add_i32 s47, s49, s62
	global_load_lds_dwordx4 v[68:69], off
	s_mov_b32 m0, s47
	v_lshl_add_u64 v[68:69], v[248:249], 0, s[24:25]
	global_load_lds_dwordx4 v2, s[28:29]
	s_add_i32 m0, s47, 0x2000
	s_nop 0
	global_load_lds_dwordx4 v134, s[28:29]
	s_mov_b32 m0, s69
	s_nop 0
	global_load_lds_dwordx4 v[68:69], off
	v_lshl_add_u64 v[68:69], v[250:251], 0, s[24:25]
	s_mov_b32 m0, s70
	s_nop 0
	global_load_lds_dwordx4 v[68:69], off
	s_setprio 0
	s_waitcnt vmcnt(8)
	s_waitcnt lgkmcnt(0)
	s_barrier
	s_setprio 1
	s_waitcnt lgkmcnt(0)
	v_mfma_f32_16x16x32_f16 v[68:71], v[192:195], v[104:107], v[140:143]
	v_mfma_f32_16x16x32_f16 v[72:75], v[200:203], v[104:107], v[148:151]
	v_mfma_f32_16x16x32_f16 v[76:79], v[192:195], v[112:115], v[152:155]
	v_mfma_f32_16x16x32_f16 v[80:83], v[200:203], v[112:115], v[156:159]
	v_mfma_f32_16x16x32_f16 v[84:87], v[192:195], v[232:235], v[160:163]
	v_mfma_f32_16x16x32_f16 v[88:91], v[200:203], v[232:235], v[164:167]
	v_mfma_f32_16x16x32_f16 v[92:95], v[192:195], v[240:243], v[168:171]
	v_mfma_f32_16x16x32_f16 v[96:99], v[200:203], v[240:243], v[172:175]
	v_mfma_f32_16x16x32_f16 v[68:71], v[196:199], v[108:111], v[68:71]
	v_mfma_f32_16x16x32_f16 v[72:75], v[204:207], v[108:111], v[72:75]
	v_mfma_f32_16x16x32_f16 v[76:79], v[196:199], v[224:227], v[76:79]
	v_mfma_f32_16x16x32_f16 v[80:83], v[204:207], v[224:227], v[80:83]
	v_mfma_f32_16x16x32_f16 v[84:87], v[196:199], v[236:239], v[84:87]
	v_mfma_f32_16x16x32_f16 v[88:91], v[204:207], v[236:239], v[88:91]
	v_mfma_f32_16x16x32_f16 v[92:95], v[196:199], v[244:247], v[92:95]
	v_mfma_f32_16x16x32_f16 v[96:99], v[204:207], v[244:247], v[96:99]
	s_setprio 0
	s_setprio 1
	v_mfma_f32_16x16x32_f16 v[100:103], v[208:211], v[104:107], v[116:119]
	v_mfma_f32_16x16x32_f16 v[104:107], v[216:219], v[104:107], v[124:127]
	v_mfma_f32_16x16x32_f16 v[100:103], v[212:215], v[108:111], v[100:103]
	v_mfma_f32_16x16x32_f16 v[104:107], v[220:223], v[108:111], v[104:107]
	v_mfma_f32_16x16x32_f16 v[108:111], v[208:211], v[112:115], v[176:179]
	v_mfma_f32_16x16x32_f16 v[112:115], v[216:219], v[112:115], v[180:183]
	v_mfma_f32_16x16x32_f16 v[116:119], v[208:211], v[232:235], v[184:187]
	v_mfma_f32_16x16x32_f16 v[120:123], v[216:219], v[232:235], v[120:123]
	v_mfma_f32_16x16x32_f16 v[124:127], v[208:211], v[240:243], v[188:191]
	v_mfma_f32_16x16x32_f16 v[128:131], v[216:219], v[240:243], v[128:131]
	v_mfma_f32_16x16x32_f16 v[108:111], v[212:215], v[224:227], v[108:111]
	v_mfma_f32_16x16x32_f16 v[112:115], v[220:223], v[224:227], v[112:115]
	v_mfma_f32_16x16x32_f16 v[116:119], v[212:215], v[236:239], v[116:119]
	v_mfma_f32_16x16x32_f16 v[120:123], v[220:223], v[236:239], v[120:123]
	s_setprio 2
	s_barrier
	v_mfma_f32_16x16x32_f16 v[124:127], v[212:215], v[244:247], v[124:127]
	v_mfma_f32_16x16x32_f16 v[128:131], v[220:223], v[244:247], v[128:131]
	s_setprio 0
	s_add_i32 s45, s45, 2
	s_cmp_ge_i32 s45, s44
	s_cbranch_scc0 .LBB0_749
	v_mov_b32_e32 v136, v2
	s_branch .LBB0_752

.LBB0_753:
	s_add_u32 s6, s8, 0xfff80080
	s_addc_u32 s7, s9, -1
	s_add_i32 s29, 0, 0x10000
	s_cmp_eq_u32 s28, 28
	s_cselect_b32 s17, s13, s7
	s_cselect_b32 s16, s12, s6
	v_add_u32_e32 v133, s29, v147
	s_cselect_b32 s7, s15, s27
	s_cselect_b32 s6, s14, s26
	s_add_i32 s47, 0, 0x14000
	ds_read_b128 v[138:141], v133
	ds_read_b128 v[142:145], v133 offset:1024
	ds_read_b128 v[148:151], v133 offset:2048
	ds_read_b128 v[152:155], v133 offset:3072
	v_add_u32_e32 v133, s47, v147
	ds_read_b128 v[156:159], v133
	ds_read_b128 v[160:163], v133 offset:1024
	ds_read_b128 v[164:167], v133 offset:2048
	ds_read_b128 v[168:171], v133 offset:3072
	s_mov_b32 m0, s71
	v_add_u32_e32 v212, 0, v146
	ds_read_b128 v[172:175], v212
	ds_read_b128 v[176:179], v212 offset:1024
	ds_read_b128 v[180:183], v212 offset:2048
	ds_read_b128 v[184:187], v212 offset:3072
	ds_read_b128 v[188:191], v212 offset:4096
	ds_read_b128 v[192:195], v212 offset:5120
	ds_read_b128 v[196:199], v212 offset:6144
	ds_read_b128 v[200:203], v212 offset:7168
	global_load_lds_dwordx4 v2, s[8:9]
	s_mov_b32 m0, s72
	v_mov_b32_e32 v133, v3
	global_load_lds_dwordx4 v132, s[8:9]
	s_waitcnt vmcnt(8)
	s_waitcnt lgkmcnt(0)
	s_barrier
	s_setprio 1
	s_waitcnt lgkmcnt(0)
	v_mfma_f32_16x16x32_f16 v[4:7], v[138:141], v[172:175], v[4:7]
	v_mfma_f32_16x16x32_f16 v[4:7], v[142:145], v[176:179], v[4:7]
	v_mfma_f32_16x16x32_f16 v[8:11], v[152:155], v[176:179], v[8:11]
	v_mfma_f32_16x16x32_f16 v[8:11], v[148:151], v[172:175], v[8:11]
	v_mfma_f32_16x16x32_f16 v[16:19], v[148:151], v[180:183], v[16:19]
	v_mfma_f32_16x16x32_f16 v[16:19], v[152:155], v[184:187], v[16:19]
	v_mfma_f32_16x16x32_f16 v[12:15], v[142:145], v[184:187], v[12:15]
	v_mfma_f32_16x16x32_f16 v[12:15], v[138:141], v[180:183], v[12:15]
	v_mfma_f32_16x16x32_f16 v[20:23], v[138:141], v[188:191], v[20:23]
	v_mfma_f32_16x16x32_f16 v[20:23], v[142:145], v[192:195], v[20:23]
	v_mfma_f32_16x16x32_f16 v[24:27], v[152:155], v[192:195], v[24:27]
	v_mfma_f32_16x16x32_f16 v[24:27], v[148:151], v[188:191], v[24:27]
	v_mfma_f32_16x16x32_f16 v[32:35], v[148:151], v[196:199], v[32:35]
	v_mfma_f32_16x16x32_f16 v[32:35], v[152:155], v[200:203], v[32:35]
	v_mfma_f32_16x16x32_f16 v[28:31], v[142:145], v[200:203], v[28:31]
	v_mfma_f32_16x16x32_f16 v[28:31], v[138:141], v[196:199], v[28:31]
	s_setprio 0
	s_setprio 1
	v_mfma_f32_16x16x32_f16 v[36:39], v[156:159], v[172:175], v[36:39]
	v_mfma_f32_16x16x32_f16 v[36:39], v[160:163], v[176:179], v[36:39]
	v_mfma_f32_16x16x32_f16 v[40:43], v[168:171], v[176:179], v[40:43]
	v_mfma_f32_16x16x32_f16 v[40:43], v[164:167], v[172:175], v[40:43]
	v_mfma_f32_16x16x32_f16 v[48:51], v[164:167], v[180:183], v[48:51]
	v_mfma_f32_16x16x32_f16 v[48:51], v[168:171], v[184:187], v[48:51]
	v_mfma_f32_16x16x32_f16 v[44:47], v[160:163], v[184:187], v[44:47]
	v_mfma_f32_16x16x32_f16 v[44:47], v[156:159], v[180:183], v[44:47]
	v_mfma_f32_16x16x32_f16 v[52:55], v[156:159], v[188:191], v[52:55]
	v_mfma_f32_16x16x32_f16 v[52:55], v[160:163], v[192:195], v[52:55]
	v_mfma_f32_16x16x32_f16 v[56:59], v[168:171], v[192:195], v[56:59]
	v_mfma_f32_16x16x32_f16 v[56:59], v[164:167], v[188:191], v[56:59]
	v_mfma_f32_16x16x32_f16 v[64:67], v[164:167], v[196:199], v[64:67]
	v_mfma_f32_16x16x32_f16 v[64:67], v[168:171], v[200:203], v[64:67]
	s_setprio 2
	s_barrier
	v_mfma_f32_16x16x32_f16 v[60:63], v[160:163], v[200:203], v[60:63]
	v_mfma_f32_16x16x32_f16 v[60:63], v[156:159], v[196:199], v[60:63]
	s_add_i32 s29, s29, s62
	s_mov_b32 m0, s29
	ds_read_b128 v[172:175], v212 offset:16384
	ds_read_b128 v[176:179], v212 offset:17408
	ds_read_b128 v[180:183], v212 offset:18432
	ds_read_b128 v[184:187], v212 offset:19456
	ds_read_b128 v[188:191], v212 offset:20480
	ds_read_b128 v[192:195], v212 offset:21504
	ds_read_b128 v[196:199], v212 offset:22528
	ds_read_b128 v[200:203], v212 offset:23552
	global_load_lds_dwordx4 v136, s[6:7]
	s_add_i32 m0, s29, 0x2000
	s_add_u32 s44, s6, 0x80000
	s_addc_u32 s45, s7, 0
	s_add_i32 s29, s47, s62
	global_load_lds_dwordx4 v134, s[6:7]
	s_mov_b32 m0, s29
	v_mov_b32_e32 v137, v3
	global_load_lds_dwordx4 v136, s[44:45]
	s_add_i32 m0, s29, 0x2000
	v_mov_b32_e32 v135, v3
	global_load_lds_dwordx4 v134, s[44:45]
	s_mov_b32 m0, s63
	v_lshl_add_u64 v[204:205], s[6:7], 0, v[136:137]
	global_load_lds_dwordx4 v2, s[16:17]
	s_mov_b32 m0, s64
	v_lshl_add_u64 v[206:207], s[6:7], 0, v[134:135]
	global_load_lds_dwordx4 v132, s[16:17]
	s_setprio 0
	s_waitcnt vmcnt(8)
	s_waitcnt lgkmcnt(0)
	v_lshl_add_u64 v[208:209], s[16:17], 0, v[2:3]
	v_lshl_add_u64 v[210:211], s[16:17], 0, v[132:133]
	s_barrier
	s_setprio 1
	s_waitcnt lgkmcnt(0)
	v_mfma_f32_16x16x32_f16 v[68:71], v[138:141], v[172:175], v[68:71]
	v_mfma_f32_16x16x32_f16 v[68:71], v[142:145], v[176:179], v[68:71]
	v_mfma_f32_16x16x32_f16 v[72:75], v[152:155], v[176:179], v[72:75]
	v_mfma_f32_16x16x32_f16 v[72:75], v[148:151], v[172:175], v[72:75]
	v_mfma_f32_16x16x32_f16 v[80:83], v[148:151], v[180:183], v[80:83]
	v_mfma_f32_16x16x32_f16 v[80:83], v[152:155], v[184:187], v[80:83]
	v_mfma_f32_16x16x32_f16 v[76:79], v[142:145], v[184:187], v[76:79]
	v_mfma_f32_16x16x32_f16 v[76:79], v[138:141], v[180:183], v[76:79]
	v_mfma_f32_16x16x32_f16 v[84:87], v[138:141], v[188:191], v[84:87]
	v_mfma_f32_16x16x32_f16 v[84:87], v[142:145], v[192:195], v[84:87]
	v_mfma_f32_16x16x32_f16 v[88:91], v[152:155], v[192:195], v[88:91]
	v_mfma_f32_16x16x32_f16 v[88:91], v[148:151], v[188:191], v[88:91]
	v_mfma_f32_16x16x32_f16 v[96:99], v[148:151], v[196:199], v[96:99]
	v_mfma_f32_16x16x32_f16 v[96:99], v[152:155], v[200:203], v[96:99]
	v_mfma_f32_16x16x32_f16 v[92:95], v[142:145], v[200:203], v[92:95]
	v_mfma_f32_16x16x32_f16 v[92:95], v[138:141], v[196:199], v[92:95]
	s_setprio 0
	s_setprio 1
	v_mfma_f32_16x16x32_f16 v[100:103], v[156:159], v[172:175], v[100:103]
	v_mfma_f32_16x16x32_f16 v[100:103], v[160:163], v[176:179], v[100:103]
	v_mfma_f32_16x16x32_f16 v[104:107], v[168:171], v[176:179], v[104:107]
	v_mfma_f32_16x16x32_f16 v[104:107], v[164:167], v[172:175], v[104:107]
	v_mfma_f32_16x16x32_f16 v[112:115], v[164:167], v[180:183], v[112:115]
	v_mfma_f32_16x16x32_f16 v[112:115], v[168:171], v[184:187], v[112:115]
	v_mfma_f32_16x16x32_f16 v[108:111], v[160:163], v[184:187], v[108:111]
	v_mfma_f32_16x16x32_f16 v[108:111], v[156:159], v[180:183], v[108:111]
	v_mfma_f32_16x16x32_f16 v[116:119], v[156:159], v[188:191], v[116:119]
	v_mfma_f32_16x16x32_f16 v[116:119], v[160:163], v[192:195], v[116:119]
	v_mfma_f32_16x16x32_f16 v[120:123], v[168:171], v[192:195], v[120:123]
	v_mfma_f32_16x16x32_f16 v[120:123], v[164:167], v[188:191], v[120:123]
	v_mfma_f32_16x16x32_f16 v[128:131], v[164:167], v[196:199], v[128:131]
	v_mfma_f32_16x16x32_f16 v[128:131], v[168:171], v[200:203], v[128:131]
	s_setprio 2
	s_barrier
	v_mfma_f32_16x16x32_f16 v[124:127], v[160:163], v[200:203], v[124:127]
	v_mfma_f32_16x16x32_f16 v[124:127], v[156:159], v[196:199], v[124:127]
	s_add_i32 s29, 0, 0x18000
	v_add_u32_e32 v135, s29, v147
	s_add_i32 s44, 0, 0x1c000
	ds_read_b128 v[138:141], v135
	ds_read_b128 v[142:145], v135 offset:1024
	ds_read_b128 v[148:151], v135 offset:2048
	ds_read_b128 v[152:155], v135 offset:3072
	v_add_u32_e32 v135, s44, v147
	ds_read_b128 v[156:159], v135
	ds_read_b128 v[160:163], v135 offset:1024
	ds_read_b128 v[164:167], v135 offset:2048
	ds_read_b128 v[168:171], v135 offset:3072
	s_add_u32 s16, s16, 0x80000
	s_addc_u32 s17, s17, 0
	s_mov_b32 m0, s65
	ds_read_b128 v[172:175], v212 offset:32768
	ds_read_b128 v[176:179], v212 offset:33792
	ds_read_b128 v[180:183], v212 offset:34816
	ds_read_b128 v[184:187], v212 offset:35840
	ds_read_b128 v[188:191], v212 offset:36864
	ds_read_b128 v[192:195], v212 offset:37888
	ds_read_b128 v[196:199], v212 offset:38912
	ds_read_b128 v[200:203], v212 offset:39936
	global_load_lds_dwordx4 v2, s[16:17]
	s_mov_b32 m0, s66
	s_nop 0
	global_load_lds_dwordx4 v132, s[16:17]
	s_setprio 0
	s_waitcnt vmcnt(8)
	s_waitcnt lgkmcnt(0)
	s_barrier
	s_setprio 1
	s_waitcnt lgkmcnt(0)
	v_mfma_f32_16x16x32_f16 v[4:7], v[138:141], v[172:175], v[4:7]
	v_mfma_f32_16x16x32_f16 v[4:7], v[142:145], v[176:179], v[4:7]
	v_mfma_f32_16x16x32_f16 v[8:11], v[152:155], v[176:179], v[8:11]
	v_mfma_f32_16x16x32_f16 v[8:11], v[148:151], v[172:175], v[8:11]
	v_mfma_f32_16x16x32_f16 v[16:19], v[148:151], v[180:183], v[16:19]
	v_mfma_f32_16x16x32_f16 v[16:19], v[152:155], v[184:187], v[16:19]
	v_mfma_f32_16x16x32_f16 v[12:15], v[142:145], v[184:187], v[12:15]
	v_mfma_f32_16x16x32_f16 v[12:15], v[138:141], v[180:183], v[12:15]
	v_mfma_f32_16x16x32_f16 v[20:23], v[138:141], v[188:191], v[20:23]
	v_mfma_f32_16x16x32_f16 v[20:23], v[142:145], v[192:195], v[20:23]
	v_mfma_f32_16x16x32_f16 v[24:27], v[152:155], v[192:195], v[24:27]
	v_mfma_f32_16x16x32_f16 v[24:27], v[148:151], v[188:191], v[24:27]
	v_mfma_f32_16x16x32_f16 v[32:35], v[148:151], v[196:199], v[32:35]
	v_mfma_f32_16x16x32_f16 v[32:35], v[152:155], v[200:203], v[32:35]
	v_mfma_f32_16x16x32_f16 v[28:31], v[142:145], v[200:203], v[28:31]
	v_mfma_f32_16x16x32_f16 v[28:31], v[138:141], v[196:199], v[28:31]
	s_setprio 0
	s_setprio 1
	v_mfma_f32_16x16x32_f16 v[36:39], v[156:159], v[172:175], v[36:39]
	v_mfma_f32_16x16x32_f16 v[36:39], v[160:163], v[176:179], v[36:39]
	v_mfma_f32_16x16x32_f16 v[40:43], v[168:171], v[176:179], v[40:43]
	v_mfma_f32_16x16x32_f16 v[40:43], v[164:167], v[172:175], v[40:43]
	v_mfma_f32_16x16x32_f16 v[48:51], v[164:167], v[180:183], v[48:51]
	v_mfma_f32_16x16x32_f16 v[48:51], v[168:171], v[184:187], v[48:51]
	v_mfma_f32_16x16x32_f16 v[44:47], v[160:163], v[184:187], v[44:47]
	v_mfma_f32_16x16x32_f16 v[44:47], v[156:159], v[180:183], v[44:47]
	v_mfma_f32_16x16x32_f16 v[52:55], v[156:159], v[188:191], v[52:55]
	v_mfma_f32_16x16x32_f16 v[52:55], v[160:163], v[192:195], v[52:55]
	v_mfma_f32_16x16x32_f16 v[56:59], v[168:171], v[192:195], v[56:59]
	v_mfma_f32_16x16x32_f16 v[56:59], v[164:167], v[188:191], v[56:59]
	v_mfma_f32_16x16x32_f16 v[64:67], v[164:167], v[196:199], v[64:67]
	v_mfma_f32_16x16x32_f16 v[64:67], v[168:171], v[200:203], v[64:67]
	s_setprio 2
	s_barrier
	v_mfma_f32_16x16x32_f16 v[60:63], v[160:163], v[200:203], v[60:63]
	v_mfma_f32_16x16x32_f16 v[60:63], v[156:159], v[196:199], v[60:63]
	s_add_i32 s16, s29, s62
	v_lshl_add_u64 v[204:205], v[204:205], 0, s[86:87]
	s_mov_b32 m0, s16
	ds_read_b128 v[172:175], v212 offset:49152
	ds_read_b128 v[176:179], v212 offset:50176
	ds_read_b128 v[180:183], v212 offset:51200
	ds_read_b128 v[184:187], v212 offset:52224
	ds_read_b128 v[188:191], v212 offset:53248
	ds_read_b128 v[192:195], v212 offset:54272
	ds_read_b128 v[196:199], v212 offset:55296
	ds_read_b128 v[200:203], v212 offset:56320
	global_load_lds_dwordx4 v[204:205], off
	s_add_i32 m0, s16, 0x2000
	s_add_u32 s6, s6, 0x80080
	v_lshl_add_u64 v[204:205], v[206:207], 0, s[86:87]
	s_addc_u32 s7, s7, 0
	s_add_i32 s16, s44, s62
	global_load_lds_dwordx4 v[204:205], off
	s_mov_b32 m0, s16
	v_lshl_add_u64 v[204:205], v[208:209], 0, s[86:87]
	global_load_lds_dwordx4 v136, s[6:7]
	s_add_i32 m0, s16, 0x2000
	s_nop 0
	global_load_lds_dwordx4 v134, s[6:7]
	s_mov_b32 m0, s69
	s_nop 0
	global_load_lds_dwordx4 v[204:205], off
	v_lshl_add_u64 v[204:205], v[210:211], 0, s[86:87]
	s_mov_b32 m0, s70
	s_nop 0
	global_load_lds_dwordx4 v[204:205], off
	s_setprio 0
	s_waitcnt vmcnt(8)
	s_waitcnt lgkmcnt(0)
	s_barrier
	s_setprio 1
	s_waitcnt lgkmcnt(0)
	v_mfma_f32_16x16x32_f16 v[68:71], v[138:141], v[172:175], v[68:71]
	v_mfma_f32_16x16x32_f16 v[68:71], v[142:145], v[176:179], v[68:71]
	v_mfma_f32_16x16x32_f16 v[72:75], v[152:155], v[176:179], v[72:75]
	v_mfma_f32_16x16x32_f16 v[72:75], v[148:151], v[172:175], v[72:75]
	v_mfma_f32_16x16x32_f16 v[80:83], v[148:151], v[180:183], v[80:83]
	v_mfma_f32_16x16x32_f16 v[80:83], v[152:155], v[184:187], v[80:83]
	v_mfma_f32_16x16x32_f16 v[76:79], v[142:145], v[184:187], v[76:79]
	v_mfma_f32_16x16x32_f16 v[76:79], v[138:141], v[180:183], v[76:79]
	v_mfma_f32_16x16x32_f16 v[84:87], v[138:141], v[188:191], v[84:87]
	v_mfma_f32_16x16x32_f16 v[84:87], v[142:145], v[192:195], v[84:87]
	v_mfma_f32_16x16x32_f16 v[88:91], v[152:155], v[192:195], v[88:91]
	v_mfma_f32_16x16x32_f16 v[88:91], v[148:151], v[188:191], v[88:91]
	v_mfma_f32_16x16x32_f16 v[96:99], v[148:151], v[196:199], v[96:99]
	v_mfma_f32_16x16x32_f16 v[96:99], v[152:155], v[200:203], v[96:99]
	v_mfma_f32_16x16x32_f16 v[92:95], v[142:145], v[200:203], v[92:95]
	v_mfma_f32_16x16x32_f16 v[92:95], v[138:141], v[196:199], v[92:95]
	s_setprio 0
	s_setprio 1
	v_mfma_f32_16x16x32_f16 v[100:103], v[156:159], v[172:175], v[100:103]
	v_mfma_f32_16x16x32_f16 v[100:103], v[160:163], v[176:179], v[100:103]
	v_mfma_f32_16x16x32_f16 v[104:107], v[168:171], v[176:179], v[104:107]
	v_mfma_f32_16x16x32_f16 v[104:107], v[164:167], v[172:175], v[104:107]
	v_mfma_f32_16x16x32_f16 v[112:115], v[164:167], v[180:183], v[112:115]
	v_mfma_f32_16x16x32_f16 v[112:115], v[168:171], v[184:187], v[112:115]
	v_mfma_f32_16x16x32_f16 v[108:111], v[160:163], v[184:187], v[108:111]
	v_mfma_f32_16x16x32_f16 v[108:111], v[156:159], v[180:183], v[108:111]
	v_mfma_f32_16x16x32_f16 v[116:119], v[156:159], v[188:191], v[116:119]
	v_mfma_f32_16x16x32_f16 v[116:119], v[160:163], v[192:195], v[116:119]
	v_mfma_f32_16x16x32_f16 v[120:123], v[168:171], v[192:195], v[120:123]
	v_mfma_f32_16x16x32_f16 v[120:123], v[164:167], v[188:191], v[120:123]
	v_mfma_f32_16x16x32_f16 v[128:131], v[164:167], v[196:199], v[128:131]
	v_mfma_f32_16x16x32_f16 v[128:131], v[168:171], v[200:203], v[128:131]
	s_setprio 2
	s_barrier
	v_mfma_f32_16x16x32_f16 v[124:127], v[160:163], v[200:203], v[124:127]
	v_mfma_f32_16x16x32_f16 v[124:127], v[156:159], v[196:199], v[124:127]
	s_setprio 0
	s_add_i32 s28, s28, 2
	s_add_u32 s8, s8, 0x100
	s_addc_u32 s9, s9, 0
	s_add_u32 s26, s26, 0x100
	s_addc_u32 s27, s27, 0
	s_cmp_gt_u32 s28, 29
	s_cbranch_scc0 .LBB0_753
	s_and_b64 vcc, exec, s[52:53]
	s_cbranch_vccz .LBB0_756
	s_barrier

.LBB0_1175:
	s_add_i32 s61, 0, 0x10000
	s_add_i32 s79, 0, 0x14000
	v_add_u32_e32 v16, s61, v209
	v_add_u32_e32 v32, s79, v209
	ds_read_b128 v[4:7], v16
	ds_read_b128 v[8:11], v16 offset:1024
	ds_read_b128 v[12:15], v16 offset:2048
	ds_read_b128 v[16:19], v16 offset:3072
	ds_read_b128 v[20:23], v32
	ds_read_b128 v[24:27], v32 offset:1024
	ds_read_b128 v[28:31], v32 offset:2048
	ds_read_b128 v[32:35], v32 offset:3072
	v_add_u32_e32 v231, 0, v208
	ds_read_b128 v[36:39], v231
	ds_read_b128 v[40:43], v231 offset:1024
	ds_read_b128 v[44:47], v231 offset:2048
	ds_read_b128 v[48:51], v231 offset:3072
	ds_read_b128 v[52:55], v231 offset:4096
	ds_read_b128 v[56:59], v231 offset:5120
	ds_read_b128 v[60:63], v231 offset:6144
	ds_read_b128 v[64:67], v231 offset:7168
	s_waitcnt vmcnt(8)
	s_waitcnt lgkmcnt(0)
	s_barrier
	s_setprio 1
	s_waitcnt lgkmcnt(0)
	v_mfma_f32_16x16x32_bf16 v[68:71], v[4:7], v[36:39], 0
	v_mfma_f32_16x16x32_bf16 v[68:71], v[8:11], v[40:43], v[68:71]
	v_mfma_f32_16x16x32_bf16 v[72:75], v[12:15], v[36:39], 0
	v_mfma_f32_16x16x32_bf16 v[72:75], v[16:19], v[40:43], v[72:75]
	v_mfma_f32_16x16x32_bf16 v[80:83], v[12:15], v[44:47], 0
	v_mfma_f32_16x16x32_bf16 v[80:83], v[16:19], v[48:51], v[80:83]
	v_mfma_f32_16x16x32_bf16 v[76:79], v[4:7], v[44:47], 0
	v_mfma_f32_16x16x32_bf16 v[76:79], v[8:11], v[48:51], v[76:79]
	v_mfma_f32_16x16x32_bf16 v[84:87], v[4:7], v[52:55], 0
	v_mfma_f32_16x16x32_bf16 v[84:87], v[8:11], v[56:59], v[84:87]
	v_mfma_f32_16x16x32_bf16 v[88:91], v[12:15], v[52:55], 0
	v_mfma_f32_16x16x32_bf16 v[88:91], v[16:19], v[56:59], v[88:91]
	v_mfma_f32_16x16x32_bf16 v[96:99], v[12:15], v[60:63], 0
	v_mfma_f32_16x16x32_bf16 v[96:99], v[16:19], v[64:67], v[96:99]
	v_mfma_f32_16x16x32_bf16 v[92:95], v[4:7], v[60:63], 0
	v_mfma_f32_16x16x32_bf16 v[92:95], v[8:11], v[64:67], v[92:95]
	s_setprio 0
	s_setprio 1
	v_mfma_f32_16x16x32_bf16 v[100:103], v[20:23], v[36:39], 0
	v_mfma_f32_16x16x32_bf16 v[36:39], v[28:31], v[36:39], 0
	v_mfma_f32_16x16x32_bf16 v[104:107], v[20:23], v[44:47], 0
	v_mfma_f32_16x16x32_bf16 v[44:47], v[28:31], v[44:47], 0
	v_mfma_f32_16x16x32_bf16 v[108:111], v[20:23], v[52:55], 0
	v_mfma_f32_16x16x32_bf16 v[52:55], v[28:31], v[52:55], 0
	v_mfma_f32_16x16x32_bf16 v[112:115], v[20:23], v[60:63], 0
	v_mfma_f32_16x16x32_bf16 v[60:63], v[28:31], v[60:63], 0
	v_mfma_f32_16x16x32_bf16 v[100:103], v[24:27], v[40:43], v[100:103]
	v_mfma_f32_16x16x32_bf16 v[40:43], v[32:35], v[40:43], v[36:39]
	v_mfma_f32_16x16x32_bf16 v[104:107], v[24:27], v[48:51], v[104:107]
	v_mfma_f32_16x16x32_bf16 v[48:51], v[32:35], v[48:51], v[44:47]
	v_mfma_f32_16x16x32_bf16 v[108:111], v[24:27], v[56:59], v[108:111]
	v_mfma_f32_16x16x32_bf16 v[56:59], v[32:35], v[56:59], v[52:55]
	s_setprio 2
	s_barrier
	v_mfma_f32_16x16x32_bf16 v[112:115], v[24:27], v[64:67], v[112:115]
	v_mfma_f32_16x16x32_bf16 v[64:67], v[32:35], v[64:67], v[60:63]
	v_lshl_add_u64 v[186:187], s[12:13], 0, v[2:3]
	s_add_i32 s61, s61, s36
	v_mov_b32_e32 v191, v3
	v_lshl_add_u64 v[134:135], v[186:187], 0, s[74:75]
	s_mov_b32 m0, s61
	v_lshl_add_u64 v[226:227], s[12:13], 0, v[190:191]
	ds_read_b128 v[36:39], v231 offset:16384
	ds_read_b128 v[44:47], v231 offset:17408
	ds_read_b128 v[52:55], v231 offset:18432
	ds_read_b128 v[60:63], v231 offset:19456
	ds_read_b128 v[116:119], v231 offset:20480
	ds_read_b128 v[120:123], v231 offset:21504
	ds_read_b128 v[124:127], v231 offset:22528
	ds_read_b128 v[128:131], v231 offset:23552
	global_load_lds_dwordx4 v[134:135], off
	v_lshl_add_u64 v[134:135], v[226:227], 0, s[74:75]
	s_add_i32 m0, s61, 0x2000
	s_add_i32 s61, s79, s36
	global_load_lds_dwordx4 v[134:135], off
	s_mov_b32 m0, s61
	v_mov_b32_e32 v133, v3
	global_load_lds_dwordx4 v2, s[16:17]
	s_add_i32 m0, s61, 0x2000
	v_lshl_add_u64 v[248:249], s[6:7], 0, v[132:133]
	v_mov_b32_e32 v189, v3
	global_load_lds_dwordx4 v190, s[16:17]
	v_lshl_add_u64 v[134:135], v[248:249], 0, s[74:75]
	s_mov_b32 m0, s37
	v_lshl_add_u64 v[250:251], s[6:7], 0, v[188:189]
	global_load_lds_dwordx4 v[134:135], off
	v_lshl_add_u64 v[134:135], v[250:251], 0, s[74:75]
	s_mov_b32 m0, s66
	s_nop 0
	global_load_lds_dwordx4 v[134:135], off
	s_setprio 0
	s_waitcnt vmcnt(8)
	s_waitcnt lgkmcnt(0)
	s_barrier
	s_setprio 1
	s_waitcnt lgkmcnt(0)
	v_mfma_f32_16x16x32_bf16 v[134:137], v[4:7], v[36:39], 0
	v_mfma_f32_16x16x32_bf16 v[138:141], v[12:15], v[36:39], 0
	v_mfma_f32_16x16x32_bf16 v[142:145], v[4:7], v[52:55], 0
	v_mfma_f32_16x16x32_bf16 v[146:149], v[12:15], v[52:55], 0
	v_mfma_f32_16x16x32_bf16 v[150:153], v[4:7], v[116:119], 0
	v_mfma_f32_16x16x32_bf16 v[154:157], v[12:15], v[116:119], 0
	v_mfma_f32_16x16x32_bf16 v[4:7], v[4:7], v[124:127], 0
	v_mfma_f32_16x16x32_bf16 v[12:15], v[12:15], v[124:127], 0
	v_mfma_f32_16x16x32_bf16 v[134:137], v[8:11], v[44:47], v[134:137]
	v_mfma_f32_16x16x32_bf16 v[138:141], v[16:19], v[44:47], v[138:141]
	v_mfma_f32_16x16x32_bf16 v[142:145], v[8:11], v[60:63], v[142:145]
	v_mfma_f32_16x16x32_bf16 v[146:149], v[16:19], v[60:63], v[146:149]
	v_mfma_f32_16x16x32_bf16 v[150:153], v[8:11], v[120:123], v[150:153]
	v_mfma_f32_16x16x32_bf16 v[154:157], v[16:19], v[120:123], v[154:157]
	v_mfma_f32_16x16x32_bf16 v[158:161], v[8:11], v[128:131], v[4:7]
	v_mfma_f32_16x16x32_bf16 v[162:165], v[16:19], v[128:131], v[12:15]
	s_setprio 0
	s_setprio 1
	v_mfma_f32_16x16x32_bf16 v[4:7], v[20:23], v[36:39], 0
	v_mfma_f32_16x16x32_bf16 v[8:11], v[28:31], v[36:39], 0
	v_mfma_f32_16x16x32_bf16 v[12:15], v[20:23], v[52:55], 0
	v_mfma_f32_16x16x32_bf16 v[16:19], v[28:31], v[52:55], 0
	v_mfma_f32_16x16x32_bf16 v[36:39], v[20:23], v[116:119], 0
	v_mfma_f32_16x16x32_bf16 v[52:55], v[28:31], v[116:119], 0
	v_mfma_f32_16x16x32_bf16 v[20:23], v[20:23], v[124:127], 0
	v_mfma_f32_16x16x32_bf16 v[28:31], v[28:31], v[124:127], 0
	v_mfma_f32_16x16x32_bf16 v[116:119], v[24:27], v[44:47], v[4:7]
	v_mfma_f32_16x16x32_bf16 v[124:127], v[32:35], v[44:47], v[8:11]
	v_mfma_f32_16x16x32_bf16 v[174:177], v[24:27], v[120:123], v[36:39]
	v_mfma_f32_16x16x32_bf16 v[120:123], v[32:35], v[120:123], v[52:55]
	v_mfma_f32_16x16x32_bf16 v[178:181], v[24:27], v[128:131], v[20:23]
	v_mfma_f32_16x16x32_bf16 v[128:131], v[32:35], v[128:131], v[28:31]
	s_setprio 2
	s_barrier
	v_mfma_f32_16x16x32_bf16 v[166:169], v[24:27], v[60:63], v[12:15]
	v_mfma_f32_16x16x32_bf16 v[170:173], v[32:35], v[60:63], v[16:19]
	s_add_i32 s61, 0, 0x18000
	v_add_u32_e32 v4, s61, v209
	s_add_i32 s79, 0, 0x1c000
	ds_read_b128 v[182:185], v4
	ds_read_b128 v[192:195], v4 offset:1024
	ds_read_b128 v[196:199], v4 offset:2048
	ds_read_b128 v[200:203], v4 offset:3072
	v_add_u32_e32 v4, s79, v209
	ds_read_b128 v[204:207], v4
	ds_read_b128 v[210:213], v4 offset:1024
	ds_read_b128 v[214:217], v4 offset:2048
	ds_read_b128 v[218:221], v4 offset:3072
	s_mov_b32 m0, s67
	ds_read_b128 v[44:47], v231 offset:32768
	ds_read_b128 v[52:55], v231 offset:33792
	ds_read_b128 v[60:63], v231 offset:34816
	ds_read_b128 v[222:225], v231 offset:35840
	ds_read_b128 v[232:235], v231 offset:36864
	ds_read_b128 v[236:239], v231 offset:37888
	ds_read_b128 v[240:243], v231 offset:38912
	ds_read_b128 v[244:247], v231 offset:39936
	global_load_lds_dwordx4 v132, s[26:27]
	s_mov_b32 m0, s68
	s_nop 0
	global_load_lds_dwordx4 v188, s[26:27]
	s_setprio 0
	s_waitcnt vmcnt(8)
	s_waitcnt lgkmcnt(0)
	s_barrier
	s_setprio 1
	s_waitcnt lgkmcnt(0)
	v_mfma_f32_16x16x32_bf16 v[4:7], v[182:185], v[44:47], v[68:71]
	v_mfma_f32_16x16x32_bf16 v[8:11], v[196:199], v[44:47], v[72:75]
	v_mfma_f32_16x16x32_bf16 v[12:15], v[182:185], v[60:63], v[76:79]
	v_mfma_f32_16x16x32_bf16 v[16:19], v[196:199], v[60:63], v[80:83]
	v_mfma_f32_16x16x32_bf16 v[20:23], v[182:185], v[232:235], v[84:87]
	v_mfma_f32_16x16x32_bf16 v[24:27], v[196:199], v[232:235], v[88:91]
	v_mfma_f32_16x16x32_bf16 v[28:31], v[182:185], v[240:243], v[92:95]
	v_mfma_f32_16x16x32_bf16 v[32:35], v[196:199], v[240:243], v[96:99]
	v_mfma_f32_16x16x32_bf16 v[4:7], v[192:195], v[52:55], v[4:7]
	v_mfma_f32_16x16x32_bf16 v[8:11], v[200:203], v[52:55], v[8:11]
	v_mfma_f32_16x16x32_bf16 v[12:15], v[192:195], v[222:225], v[12:15]
	v_mfma_f32_16x16x32_bf16 v[16:19], v[200:203], v[222:225], v[16:19]
	v_mfma_f32_16x16x32_bf16 v[20:23], v[192:195], v[236:239], v[20:23]
	v_mfma_f32_16x16x32_bf16 v[24:27], v[200:203], v[236:239], v[24:27]
	v_mfma_f32_16x16x32_bf16 v[28:31], v[192:195], v[244:247], v[28:31]
	v_mfma_f32_16x16x32_bf16 v[32:35], v[200:203], v[244:247], v[32:35]
	s_setprio 0
	s_setprio 1
	v_mfma_f32_16x16x32_bf16 v[36:39], v[204:207], v[44:47], v[100:103]
	v_mfma_f32_16x16x32_bf16 v[40:43], v[214:217], v[44:47], v[40:43]
	v_mfma_f32_16x16x32_bf16 v[36:39], v[210:213], v[52:55], v[36:39]
	v_mfma_f32_16x16x32_bf16 v[40:43], v[218:221], v[52:55], v[40:43]
	v_mfma_f32_16x16x32_bf16 v[44:47], v[204:207], v[60:63], v[104:107]
	v_mfma_f32_16x16x32_bf16 v[48:51], v[214:217], v[60:63], v[48:51]
	v_mfma_f32_16x16x32_bf16 v[52:55], v[204:207], v[232:235], v[108:111]
	v_mfma_f32_16x16x32_bf16 v[56:59], v[214:217], v[232:235], v[56:59]
	v_mfma_f32_16x16x32_bf16 v[60:63], v[204:207], v[240:243], v[112:115]
	v_mfma_f32_16x16x32_bf16 v[64:67], v[214:217], v[240:243], v[64:67]
	v_mfma_f32_16x16x32_bf16 v[44:47], v[210:213], v[222:225], v[44:47]
	v_mfma_f32_16x16x32_bf16 v[48:51], v[218:221], v[222:225], v[48:51]
	v_mfma_f32_16x16x32_bf16 v[52:55], v[210:213], v[236:239], v[52:55]
	v_mfma_f32_16x16x32_bf16 v[56:59], v[218:221], v[236:239], v[56:59]
	s_setprio 2
	s_barrier
	v_mfma_f32_16x16x32_bf16 v[60:63], v[210:213], v[244:247], v[60:63]
	v_mfma_f32_16x16x32_bf16 v[64:67], v[218:221], v[244:247], v[64:67]
	s_add_i32 s61, s61, s36
	v_lshl_add_u64 v[68:69], v[186:187], 0, s[24:25]
	s_mov_b32 m0, s61
	ds_read_b128 v[104:107], v231 offset:49152
	ds_read_b128 v[108:111], v231 offset:50176
	ds_read_b128 v[112:115], v231 offset:51200
	ds_read_b128 v[222:225], v231 offset:52224
	ds_read_b128 v[232:235], v231 offset:53248
	ds_read_b128 v[236:239], v231 offset:54272
	ds_read_b128 v[240:243], v231 offset:55296
	ds_read_b128 v[244:247], v231 offset:56320
	global_load_lds_dwordx4 v[68:69], off
	v_lshl_add_u64 v[68:69], v[226:227], 0, s[24:25]
	s_add_i32 m0, s61, 0x2000
	s_add_i32 s61, s79, s36
	global_load_lds_dwordx4 v[68:69], off
	s_mov_b32 m0, s61
	v_lshl_add_u64 v[68:69], v[248:249], 0, s[24:25]
	global_load_lds_dwordx4 v2, s[28:29]
	s_add_i32 m0, s61, 0x2000
	s_nop 0
	global_load_lds_dwordx4 v190, s[28:29]
	s_mov_b32 m0, s71
	s_nop 0
	global_load_lds_dwordx4 v[68:69], off
	v_lshl_add_u64 v[68:69], v[250:251], 0, s[24:25]
	s_mov_b32 m0, s72
	s_nop 0
	global_load_lds_dwordx4 v[68:69], off
	s_setprio 0
	s_waitcnt vmcnt(8)
	s_waitcnt lgkmcnt(0)
	s_barrier
	s_setprio 1
	s_waitcnt lgkmcnt(0)
	v_mfma_f32_16x16x32_bf16 v[68:71], v[182:185], v[104:107], v[134:137]
	v_mfma_f32_16x16x32_bf16 v[72:75], v[196:199], v[104:107], v[138:141]
	v_mfma_f32_16x16x32_bf16 v[76:79], v[182:185], v[112:115], v[142:145]
	v_mfma_f32_16x16x32_bf16 v[80:83], v[196:199], v[112:115], v[146:149]
	v_mfma_f32_16x16x32_bf16 v[84:87], v[182:185], v[232:235], v[150:153]
	v_mfma_f32_16x16x32_bf16 v[88:91], v[196:199], v[232:235], v[154:157]
	v_mfma_f32_16x16x32_bf16 v[92:95], v[182:185], v[240:243], v[158:161]
	v_mfma_f32_16x16x32_bf16 v[96:99], v[196:199], v[240:243], v[162:165]
	v_mfma_f32_16x16x32_bf16 v[68:71], v[192:195], v[108:111], v[68:71]
	v_mfma_f32_16x16x32_bf16 v[72:75], v[200:203], v[108:111], v[72:75]
	v_mfma_f32_16x16x32_bf16 v[76:79], v[192:195], v[222:225], v[76:79]
	v_mfma_f32_16x16x32_bf16 v[80:83], v[200:203], v[222:225], v[80:83]
	v_mfma_f32_16x16x32_bf16 v[84:87], v[192:195], v[236:239], v[84:87]
	v_mfma_f32_16x16x32_bf16 v[88:91], v[200:203], v[236:239], v[88:91]
	v_mfma_f32_16x16x32_bf16 v[92:95], v[192:195], v[244:247], v[92:95]
	v_mfma_f32_16x16x32_bf16 v[96:99], v[200:203], v[244:247], v[96:99]
	s_setprio 0
	s_setprio 1
	v_mfma_f32_16x16x32_bf16 v[100:103], v[204:207], v[104:107], v[116:119]
	v_mfma_f32_16x16x32_bf16 v[104:107], v[214:217], v[104:107], v[124:127]
	v_mfma_f32_16x16x32_bf16 v[100:103], v[210:213], v[108:111], v[100:103]
	v_mfma_f32_16x16x32_bf16 v[104:107], v[218:221], v[108:111], v[104:107]
	v_mfma_f32_16x16x32_bf16 v[108:111], v[204:207], v[112:115], v[166:169]
	v_mfma_f32_16x16x32_bf16 v[112:115], v[214:217], v[112:115], v[170:173]
	v_mfma_f32_16x16x32_bf16 v[116:119], v[204:207], v[232:235], v[174:177]
	v_mfma_f32_16x16x32_bf16 v[120:123], v[214:217], v[232:235], v[120:123]
	v_mfma_f32_16x16x32_bf16 v[124:127], v[204:207], v[240:243], v[178:181]
	v_mfma_f32_16x16x32_bf16 v[128:131], v[214:217], v[240:243], v[128:131]
	v_mfma_f32_16x16x32_bf16 v[108:111], v[210:213], v[222:225], v[108:111]
	v_mfma_f32_16x16x32_bf16 v[112:115], v[218:221], v[222:225], v[112:115]
	v_mfma_f32_16x16x32_bf16 v[116:119], v[210:213], v[236:239], v[116:119]
	v_mfma_f32_16x16x32_bf16 v[120:123], v[218:221], v[236:239], v[120:123]
	s_setprio 2
	s_barrier
	v_mfma_f32_16x16x32_bf16 v[124:127], v[210:213], v[244:247], v[124:127]
	v_mfma_f32_16x16x32_bf16 v[128:131], v[218:221], v[244:247], v[128:131]
	s_setprio 0
	s_add_i32 s43, s43, 2
	s_cmp_ge_i32 s43, s42
	s_cbranch_scc0 .LBB0_1175
.LBB0_1176:
	s_add_i32 s12, 0, 0x10000
	s_add_i32 s13, 0, 0x14000
	v_mov_b32_e32 v192, v2
	v_mov_b32_e32 v2, v132
	v_add_u32_e32 v144, s12, v209
	v_add_u32_e32 v160, s13, v209
	ds_read_b128 v[132:135], v144
	ds_read_b128 v[136:139], v144 offset:1024
	ds_read_b128 v[140:143], v144 offset:2048
	ds_read_b128 v[144:147], v144 offset:3072
	ds_read_b128 v[148:151], v160
	ds_read_b128 v[152:155], v160 offset:1024
	ds_read_b128 v[156:159], v160 offset:2048
	ds_read_b128 v[160:163], v160 offset:3072
	s_add_u32 s6, s6, 0x80180
	s_mov_b32 m0, s73
	v_add_u32_e32 v212, 0, v208
	s_addc_u32 s7, s7, 0
	ds_read_b128 v[164:167], v212
	ds_read_b128 v[168:171], v212 offset:1024
	ds_read_b128 v[172:175], v212 offset:2048
	ds_read_b128 v[176:179], v212 offset:3072
	ds_read_b128 v[180:183], v212 offset:4096
	ds_read_b128 v[184:187], v212 offset:5120
	ds_read_b128 v[194:197], v212 offset:6144
	ds_read_b128 v[198:201], v212 offset:7168
	global_load_lds_dwordx4 v2, s[6:7]
	s_mov_b32 m0, s76
	v_mov_b32_e32 v189, v3
	global_load_lds_dwordx4 v188, s[6:7]
	s_waitcnt vmcnt(8)
	s_waitcnt lgkmcnt(0)
	s_barrier
	s_setprio 1
	s_waitcnt lgkmcnt(0)
	v_mfma_f32_16x16x32_bf16 v[4:7], v[132:135], v[164:167], v[4:7]
	v_mfma_f32_16x16x32_bf16 v[4:7], v[136:139], v[168:171], v[4:7]
	v_mfma_f32_16x16x32_bf16 v[8:11], v[144:147], v[168:171], v[8:11]
	v_mfma_f32_16x16x32_bf16 v[8:11], v[140:143], v[164:167], v[8:11]
	v_mfma_f32_16x16x32_bf16 v[16:19], v[140:143], v[172:175], v[16:19]
	v_mfma_f32_16x16x32_bf16 v[16:19], v[144:147], v[176:179], v[16:19]
	v_mfma_f32_16x16x32_bf16 v[12:15], v[136:139], v[176:179], v[12:15]
	v_mfma_f32_16x16x32_bf16 v[12:15], v[132:135], v[172:175], v[12:15]
	v_mfma_f32_16x16x32_bf16 v[20:23], v[132:135], v[180:183], v[20:23]
	v_mfma_f32_16x16x32_bf16 v[20:23], v[136:139], v[184:187], v[20:23]
	v_mfma_f32_16x16x32_bf16 v[24:27], v[144:147], v[184:187], v[24:27]
	v_mfma_f32_16x16x32_bf16 v[24:27], v[140:143], v[180:183], v[24:27]
	v_mfma_f32_16x16x32_bf16 v[32:35], v[140:143], v[194:197], v[32:35]
	v_mfma_f32_16x16x32_bf16 v[32:35], v[144:147], v[198:201], v[32:35]
	v_mfma_f32_16x16x32_bf16 v[28:31], v[136:139], v[198:201], v[28:31]
	v_mfma_f32_16x16x32_bf16 v[28:31], v[132:135], v[194:197], v[28:31]
	s_setprio 0
	s_setprio 1
	v_mfma_f32_16x16x32_bf16 v[36:39], v[148:151], v[164:167], v[36:39]
	v_mfma_f32_16x16x32_bf16 v[36:39], v[152:155], v[168:171], v[36:39]
	v_mfma_f32_16x16x32_bf16 v[40:43], v[160:163], v[168:171], v[40:43]
	v_mfma_f32_16x16x32_bf16 v[40:43], v[156:159], v[164:167], v[40:43]
	v_mfma_f32_16x16x32_bf16 v[48:51], v[156:159], v[172:175], v[48:51]
	v_mfma_f32_16x16x32_bf16 v[48:51], v[160:163], v[176:179], v[48:51]
	v_mfma_f32_16x16x32_bf16 v[44:47], v[152:155], v[176:179], v[44:47]
	v_mfma_f32_16x16x32_bf16 v[44:47], v[148:151], v[172:175], v[44:47]
	v_mfma_f32_16x16x32_bf16 v[52:55], v[148:151], v[180:183], v[52:55]
	v_mfma_f32_16x16x32_bf16 v[52:55], v[152:155], v[184:187], v[52:55]
	v_mfma_f32_16x16x32_bf16 v[56:59], v[160:163], v[184:187], v[56:59]
	v_mfma_f32_16x16x32_bf16 v[56:59], v[156:159], v[180:183], v[56:59]
	v_mfma_f32_16x16x32_bf16 v[64:67], v[156:159], v[194:197], v[64:67]
	v_mfma_f32_16x16x32_bf16 v[64:67], v[160:163], v[198:201], v[64:67]
	s_setprio 2
	s_barrier
	v_mfma_f32_16x16x32_bf16 v[60:63], v[152:155], v[198:201], v[60:63]
	v_mfma_f32_16x16x32_bf16 v[60:63], v[148:151], v[194:197], v[60:63]
	s_add_i32 s6, s12, s36
	s_mov_b32 m0, s6
	ds_read_b128 v[164:167], v212 offset:16384
	ds_read_b128 v[168:171], v212 offset:17408
	ds_read_b128 v[172:175], v212 offset:18432
	ds_read_b128 v[176:179], v212 offset:19456
	ds_read_b128 v[180:183], v212 offset:20480
	ds_read_b128 v[184:187], v212 offset:21504
	ds_read_b128 v[194:197], v212 offset:22528
	ds_read_b128 v[198:201], v212 offset:23552
	global_load_lds_dwordx4 v192, s[14:15]
	s_add_i32 m0, s6, 0x2000
	s_add_u32 s6, s14, 0x10000
	s_addc_u32 s7, s15, 0
	s_add_i32 s12, s13, s36
	global_load_lds_dwordx4 v190, s[14:15]
	s_mov_b32 m0, s12
	v_mov_b32_e32 v193, v3
	global_load_lds_dwordx4 v192, s[6:7]
	s_add_i32 m0, s12, 0x2000
	v_mov_b32_e32 v191, v3
	global_load_lds_dwordx4 v190, s[6:7]
	s_mov_b32 m0, s37
	v_lshl_add_u64 v[202:203], s[14:15], 0, v[192:193]
	global_load_lds_dwordx4 v2, s[10:11]
	s_mov_b32 m0, s66
	v_lshl_add_u64 v[204:205], s[14:15], 0, v[190:191]
	global_load_lds_dwordx4 v188, s[10:11]
	s_setprio 0
	s_waitcnt vmcnt(8)
	s_waitcnt lgkmcnt(0)
	v_lshl_add_u64 v[206:207], s[10:11], 0, v[2:3]
	v_lshl_add_u64 v[210:211], s[10:11], 0, v[188:189]
	s_barrier
	s_setprio 1
	s_waitcnt lgkmcnt(0)
	v_mfma_f32_16x16x32_bf16 v[68:71], v[132:135], v[164:167], v[68:71]
	v_mfma_f32_16x16x32_bf16 v[68:71], v[136:139], v[168:171], v[68:71]
	v_mfma_f32_16x16x32_bf16 v[72:75], v[144:147], v[168:171], v[72:75]
	v_mfma_f32_16x16x32_bf16 v[72:75], v[140:143], v[164:167], v[72:75]
	v_mfma_f32_16x16x32_bf16 v[80:83], v[140:143], v[172:175], v[80:83]
	v_mfma_f32_16x16x32_bf16 v[80:83], v[144:147], v[176:179], v[80:83]
	v_mfma_f32_16x16x32_bf16 v[76:79], v[136:139], v[176:179], v[76:79]
	v_mfma_f32_16x16x32_bf16 v[76:79], v[132:135], v[172:175], v[76:79]
	v_mfma_f32_16x16x32_bf16 v[84:87], v[132:135], v[180:183], v[84:87]
	v_mfma_f32_16x16x32_bf16 v[84:87], v[136:139], v[184:187], v[84:87]
	v_mfma_f32_16x16x32_bf16 v[88:91], v[144:147], v[184:187], v[88:91]
	v_mfma_f32_16x16x32_bf16 v[88:91], v[140:143], v[180:183], v[88:91]
	v_mfma_f32_16x16x32_bf16 v[96:99], v[140:143], v[194:197], v[96:99]
	v_mfma_f32_16x16x32_bf16 v[96:99], v[144:147], v[198:201], v[96:99]
	v_mfma_f32_16x16x32_bf16 v[92:95], v[136:139], v[198:201], v[92:95]
	v_mfma_f32_16x16x32_bf16 v[92:95], v[132:135], v[194:197], v[92:95]
	s_setprio 0
	s_setprio 1
	v_mfma_f32_16x16x32_bf16 v[100:103], v[148:151], v[164:167], v[100:103]
	v_mfma_f32_16x16x32_bf16 v[100:103], v[152:155], v[168:171], v[100:103]
	v_mfma_f32_16x16x32_bf16 v[104:107], v[160:163], v[168:171], v[104:107]
	v_mfma_f32_16x16x32_bf16 v[104:107], v[156:159], v[164:167], v[104:107]
	v_mfma_f32_16x16x32_bf16 v[112:115], v[156:159], v[172:175], v[112:115]
	v_mfma_f32_16x16x32_bf16 v[112:115], v[160:163], v[176:179], v[112:115]
	v_mfma_f32_16x16x32_bf16 v[108:111], v[152:155], v[176:179], v[108:111]
	v_mfma_f32_16x16x32_bf16 v[108:111], v[148:151], v[172:175], v[108:111]
	v_mfma_f32_16x16x32_bf16 v[116:119], v[148:151], v[180:183], v[116:119]
	v_mfma_f32_16x16x32_bf16 v[116:119], v[152:155], v[184:187], v[116:119]
	v_mfma_f32_16x16x32_bf16 v[120:123], v[160:163], v[184:187], v[120:123]
	v_mfma_f32_16x16x32_bf16 v[120:123], v[156:159], v[180:183], v[120:123]
	v_mfma_f32_16x16x32_bf16 v[128:131], v[156:159], v[194:197], v[128:131]
	v_mfma_f32_16x16x32_bf16 v[128:131], v[160:163], v[198:201], v[128:131]
	s_setprio 2
	s_barrier
	v_mfma_f32_16x16x32_bf16 v[124:127], v[152:155], v[198:201], v[124:127]
	v_mfma_f32_16x16x32_bf16 v[124:127], v[148:151], v[194:197], v[124:127]
	s_add_i32 s12, 0, 0x18000
	s_add_i32 s13, 0, 0x1c000
	v_add_u32_e32 v144, s12, v209
	v_add_u32_e32 v160, s13, v209
	ds_read_b128 v[132:135], v144
	ds_read_b128 v[136:139], v144 offset:1024
	ds_read_b128 v[140:143], v144 offset:2048
	ds_read_b128 v[144:147], v144 offset:3072
	ds_read_b128 v[148:151], v160
	ds_read_b128 v[152:155], v160 offset:1024
	ds_read_b128 v[156:159], v160 offset:2048
	ds_read_b128 v[160:163], v160 offset:3072
	s_add_u32 s6, s10, 0x80000
	s_addc_u32 s7, s11, 0
	s_mov_b32 m0, s67
	ds_read_b128 v[164:167], v212 offset:32768
	ds_read_b128 v[168:171], v212 offset:33792
	ds_read_b128 v[172:175], v212 offset:34816
	ds_read_b128 v[176:179], v212 offset:35840
	ds_read_b128 v[180:183], v212 offset:36864
	ds_read_b128 v[184:187], v212 offset:37888
	ds_read_b128 v[194:197], v212 offset:38912
	ds_read_b128 v[198:201], v212 offset:39936
	global_load_lds_dwordx4 v2, s[6:7]
	s_mov_b32 m0, s68
	s_nop 0
	global_load_lds_dwordx4 v188, s[6:7]
	s_setprio 0
	s_waitcnt vmcnt(8)
	s_waitcnt lgkmcnt(0)
	s_barrier
	s_setprio 1
	s_waitcnt lgkmcnt(0)
	v_mfma_f32_16x16x32_bf16 v[4:7], v[132:135], v[164:167], v[4:7]
	v_mfma_f32_16x16x32_bf16 v[4:7], v[136:139], v[168:171], v[4:7]
	v_mfma_f32_16x16x32_bf16 v[8:11], v[144:147], v[168:171], v[8:11]
	v_mfma_f32_16x16x32_bf16 v[8:11], v[140:143], v[164:167], v[8:11]
	v_mfma_f32_16x16x32_bf16 v[16:19], v[140:143], v[172:175], v[16:19]
	v_mfma_f32_16x16x32_bf16 v[16:19], v[144:147], v[176:179], v[16:19]
	v_mfma_f32_16x16x32_bf16 v[12:15], v[136:139], v[176:179], v[12:15]
	v_mfma_f32_16x16x32_bf16 v[12:15], v[132:135], v[172:175], v[12:15]
	v_mfma_f32_16x16x32_bf16 v[20:23], v[132:135], v[180:183], v[20:23]
	v_mfma_f32_16x16x32_bf16 v[20:23], v[136:139], v[184:187], v[20:23]
	v_mfma_f32_16x16x32_bf16 v[24:27], v[144:147], v[184:187], v[24:27]
	v_mfma_f32_16x16x32_bf16 v[24:27], v[140:143], v[180:183], v[24:27]
	v_mfma_f32_16x16x32_bf16 v[32:35], v[140:143], v[194:197], v[32:35]
	v_mfma_f32_16x16x32_bf16 v[32:35], v[144:147], v[198:201], v[32:35]
	v_mfma_f32_16x16x32_bf16 v[28:31], v[136:139], v[198:201], v[28:31]
	v_mfma_f32_16x16x32_bf16 v[28:31], v[132:135], v[194:197], v[28:31]
	s_setprio 0
	s_setprio 1
	v_mfma_f32_16x16x32_bf16 v[36:39], v[148:151], v[164:167], v[36:39]
	v_mfma_f32_16x16x32_bf16 v[36:39], v[152:155], v[168:171], v[36:39]
	v_mfma_f32_16x16x32_bf16 v[40:43], v[160:163], v[168:171], v[40:43]
	v_mfma_f32_16x16x32_bf16 v[40:43], v[156:159], v[164:167], v[40:43]
	v_mfma_f32_16x16x32_bf16 v[48:51], v[156:159], v[172:175], v[48:51]
	v_mfma_f32_16x16x32_bf16 v[48:51], v[160:163], v[176:179], v[48:51]
	v_mfma_f32_16x16x32_bf16 v[44:47], v[152:155], v[176:179], v[44:47]
	v_mfma_f32_16x16x32_bf16 v[44:47], v[148:151], v[172:175], v[44:47]
	v_mfma_f32_16x16x32_bf16 v[52:55], v[148:151], v[180:183], v[52:55]
	v_mfma_f32_16x16x32_bf16 v[52:55], v[152:155], v[184:187], v[52:55]
	v_mfma_f32_16x16x32_bf16 v[56:59], v[160:163], v[184:187], v[56:59]
	v_mfma_f32_16x16x32_bf16 v[56:59], v[156:159], v[180:183], v[56:59]
	v_mfma_f32_16x16x32_bf16 v[64:67], v[156:159], v[194:197], v[64:67]
	v_mfma_f32_16x16x32_bf16 v[64:67], v[160:163], v[198:201], v[64:67]
	s_setprio 2
	s_barrier
	v_mfma_f32_16x16x32_bf16 v[60:63], v[152:155], v[198:201], v[60:63]
	v_mfma_f32_16x16x32_bf16 v[60:63], v[148:151], v[194:197], v[60:63]
	s_add_i32 s6, s12, s36
	v_lshl_add_u64 v[202:203], v[202:203], 0, s[86:87]
	s_mov_b32 m0, s6
	ds_read_b128 v[164:167], v212 offset:49152
	ds_read_b128 v[168:171], v212 offset:50176
	ds_read_b128 v[172:175], v212 offset:51200
	ds_read_b128 v[176:179], v212 offset:52224
	ds_read_b128 v[180:183], v212 offset:53248
	ds_read_b128 v[184:187], v212 offset:54272
	ds_read_b128 v[194:197], v212 offset:55296
	ds_read_b128 v[198:201], v212 offset:56320
	global_load_lds_dwordx4 v[202:203], off
	s_add_i32 m0, s6, 0x2000
	s_add_u32 s6, s14, 0x10080
	v_lshl_add_u64 v[202:203], v[204:205], 0, s[86:87]
	s_addc_u32 s7, s15, 0
	s_add_i32 s12, s13, s36
	global_load_lds_dwordx4 v[202:203], off
	s_mov_b32 m0, s12
	v_lshl_add_u64 v[202:203], v[206:207], 0, s[86:87]
	global_load_lds_dwordx4 v192, s[6:7]
	s_add_i32 m0, s12, 0x2000
	s_nop 0
	global_load_lds_dwordx4 v190, s[6:7]
	s_mov_b32 m0, s71
	s_nop 0
	global_load_lds_dwordx4 v[202:203], off
	v_lshl_add_u64 v[202:203], v[210:211], 0, s[86:87]
	s_mov_b32 m0, s72
	s_nop 0
	global_load_lds_dwordx4 v[202:203], off
	s_setprio 0
	s_waitcnt vmcnt(8)
	s_waitcnt lgkmcnt(0)
	s_barrier
	s_setprio 1
	s_waitcnt lgkmcnt(0)
	v_mfma_f32_16x16x32_bf16 v[68:71], v[132:135], v[164:167], v[68:71]
	v_mfma_f32_16x16x32_bf16 v[68:71], v[136:139], v[168:171], v[68:71]
	v_mfma_f32_16x16x32_bf16 v[72:75], v[144:147], v[168:171], v[72:75]
	v_mfma_f32_16x16x32_bf16 v[72:75], v[140:143], v[164:167], v[72:75]
	v_mfma_f32_16x16x32_bf16 v[80:83], v[140:143], v[172:175], v[80:83]
	v_mfma_f32_16x16x32_bf16 v[80:83], v[144:147], v[176:179], v[80:83]
	v_mfma_f32_16x16x32_bf16 v[76:79], v[136:139], v[176:179], v[76:79]
	v_mfma_f32_16x16x32_bf16 v[76:79], v[132:135], v[172:175], v[76:79]
	v_mfma_f32_16x16x32_bf16 v[84:87], v[132:135], v[180:183], v[84:87]
	v_mfma_f32_16x16x32_bf16 v[84:87], v[136:139], v[184:187], v[84:87]
	v_mfma_f32_16x16x32_bf16 v[88:91], v[144:147], v[184:187], v[88:91]
	v_mfma_f32_16x16x32_bf16 v[88:91], v[140:143], v[180:183], v[88:91]
	v_mfma_f32_16x16x32_bf16 v[96:99], v[140:143], v[194:197], v[96:99]
	v_mfma_f32_16x16x32_bf16 v[96:99], v[144:147], v[198:201], v[96:99]
	v_mfma_f32_16x16x32_bf16 v[92:95], v[136:139], v[198:201], v[92:95]
	v_mfma_f32_16x16x32_bf16 v[92:95], v[132:135], v[194:197], v[92:95]
	s_setprio 0
	s_setprio 1
	v_mfma_f32_16x16x32_bf16 v[100:103], v[148:151], v[164:167], v[100:103]
	v_mfma_f32_16x16x32_bf16 v[100:103], v[152:155], v[168:171], v[100:103]
	v_mfma_f32_16x16x32_bf16 v[104:107], v[160:163], v[168:171], v[104:107]
	v_mfma_f32_16x16x32_bf16 v[104:107], v[156:159], v[164:167], v[104:107]
	v_mfma_f32_16x16x32_bf16 v[112:115], v[156:159], v[172:175], v[112:115]
	v_mfma_f32_16x16x32_bf16 v[112:115], v[160:163], v[176:179], v[112:115]
	v_mfma_f32_16x16x32_bf16 v[108:111], v[152:155], v[176:179], v[108:111]
	v_mfma_f32_16x16x32_bf16 v[108:111], v[148:151], v[172:175], v[108:111]
	v_mfma_f32_16x16x32_bf16 v[116:119], v[148:151], v[180:183], v[116:119]
	v_mfma_f32_16x16x32_bf16 v[116:119], v[152:155], v[184:187], v[116:119]
	v_mfma_f32_16x16x32_bf16 v[120:123], v[160:163], v[184:187], v[120:123]
	v_mfma_f32_16x16x32_bf16 v[120:123], v[156:159], v[180:183], v[120:123]
	v_mfma_f32_16x16x32_bf16 v[128:131], v[156:159], v[194:197], v[128:131]
	v_mfma_f32_16x16x32_bf16 v[128:131], v[160:163], v[198:201], v[128:131]
	s_setprio 2
	s_barrier
	v_mfma_f32_16x16x32_bf16 v[124:127], v[152:155], v[198:201], v[124:127]
	v_mfma_f32_16x16x32_bf16 v[124:127], v[148:151], v[194:197], v[124:127]
	s_setprio 0
	s_and_b64 vcc, exec, s[58:59]
	s_cbranch_vccz .LBB0_1178
	s_barrier

.LBB0_1625:
	s_add_i32 s51, 0, 0x10000
	s_add_i32 s72, 0, 0x14000
	v_add_u32_e32 v16, s51, v232
	v_add_u32_e32 v32, s72, v232
	ds_read_b128 v[4:7], v16
	ds_read_b128 v[8:11], v16 offset:1024
	ds_read_b128 v[12:15], v16 offset:2048
	ds_read_b128 v[16:19], v16 offset:3072
	ds_read_b128 v[20:23], v32
	ds_read_b128 v[24:27], v32 offset:1024
	ds_read_b128 v[28:31], v32 offset:2048
	ds_read_b128 v[32:35], v32 offset:3072
	v_add_u32_e32 v233, 0, v231
	ds_read_b128 v[36:39], v233
	ds_read_b128 v[40:43], v233 offset:1024
	ds_read_b128 v[44:47], v233 offset:2048
	ds_read_b128 v[48:51], v233 offset:3072
	ds_read_b128 v[52:55], v233 offset:4096
	ds_read_b128 v[56:59], v233 offset:5120
	ds_read_b128 v[60:63], v233 offset:6144
	ds_read_b128 v[64:67], v233 offset:7168
	s_waitcnt vmcnt(8)
	s_waitcnt lgkmcnt(0)
	s_barrier
	s_setprio 1
	s_waitcnt lgkmcnt(0)
	v_mfma_f32_16x16x32_bf16 v[68:71], v[4:7], v[36:39], 0
	v_mfma_f32_16x16x32_bf16 v[68:71], v[8:11], v[40:43], v[68:71]
	v_mfma_f32_16x16x32_bf16 v[72:75], v[12:15], v[36:39], 0
	v_mfma_f32_16x16x32_bf16 v[72:75], v[16:19], v[40:43], v[72:75]
	v_mfma_f32_16x16x32_bf16 v[80:83], v[12:15], v[44:47], 0
	v_mfma_f32_16x16x32_bf16 v[80:83], v[16:19], v[48:51], v[80:83]
	v_mfma_f32_16x16x32_bf16 v[76:79], v[4:7], v[44:47], 0
	v_mfma_f32_16x16x32_bf16 v[76:79], v[8:11], v[48:51], v[76:79]
	v_mfma_f32_16x16x32_bf16 v[84:87], v[4:7], v[52:55], 0
	v_mfma_f32_16x16x32_bf16 v[84:87], v[8:11], v[56:59], v[84:87]
	v_mfma_f32_16x16x32_bf16 v[88:91], v[12:15], v[52:55], 0
	v_mfma_f32_16x16x32_bf16 v[88:91], v[16:19], v[56:59], v[88:91]
	v_mfma_f32_16x16x32_bf16 v[96:99], v[12:15], v[60:63], 0
	v_mfma_f32_16x16x32_bf16 v[96:99], v[16:19], v[64:67], v[96:99]
	v_mfma_f32_16x16x32_bf16 v[92:95], v[4:7], v[60:63], 0
	v_mfma_f32_16x16x32_bf16 v[92:95], v[8:11], v[64:67], v[92:95]
	s_setprio 0
	s_setprio 1
	v_mfma_f32_16x16x32_bf16 v[100:103], v[20:23], v[36:39], 0
	v_mfma_f32_16x16x32_bf16 v[36:39], v[28:31], v[36:39], 0
	v_mfma_f32_16x16x32_bf16 v[104:107], v[20:23], v[44:47], 0
	v_mfma_f32_16x16x32_bf16 v[44:47], v[28:31], v[44:47], 0
	v_mfma_f32_16x16x32_bf16 v[108:111], v[20:23], v[52:55], 0
	v_mfma_f32_16x16x32_bf16 v[52:55], v[28:31], v[52:55], 0
	v_mfma_f32_16x16x32_bf16 v[112:115], v[20:23], v[60:63], 0
	v_mfma_f32_16x16x32_bf16 v[60:63], v[28:31], v[60:63], 0
	v_mfma_f32_16x16x32_bf16 v[100:103], v[24:27], v[40:43], v[100:103]
	v_mfma_f32_16x16x32_bf16 v[40:43], v[32:35], v[40:43], v[36:39]
	v_mfma_f32_16x16x32_bf16 v[104:107], v[24:27], v[48:51], v[104:107]
	v_mfma_f32_16x16x32_bf16 v[48:51], v[32:35], v[48:51], v[44:47]
	v_mfma_f32_16x16x32_bf16 v[108:111], v[24:27], v[56:59], v[108:111]
	v_mfma_f32_16x16x32_bf16 v[56:59], v[32:35], v[56:59], v[52:55]
	s_setprio 2
	s_barrier
	v_mfma_f32_16x16x32_bf16 v[112:115], v[24:27], v[64:67], v[112:115]
	v_mfma_f32_16x16x32_bf16 v[64:67], v[32:35], v[64:67], v[60:63]
	v_lshl_add_u64 v[186:187], s[12:13], 0, v[2:3]
	s_add_i32 s51, s51, s56
	v_mov_b32_e32 v191, v3
	v_lshl_add_u64 v[134:135], v[186:187], 0, s[74:75]
	s_mov_b32 m0, s51
	v_lshl_add_u64 v[246:247], s[12:13], 0, v[190:191]
	ds_read_b128 v[36:39], v233 offset:16384
	ds_read_b128 v[44:47], v233 offset:17408
	ds_read_b128 v[52:55], v233 offset:18432
	ds_read_b128 v[60:63], v233 offset:19456
	ds_read_b128 v[116:119], v233 offset:20480
	ds_read_b128 v[120:123], v233 offset:21504
	ds_read_b128 v[124:127], v233 offset:22528
	ds_read_b128 v[128:131], v233 offset:23552
	global_load_lds_dwordx4 v[134:135], off
	v_lshl_add_u64 v[134:135], v[246:247], 0, s[74:75]
	s_add_i32 m0, s51, 0x2000
	s_add_i32 s51, s72, s56
	global_load_lds_dwordx4 v[134:135], off
	s_mov_b32 m0, s51
	v_mov_b32_e32 v133, v3
	global_load_lds_dwordx4 v2, s[16:17]
	s_add_i32 m0, s51, 0x2000
	v_lshl_add_u64 v[248:249], s[14:15], 0, v[132:133]
	v_mov_b32_e32 v189, v3
	global_load_lds_dwordx4 v190, s[16:17]
	v_lshl_add_u64 v[134:135], v[248:249], 0, s[74:75]
	s_mov_b32 m0, s57
	v_lshl_add_u64 v[250:251], s[14:15], 0, v[188:189]
	global_load_lds_dwordx4 v[134:135], off
	v_lshl_add_u64 v[134:135], v[250:251], 0, s[74:75]
	s_mov_b32 m0, s58
	s_nop 0
	global_load_lds_dwordx4 v[134:135], off
	s_setprio 0
	s_waitcnt vmcnt(8)
	s_waitcnt lgkmcnt(0)
	s_barrier
	s_setprio 1
	s_waitcnt lgkmcnt(0)
	v_mfma_f32_16x16x32_bf16 v[134:137], v[4:7], v[36:39], 0
	v_mfma_f32_16x16x32_bf16 v[138:141], v[12:15], v[36:39], 0
	v_mfma_f32_16x16x32_bf16 v[142:145], v[4:7], v[52:55], 0
	v_mfma_f32_16x16x32_bf16 v[146:149], v[12:15], v[52:55], 0
	v_mfma_f32_16x16x32_bf16 v[150:153], v[4:7], v[116:119], 0
	v_mfma_f32_16x16x32_bf16 v[154:157], v[12:15], v[116:119], 0
	v_mfma_f32_16x16x32_bf16 v[4:7], v[4:7], v[124:127], 0
	v_mfma_f32_16x16x32_bf16 v[12:15], v[12:15], v[124:127], 0
	v_mfma_f32_16x16x32_bf16 v[134:137], v[8:11], v[44:47], v[134:137]
	v_mfma_f32_16x16x32_bf16 v[138:141], v[16:19], v[44:47], v[138:141]
	v_mfma_f32_16x16x32_bf16 v[142:145], v[8:11], v[60:63], v[142:145]
	v_mfma_f32_16x16x32_bf16 v[146:149], v[16:19], v[60:63], v[146:149]
	v_mfma_f32_16x16x32_bf16 v[150:153], v[8:11], v[120:123], v[150:153]
	v_mfma_f32_16x16x32_bf16 v[154:157], v[16:19], v[120:123], v[154:157]
	v_mfma_f32_16x16x32_bf16 v[158:161], v[8:11], v[128:131], v[4:7]
	v_mfma_f32_16x16x32_bf16 v[162:165], v[16:19], v[128:131], v[12:15]
	s_setprio 0
	s_setprio 1
	v_mfma_f32_16x16x32_bf16 v[4:7], v[20:23], v[36:39], 0
	v_mfma_f32_16x16x32_bf16 v[8:11], v[28:31], v[36:39], 0
	v_mfma_f32_16x16x32_bf16 v[12:15], v[20:23], v[52:55], 0
	v_mfma_f32_16x16x32_bf16 v[16:19], v[28:31], v[52:55], 0
	v_mfma_f32_16x16x32_bf16 v[36:39], v[20:23], v[116:119], 0
	v_mfma_f32_16x16x32_bf16 v[52:55], v[28:31], v[116:119], 0
	v_mfma_f32_16x16x32_bf16 v[20:23], v[20:23], v[124:127], 0
	v_mfma_f32_16x16x32_bf16 v[28:31], v[28:31], v[124:127], 0
	v_mfma_f32_16x16x32_bf16 v[116:119], v[24:27], v[44:47], v[4:7]
	v_mfma_f32_16x16x32_bf16 v[124:127], v[32:35], v[44:47], v[8:11]
	v_mfma_f32_16x16x32_bf16 v[174:177], v[24:27], v[120:123], v[36:39]
	v_mfma_f32_16x16x32_bf16 v[120:123], v[32:35], v[120:123], v[52:55]
	v_mfma_f32_16x16x32_bf16 v[178:181], v[24:27], v[128:131], v[20:23]
	v_mfma_f32_16x16x32_bf16 v[128:131], v[32:35], v[128:131], v[28:31]
	s_setprio 2
	s_barrier
	v_mfma_f32_16x16x32_bf16 v[166:169], v[24:27], v[60:63], v[12:15]
	v_mfma_f32_16x16x32_bf16 v[170:173], v[32:35], v[60:63], v[16:19]
	s_add_i32 s51, 0, 0x18000
	v_add_u32_e32 v4, s51, v232
	s_add_i32 s72, 0, 0x1c000
	ds_read_b128 v[182:185], v4
	ds_read_b128 v[192:195], v4 offset:1024
	ds_read_b128 v[196:199], v4 offset:2048
	ds_read_b128 v[200:203], v4 offset:3072
	v_add_u32_e32 v4, s72, v232
	ds_read_b128 v[204:207], v4
	ds_read_b128 v[208:211], v4 offset:1024
	ds_read_b128 v[212:215], v4 offset:2048
	ds_read_b128 v[216:219], v4 offset:3072
	s_mov_b32 m0, s59
	ds_read_b128 v[44:47], v233 offset:32768
	ds_read_b128 v[52:55], v233 offset:33792
	ds_read_b128 v[60:63], v233 offset:34816
	ds_read_b128 v[220:223], v233 offset:35840
	ds_read_b128 v[224:227], v233 offset:36864
	ds_read_b128 v[234:237], v233 offset:37888
	ds_read_b128 v[238:241], v233 offset:38912
	ds_read_b128 v[242:245], v233 offset:39936
	global_load_lds_dwordx4 v132, s[26:27]
	s_mov_b32 m0, s60
	s_nop 0
	global_load_lds_dwordx4 v188, s[26:27]
	s_setprio 0
	s_waitcnt vmcnt(8)
	s_waitcnt lgkmcnt(0)
	s_barrier
	s_setprio 1
	s_waitcnt lgkmcnt(0)
	v_mfma_f32_16x16x32_bf16 v[4:7], v[182:185], v[44:47], v[68:71]
	v_mfma_f32_16x16x32_bf16 v[8:11], v[196:199], v[44:47], v[72:75]
	v_mfma_f32_16x16x32_bf16 v[12:15], v[182:185], v[60:63], v[76:79]
	v_mfma_f32_16x16x32_bf16 v[16:19], v[196:199], v[60:63], v[80:83]
	v_mfma_f32_16x16x32_bf16 v[20:23], v[182:185], v[224:227], v[84:87]
	v_mfma_f32_16x16x32_bf16 v[24:27], v[196:199], v[224:227], v[88:91]
	v_mfma_f32_16x16x32_bf16 v[28:31], v[182:185], v[238:241], v[92:95]
	v_mfma_f32_16x16x32_bf16 v[32:35], v[196:199], v[238:241], v[96:99]
	v_mfma_f32_16x16x32_bf16 v[4:7], v[192:195], v[52:55], v[4:7]
	v_mfma_f32_16x16x32_bf16 v[8:11], v[200:203], v[52:55], v[8:11]
	v_mfma_f32_16x16x32_bf16 v[12:15], v[192:195], v[220:223], v[12:15]
	v_mfma_f32_16x16x32_bf16 v[16:19], v[200:203], v[220:223], v[16:19]
	v_mfma_f32_16x16x32_bf16 v[20:23], v[192:195], v[234:237], v[20:23]
	v_mfma_f32_16x16x32_bf16 v[24:27], v[200:203], v[234:237], v[24:27]
	v_mfma_f32_16x16x32_bf16 v[28:31], v[192:195], v[242:245], v[28:31]
	v_mfma_f32_16x16x32_bf16 v[32:35], v[200:203], v[242:245], v[32:35]
	s_setprio 0
	s_setprio 1
	v_mfma_f32_16x16x32_bf16 v[36:39], v[204:207], v[44:47], v[100:103]
	v_mfma_f32_16x16x32_bf16 v[40:43], v[212:215], v[44:47], v[40:43]
	v_mfma_f32_16x16x32_bf16 v[36:39], v[208:211], v[52:55], v[36:39]
	v_mfma_f32_16x16x32_bf16 v[40:43], v[216:219], v[52:55], v[40:43]
	v_mfma_f32_16x16x32_bf16 v[44:47], v[204:207], v[60:63], v[104:107]
	v_mfma_f32_16x16x32_bf16 v[48:51], v[212:215], v[60:63], v[48:51]
	v_mfma_f32_16x16x32_bf16 v[52:55], v[204:207], v[224:227], v[108:111]
	v_mfma_f32_16x16x32_bf16 v[56:59], v[212:215], v[224:227], v[56:59]
	v_mfma_f32_16x16x32_bf16 v[60:63], v[204:207], v[238:241], v[112:115]
	v_mfma_f32_16x16x32_bf16 v[64:67], v[212:215], v[238:241], v[64:67]
	v_mfma_f32_16x16x32_bf16 v[44:47], v[208:211], v[220:223], v[44:47]
	v_mfma_f32_16x16x32_bf16 v[48:51], v[216:219], v[220:223], v[48:51]
	v_mfma_f32_16x16x32_bf16 v[52:55], v[208:211], v[234:237], v[52:55]
	v_mfma_f32_16x16x32_bf16 v[56:59], v[216:219], v[234:237], v[56:59]
	s_setprio 2
	s_barrier
	v_mfma_f32_16x16x32_bf16 v[60:63], v[208:211], v[242:245], v[60:63]
	v_mfma_f32_16x16x32_bf16 v[64:67], v[216:219], v[242:245], v[64:67]
	s_add_i32 s51, s51, s56
	v_lshl_add_u64 v[68:69], v[186:187], 0, s[24:25]
	s_mov_b32 m0, s51
	ds_read_b128 v[104:107], v233 offset:49152
	ds_read_b128 v[108:111], v233 offset:50176
	ds_read_b128 v[112:115], v233 offset:51200
	ds_read_b128 v[220:223], v233 offset:52224
	ds_read_b128 v[224:227], v233 offset:53248
	ds_read_b128 v[234:237], v233 offset:54272
	ds_read_b128 v[238:241], v233 offset:55296
	ds_read_b128 v[242:245], v233 offset:56320
	global_load_lds_dwordx4 v[68:69], off
	v_lshl_add_u64 v[68:69], v[246:247], 0, s[24:25]
	s_add_i32 m0, s51, 0x2000
	s_add_i32 s51, s72, s56
	global_load_lds_dwordx4 v[68:69], off
	s_mov_b32 m0, s51
	v_lshl_add_u64 v[68:69], v[248:249], 0, s[24:25]
	global_load_lds_dwordx4 v2, s[28:29]
	s_add_i32 m0, s51, 0x2000
	s_nop 0
	global_load_lds_dwordx4 v190, s[28:29]
	s_mov_b32 m0, s64
	s_nop 0
	global_load_lds_dwordx4 v[68:69], off
	v_lshl_add_u64 v[68:69], v[250:251], 0, s[24:25]
	s_mov_b32 m0, s65
	s_nop 0
	global_load_lds_dwordx4 v[68:69], off
	s_setprio 0
	s_waitcnt vmcnt(8)
	s_waitcnt lgkmcnt(0)
	s_barrier
	s_setprio 1
	s_waitcnt lgkmcnt(0)
	v_mfma_f32_16x16x32_bf16 v[68:71], v[182:185], v[104:107], v[134:137]
	v_mfma_f32_16x16x32_bf16 v[72:75], v[196:199], v[104:107], v[138:141]
	v_mfma_f32_16x16x32_bf16 v[76:79], v[182:185], v[112:115], v[142:145]
	v_mfma_f32_16x16x32_bf16 v[80:83], v[196:199], v[112:115], v[146:149]
	v_mfma_f32_16x16x32_bf16 v[84:87], v[182:185], v[224:227], v[150:153]
	v_mfma_f32_16x16x32_bf16 v[88:91], v[196:199], v[224:227], v[154:157]
	v_mfma_f32_16x16x32_bf16 v[92:95], v[182:185], v[238:241], v[158:161]
	v_mfma_f32_16x16x32_bf16 v[96:99], v[196:199], v[238:241], v[162:165]
	v_mfma_f32_16x16x32_bf16 v[68:71], v[192:195], v[108:111], v[68:71]
	v_mfma_f32_16x16x32_bf16 v[72:75], v[200:203], v[108:111], v[72:75]
	v_mfma_f32_16x16x32_bf16 v[76:79], v[192:195], v[220:223], v[76:79]
	v_mfma_f32_16x16x32_bf16 v[80:83], v[200:203], v[220:223], v[80:83]
	v_mfma_f32_16x16x32_bf16 v[84:87], v[192:195], v[234:237], v[84:87]
	v_mfma_f32_16x16x32_bf16 v[88:91], v[200:203], v[234:237], v[88:91]
	v_mfma_f32_16x16x32_bf16 v[92:95], v[192:195], v[242:245], v[92:95]
	v_mfma_f32_16x16x32_bf16 v[96:99], v[200:203], v[242:245], v[96:99]
	s_setprio 0
	s_setprio 1
	v_mfma_f32_16x16x32_bf16 v[100:103], v[204:207], v[104:107], v[116:119]
	v_mfma_f32_16x16x32_bf16 v[104:107], v[212:215], v[104:107], v[124:127]
	v_mfma_f32_16x16x32_bf16 v[100:103], v[208:211], v[108:111], v[100:103]
	v_mfma_f32_16x16x32_bf16 v[104:107], v[216:219], v[108:111], v[104:107]
	v_mfma_f32_16x16x32_bf16 v[108:111], v[204:207], v[112:115], v[166:169]
	v_mfma_f32_16x16x32_bf16 v[112:115], v[212:215], v[112:115], v[170:173]
	v_mfma_f32_16x16x32_bf16 v[116:119], v[204:207], v[224:227], v[174:177]
	v_mfma_f32_16x16x32_bf16 v[120:123], v[212:215], v[224:227], v[120:123]
	v_mfma_f32_16x16x32_bf16 v[124:127], v[204:207], v[238:241], v[178:181]
	v_mfma_f32_16x16x32_bf16 v[128:131], v[212:215], v[238:241], v[128:131]
	v_mfma_f32_16x16x32_bf16 v[108:111], v[208:211], v[220:223], v[108:111]
	v_mfma_f32_16x16x32_bf16 v[112:115], v[216:219], v[220:223], v[112:115]
	v_mfma_f32_16x16x32_bf16 v[116:119], v[208:211], v[234:237], v[116:119]
	v_mfma_f32_16x16x32_bf16 v[120:123], v[216:219], v[234:237], v[120:123]
	s_setprio 2
	s_barrier
	v_mfma_f32_16x16x32_bf16 v[124:127], v[208:211], v[242:245], v[124:127]
	v_mfma_f32_16x16x32_bf16 v[128:131], v[216:219], v[242:245], v[128:131]
	s_setprio 0
	s_add_i32 s43, s43, 2
	s_cmp_ge_i32 s43, s42
	s_cbranch_scc0 .LBB0_1625
	v_mov_b32_e32 v192, v2
	s_branch .LBB0_1628

.LBB0_1629:
	s_add_u32 s12, s14, 0xfff80080
	s_addc_u32 s13, s15, -1
	s_add_i32 s29, 0, 0x10000
	s_cmp_eq_u32 s28, 28
	s_cselect_b32 s17, s9, s13
	s_cselect_b32 s16, s8, s12
	s_cselect_b32 s13, s11, s27
	s_cselect_b32 s12, s10, s26
	s_add_i32 s51, 0, 0x14000
	v_add_u32_e32 v144, s29, v232
	v_add_u32_e32 v160, s51, v232
	s_waitcnt lgkmcnt(0)
	ds_read_b128 v[132:135], v144
	ds_read_b128 v[136:139], v144 offset:1024
	ds_read_b128 v[140:143], v144 offset:2048
	ds_read_b128 v[144:147], v144 offset:3072
	ds_read_b128 v[148:151], v160
	ds_read_b128 v[152:155], v160 offset:1024
	ds_read_b128 v[156:159], v160 offset:2048
	ds_read_b128 v[160:163], v160 offset:3072
	s_mov_b32 m0, s66
	v_add_u32_e32 v210, 0, v231
	ds_read_b128 v[164:167], v210
	ds_read_b128 v[168:171], v210 offset:1024
	ds_read_b128 v[172:175], v210 offset:2048
	ds_read_b128 v[176:179], v210 offset:3072
	ds_read_b128 v[180:183], v210 offset:4096
	ds_read_b128 v[184:187], v210 offset:5120
	ds_read_b128 v[194:197], v210 offset:6144
	ds_read_b128 v[198:201], v210 offset:7168
	global_load_lds_dwordx4 v2, s[14:15]
	s_mov_b32 m0, s67
	v_mov_b32_e32 v189, v3
	global_load_lds_dwordx4 v188, s[14:15]
	s_waitcnt vmcnt(8)
	s_waitcnt lgkmcnt(0)
	s_barrier
	s_setprio 1
	s_waitcnt lgkmcnt(0)
	v_mfma_f32_16x16x32_bf16 v[4:7], v[132:135], v[164:167], v[4:7]
	v_mfma_f32_16x16x32_bf16 v[4:7], v[136:139], v[168:171], v[4:7]
	v_mfma_f32_16x16x32_bf16 v[8:11], v[144:147], v[168:171], v[8:11]
	v_mfma_f32_16x16x32_bf16 v[8:11], v[140:143], v[164:167], v[8:11]
	v_mfma_f32_16x16x32_bf16 v[16:19], v[140:143], v[172:175], v[16:19]
	v_mfma_f32_16x16x32_bf16 v[16:19], v[144:147], v[176:179], v[16:19]
	v_mfma_f32_16x16x32_bf16 v[12:15], v[136:139], v[176:179], v[12:15]
	v_mfma_f32_16x16x32_bf16 v[12:15], v[132:135], v[172:175], v[12:15]
	v_mfma_f32_16x16x32_bf16 v[20:23], v[132:135], v[180:183], v[20:23]
	v_mfma_f32_16x16x32_bf16 v[20:23], v[136:139], v[184:187], v[20:23]
	v_mfma_f32_16x16x32_bf16 v[24:27], v[144:147], v[184:187], v[24:27]
	v_mfma_f32_16x16x32_bf16 v[24:27], v[140:143], v[180:183], v[24:27]
	v_mfma_f32_16x16x32_bf16 v[32:35], v[140:143], v[194:197], v[32:35]
	v_mfma_f32_16x16x32_bf16 v[32:35], v[144:147], v[198:201], v[32:35]
	v_mfma_f32_16x16x32_bf16 v[28:31], v[136:139], v[198:201], v[28:31]
	v_mfma_f32_16x16x32_bf16 v[28:31], v[132:135], v[194:197], v[28:31]
	s_setprio 0
	s_setprio 1
	v_mfma_f32_16x16x32_bf16 v[36:39], v[148:151], v[164:167], v[36:39]
	v_mfma_f32_16x16x32_bf16 v[36:39], v[152:155], v[168:171], v[36:39]
	v_mfma_f32_16x16x32_bf16 v[40:43], v[160:163], v[168:171], v[40:43]
	v_mfma_f32_16x16x32_bf16 v[40:43], v[156:159], v[164:167], v[40:43]
	v_mfma_f32_16x16x32_bf16 v[48:51], v[156:159], v[172:175], v[48:51]
	v_mfma_f32_16x16x32_bf16 v[48:51], v[160:163], v[176:179], v[48:51]
	v_mfma_f32_16x16x32_bf16 v[44:47], v[152:155], v[176:179], v[44:47]
	v_mfma_f32_16x16x32_bf16 v[44:47], v[148:151], v[172:175], v[44:47]
	v_mfma_f32_16x16x32_bf16 v[52:55], v[148:151], v[180:183], v[52:55]
	v_mfma_f32_16x16x32_bf16 v[52:55], v[152:155], v[184:187], v[52:55]
	v_mfma_f32_16x16x32_bf16 v[56:59], v[160:163], v[184:187], v[56:59]
	v_mfma_f32_16x16x32_bf16 v[56:59], v[156:159], v[180:183], v[56:59]
	v_mfma_f32_16x16x32_bf16 v[64:67], v[156:159], v[194:197], v[64:67]
	v_mfma_f32_16x16x32_bf16 v[64:67], v[160:163], v[198:201], v[64:67]
	s_setprio 2
	s_barrier
	v_mfma_f32_16x16x32_bf16 v[60:63], v[152:155], v[198:201], v[60:63]
	v_mfma_f32_16x16x32_bf16 v[60:63], v[148:151], v[194:197], v[60:63]
	s_add_i32 s29, s29, s56
	s_mov_b32 m0, s29
	ds_read_b128 v[164:167], v210 offset:16384
	ds_read_b128 v[168:171], v210 offset:17408
	ds_read_b128 v[172:175], v210 offset:18432
	ds_read_b128 v[176:179], v210 offset:19456
	ds_read_b128 v[180:183], v210 offset:20480
	ds_read_b128 v[184:187], v210 offset:21504
	ds_read_b128 v[194:197], v210 offset:22528
	ds_read_b128 v[198:201], v210 offset:23552
	global_load_lds_dwordx4 v192, s[12:13]
	s_add_i32 m0, s29, 0x2000
	s_add_u32 s42, s12, 0x80000
	s_addc_u32 s43, s13, 0
	s_add_i32 s29, s51, s56
	global_load_lds_dwordx4 v190, s[12:13]
	s_mov_b32 m0, s29
	v_mov_b32_e32 v193, v3
	global_load_lds_dwordx4 v192, s[42:43]
	s_add_i32 m0, s29, 0x2000
	v_mov_b32_e32 v191, v3
	global_load_lds_dwordx4 v190, s[42:43]
	s_mov_b32 m0, s57
	v_lshl_add_u64 v[202:203], s[12:13], 0, v[192:193]
	global_load_lds_dwordx4 v2, s[16:17]
	s_mov_b32 m0, s58
	v_lshl_add_u64 v[204:205], s[12:13], 0, v[190:191]
	global_load_lds_dwordx4 v188, s[16:17]
	s_setprio 0
	s_waitcnt vmcnt(8)
	s_waitcnt lgkmcnt(0)
	v_lshl_add_u64 v[206:207], s[16:17], 0, v[2:3]
	v_lshl_add_u64 v[208:209], s[16:17], 0, v[188:189]
	s_barrier
	s_setprio 1
	s_waitcnt lgkmcnt(0)
	v_mfma_f32_16x16x32_bf16 v[68:71], v[132:135], v[164:167], v[68:71]
	v_mfma_f32_16x16x32_bf16 v[68:71], v[136:139], v[168:171], v[68:71]
	v_mfma_f32_16x16x32_bf16 v[72:75], v[144:147], v[168:171], v[72:75]
	v_mfma_f32_16x16x32_bf16 v[72:75], v[140:143], v[164:167], v[72:75]
	v_mfma_f32_16x16x32_bf16 v[80:83], v[140:143], v[172:175], v[80:83]
	v_mfma_f32_16x16x32_bf16 v[80:83], v[144:147], v[176:179], v[80:83]
	v_mfma_f32_16x16x32_bf16 v[76:79], v[136:139], v[176:179], v[76:79]
	v_mfma_f32_16x16x32_bf16 v[76:79], v[132:135], v[172:175], v[76:79]
	v_mfma_f32_16x16x32_bf16 v[84:87], v[132:135], v[180:183], v[84:87]
	v_mfma_f32_16x16x32_bf16 v[84:87], v[136:139], v[184:187], v[84:87]
	v_mfma_f32_16x16x32_bf16 v[88:91], v[144:147], v[184:187], v[88:91]
	v_mfma_f32_16x16x32_bf16 v[88:91], v[140:143], v[180:183], v[88:91]
	v_mfma_f32_16x16x32_bf16 v[96:99], v[140:143], v[194:197], v[96:99]
	v_mfma_f32_16x16x32_bf16 v[96:99], v[144:147], v[198:201], v[96:99]
	v_mfma_f32_16x16x32_bf16 v[92:95], v[136:139], v[198:201], v[92:95]
	v_mfma_f32_16x16x32_bf16 v[92:95], v[132:135], v[194:197], v[92:95]
	s_setprio 0
	s_setprio 1
	v_mfma_f32_16x16x32_bf16 v[100:103], v[148:151], v[164:167], v[100:103]
	v_mfma_f32_16x16x32_bf16 v[100:103], v[152:155], v[168:171], v[100:103]
	v_mfma_f32_16x16x32_bf16 v[104:107], v[160:163], v[168:171], v[104:107]
	v_mfma_f32_16x16x32_bf16 v[104:107], v[156:159], v[164:167], v[104:107]
	v_mfma_f32_16x16x32_bf16 v[112:115], v[156:159], v[172:175], v[112:115]
	v_mfma_f32_16x16x32_bf16 v[112:115], v[160:163], v[176:179], v[112:115]
	v_mfma_f32_16x16x32_bf16 v[108:111], v[152:155], v[176:179], v[108:111]
	v_mfma_f32_16x16x32_bf16 v[108:111], v[148:151], v[172:175], v[108:111]
	v_mfma_f32_16x16x32_bf16 v[116:119], v[148:151], v[180:183], v[116:119]
	v_mfma_f32_16x16x32_bf16 v[116:119], v[152:155], v[184:187], v[116:119]
	v_mfma_f32_16x16x32_bf16 v[120:123], v[160:163], v[184:187], v[120:123]
	v_mfma_f32_16x16x32_bf16 v[120:123], v[156:159], v[180:183], v[120:123]
	v_mfma_f32_16x16x32_bf16 v[128:131], v[156:159], v[194:197], v[128:131]
	v_mfma_f32_16x16x32_bf16 v[128:131], v[160:163], v[198:201], v[128:131]
	s_setprio 2
	s_barrier
	v_mfma_f32_16x16x32_bf16 v[124:127], v[152:155], v[198:201], v[124:127]
	v_mfma_f32_16x16x32_bf16 v[124:127], v[148:151], v[194:197], v[124:127]
	s_add_i32 s29, 0, 0x18000
	s_add_i32 s42, 0, 0x1c000
	v_add_u32_e32 v144, s29, v232
	v_add_u32_e32 v160, s42, v232
	ds_read_b128 v[132:135], v144
	ds_read_b128 v[136:139], v144 offset:1024
	ds_read_b128 v[140:143], v144 offset:2048
	ds_read_b128 v[144:147], v144 offset:3072
	ds_read_b128 v[148:151], v160
	ds_read_b128 v[152:155], v160 offset:1024
	ds_read_b128 v[156:159], v160 offset:2048
	ds_read_b128 v[160:163], v160 offset:3072
	s_add_u32 s16, s16, 0x80000
	s_addc_u32 s17, s17, 0
	s_mov_b32 m0, s59
	ds_read_b128 v[164:167], v210 offset:32768
	ds_read_b128 v[168:171], v210 offset:33792
	ds_read_b128 v[172:175], v210 offset:34816
	ds_read_b128 v[176:179], v210 offset:35840
	ds_read_b128 v[180:183], v210 offset:36864
	ds_read_b128 v[184:187], v210 offset:37888
	ds_read_b128 v[194:197], v210 offset:38912
	ds_read_b128 v[198:201], v210 offset:39936
	global_load_lds_dwordx4 v2, s[16:17]
	s_mov_b32 m0, s60
	s_nop 0
	global_load_lds_dwordx4 v188, s[16:17]
	s_setprio 0
	s_waitcnt vmcnt(8)
	s_waitcnt lgkmcnt(0)
	s_barrier
	s_setprio 1
	s_waitcnt lgkmcnt(0)
	v_mfma_f32_16x16x32_bf16 v[4:7], v[132:135], v[164:167], v[4:7]
	v_mfma_f32_16x16x32_bf16 v[4:7], v[136:139], v[168:171], v[4:7]
	v_mfma_f32_16x16x32_bf16 v[8:11], v[144:147], v[168:171], v[8:11]
	v_mfma_f32_16x16x32_bf16 v[8:11], v[140:143], v[164:167], v[8:11]
	v_mfma_f32_16x16x32_bf16 v[16:19], v[140:143], v[172:175], v[16:19]
	v_mfma_f32_16x16x32_bf16 v[16:19], v[144:147], v[176:179], v[16:19]
	v_mfma_f32_16x16x32_bf16 v[12:15], v[136:139], v[176:179], v[12:15]
	v_mfma_f32_16x16x32_bf16 v[12:15], v[132:135], v[172:175], v[12:15]
	v_mfma_f32_16x16x32_bf16 v[20:23], v[132:135], v[180:183], v[20:23]
	v_mfma_f32_16x16x32_bf16 v[20:23], v[136:139], v[184:187], v[20:23]
	v_mfma_f32_16x16x32_bf16 v[24:27], v[144:147], v[184:187], v[24:27]
	v_mfma_f32_16x16x32_bf16 v[24:27], v[140:143], v[180:183], v[24:27]
	v_mfma_f32_16x16x32_bf16 v[32:35], v[140:143], v[194:197], v[32:35]
	v_mfma_f32_16x16x32_bf16 v[32:35], v[144:147], v[198:201], v[32:35]
	v_mfma_f32_16x16x32_bf16 v[28:31], v[136:139], v[198:201], v[28:31]
	v_mfma_f32_16x16x32_bf16 v[28:31], v[132:135], v[194:197], v[28:31]
	s_setprio 0
	s_setprio 1
	v_mfma_f32_16x16x32_bf16 v[36:39], v[148:151], v[164:167], v[36:39]
	v_mfma_f32_16x16x32_bf16 v[36:39], v[152:155], v[168:171], v[36:39]
	v_mfma_f32_16x16x32_bf16 v[40:43], v[160:163], v[168:171], v[40:43]
	v_mfma_f32_16x16x32_bf16 v[40:43], v[156:159], v[164:167], v[40:43]
	v_mfma_f32_16x16x32_bf16 v[48:51], v[156:159], v[172:175], v[48:51]
	v_mfma_f32_16x16x32_bf16 v[48:51], v[160:163], v[176:179], v[48:51]
	v_mfma_f32_16x16x32_bf16 v[44:47], v[152:155], v[176:179], v[44:47]
	v_mfma_f32_16x16x32_bf16 v[44:47], v[148:151], v[172:175], v[44:47]
	v_mfma_f32_16x16x32_bf16 v[52:55], v[148:151], v[180:183], v[52:55]
	v_mfma_f32_16x16x32_bf16 v[52:55], v[152:155], v[184:187], v[52:55]
	v_mfma_f32_16x16x32_bf16 v[56:59], v[160:163], v[184:187], v[56:59]
	v_mfma_f32_16x16x32_bf16 v[56:59], v[156:159], v[180:183], v[56:59]
	v_mfma_f32_16x16x32_bf16 v[64:67], v[156:159], v[194:197], v[64:67]
	v_mfma_f32_16x16x32_bf16 v[64:67], v[160:163], v[198:201], v[64:67]
	s_setprio 2
	s_barrier
	v_mfma_f32_16x16x32_bf16 v[60:63], v[152:155], v[198:201], v[60:63]
	v_mfma_f32_16x16x32_bf16 v[60:63], v[148:151], v[194:197], v[60:63]
	s_add_i32 s16, s29, s56
	v_lshl_add_u64 v[202:203], v[202:203], 0, s[86:87]
	s_mov_b32 m0, s16
	ds_read_b128 v[164:167], v210 offset:49152
	ds_read_b128 v[168:171], v210 offset:50176
	ds_read_b128 v[172:175], v210 offset:51200
	ds_read_b128 v[176:179], v210 offset:52224
	ds_read_b128 v[180:183], v210 offset:53248
	ds_read_b128 v[184:187], v210 offset:54272
	ds_read_b128 v[194:197], v210 offset:55296
	ds_read_b128 v[198:201], v210 offset:56320
	global_load_lds_dwordx4 v[202:203], off
	s_add_i32 m0, s16, 0x2000
	s_add_u32 s12, s12, 0x80080
	v_lshl_add_u64 v[202:203], v[204:205], 0, s[86:87]
	s_addc_u32 s13, s13, 0
	s_add_i32 s16, s42, s56
	global_load_lds_dwordx4 v[202:203], off
	s_mov_b32 m0, s16
	v_lshl_add_u64 v[202:203], v[206:207], 0, s[86:87]
	global_load_lds_dwordx4 v192, s[12:13]
	s_add_i32 m0, s16, 0x2000
	s_nop 0
	global_load_lds_dwordx4 v190, s[12:13]
	s_mov_b32 m0, s64
	s_nop 0
	global_load_lds_dwordx4 v[202:203], off
	v_lshl_add_u64 v[202:203], v[208:209], 0, s[86:87]
	s_mov_b32 m0, s65
	s_nop 0
	global_load_lds_dwordx4 v[202:203], off
	s_setprio 0
	s_waitcnt vmcnt(8)
	s_waitcnt lgkmcnt(0)
	s_barrier
	s_setprio 1
	s_waitcnt lgkmcnt(0)
	v_mfma_f32_16x16x32_bf16 v[68:71], v[132:135], v[164:167], v[68:71]
	v_mfma_f32_16x16x32_bf16 v[68:71], v[136:139], v[168:171], v[68:71]
	v_mfma_f32_16x16x32_bf16 v[72:75], v[144:147], v[168:171], v[72:75]
	v_mfma_f32_16x16x32_bf16 v[72:75], v[140:143], v[164:167], v[72:75]
	v_mfma_f32_16x16x32_bf16 v[80:83], v[140:143], v[172:175], v[80:83]
	v_mfma_f32_16x16x32_bf16 v[80:83], v[144:147], v[176:179], v[80:83]
	v_mfma_f32_16x16x32_bf16 v[76:79], v[136:139], v[176:179], v[76:79]
	v_mfma_f32_16x16x32_bf16 v[76:79], v[132:135], v[172:175], v[76:79]
	v_mfma_f32_16x16x32_bf16 v[84:87], v[132:135], v[180:183], v[84:87]
	v_mfma_f32_16x16x32_bf16 v[84:87], v[136:139], v[184:187], v[84:87]
	v_mfma_f32_16x16x32_bf16 v[88:91], v[144:147], v[184:187], v[88:91]
	v_mfma_f32_16x16x32_bf16 v[88:91], v[140:143], v[180:183], v[88:91]
	v_mfma_f32_16x16x32_bf16 v[96:99], v[140:143], v[194:197], v[96:99]
	v_mfma_f32_16x16x32_bf16 v[96:99], v[144:147], v[198:201], v[96:99]
	v_mfma_f32_16x16x32_bf16 v[92:95], v[136:139], v[198:201], v[92:95]
	v_mfma_f32_16x16x32_bf16 v[92:95], v[132:135], v[194:197], v[92:95]
	s_setprio 0
	s_setprio 1
	v_mfma_f32_16x16x32_bf16 v[100:103], v[148:151], v[164:167], v[100:103]
	v_mfma_f32_16x16x32_bf16 v[100:103], v[152:155], v[168:171], v[100:103]
	v_mfma_f32_16x16x32_bf16 v[104:107], v[160:163], v[168:171], v[104:107]
	v_mfma_f32_16x16x32_bf16 v[104:107], v[156:159], v[164:167], v[104:107]
	v_mfma_f32_16x16x32_bf16 v[112:115], v[156:159], v[172:175], v[112:115]
	v_mfma_f32_16x16x32_bf16 v[112:115], v[160:163], v[176:179], v[112:115]
	v_mfma_f32_16x16x32_bf16 v[108:111], v[152:155], v[176:179], v[108:111]
	v_mfma_f32_16x16x32_bf16 v[108:111], v[148:151], v[172:175], v[108:111]
	v_mfma_f32_16x16x32_bf16 v[116:119], v[148:151], v[180:183], v[116:119]
	v_mfma_f32_16x16x32_bf16 v[116:119], v[152:155], v[184:187], v[116:119]
	v_mfma_f32_16x16x32_bf16 v[120:123], v[160:163], v[184:187], v[120:123]
	v_mfma_f32_16x16x32_bf16 v[120:123], v[156:159], v[180:183], v[120:123]
	v_mfma_f32_16x16x32_bf16 v[128:131], v[156:159], v[194:197], v[128:131]
	v_mfma_f32_16x16x32_bf16 v[128:131], v[160:163], v[198:201], v[128:131]
	s_setprio 2
	s_barrier
	v_mfma_f32_16x16x32_bf16 v[124:127], v[152:155], v[198:201], v[124:127]
	v_mfma_f32_16x16x32_bf16 v[124:127], v[148:151], v[194:197], v[124:127]
	s_setprio 0
	s_add_i32 s28, s28, 2
	s_add_u32 s14, s14, 0x100
	s_addc_u32 s15, s15, 0
	s_add_u32 s26, s26, 0x100
	s_addc_u32 s27, s27, 0
	s_cmp_gt_u32 s28, 29
	s_cbranch_scc0 .LBB0_1629
	s_and_b64 vcc, exec, s[48:49]
	s_cbranch_vccz .LBB0_1632
	s_barrier

.LBB0_2065:
	s_add_i32 s51, 0, 0x10000
	s_add_i32 s71, 0, 0x14000
	v_add_u32_e32 v16, s51, v232
	v_add_u32_e32 v32, s71, v232
	ds_read_b128 v[4:7], v16
	ds_read_b128 v[8:11], v16 offset:1024
	ds_read_b128 v[12:15], v16 offset:2048
	ds_read_b128 v[16:19], v16 offset:3072
	ds_read_b128 v[20:23], v32
	ds_read_b128 v[24:27], v32 offset:1024
	ds_read_b128 v[28:31], v32 offset:2048
	ds_read_b128 v[32:35], v32 offset:3072
	v_add_u32_e32 v233, 0, v231
	ds_read_b128 v[36:39], v233
	ds_read_b128 v[40:43], v233 offset:1024
	ds_read_b128 v[44:47], v233 offset:2048
	ds_read_b128 v[48:51], v233 offset:3072
	ds_read_b128 v[52:55], v233 offset:4096
	ds_read_b128 v[56:59], v233 offset:5120
	ds_read_b128 v[60:63], v233 offset:6144
	ds_read_b128 v[64:67], v233 offset:7168
	s_waitcnt vmcnt(8)
	s_waitcnt lgkmcnt(0)
	s_barrier
	s_setprio 1
	s_waitcnt lgkmcnt(0)
	v_mfma_f32_16x16x32_bf16 v[68:71], v[4:7], v[36:39], 0
	v_mfma_f32_16x16x32_bf16 v[68:71], v[8:11], v[40:43], v[68:71]
	v_mfma_f32_16x16x32_bf16 v[72:75], v[12:15], v[36:39], 0
	v_mfma_f32_16x16x32_bf16 v[72:75], v[16:19], v[40:43], v[72:75]
	v_mfma_f32_16x16x32_bf16 v[80:83], v[12:15], v[44:47], 0
	v_mfma_f32_16x16x32_bf16 v[80:83], v[16:19], v[48:51], v[80:83]
	v_mfma_f32_16x16x32_bf16 v[76:79], v[4:7], v[44:47], 0
	v_mfma_f32_16x16x32_bf16 v[76:79], v[8:11], v[48:51], v[76:79]
	v_mfma_f32_16x16x32_bf16 v[84:87], v[4:7], v[52:55], 0
	v_mfma_f32_16x16x32_bf16 v[84:87], v[8:11], v[56:59], v[84:87]
	v_mfma_f32_16x16x32_bf16 v[88:91], v[12:15], v[52:55], 0
	v_mfma_f32_16x16x32_bf16 v[88:91], v[16:19], v[56:59], v[88:91]
	v_mfma_f32_16x16x32_bf16 v[96:99], v[12:15], v[60:63], 0
	v_mfma_f32_16x16x32_bf16 v[96:99], v[16:19], v[64:67], v[96:99]
	v_mfma_f32_16x16x32_bf16 v[92:95], v[4:7], v[60:63], 0
	v_mfma_f32_16x16x32_bf16 v[92:95], v[8:11], v[64:67], v[92:95]
	s_setprio 0
	s_setprio 1
	v_mfma_f32_16x16x32_bf16 v[100:103], v[20:23], v[36:39], 0
	v_mfma_f32_16x16x32_bf16 v[36:39], v[28:31], v[36:39], 0
	v_mfma_f32_16x16x32_bf16 v[104:107], v[20:23], v[44:47], 0
	v_mfma_f32_16x16x32_bf16 v[44:47], v[28:31], v[44:47], 0
	v_mfma_f32_16x16x32_bf16 v[108:111], v[20:23], v[52:55], 0
	v_mfma_f32_16x16x32_bf16 v[52:55], v[28:31], v[52:55], 0
	v_mfma_f32_16x16x32_bf16 v[112:115], v[20:23], v[60:63], 0
	v_mfma_f32_16x16x32_bf16 v[60:63], v[28:31], v[60:63], 0
	v_mfma_f32_16x16x32_bf16 v[100:103], v[24:27], v[40:43], v[100:103]
	v_mfma_f32_16x16x32_bf16 v[40:43], v[32:35], v[40:43], v[36:39]
	v_mfma_f32_16x16x32_bf16 v[104:107], v[24:27], v[48:51], v[104:107]
	v_mfma_f32_16x16x32_bf16 v[48:51], v[32:35], v[48:51], v[44:47]
	v_mfma_f32_16x16x32_bf16 v[108:111], v[24:27], v[56:59], v[108:111]
	v_mfma_f32_16x16x32_bf16 v[56:59], v[32:35], v[56:59], v[52:55]
	s_setprio 2
	s_barrier
	v_mfma_f32_16x16x32_bf16 v[112:115], v[24:27], v[64:67], v[112:115]
	v_mfma_f32_16x16x32_bf16 v[64:67], v[32:35], v[64:67], v[60:63]
	v_lshl_add_u64 v[186:187], s[12:13], 0, v[2:3]
	s_add_i32 s51, s51, s38
	v_mov_b32_e32 v191, v3
	v_lshl_add_u64 v[134:135], v[186:187], 0, s[74:75]
	s_mov_b32 m0, s51
	v_lshl_add_u64 v[246:247], s[12:13], 0, v[190:191]
	ds_read_b128 v[36:39], v233 offset:16384
	ds_read_b128 v[44:47], v233 offset:17408
	ds_read_b128 v[52:55], v233 offset:18432
	ds_read_b128 v[60:63], v233 offset:19456
	ds_read_b128 v[116:119], v233 offset:20480
	ds_read_b128 v[120:123], v233 offset:21504
	ds_read_b128 v[124:127], v233 offset:22528
	ds_read_b128 v[128:131], v233 offset:23552
	global_load_lds_dwordx4 v[134:135], off
	v_lshl_add_u64 v[134:135], v[246:247], 0, s[74:75]
	s_add_i32 m0, s51, 0x2000
	s_add_i32 s51, s71, s38
	global_load_lds_dwordx4 v[134:135], off
	s_mov_b32 m0, s51
	v_mov_b32_e32 v133, v3
	global_load_lds_dwordx4 v2, s[16:17]
	s_add_i32 m0, s51, 0x2000
	v_lshl_add_u64 v[248:249], s[14:15], 0, v[132:133]
	v_mov_b32_e32 v189, v3
	global_load_lds_dwordx4 v190, s[16:17]
	v_lshl_add_u64 v[134:135], v[248:249], 0, s[74:75]
	s_mov_b32 m0, s56
	v_lshl_add_u64 v[250:251], s[14:15], 0, v[188:189]
	global_load_lds_dwordx4 v[134:135], off
	v_lshl_add_u64 v[134:135], v[250:251], 0, s[74:75]
	s_mov_b32 m0, s57
	s_nop 0
	global_load_lds_dwordx4 v[134:135], off
	s_setprio 0
	s_waitcnt vmcnt(8)
	s_waitcnt lgkmcnt(0)
	s_barrier
	s_setprio 1
	s_waitcnt lgkmcnt(0)
	v_mfma_f32_16x16x32_bf16 v[134:137], v[4:7], v[36:39], 0
	v_mfma_f32_16x16x32_bf16 v[138:141], v[12:15], v[36:39], 0
	v_mfma_f32_16x16x32_bf16 v[142:145], v[4:7], v[52:55], 0
	v_mfma_f32_16x16x32_bf16 v[146:149], v[12:15], v[52:55], 0
	v_mfma_f32_16x16x32_bf16 v[150:153], v[4:7], v[116:119], 0
	v_mfma_f32_16x16x32_bf16 v[154:157], v[12:15], v[116:119], 0
	v_mfma_f32_16x16x32_bf16 v[4:7], v[4:7], v[124:127], 0
	v_mfma_f32_16x16x32_bf16 v[12:15], v[12:15], v[124:127], 0
	v_mfma_f32_16x16x32_bf16 v[134:137], v[8:11], v[44:47], v[134:137]
	v_mfma_f32_16x16x32_bf16 v[138:141], v[16:19], v[44:47], v[138:141]
	v_mfma_f32_16x16x32_bf16 v[142:145], v[8:11], v[60:63], v[142:145]
	v_mfma_f32_16x16x32_bf16 v[146:149], v[16:19], v[60:63], v[146:149]
	v_mfma_f32_16x16x32_bf16 v[150:153], v[8:11], v[120:123], v[150:153]
	v_mfma_f32_16x16x32_bf16 v[154:157], v[16:19], v[120:123], v[154:157]
	v_mfma_f32_16x16x32_bf16 v[158:161], v[8:11], v[128:131], v[4:7]
	v_mfma_f32_16x16x32_bf16 v[162:165], v[16:19], v[128:131], v[12:15]
	s_setprio 0
	s_setprio 1
	v_mfma_f32_16x16x32_bf16 v[4:7], v[20:23], v[36:39], 0
	v_mfma_f32_16x16x32_bf16 v[8:11], v[28:31], v[36:39], 0
	v_mfma_f32_16x16x32_bf16 v[12:15], v[20:23], v[52:55], 0
	v_mfma_f32_16x16x32_bf16 v[16:19], v[28:31], v[52:55], 0
	v_mfma_f32_16x16x32_bf16 v[36:39], v[20:23], v[116:119], 0
	v_mfma_f32_16x16x32_bf16 v[52:55], v[28:31], v[116:119], 0
	v_mfma_f32_16x16x32_bf16 v[20:23], v[20:23], v[124:127], 0
	v_mfma_f32_16x16x32_bf16 v[28:31], v[28:31], v[124:127], 0
	v_mfma_f32_16x16x32_bf16 v[116:119], v[24:27], v[44:47], v[4:7]
	v_mfma_f32_16x16x32_bf16 v[124:127], v[32:35], v[44:47], v[8:11]
	v_mfma_f32_16x16x32_bf16 v[174:177], v[24:27], v[120:123], v[36:39]
	v_mfma_f32_16x16x32_bf16 v[120:123], v[32:35], v[120:123], v[52:55]
	v_mfma_f32_16x16x32_bf16 v[178:181], v[24:27], v[128:131], v[20:23]
	v_mfma_f32_16x16x32_bf16 v[128:131], v[32:35], v[128:131], v[28:31]
	s_setprio 2
	s_barrier
	v_mfma_f32_16x16x32_bf16 v[166:169], v[24:27], v[60:63], v[12:15]
	v_mfma_f32_16x16x32_bf16 v[170:173], v[32:35], v[60:63], v[16:19]
	s_add_i32 s51, 0, 0x18000
	v_add_u32_e32 v4, s51, v232
	s_add_i32 s71, 0, 0x1c000
	ds_read_b128 v[182:185], v4
	ds_read_b128 v[192:195], v4 offset:1024
	ds_read_b128 v[196:199], v4 offset:2048
	ds_read_b128 v[200:203], v4 offset:3072
	v_add_u32_e32 v4, s71, v232
	ds_read_b128 v[204:207], v4
	ds_read_b128 v[208:211], v4 offset:1024
	ds_read_b128 v[212:215], v4 offset:2048
	ds_read_b128 v[216:219], v4 offset:3072
	s_mov_b32 m0, s58
	ds_read_b128 v[44:47], v233 offset:32768
	ds_read_b128 v[52:55], v233 offset:33792
	ds_read_b128 v[60:63], v233 offset:34816
	ds_read_b128 v[220:223], v233 offset:35840
	ds_read_b128 v[224:227], v233 offset:36864
	ds_read_b128 v[234:237], v233 offset:37888
	ds_read_b128 v[238:241], v233 offset:38912
	ds_read_b128 v[242:245], v233 offset:39936
	global_load_lds_dwordx4 v132, s[26:27]
	s_mov_b32 m0, s59
	s_nop 0
	global_load_lds_dwordx4 v188, s[26:27]
	s_setprio 0
	s_waitcnt vmcnt(8)
	s_waitcnt lgkmcnt(0)
	s_barrier
	s_setprio 1
	s_waitcnt lgkmcnt(0)
	v_mfma_f32_16x16x32_bf16 v[4:7], v[182:185], v[44:47], v[68:71]
	v_mfma_f32_16x16x32_bf16 v[8:11], v[196:199], v[44:47], v[72:75]
	v_mfma_f32_16x16x32_bf16 v[12:15], v[182:185], v[60:63], v[76:79]
	v_mfma_f32_16x16x32_bf16 v[16:19], v[196:199], v[60:63], v[80:83]
	v_mfma_f32_16x16x32_bf16 v[20:23], v[182:185], v[224:227], v[84:87]
	v_mfma_f32_16x16x32_bf16 v[24:27], v[196:199], v[224:227], v[88:91]
	v_mfma_f32_16x16x32_bf16 v[28:31], v[182:185], v[238:241], v[92:95]
	v_mfma_f32_16x16x32_bf16 v[32:35], v[196:199], v[238:241], v[96:99]
	v_mfma_f32_16x16x32_bf16 v[4:7], v[192:195], v[52:55], v[4:7]
	v_mfma_f32_16x16x32_bf16 v[8:11], v[200:203], v[52:55], v[8:11]
	v_mfma_f32_16x16x32_bf16 v[12:15], v[192:195], v[220:223], v[12:15]
	v_mfma_f32_16x16x32_bf16 v[16:19], v[200:203], v[220:223], v[16:19]
	v_mfma_f32_16x16x32_bf16 v[20:23], v[192:195], v[234:237], v[20:23]
	v_mfma_f32_16x16x32_bf16 v[24:27], v[200:203], v[234:237], v[24:27]
	v_mfma_f32_16x16x32_bf16 v[28:31], v[192:195], v[242:245], v[28:31]
	v_mfma_f32_16x16x32_bf16 v[32:35], v[200:203], v[242:245], v[32:35]
	s_setprio 0
	s_setprio 1
	v_mfma_f32_16x16x32_bf16 v[36:39], v[204:207], v[44:47], v[100:103]
	v_mfma_f32_16x16x32_bf16 v[40:43], v[212:215], v[44:47], v[40:43]
	v_mfma_f32_16x16x32_bf16 v[36:39], v[208:211], v[52:55], v[36:39]
	v_mfma_f32_16x16x32_bf16 v[40:43], v[216:219], v[52:55], v[40:43]
	v_mfma_f32_16x16x32_bf16 v[44:47], v[204:207], v[60:63], v[104:107]
	v_mfma_f32_16x16x32_bf16 v[48:51], v[212:215], v[60:63], v[48:51]
	v_mfma_f32_16x16x32_bf16 v[52:55], v[204:207], v[224:227], v[108:111]
	v_mfma_f32_16x16x32_bf16 v[56:59], v[212:215], v[224:227], v[56:59]
	v_mfma_f32_16x16x32_bf16 v[60:63], v[204:207], v[238:241], v[112:115]
	v_mfma_f32_16x16x32_bf16 v[64:67], v[212:215], v[238:241], v[64:67]
	v_mfma_f32_16x16x32_bf16 v[44:47], v[208:211], v[220:223], v[44:47]
	v_mfma_f32_16x16x32_bf16 v[48:51], v[216:219], v[220:223], v[48:51]
	v_mfma_f32_16x16x32_bf16 v[52:55], v[208:211], v[234:237], v[52:55]
	v_mfma_f32_16x16x32_bf16 v[56:59], v[216:219], v[234:237], v[56:59]
	s_setprio 2
	s_barrier
	v_mfma_f32_16x16x32_bf16 v[60:63], v[208:211], v[242:245], v[60:63]
	v_mfma_f32_16x16x32_bf16 v[64:67], v[216:219], v[242:245], v[64:67]
	s_add_i32 s51, s51, s38
	v_lshl_add_u64 v[68:69], v[186:187], 0, s[24:25]
	s_mov_b32 m0, s51
	ds_read_b128 v[104:107], v233 offset:49152
	ds_read_b128 v[108:111], v233 offset:50176
	ds_read_b128 v[112:115], v233 offset:51200
	ds_read_b128 v[220:223], v233 offset:52224
	ds_read_b128 v[224:227], v233 offset:53248
	ds_read_b128 v[234:237], v233 offset:54272
	ds_read_b128 v[238:241], v233 offset:55296
	ds_read_b128 v[242:245], v233 offset:56320
	global_load_lds_dwordx4 v[68:69], off
	v_lshl_add_u64 v[68:69], v[246:247], 0, s[24:25]
	s_add_i32 m0, s51, 0x2000
	s_add_i32 s51, s71, s38
	global_load_lds_dwordx4 v[68:69], off
	s_mov_b32 m0, s51
	v_lshl_add_u64 v[68:69], v[248:249], 0, s[24:25]
	global_load_lds_dwordx4 v2, s[28:29]
	s_add_i32 m0, s51, 0x2000
	s_nop 0
	global_load_lds_dwordx4 v190, s[28:29]
	s_mov_b32 m0, s63
	s_nop 0
	global_load_lds_dwordx4 v[68:69], off
	v_lshl_add_u64 v[68:69], v[250:251], 0, s[24:25]
	s_mov_b32 m0, s64
	s_nop 0
	global_load_lds_dwordx4 v[68:69], off
	s_setprio 0
	s_waitcnt vmcnt(8)
	s_waitcnt lgkmcnt(0)
	s_barrier
	s_setprio 1
	s_waitcnt lgkmcnt(0)
	v_mfma_f32_16x16x32_bf16 v[68:71], v[182:185], v[104:107], v[134:137]
	v_mfma_f32_16x16x32_bf16 v[72:75], v[196:199], v[104:107], v[138:141]
	v_mfma_f32_16x16x32_bf16 v[76:79], v[182:185], v[112:115], v[142:145]
	v_mfma_f32_16x16x32_bf16 v[80:83], v[196:199], v[112:115], v[146:149]
	v_mfma_f32_16x16x32_bf16 v[84:87], v[182:185], v[224:227], v[150:153]
	v_mfma_f32_16x16x32_bf16 v[88:91], v[196:199], v[224:227], v[154:157]
	v_mfma_f32_16x16x32_bf16 v[92:95], v[182:185], v[238:241], v[158:161]
	v_mfma_f32_16x16x32_bf16 v[96:99], v[196:199], v[238:241], v[162:165]
	v_mfma_f32_16x16x32_bf16 v[68:71], v[192:195], v[108:111], v[68:71]
	v_mfma_f32_16x16x32_bf16 v[72:75], v[200:203], v[108:111], v[72:75]
	v_mfma_f32_16x16x32_bf16 v[76:79], v[192:195], v[220:223], v[76:79]
	v_mfma_f32_16x16x32_bf16 v[80:83], v[200:203], v[220:223], v[80:83]
	v_mfma_f32_16x16x32_bf16 v[84:87], v[192:195], v[234:237], v[84:87]
	v_mfma_f32_16x16x32_bf16 v[88:91], v[200:203], v[234:237], v[88:91]
	v_mfma_f32_16x16x32_bf16 v[92:95], v[192:195], v[242:245], v[92:95]
	v_mfma_f32_16x16x32_bf16 v[96:99], v[200:203], v[242:245], v[96:99]
	s_setprio 0
	s_setprio 1
	v_mfma_f32_16x16x32_bf16 v[100:103], v[204:207], v[104:107], v[116:119]
	v_mfma_f32_16x16x32_bf16 v[104:107], v[212:215], v[104:107], v[124:127]
	v_mfma_f32_16x16x32_bf16 v[100:103], v[208:211], v[108:111], v[100:103]
	v_mfma_f32_16x16x32_bf16 v[104:107], v[216:219], v[108:111], v[104:107]
	v_mfma_f32_16x16x32_bf16 v[108:111], v[204:207], v[112:115], v[166:169]
	v_mfma_f32_16x16x32_bf16 v[112:115], v[212:215], v[112:115], v[170:173]
	v_mfma_f32_16x16x32_bf16 v[116:119], v[204:207], v[224:227], v[174:177]
	v_mfma_f32_16x16x32_bf16 v[120:123], v[212:215], v[224:227], v[120:123]
	v_mfma_f32_16x16x32_bf16 v[124:127], v[204:207], v[238:241], v[178:181]
	v_mfma_f32_16x16x32_bf16 v[128:131], v[212:215], v[238:241], v[128:131]
	v_mfma_f32_16x16x32_bf16 v[108:111], v[208:211], v[220:223], v[108:111]
	v_mfma_f32_16x16x32_bf16 v[112:115], v[216:219], v[220:223], v[112:115]
	v_mfma_f32_16x16x32_bf16 v[116:119], v[208:211], v[234:237], v[116:119]
	v_mfma_f32_16x16x32_bf16 v[120:123], v[216:219], v[234:237], v[120:123]
	s_setprio 2
	s_barrier
	v_mfma_f32_16x16x32_bf16 v[124:127], v[208:211], v[242:245], v[124:127]
	v_mfma_f32_16x16x32_bf16 v[128:131], v[216:219], v[242:245], v[128:131]
	s_setprio 0
	s_add_i32 s45, s45, 2
	s_cmp_ge_i32 s45, s44
	s_cbranch_scc0 .LBB0_2065
	v_mov_b32_e32 v192, v2
	s_branch .LBB0_2068

.LBB0_2069:
	s_add_u32 s12, s14, 0xfff80080
	s_addc_u32 s13, s15, -1
	s_add_i32 s29, 0, 0x10000
	s_cmp_eq_u32 s28, 4
	s_cselect_b32 s17, s9, s13
	s_cselect_b32 s16, s8, s12
	s_cselect_b32 s13, s11, s27
	s_cselect_b32 s12, s10, s26
	s_add_i32 s51, 0, 0x14000
	v_add_u32_e32 v144, s29, v232
	v_add_u32_e32 v160, s51, v232
	s_waitcnt lgkmcnt(0)
	ds_read_b128 v[132:135], v144
	ds_read_b128 v[136:139], v144 offset:1024
	ds_read_b128 v[140:143], v144 offset:2048
	ds_read_b128 v[144:147], v144 offset:3072
	ds_read_b128 v[148:151], v160
	ds_read_b128 v[152:155], v160 offset:1024
	ds_read_b128 v[156:159], v160 offset:2048
	ds_read_b128 v[160:163], v160 offset:3072
	s_mov_b32 m0, s65
	v_add_u32_e32 v210, 0, v231
	ds_read_b128 v[164:167], v210
	ds_read_b128 v[168:171], v210 offset:1024
	ds_read_b128 v[172:175], v210 offset:2048
	ds_read_b128 v[176:179], v210 offset:3072
	ds_read_b128 v[180:183], v210 offset:4096
	ds_read_b128 v[184:187], v210 offset:5120
	ds_read_b128 v[194:197], v210 offset:6144
	ds_read_b128 v[198:201], v210 offset:7168
	global_load_lds_dwordx4 v2, s[14:15]
	s_mov_b32 m0, s66
	v_mov_b32_e32 v189, v3
	global_load_lds_dwordx4 v188, s[14:15]
	s_waitcnt vmcnt(8)
	s_waitcnt lgkmcnt(0)
	s_barrier
	s_setprio 1
	s_waitcnt lgkmcnt(0)
	v_mfma_f32_16x16x32_bf16 v[4:7], v[132:135], v[164:167], v[4:7]
	v_mfma_f32_16x16x32_bf16 v[4:7], v[136:139], v[168:171], v[4:7]
	v_mfma_f32_16x16x32_bf16 v[8:11], v[144:147], v[168:171], v[8:11]
	v_mfma_f32_16x16x32_bf16 v[8:11], v[140:143], v[164:167], v[8:11]
	v_mfma_f32_16x16x32_bf16 v[16:19], v[140:143], v[172:175], v[16:19]
	v_mfma_f32_16x16x32_bf16 v[16:19], v[144:147], v[176:179], v[16:19]
	v_mfma_f32_16x16x32_bf16 v[12:15], v[136:139], v[176:179], v[12:15]
	v_mfma_f32_16x16x32_bf16 v[12:15], v[132:135], v[172:175], v[12:15]
	v_mfma_f32_16x16x32_bf16 v[20:23], v[132:135], v[180:183], v[20:23]
	v_mfma_f32_16x16x32_bf16 v[20:23], v[136:139], v[184:187], v[20:23]
	v_mfma_f32_16x16x32_bf16 v[24:27], v[144:147], v[184:187], v[24:27]
	v_mfma_f32_16x16x32_bf16 v[24:27], v[140:143], v[180:183], v[24:27]
	v_mfma_f32_16x16x32_bf16 v[32:35], v[140:143], v[194:197], v[32:35]
	v_mfma_f32_16x16x32_bf16 v[32:35], v[144:147], v[198:201], v[32:35]
	v_mfma_f32_16x16x32_bf16 v[28:31], v[136:139], v[198:201], v[28:31]
	v_mfma_f32_16x16x32_bf16 v[28:31], v[132:135], v[194:197], v[28:31]
	s_setprio 0
	s_setprio 1
	v_mfma_f32_16x16x32_bf16 v[36:39], v[148:151], v[164:167], v[36:39]
	v_mfma_f32_16x16x32_bf16 v[36:39], v[152:155], v[168:171], v[36:39]
	v_mfma_f32_16x16x32_bf16 v[40:43], v[160:163], v[168:171], v[40:43]
	v_mfma_f32_16x16x32_bf16 v[40:43], v[156:159], v[164:167], v[40:43]
	v_mfma_f32_16x16x32_bf16 v[48:51], v[156:159], v[172:175], v[48:51]
	v_mfma_f32_16x16x32_bf16 v[48:51], v[160:163], v[176:179], v[48:51]
	v_mfma_f32_16x16x32_bf16 v[44:47], v[152:155], v[176:179], v[44:47]
	v_mfma_f32_16x16x32_bf16 v[44:47], v[148:151], v[172:175], v[44:47]
	v_mfma_f32_16x16x32_bf16 v[52:55], v[148:151], v[180:183], v[52:55]
	v_mfma_f32_16x16x32_bf16 v[52:55], v[152:155], v[184:187], v[52:55]
	v_mfma_f32_16x16x32_bf16 v[56:59], v[160:163], v[184:187], v[56:59]
	v_mfma_f32_16x16x32_bf16 v[56:59], v[156:159], v[180:183], v[56:59]
	v_mfma_f32_16x16x32_bf16 v[64:67], v[156:159], v[194:197], v[64:67]
	v_mfma_f32_16x16x32_bf16 v[64:67], v[160:163], v[198:201], v[64:67]
	s_setprio 2
	s_barrier
	v_mfma_f32_16x16x32_bf16 v[60:63], v[152:155], v[198:201], v[60:63]
	v_mfma_f32_16x16x32_bf16 v[60:63], v[148:151], v[194:197], v[60:63]
	s_add_i32 s29, s29, s38
	s_mov_b32 m0, s29
	ds_read_b128 v[164:167], v210 offset:16384
	ds_read_b128 v[168:171], v210 offset:17408
	ds_read_b128 v[172:175], v210 offset:18432
	ds_read_b128 v[176:179], v210 offset:19456
	ds_read_b128 v[180:183], v210 offset:20480
	ds_read_b128 v[184:187], v210 offset:21504
	ds_read_b128 v[194:197], v210 offset:22528
	ds_read_b128 v[198:201], v210 offset:23552
	global_load_lds_dwordx4 v192, s[12:13]
	s_add_i32 m0, s29, 0x2000
	s_add_u32 s44, s12, 0x20000
	s_addc_u32 s45, s13, 0
	s_add_i32 s29, s51, s38
	global_load_lds_dwordx4 v190, s[12:13]
	s_mov_b32 m0, s29
	v_mov_b32_e32 v193, v3
	global_load_lds_dwordx4 v192, s[44:45]
	s_add_i32 m0, s29, 0x2000
	v_mov_b32_e32 v191, v3
	global_load_lds_dwordx4 v190, s[44:45]
	s_mov_b32 m0, s56
	v_lshl_add_u64 v[202:203], s[12:13], 0, v[192:193]
	global_load_lds_dwordx4 v2, s[16:17]
	s_mov_b32 m0, s57
	v_lshl_add_u64 v[204:205], s[12:13], 0, v[190:191]
	global_load_lds_dwordx4 v188, s[16:17]
	s_setprio 0
	s_waitcnt vmcnt(8)
	s_waitcnt lgkmcnt(0)
	v_lshl_add_u64 v[206:207], s[16:17], 0, v[2:3]
	v_lshl_add_u64 v[208:209], s[16:17], 0, v[188:189]
	s_barrier
	s_setprio 1
	s_waitcnt lgkmcnt(0)
	v_mfma_f32_16x16x32_bf16 v[68:71], v[132:135], v[164:167], v[68:71]
	v_mfma_f32_16x16x32_bf16 v[68:71], v[136:139], v[168:171], v[68:71]
	v_mfma_f32_16x16x32_bf16 v[72:75], v[144:147], v[168:171], v[72:75]
	v_mfma_f32_16x16x32_bf16 v[72:75], v[140:143], v[164:167], v[72:75]
	v_mfma_f32_16x16x32_bf16 v[80:83], v[140:143], v[172:175], v[80:83]
	v_mfma_f32_16x16x32_bf16 v[80:83], v[144:147], v[176:179], v[80:83]
	v_mfma_f32_16x16x32_bf16 v[76:79], v[136:139], v[176:179], v[76:79]
	v_mfma_f32_16x16x32_bf16 v[76:79], v[132:135], v[172:175], v[76:79]
	v_mfma_f32_16x16x32_bf16 v[84:87], v[132:135], v[180:183], v[84:87]
	v_mfma_f32_16x16x32_bf16 v[84:87], v[136:139], v[184:187], v[84:87]
	v_mfma_f32_16x16x32_bf16 v[88:91], v[144:147], v[184:187], v[88:91]
	v_mfma_f32_16x16x32_bf16 v[88:91], v[140:143], v[180:183], v[88:91]
	v_mfma_f32_16x16x32_bf16 v[96:99], v[140:143], v[194:197], v[96:99]
	v_mfma_f32_16x16x32_bf16 v[96:99], v[144:147], v[198:201], v[96:99]
	v_mfma_f32_16x16x32_bf16 v[92:95], v[136:139], v[198:201], v[92:95]
	v_mfma_f32_16x16x32_bf16 v[92:95], v[132:135], v[194:197], v[92:95]
	s_setprio 0
	s_setprio 1
	v_mfma_f32_16x16x32_bf16 v[100:103], v[148:151], v[164:167], v[100:103]
	v_mfma_f32_16x16x32_bf16 v[100:103], v[152:155], v[168:171], v[100:103]
	v_mfma_f32_16x16x32_bf16 v[104:107], v[160:163], v[168:171], v[104:107]
	v_mfma_f32_16x16x32_bf16 v[104:107], v[156:159], v[164:167], v[104:107]
	v_mfma_f32_16x16x32_bf16 v[112:115], v[156:159], v[172:175], v[112:115]
	v_mfma_f32_16x16x32_bf16 v[112:115], v[160:163], v[176:179], v[112:115]
	v_mfma_f32_16x16x32_bf16 v[108:111], v[152:155], v[176:179], v[108:111]
	v_mfma_f32_16x16x32_bf16 v[108:111], v[148:151], v[172:175], v[108:111]
	v_mfma_f32_16x16x32_bf16 v[116:119], v[148:151], v[180:183], v[116:119]
	v_mfma_f32_16x16x32_bf16 v[116:119], v[152:155], v[184:187], v[116:119]
	v_mfma_f32_16x16x32_bf16 v[120:123], v[160:163], v[184:187], v[120:123]
	v_mfma_f32_16x16x32_bf16 v[120:123], v[156:159], v[180:183], v[120:123]
	v_mfma_f32_16x16x32_bf16 v[128:131], v[156:159], v[194:197], v[128:131]
	v_mfma_f32_16x16x32_bf16 v[128:131], v[160:163], v[198:201], v[128:131]
	s_setprio 2
	s_barrier
	v_mfma_f32_16x16x32_bf16 v[124:127], v[152:155], v[198:201], v[124:127]
	v_mfma_f32_16x16x32_bf16 v[124:127], v[148:151], v[194:197], v[124:127]
	s_add_i32 s29, 0, 0x18000
	s_add_i32 s44, 0, 0x1c000
	v_add_u32_e32 v144, s29, v232
	v_add_u32_e32 v160, s44, v232
	ds_read_b128 v[132:135], v144
	ds_read_b128 v[136:139], v144 offset:1024
	ds_read_b128 v[140:143], v144 offset:2048
	ds_read_b128 v[144:147], v144 offset:3072
	ds_read_b128 v[148:151], v160
	ds_read_b128 v[152:155], v160 offset:1024
	ds_read_b128 v[156:159], v160 offset:2048
	ds_read_b128 v[160:163], v160 offset:3072
	s_add_u32 s16, s16, 0x80000
	s_addc_u32 s17, s17, 0
	s_mov_b32 m0, s58
	ds_read_b128 v[164:167], v210 offset:32768
	ds_read_b128 v[168:171], v210 offset:33792
	ds_read_b128 v[172:175], v210 offset:34816
	ds_read_b128 v[176:179], v210 offset:35840
	ds_read_b128 v[180:183], v210 offset:36864
	ds_read_b128 v[184:187], v210 offset:37888
	ds_read_b128 v[194:197], v210 offset:38912
	ds_read_b128 v[198:201], v210 offset:39936
	global_load_lds_dwordx4 v2, s[16:17]
	s_mov_b32 m0, s59
	s_nop 0
	global_load_lds_dwordx4 v188, s[16:17]
	s_setprio 0
	s_waitcnt vmcnt(8)
	s_waitcnt lgkmcnt(0)
	s_barrier
	s_setprio 1
	s_waitcnt lgkmcnt(0)
	v_mfma_f32_16x16x32_bf16 v[4:7], v[132:135], v[164:167], v[4:7]
	v_mfma_f32_16x16x32_bf16 v[4:7], v[136:139], v[168:171], v[4:7]
	v_mfma_f32_16x16x32_bf16 v[8:11], v[144:147], v[168:171], v[8:11]
	v_mfma_f32_16x16x32_bf16 v[8:11], v[140:143], v[164:167], v[8:11]
	v_mfma_f32_16x16x32_bf16 v[16:19], v[140:143], v[172:175], v[16:19]
	v_mfma_f32_16x16x32_bf16 v[16:19], v[144:147], v[176:179], v[16:19]
	v_mfma_f32_16x16x32_bf16 v[12:15], v[136:139], v[176:179], v[12:15]
	v_mfma_f32_16x16x32_bf16 v[12:15], v[132:135], v[172:175], v[12:15]
	v_mfma_f32_16x16x32_bf16 v[20:23], v[132:135], v[180:183], v[20:23]
	v_mfma_f32_16x16x32_bf16 v[20:23], v[136:139], v[184:187], v[20:23]
	v_mfma_f32_16x16x32_bf16 v[24:27], v[144:147], v[184:187], v[24:27]
	v_mfma_f32_16x16x32_bf16 v[24:27], v[140:143], v[180:183], v[24:27]
	v_mfma_f32_16x16x32_bf16 v[32:35], v[140:143], v[194:197], v[32:35]
	v_mfma_f32_16x16x32_bf16 v[32:35], v[144:147], v[198:201], v[32:35]
	v_mfma_f32_16x16x32_bf16 v[28:31], v[136:139], v[198:201], v[28:31]
	v_mfma_f32_16x16x32_bf16 v[28:31], v[132:135], v[194:197], v[28:31]
	s_setprio 0
	s_setprio 1
	v_mfma_f32_16x16x32_bf16 v[36:39], v[148:151], v[164:167], v[36:39]
	v_mfma_f32_16x16x32_bf16 v[36:39], v[152:155], v[168:171], v[36:39]
	v_mfma_f32_16x16x32_bf16 v[40:43], v[160:163], v[168:171], v[40:43]
	v_mfma_f32_16x16x32_bf16 v[40:43], v[156:159], v[164:167], v[40:43]
	v_mfma_f32_16x16x32_bf16 v[48:51], v[156:159], v[172:175], v[48:51]
	v_mfma_f32_16x16x32_bf16 v[48:51], v[160:163], v[176:179], v[48:51]
	v_mfma_f32_16x16x32_bf16 v[44:47], v[152:155], v[176:179], v[44:47]
	v_mfma_f32_16x16x32_bf16 v[44:47], v[148:151], v[172:175], v[44:47]
	v_mfma_f32_16x16x32_bf16 v[52:55], v[148:151], v[180:183], v[52:55]
	v_mfma_f32_16x16x32_bf16 v[52:55], v[152:155], v[184:187], v[52:55]
	v_mfma_f32_16x16x32_bf16 v[56:59], v[160:163], v[184:187], v[56:59]
	v_mfma_f32_16x16x32_bf16 v[56:59], v[156:159], v[180:183], v[56:59]
	v_mfma_f32_16x16x32_bf16 v[64:67], v[156:159], v[194:197], v[64:67]
	v_mfma_f32_16x16x32_bf16 v[64:67], v[160:163], v[198:201], v[64:67]
	s_setprio 2
	s_barrier
	v_mfma_f32_16x16x32_bf16 v[60:63], v[152:155], v[198:201], v[60:63]
	v_mfma_f32_16x16x32_bf16 v[60:63], v[148:151], v[194:197], v[60:63]
	s_add_i32 s16, s29, s38
	v_lshl_add_u64 v[202:203], v[202:203], 0, s[86:87]
	s_mov_b32 m0, s16
	ds_read_b128 v[164:167], v210 offset:49152
	ds_read_b128 v[168:171], v210 offset:50176
	ds_read_b128 v[172:175], v210 offset:51200
	ds_read_b128 v[176:179], v210 offset:52224
	ds_read_b128 v[180:183], v210 offset:53248
	ds_read_b128 v[184:187], v210 offset:54272
	ds_read_b128 v[194:197], v210 offset:55296
	ds_read_b128 v[198:201], v210 offset:56320
	global_load_lds_dwordx4 v[202:203], off
	s_add_i32 m0, s16, 0x2000
	s_add_u32 s12, s12, 0x20080
	v_lshl_add_u64 v[202:203], v[204:205], 0, s[86:87]
	s_addc_u32 s13, s13, 0
	s_add_i32 s16, s44, s38
	global_load_lds_dwordx4 v[202:203], off
	s_mov_b32 m0, s16
	v_lshl_add_u64 v[202:203], v[206:207], 0, s[86:87]
	global_load_lds_dwordx4 v192, s[12:13]
	s_add_i32 m0, s16, 0x2000
	s_nop 0
	global_load_lds_dwordx4 v190, s[12:13]
	s_mov_b32 m0, s63
	s_nop 0
	global_load_lds_dwordx4 v[202:203], off
	v_lshl_add_u64 v[202:203], v[208:209], 0, s[86:87]
	s_mov_b32 m0, s64
	s_nop 0
	global_load_lds_dwordx4 v[202:203], off
	s_setprio 0
	s_waitcnt vmcnt(8)
	s_waitcnt lgkmcnt(0)
	s_barrier
	s_setprio 1
	s_waitcnt lgkmcnt(0)
	v_mfma_f32_16x16x32_bf16 v[68:71], v[132:135], v[164:167], v[68:71]
	v_mfma_f32_16x16x32_bf16 v[68:71], v[136:139], v[168:171], v[68:71]
	v_mfma_f32_16x16x32_bf16 v[72:75], v[144:147], v[168:171], v[72:75]
	v_mfma_f32_16x16x32_bf16 v[72:75], v[140:143], v[164:167], v[72:75]
	v_mfma_f32_16x16x32_bf16 v[80:83], v[140:143], v[172:175], v[80:83]
	v_mfma_f32_16x16x32_bf16 v[80:83], v[144:147], v[176:179], v[80:83]
	v_mfma_f32_16x16x32_bf16 v[76:79], v[136:139], v[176:179], v[76:79]
	v_mfma_f32_16x16x32_bf16 v[76:79], v[132:135], v[172:175], v[76:79]
	v_mfma_f32_16x16x32_bf16 v[84:87], v[132:135], v[180:183], v[84:87]
	v_mfma_f32_16x16x32_bf16 v[84:87], v[136:139], v[184:187], v[84:87]
	v_mfma_f32_16x16x32_bf16 v[88:91], v[144:147], v[184:187], v[88:91]
	v_mfma_f32_16x16x32_bf16 v[88:91], v[140:143], v[180:183], v[88:91]
	v_mfma_f32_16x16x32_bf16 v[96:99], v[140:143], v[194:197], v[96:99]
	v_mfma_f32_16x16x32_bf16 v[96:99], v[144:147], v[198:201], v[96:99]
	v_mfma_f32_16x16x32_bf16 v[92:95], v[136:139], v[198:201], v[92:95]
	v_mfma_f32_16x16x32_bf16 v[92:95], v[132:135], v[194:197], v[92:95]
	s_setprio 0
	s_setprio 1
	v_mfma_f32_16x16x32_bf16 v[100:103], v[148:151], v[164:167], v[100:103]
	v_mfma_f32_16x16x32_bf16 v[100:103], v[152:155], v[168:171], v[100:103]
	v_mfma_f32_16x16x32_bf16 v[104:107], v[160:163], v[168:171], v[104:107]
	v_mfma_f32_16x16x32_bf16 v[104:107], v[156:159], v[164:167], v[104:107]
	v_mfma_f32_16x16x32_bf16 v[112:115], v[156:159], v[172:175], v[112:115]
	v_mfma_f32_16x16x32_bf16 v[112:115], v[160:163], v[176:179], v[112:115]
	v_mfma_f32_16x16x32_bf16 v[108:111], v[152:155], v[176:179], v[108:111]
	v_mfma_f32_16x16x32_bf16 v[108:111], v[148:151], v[172:175], v[108:111]
	v_mfma_f32_16x16x32_bf16 v[116:119], v[148:151], v[180:183], v[116:119]
	v_mfma_f32_16x16x32_bf16 v[116:119], v[152:155], v[184:187], v[116:119]
	v_mfma_f32_16x16x32_bf16 v[120:123], v[160:163], v[184:187], v[120:123]
	v_mfma_f32_16x16x32_bf16 v[120:123], v[156:159], v[180:183], v[120:123]
	v_mfma_f32_16x16x32_bf16 v[128:131], v[156:159], v[194:197], v[128:131]
	v_mfma_f32_16x16x32_bf16 v[128:131], v[160:163], v[198:201], v[128:131]
	s_setprio 2
	s_barrier
	v_mfma_f32_16x16x32_bf16 v[124:127], v[152:155], v[198:201], v[124:127]
	v_mfma_f32_16x16x32_bf16 v[124:127], v[148:151], v[194:197], v[124:127]
	s_setprio 0
	s_add_i32 s28, s28, 2
	s_add_u32 s14, s14, 0x100
	s_addc_u32 s15, s15, 0
	s_add_u32 s26, s26, 0x100
	s_addc_u32 s27, s27, 0
	s_cmp_gt_u32 s28, 5
	s_cbranch_scc0 .LBB0_2069
	s_and_b64 vcc, exec, s[48:49]
	s_cbranch_vccz .LBB0_2072
	s_barrier

.LBB0_2159:
	s_add_i32 s68, 0, 0x10000
	s_add_i32 s69, 0, 0x14000
	v_add_u32_e32 v16, s68, v143
	v_add_u32_e32 v32, s69, v143
	ds_read_b128 v[4:7], v16
	ds_read_b128 v[8:11], v16 offset:1024
	ds_read_b128 v[12:15], v16 offset:2048
	ds_read_b128 v[16:19], v16 offset:3072
	ds_read_b128 v[20:23], v32
	ds_read_b128 v[24:27], v32 offset:1024
	ds_read_b128 v[28:31], v32 offset:2048
	ds_read_b128 v[32:35], v32 offset:3072
	v_add_u32_e32 v231, 0, v142
	ds_read_b128 v[36:39], v231
	ds_read_b128 v[40:43], v231 offset:1024
	ds_read_b128 v[44:47], v231 offset:2048
	ds_read_b128 v[48:51], v231 offset:3072
	ds_read_b128 v[52:55], v231 offset:4096
	ds_read_b128 v[56:59], v231 offset:5120
	ds_read_b128 v[60:63], v231 offset:6144
	ds_read_b128 v[64:67], v231 offset:7168
	s_waitcnt vmcnt(8)
	s_waitcnt lgkmcnt(0)
	s_barrier
	s_setprio 1
	s_waitcnt lgkmcnt(0)
	v_mfma_f32_16x16x32_f16 v[68:71], v[4:7], v[36:39], 0
	v_mfma_f32_16x16x32_f16 v[72:75], v[12:15], v[36:39], 0
	v_mfma_f32_16x16x32_f16 v[76:79], v[4:7], v[44:47], 0
	v_mfma_f32_16x16x32_f16 v[80:83], v[12:15], v[44:47], 0
	v_mfma_f32_16x16x32_f16 v[84:87], v[4:7], v[52:55], 0
	v_mfma_f32_16x16x32_f16 v[88:91], v[12:15], v[52:55], 0
	v_mfma_f32_16x16x32_f16 v[92:95], v[4:7], v[60:63], 0
	v_mfma_f32_16x16x32_f16 v[96:99], v[12:15], v[60:63], 0
	v_mfma_f32_16x16x32_f16 v[68:71], v[8:11], v[40:43], v[68:71]
	v_mfma_f32_16x16x32_f16 v[72:75], v[16:19], v[40:43], v[72:75]
	v_mfma_f32_16x16x32_f16 v[76:79], v[8:11], v[48:51], v[76:79]
	v_mfma_f32_16x16x32_f16 v[80:83], v[16:19], v[48:51], v[80:83]
	v_mfma_f32_16x16x32_f16 v[84:87], v[8:11], v[56:59], v[84:87]
	v_mfma_f32_16x16x32_f16 v[88:91], v[16:19], v[56:59], v[88:91]
	v_mfma_f32_16x16x32_f16 v[92:95], v[8:11], v[64:67], v[92:95]
	v_mfma_f32_16x16x32_f16 v[100:103], v[16:19], v[64:67], v[96:99]
	s_setprio 0
	s_setprio 1
	v_mfma_f32_16x16x32_f16 v[96:99], v[20:23], v[36:39], 0
	v_mfma_f32_16x16x32_f16 v[36:39], v[28:31], v[36:39], 0
	v_mfma_f32_16x16x32_f16 v[104:107], v[20:23], v[44:47], 0
	v_mfma_f32_16x16x32_f16 v[44:47], v[28:31], v[44:47], 0
	v_mfma_f32_16x16x32_f16 v[108:111], v[20:23], v[52:55], 0
	v_mfma_f32_16x16x32_f16 v[52:55], v[28:31], v[52:55], 0
	v_mfma_f32_16x16x32_f16 v[112:115], v[20:23], v[60:63], 0
	v_mfma_f32_16x16x32_f16 v[60:63], v[28:31], v[60:63], 0
	v_mfma_f32_16x16x32_f16 v[116:119], v[24:27], v[40:43], v[96:99]
	v_mfma_f32_16x16x32_f16 v[36:39], v[32:35], v[40:43], v[36:39]
	v_mfma_f32_16x16x32_f16 v[40:43], v[24:27], v[48:51], v[104:107]
	v_mfma_f32_16x16x32_f16 v[44:47], v[32:35], v[48:51], v[44:47]
	v_mfma_f32_16x16x32_f16 v[48:51], v[24:27], v[56:59], v[108:111]
	v_mfma_f32_16x16x32_f16 v[52:55], v[32:35], v[56:59], v[52:55]
	s_setprio 2
	s_barrier
	v_mfma_f32_16x16x32_f16 v[56:59], v[24:27], v[64:67], v[112:115]
	v_mfma_f32_16x16x32_f16 v[60:63], v[32:35], v[64:67], v[60:63]
	v_lshl_add_u64 v[138:139], s[8:9], 0, v[2:3]
	s_add_i32 s68, s68, s53
	v_mov_b32_e32 v135, v3
	v_lshl_add_u64 v[144:145], v[138:139], 0, s[74:75]
	s_mov_b32 m0, s68
	v_lshl_add_u64 v[192:193], s[8:9], 0, v[134:135]
	ds_read_b128 v[64:67], v231 offset:16384
	ds_read_b128 v[96:99], v231 offset:17408
	ds_read_b128 v[104:107], v231 offset:18432
	ds_read_b128 v[108:111], v231 offset:19456
	ds_read_b128 v[112:115], v231 offset:20480
	ds_read_b128 v[120:123], v231 offset:21504
	ds_read_b128 v[124:127], v231 offset:22528
	ds_read_b128 v[128:131], v231 offset:23552
	global_load_lds_dwordx4 v[144:145], off
	v_lshl_add_u64 v[144:145], v[192:193], 0, s[74:75]
	s_add_i32 m0, s68, 0x2000
	s_add_i32 s68, s69, s53
	global_load_lds_dwordx4 v[144:145], off
	s_mov_b32 m0, s68
	v_mov_b32_e32 v137, v3
	global_load_lds_dwordx4 v2, s[40:41]
	s_add_i32 m0, s68, 0x2000
	v_lshl_add_u64 v[248:249], s[6:7], 0, v[136:137]
	v_mov_b32_e32 v133, v3
	global_load_lds_dwordx4 v134, s[40:41]
	v_lshl_add_u64 v[144:145], v[248:249], 0, s[74:75]
	s_mov_b32 m0, s54
	v_lshl_add_u64 v[250:251], s[6:7], 0, v[132:133]
	global_load_lds_dwordx4 v[144:145], off
	v_lshl_add_u64 v[144:145], v[250:251], 0, s[74:75]
	s_mov_b32 m0, s55
	s_nop 0
	global_load_lds_dwordx4 v[144:145], off
	s_setprio 0
	s_waitcnt vmcnt(8)
	s_waitcnt lgkmcnt(0)
	s_barrier
	s_setprio 1
	s_waitcnt lgkmcnt(0)
	v_mfma_f32_16x16x32_f16 v[144:147], v[4:7], v[64:67], 0
	v_mfma_f32_16x16x32_f16 v[148:151], v[12:15], v[64:67], 0
	v_mfma_f32_16x16x32_f16 v[152:155], v[4:7], v[104:107], 0
	v_mfma_f32_16x16x32_f16 v[156:159], v[12:15], v[104:107], 0
	v_mfma_f32_16x16x32_f16 v[160:163], v[4:7], v[112:115], 0
	v_mfma_f32_16x16x32_f16 v[164:167], v[12:15], v[112:115], 0
	v_mfma_f32_16x16x32_f16 v[4:7], v[4:7], v[124:127], 0
	v_mfma_f32_16x16x32_f16 v[12:15], v[12:15], v[124:127], 0
	v_mfma_f32_16x16x32_f16 v[144:147], v[8:11], v[96:99], v[144:147]
	v_mfma_f32_16x16x32_f16 v[152:155], v[8:11], v[108:111], v[152:155]
	v_mfma_f32_16x16x32_f16 v[160:163], v[8:11], v[120:123], v[160:163]
	v_mfma_f32_16x16x32_f16 v[4:7], v[8:11], v[128:131], v[4:7]
	v_mfma_f32_16x16x32_f16 v[8:11], v[16:19], v[128:131], v[12:15]
	v_mfma_f32_16x16x32_f16 v[148:151], v[16:19], v[96:99], v[148:151]
	v_mfma_f32_16x16x32_f16 v[156:159], v[16:19], v[108:111], v[156:159]
	v_mfma_f32_16x16x32_f16 v[164:167], v[16:19], v[120:123], v[164:167]
	s_setprio 0
	s_setprio 1
	v_mfma_f32_16x16x32_f16 v[12:15], v[20:23], v[64:67], 0
	v_mfma_f32_16x16x32_f16 v[16:19], v[28:31], v[64:67], 0
	v_mfma_f32_16x16x32_f16 v[64:67], v[20:23], v[104:107], 0
	v_mfma_f32_16x16x32_f16 v[104:107], v[28:31], v[104:107], 0
	v_mfma_f32_16x16x32_f16 v[168:171], v[20:23], v[112:115], 0
	v_mfma_f32_16x16x32_f16 v[112:115], v[28:31], v[112:115], 0
	v_mfma_f32_16x16x32_f16 v[20:23], v[20:23], v[124:127], 0
	v_mfma_f32_16x16x32_f16 v[28:31], v[28:31], v[124:127], 0
	v_mfma_f32_16x16x32_f16 v[12:15], v[24:27], v[96:99], v[12:15]
	v_mfma_f32_16x16x32_f16 v[172:175], v[32:35], v[96:99], v[16:19]
	v_mfma_f32_16x16x32_f16 v[176:179], v[24:27], v[108:111], v[64:67]
	v_mfma_f32_16x16x32_f16 v[180:183], v[32:35], v[108:111], v[104:107]
	v_mfma_f32_16x16x32_f16 v[168:171], v[24:27], v[120:123], v[168:171]
	v_mfma_f32_16x16x32_f16 v[184:187], v[32:35], v[120:123], v[112:115]
	s_setprio 2
	s_barrier
	v_mfma_f32_16x16x32_f16 v[188:191], v[24:27], v[128:131], v[20:23]
	v_mfma_f32_16x16x32_f16 v[196:199], v[32:35], v[128:131], v[28:31]
	s_add_i32 s68, 0, 0x18000
	v_add_u32_e32 v24, s68, v143
	s_add_i32 s69, 0, 0x1c000
	ds_read_b128 v[16:19], v24
	ds_read_b128 v[20:23], v24 offset:1024
	ds_read_b128 v[28:31], v24 offset:2048
	ds_read_b128 v[200:203], v24 offset:3072
	v_add_u32_e32 v24, s69, v143
	ds_read_b128 v[204:207], v24
	ds_read_b128 v[208:211], v24 offset:1024
	ds_read_b128 v[212:215], v24 offset:2048
	ds_read_b128 v[216:219], v24 offset:3072
	s_mov_b32 m0, s56
	ds_read_b128 v[24:27], v231 offset:32768
	ds_read_b128 v[32:35], v231 offset:33792
	ds_read_b128 v[64:67], v231 offset:34816
	ds_read_b128 v[220:223], v231 offset:35840
	ds_read_b128 v[224:227], v231 offset:36864
	ds_read_b128 v[232:235], v231 offset:37888
	ds_read_b128 v[236:239], v231 offset:38912
	ds_read_b128 v[240:243], v231 offset:39936
	global_load_lds_dwordx4 v136, s[42:43]
	s_mov_b32 m0, s57
	s_nop 0
	global_load_lds_dwordx4 v132, s[42:43]
	s_setprio 0
	s_waitcnt vmcnt(8)
	s_waitcnt lgkmcnt(0)
	s_barrier
	s_setprio 1
	s_waitcnt lgkmcnt(0)
	v_mfma_f32_16x16x32_f16 v[68:71], v[16:19], v[24:27], v[68:71]
	v_mfma_f32_16x16x32_f16 v[128:131], v[20:23], v[32:35], v[68:71]
	v_mfma_f32_16x16x32_f16 v[68:71], v[28:31], v[24:27], v[72:75]
	v_mfma_f32_16x16x32_f16 v[120:123], v[200:203], v[32:35], v[68:71]
	v_mfma_f32_16x16x32_f16 v[68:71], v[16:19], v[64:67], v[76:79]
	v_mfma_f32_16x16x32_f16 v[112:115], v[20:23], v[220:223], v[68:71]
	v_mfma_f32_16x16x32_f16 v[68:71], v[28:31], v[64:67], v[80:83]
	v_mfma_f32_16x16x32_f16 v[104:107], v[200:203], v[220:223], v[68:71]
	v_mfma_f32_16x16x32_f16 v[68:71], v[16:19], v[224:227], v[84:87]
	v_mfma_f32_16x16x32_f16 v[96:99], v[20:23], v[232:235], v[68:71]
	v_mfma_f32_16x16x32_f16 v[68:71], v[28:31], v[224:227], v[88:91]
	v_mfma_f32_16x16x32_f16 v[88:91], v[200:203], v[232:235], v[68:71]
	v_mfma_f32_16x16x32_f16 v[68:71], v[16:19], v[236:239], v[92:95]
	v_mfma_f32_16x16x32_f16 v[80:83], v[20:23], v[240:243], v[68:71]
	v_mfma_f32_16x16x32_f16 v[68:71], v[28:31], v[236:239], v[100:103]
	v_mfma_f32_16x16x32_f16 v[72:75], v[200:203], v[240:243], v[68:71]
	s_setprio 0
	s_setprio 1
	v_mfma_f32_16x16x32_f16 v[68:71], v[204:207], v[24:27], v[116:119]
	v_mfma_f32_16x16x32_f16 v[24:27], v[212:215], v[24:27], v[36:39]
	v_mfma_f32_16x16x32_f16 v[116:119], v[216:219], v[32:35], v[24:27]
	v_mfma_f32_16x16x32_f16 v[24:27], v[204:207], v[64:67], v[40:43]
	v_mfma_f32_16x16x32_f16 v[108:111], v[208:211], v[220:223], v[24:27]
	v_mfma_f32_16x16x32_f16 v[24:27], v[212:215], v[64:67], v[44:47]
	v_mfma_f32_16x16x32_f16 v[100:103], v[216:219], v[220:223], v[24:27]
	v_mfma_f32_16x16x32_f16 v[24:27], v[204:207], v[224:227], v[48:51]
	v_mfma_f32_16x16x32_f16 v[92:95], v[208:211], v[232:235], v[24:27]
	v_mfma_f32_16x16x32_f16 v[24:27], v[212:215], v[224:227], v[52:55]
	v_mfma_f32_16x16x32_f16 v[84:87], v[216:219], v[232:235], v[24:27]
	v_mfma_f32_16x16x32_f16 v[24:27], v[204:207], v[236:239], v[56:59]
	v_mfma_f32_16x16x32_f16 v[76:79], v[208:211], v[240:243], v[24:27]
	v_mfma_f32_16x16x32_f16 v[24:27], v[212:215], v[236:239], v[60:63]
	s_setprio 2
	s_barrier
	v_mfma_f32_16x16x32_f16 v[124:127], v[208:211], v[32:35], v[68:71]
	v_mfma_f32_16x16x32_f16 v[68:71], v[216:219], v[240:243], v[24:27]
	s_add_i32 s68, s68, s53
	s_nop 2
	v_lshl_add_u64 v[24:25], v[138:139], 0, s[24:25]
	s_mov_b32 m0, s68
	ds_read_b128 v[36:39], v231 offset:49152
	ds_read_b128 v[44:47], v231 offset:50176
	ds_read_b128 v[220:223], v231 offset:51200
	ds_read_b128 v[224:227], v231 offset:52224
	ds_read_b128 v[232:235], v231 offset:53248
	ds_read_b128 v[236:239], v231 offset:54272
	ds_read_b128 v[240:243], v231 offset:55296
	ds_read_b128 v[244:247], v231 offset:56320
	global_load_lds_dwordx4 v[24:25], off
	v_lshl_add_u64 v[24:25], v[192:193], 0, s[24:25]
	s_add_i32 m0, s68, 0x2000
	s_add_i32 s68, s69, s53
	global_load_lds_dwordx4 v[24:25], off
	s_mov_b32 m0, s68
	v_lshl_add_u64 v[24:25], v[248:249], 0, s[24:25]
	global_load_lds_dwordx4 v2, s[44:45]
	s_add_i32 m0, s68, 0x2000
	s_nop 0
	global_load_lds_dwordx4 v134, s[44:45]
	s_mov_b32 m0, s59
	s_nop 0
	global_load_lds_dwordx4 v[24:25], off
	v_lshl_add_u64 v[24:25], v[250:251], 0, s[24:25]
	s_mov_b32 m0, s60
	s_nop 0
	global_load_lds_dwordx4 v[24:25], off
	s_setprio 0
	s_waitcnt vmcnt(8)
	s_waitcnt lgkmcnt(0)
	s_barrier
	s_setprio 1
	s_waitcnt lgkmcnt(0)
	v_mfma_f32_16x16x32_f16 v[24:27], v[16:19], v[36:39], v[144:147]
	v_mfma_f32_16x16x32_f16 v[64:67], v[20:23], v[44:47], v[24:27]
	v_mfma_f32_16x16x32_f16 v[24:27], v[28:31], v[36:39], v[148:151]
	v_mfma_f32_16x16x32_f16 v[56:59], v[200:203], v[44:47], v[24:27]
	v_mfma_f32_16x16x32_f16 v[24:27], v[16:19], v[220:223], v[152:155]
	v_mfma_f32_16x16x32_f16 v[48:51], v[20:23], v[224:227], v[24:27]
	v_mfma_f32_16x16x32_f16 v[24:27], v[28:31], v[220:223], v[156:159]
	v_mfma_f32_16x16x32_f16 v[40:43], v[200:203], v[224:227], v[24:27]
	v_mfma_f32_16x16x32_f16 v[24:27], v[16:19], v[232:235], v[160:163]
	v_mfma_f32_16x16x32_f16 v[4:7], v[16:19], v[240:243], v[4:7]
	v_mfma_f32_16x16x32_f16 v[32:35], v[20:23], v[236:239], v[24:27]
	v_mfma_f32_16x16x32_f16 v[24:27], v[28:31], v[232:235], v[164:167]
	v_mfma_f32_16x16x32_f16 v[16:19], v[20:23], v[244:247], v[4:7]
	v_mfma_f32_16x16x32_f16 v[4:7], v[28:31], v[240:243], v[8:11]
	v_mfma_f32_16x16x32_f16 v[24:27], v[200:203], v[236:239], v[24:27]
	v_mfma_f32_16x16x32_f16 v[8:11], v[200:203], v[244:247], v[4:7]
	s_setprio 0
	s_setprio 1
	v_mfma_f32_16x16x32_f16 v[4:7], v[204:207], v[36:39], v[12:15]
	v_mfma_f32_16x16x32_f16 v[60:63], v[208:211], v[44:47], v[4:7]
	v_mfma_f32_16x16x32_f16 v[4:7], v[212:215], v[36:39], v[172:175]
	v_mfma_f32_16x16x32_f16 v[52:55], v[216:219], v[44:47], v[4:7]
	v_mfma_f32_16x16x32_f16 v[4:7], v[204:207], v[220:223], v[176:179]
	v_mfma_f32_16x16x32_f16 v[44:47], v[208:211], v[224:227], v[4:7]
	v_mfma_f32_16x16x32_f16 v[4:7], v[212:215], v[220:223], v[180:183]
	v_mfma_f32_16x16x32_f16 v[36:39], v[216:219], v[224:227], v[4:7]
	v_mfma_f32_16x16x32_f16 v[4:7], v[204:207], v[232:235], v[168:171]
	v_mfma_f32_16x16x32_f16 v[28:31], v[208:211], v[236:239], v[4:7]
	v_mfma_f32_16x16x32_f16 v[4:7], v[212:215], v[232:235], v[184:187]
	v_mfma_f32_16x16x32_f16 v[20:23], v[216:219], v[236:239], v[4:7]
	v_mfma_f32_16x16x32_f16 v[4:7], v[204:207], v[240:243], v[188:191]
	v_mfma_f32_16x16x32_f16 v[12:15], v[208:211], v[244:247], v[4:7]
	s_setprio 2
	s_barrier
	v_mfma_f32_16x16x32_f16 v[4:7], v[212:215], v[240:243], v[196:199]
	v_mfma_f32_16x16x32_f16 v[4:7], v[216:219], v[244:247], v[4:7]
	s_setprio 0
	s_add_i32 s67, s67, 2
	s_cmp_ge_i32 s67, s11
	s_cbranch_scc0 .LBB0_2159

.LBB0_2161:
	s_add_u32 s68, s6, s40
	s_addc_u32 s69, s7, s41
	s_add_u32 s42, s68, 0x200
	s_addc_u32 s43, s69, 0
	s_add_u32 s44, s8, s40
	s_addc_u32 s45, s9, s41
	s_add_u32 s67, s44, 0x200
	s_addc_u32 s70, s45, 0
	s_add_i32 s71, 0, 0x10000
	s_cmp_eq_u32 s11, 28
	s_cselect_b32 s45, s29, s43
	s_cselect_b32 s44, s28, s42
	v_add_u32_e32 v133, s71, v143
	s_cselect_b32 s43, s37, s70
	s_cselect_b32 s42, s36, s67
	s_add_i32 s67, 0, 0x14000
	ds_read_b128 v[144:147], v133
	ds_read_b128 v[148:151], v133 offset:1024
	ds_read_b128 v[152:155], v133 offset:2048
	ds_read_b128 v[156:159], v133 offset:3072
	v_add_u32_e32 v133, s67, v143
	ds_read_b128 v[160:163], v133
	ds_read_b128 v[164:167], v133 offset:1024
	ds_read_b128 v[168:171], v133 offset:2048
	ds_read_b128 v[172:175], v133 offset:3072
	v_lshl_add_u64 v[136:137], s[68:69], 0, v[2:3]
	s_mov_b32 m0, s61
	v_add_u32_e32 v216, 0, v142
	v_lshl_add_u64 v[136:137], v[136:137], 0, s[34:35]
	v_mov_b32_e32 v133, v3
	ds_read_b128 v[176:179], v216
	ds_read_b128 v[180:183], v216 offset:1024
	ds_read_b128 v[184:187], v216 offset:2048
	ds_read_b128 v[188:191], v216 offset:3072
	ds_read_b128 v[196:199], v216 offset:4096
	ds_read_b128 v[200:203], v216 offset:5120
	ds_read_b128 v[204:207], v216 offset:6144
	ds_read_b128 v[208:211], v216 offset:7168
	global_load_lds_dwordx4 v[136:137], off
	v_lshl_add_u64 v[136:137], s[68:69], 0, v[132:133]
	v_lshl_add_u64 v[136:137], v[136:137], 0, s[34:35]
	s_mov_b32 m0, s62
	s_nop 0
	global_load_lds_dwordx4 v[136:137], off
	s_waitcnt vmcnt(8)
	s_waitcnt lgkmcnt(0)
	s_barrier
	s_setprio 1
	s_waitcnt lgkmcnt(0)
	v_mfma_f32_16x16x32_f16 v[128:131], v[144:147], v[176:179], v[128:131]
	v_mfma_f32_16x16x32_f16 v[128:131], v[148:151], v[180:183], v[128:131]
	v_mfma_f32_16x16x32_f16 v[120:123], v[156:159], v[180:183], v[120:123]
	v_mfma_f32_16x16x32_f16 v[120:123], v[152:155], v[176:179], v[120:123]
	v_mfma_f32_16x16x32_f16 v[104:107], v[152:155], v[184:187], v[104:107]
	v_mfma_f32_16x16x32_f16 v[104:107], v[156:159], v[188:191], v[104:107]
	v_mfma_f32_16x16x32_f16 v[112:115], v[148:151], v[188:191], v[112:115]
	v_mfma_f32_16x16x32_f16 v[112:115], v[144:147], v[184:187], v[112:115]
	v_mfma_f32_16x16x32_f16 v[96:99], v[144:147], v[196:199], v[96:99]
	v_mfma_f32_16x16x32_f16 v[96:99], v[148:151], v[200:203], v[96:99]
	v_mfma_f32_16x16x32_f16 v[88:91], v[156:159], v[200:203], v[88:91]
	v_mfma_f32_16x16x32_f16 v[88:91], v[152:155], v[196:199], v[88:91]
	v_mfma_f32_16x16x32_f16 v[72:75], v[152:155], v[204:207], v[72:75]
	v_mfma_f32_16x16x32_f16 v[72:75], v[156:159], v[208:211], v[72:75]
	v_mfma_f32_16x16x32_f16 v[80:83], v[148:151], v[208:211], v[80:83]
	v_mfma_f32_16x16x32_f16 v[80:83], v[144:147], v[204:207], v[80:83]
	s_setprio 0
	s_setprio 1
	v_mfma_f32_16x16x32_f16 v[124:127], v[160:163], v[176:179], v[124:127]
	v_mfma_f32_16x16x32_f16 v[124:127], v[164:167], v[180:183], v[124:127]
	v_mfma_f32_16x16x32_f16 v[116:119], v[172:175], v[180:183], v[116:119]
	v_mfma_f32_16x16x32_f16 v[116:119], v[168:171], v[176:179], v[116:119]
	v_mfma_f32_16x16x32_f16 v[100:103], v[168:171], v[184:187], v[100:103]
	v_mfma_f32_16x16x32_f16 v[100:103], v[172:175], v[188:191], v[100:103]
	v_mfma_f32_16x16x32_f16 v[108:111], v[164:167], v[188:191], v[108:111]
	v_mfma_f32_16x16x32_f16 v[108:111], v[160:163], v[184:187], v[108:111]
	v_mfma_f32_16x16x32_f16 v[92:95], v[160:163], v[196:199], v[92:95]
	v_mfma_f32_16x16x32_f16 v[92:95], v[164:167], v[200:203], v[92:95]
	v_mfma_f32_16x16x32_f16 v[84:87], v[172:175], v[200:203], v[84:87]
	v_mfma_f32_16x16x32_f16 v[84:87], v[168:171], v[196:199], v[84:87]
	v_mfma_f32_16x16x32_f16 v[68:71], v[168:171], v[204:207], v[68:71]
	v_mfma_f32_16x16x32_f16 v[68:71], v[172:175], v[208:211], v[68:71]
	s_setprio 2
	s_barrier
	v_mfma_f32_16x16x32_f16 v[76:79], v[164:167], v[208:211], v[76:79]
	v_mfma_f32_16x16x32_f16 v[76:79], v[160:163], v[204:207], v[76:79]
	s_add_i32 s68, s71, s53
	s_mov_b32 m0, s68
	ds_read_b128 v[176:179], v216 offset:16384
	ds_read_b128 v[180:183], v216 offset:17408
	ds_read_b128 v[184:187], v216 offset:18432
	ds_read_b128 v[188:191], v216 offset:19456
	ds_read_b128 v[196:199], v216 offset:20480
	ds_read_b128 v[200:203], v216 offset:21504
	ds_read_b128 v[204:207], v216 offset:22528
	ds_read_b128 v[208:211], v216 offset:23552
	global_load_lds_dwordx4 v138, s[42:43]
	s_add_i32 m0, s68, 0x2000
	s_add_u32 s68, s42, 0x80000
	s_addc_u32 s69, s43, 0
	s_add_i32 s67, s67, s53
	global_load_lds_dwordx4 v134, s[42:43]
	s_mov_b32 m0, s67
	v_mov_b32_e32 v139, v3
	global_load_lds_dwordx4 v138, s[68:69]
	s_add_i32 m0, s67, 0x2000
	v_mov_b32_e32 v135, v3
	global_load_lds_dwordx4 v134, s[68:69]
	s_mov_b32 m0, s54
	v_lshl_add_u64 v[136:137], s[42:43], 0, v[138:139]
	global_load_lds_dwordx4 v2, s[44:45]
	s_mov_b32 m0, s55
	v_lshl_add_u64 v[192:193], s[42:43], 0, v[134:135]
	global_load_lds_dwordx4 v132, s[44:45]
	s_setprio 0
	s_waitcnt vmcnt(8)
	s_waitcnt lgkmcnt(0)
	v_lshl_add_u64 v[212:213], s[44:45], 0, v[2:3]
	v_lshl_add_u64 v[214:215], s[44:45], 0, v[132:133]
	s_barrier
	s_setprio 1
	s_waitcnt lgkmcnt(0)
	v_mfma_f32_16x16x32_f16 v[64:67], v[144:147], v[176:179], v[64:67]
	v_mfma_f32_16x16x32_f16 v[64:67], v[148:151], v[180:183], v[64:67]
	v_mfma_f32_16x16x32_f16 v[56:59], v[156:159], v[180:183], v[56:59]
	v_mfma_f32_16x16x32_f16 v[56:59], v[152:155], v[176:179], v[56:59]
	v_mfma_f32_16x16x32_f16 v[40:43], v[152:155], v[184:187], v[40:43]
	v_mfma_f32_16x16x32_f16 v[40:43], v[156:159], v[188:191], v[40:43]
	v_mfma_f32_16x16x32_f16 v[48:51], v[148:151], v[188:191], v[48:51]
	v_mfma_f32_16x16x32_f16 v[48:51], v[144:147], v[184:187], v[48:51]
	v_mfma_f32_16x16x32_f16 v[32:35], v[144:147], v[196:199], v[32:35]
	v_mfma_f32_16x16x32_f16 v[32:35], v[148:151], v[200:203], v[32:35]
	v_mfma_f32_16x16x32_f16 v[24:27], v[156:159], v[200:203], v[24:27]
	v_mfma_f32_16x16x32_f16 v[24:27], v[152:155], v[196:199], v[24:27]
	v_mfma_f32_16x16x32_f16 v[8:11], v[152:155], v[204:207], v[8:11]
	v_mfma_f32_16x16x32_f16 v[8:11], v[156:159], v[208:211], v[8:11]
	v_mfma_f32_16x16x32_f16 v[16:19], v[148:151], v[208:211], v[16:19]
	v_mfma_f32_16x16x32_f16 v[16:19], v[144:147], v[204:207], v[16:19]
	s_setprio 0
	s_setprio 1
	v_mfma_f32_16x16x32_f16 v[60:63], v[160:163], v[176:179], v[60:63]
	v_mfma_f32_16x16x32_f16 v[60:63], v[164:167], v[180:183], v[60:63]
	v_mfma_f32_16x16x32_f16 v[52:55], v[172:175], v[180:183], v[52:55]
	v_mfma_f32_16x16x32_f16 v[52:55], v[168:171], v[176:179], v[52:55]
	v_mfma_f32_16x16x32_f16 v[36:39], v[168:171], v[184:187], v[36:39]
	v_mfma_f32_16x16x32_f16 v[36:39], v[172:175], v[188:191], v[36:39]
	v_mfma_f32_16x16x32_f16 v[44:47], v[164:167], v[188:191], v[44:47]
	v_mfma_f32_16x16x32_f16 v[44:47], v[160:163], v[184:187], v[44:47]
	v_mfma_f32_16x16x32_f16 v[28:31], v[160:163], v[196:199], v[28:31]
	v_mfma_f32_16x16x32_f16 v[28:31], v[164:167], v[200:203], v[28:31]
	v_mfma_f32_16x16x32_f16 v[20:23], v[172:175], v[200:203], v[20:23]
	v_mfma_f32_16x16x32_f16 v[20:23], v[168:171], v[196:199], v[20:23]
	v_mfma_f32_16x16x32_f16 v[4:7], v[168:171], v[204:207], v[4:7]
	v_mfma_f32_16x16x32_f16 v[4:7], v[172:175], v[208:211], v[4:7]
	s_setprio 2
	s_barrier
	v_mfma_f32_16x16x32_f16 v[12:15], v[164:167], v[208:211], v[12:15]
	v_mfma_f32_16x16x32_f16 v[12:15], v[160:163], v[204:207], v[12:15]
	s_add_i32 s67, 0, 0x18000
	v_add_u32_e32 v135, s67, v143
	s_add_i32 s68, 0, 0x1c000
	ds_read_b128 v[144:147], v135
	ds_read_b128 v[148:151], v135 offset:1024
	ds_read_b128 v[152:155], v135 offset:2048
	ds_read_b128 v[156:159], v135 offset:3072
	v_add_u32_e32 v135, s68, v143
	ds_read_b128 v[160:163], v135
	ds_read_b128 v[164:167], v135 offset:1024
	ds_read_b128 v[168:171], v135 offset:2048
	ds_read_b128 v[172:175], v135 offset:3072
	s_add_u32 s44, s44, 0x80000
	s_addc_u32 s45, s45, 0
	s_mov_b32 m0, s56
	ds_read_b128 v[176:179], v216 offset:32768
	ds_read_b128 v[180:183], v216 offset:33792
	ds_read_b128 v[184:187], v216 offset:34816
	ds_read_b128 v[188:191], v216 offset:35840
	ds_read_b128 v[196:199], v216 offset:36864
	ds_read_b128 v[200:203], v216 offset:37888
	ds_read_b128 v[204:207], v216 offset:38912
	ds_read_b128 v[208:211], v216 offset:39936
	global_load_lds_dwordx4 v2, s[44:45]
	s_mov_b32 m0, s57
	s_nop 0
	global_load_lds_dwordx4 v132, s[44:45]
	s_setprio 0
	s_waitcnt vmcnt(8)
	s_waitcnt lgkmcnt(0)
	s_barrier
	s_setprio 1
	s_waitcnt lgkmcnt(0)
	v_mfma_f32_16x16x32_f16 v[128:131], v[144:147], v[176:179], v[128:131]
	v_mfma_f32_16x16x32_f16 v[128:131], v[148:151], v[180:183], v[128:131]
	v_mfma_f32_16x16x32_f16 v[120:123], v[156:159], v[180:183], v[120:123]
	v_mfma_f32_16x16x32_f16 v[120:123], v[152:155], v[176:179], v[120:123]
	v_mfma_f32_16x16x32_f16 v[104:107], v[152:155], v[184:187], v[104:107]
	v_mfma_f32_16x16x32_f16 v[104:107], v[156:159], v[188:191], v[104:107]
	v_mfma_f32_16x16x32_f16 v[112:115], v[148:151], v[188:191], v[112:115]
	v_mfma_f32_16x16x32_f16 v[112:115], v[144:147], v[184:187], v[112:115]
	v_mfma_f32_16x16x32_f16 v[96:99], v[144:147], v[196:199], v[96:99]
	v_mfma_f32_16x16x32_f16 v[96:99], v[148:151], v[200:203], v[96:99]
	v_mfma_f32_16x16x32_f16 v[88:91], v[156:159], v[200:203], v[88:91]
	v_mfma_f32_16x16x32_f16 v[88:91], v[152:155], v[196:199], v[88:91]
	v_mfma_f32_16x16x32_f16 v[72:75], v[152:155], v[204:207], v[72:75]
	v_mfma_f32_16x16x32_f16 v[72:75], v[156:159], v[208:211], v[72:75]
	v_mfma_f32_16x16x32_f16 v[80:83], v[148:151], v[208:211], v[80:83]
	v_mfma_f32_16x16x32_f16 v[80:83], v[144:147], v[204:207], v[80:83]
	s_setprio 0
	s_setprio 1
	v_mfma_f32_16x16x32_f16 v[124:127], v[160:163], v[176:179], v[124:127]
	v_mfma_f32_16x16x32_f16 v[124:127], v[164:167], v[180:183], v[124:127]
	v_mfma_f32_16x16x32_f16 v[116:119], v[172:175], v[180:183], v[116:119]
	v_mfma_f32_16x16x32_f16 v[116:119], v[168:171], v[176:179], v[116:119]
	v_mfma_f32_16x16x32_f16 v[100:103], v[168:171], v[184:187], v[100:103]
	v_mfma_f32_16x16x32_f16 v[100:103], v[172:175], v[188:191], v[100:103]
	v_mfma_f32_16x16x32_f16 v[108:111], v[164:167], v[188:191], v[108:111]
	v_mfma_f32_16x16x32_f16 v[108:111], v[160:163], v[184:187], v[108:111]
	v_mfma_f32_16x16x32_f16 v[92:95], v[160:163], v[196:199], v[92:95]
	v_mfma_f32_16x16x32_f16 v[92:95], v[164:167], v[200:203], v[92:95]
	v_mfma_f32_16x16x32_f16 v[84:87], v[172:175], v[200:203], v[84:87]
	v_mfma_f32_16x16x32_f16 v[84:87], v[168:171], v[196:199], v[84:87]
	v_mfma_f32_16x16x32_f16 v[68:71], v[168:171], v[204:207], v[68:71]
	v_mfma_f32_16x16x32_f16 v[68:71], v[172:175], v[208:211], v[68:71]
	s_setprio 2
	s_barrier
	v_mfma_f32_16x16x32_f16 v[76:79], v[164:167], v[208:211], v[76:79]
	v_mfma_f32_16x16x32_f16 v[76:79], v[160:163], v[204:207], v[76:79]
	s_add_i32 s44, s67, s53
	v_lshl_add_u64 v[136:137], v[136:137], 0, s[86:87]
	s_mov_b32 m0, s44
	ds_read_b128 v[176:179], v216 offset:49152
	ds_read_b128 v[180:183], v216 offset:50176
	ds_read_b128 v[184:187], v216 offset:51200
	ds_read_b128 v[188:191], v216 offset:52224
	ds_read_b128 v[196:199], v216 offset:53248
	ds_read_b128 v[200:203], v216 offset:54272
	ds_read_b128 v[204:207], v216 offset:55296
	ds_read_b128 v[208:211], v216 offset:56320
	global_load_lds_dwordx4 v[136:137], off
	s_add_i32 m0, s44, 0x2000
	s_add_u32 s42, s42, 0x80080
	v_lshl_add_u64 v[136:137], v[192:193], 0, s[86:87]
	s_addc_u32 s43, s43, 0
	s_add_i32 s44, s68, s53
	global_load_lds_dwordx4 v[136:137], off
	s_mov_b32 m0, s44
	v_lshl_add_u64 v[136:137], v[212:213], 0, s[86:87]
	global_load_lds_dwordx4 v138, s[42:43]
	s_add_i32 m0, s44, 0x2000
	s_nop 0
	global_load_lds_dwordx4 v134, s[42:43]
	s_mov_b32 m0, s59
	s_nop 0
	global_load_lds_dwordx4 v[136:137], off
	v_lshl_add_u64 v[136:137], v[214:215], 0, s[86:87]
	s_mov_b32 m0, s60
	s_nop 0
	global_load_lds_dwordx4 v[136:137], off
	s_setprio 0
	s_waitcnt vmcnt(8)
	s_waitcnt lgkmcnt(0)
	s_barrier
	s_setprio 1
	s_waitcnt lgkmcnt(0)
	v_mfma_f32_16x16x32_f16 v[64:67], v[144:147], v[176:179], v[64:67]
	v_mfma_f32_16x16x32_f16 v[64:67], v[148:151], v[180:183], v[64:67]
	v_mfma_f32_16x16x32_f16 v[56:59], v[156:159], v[180:183], v[56:59]
	v_mfma_f32_16x16x32_f16 v[56:59], v[152:155], v[176:179], v[56:59]
	v_mfma_f32_16x16x32_f16 v[40:43], v[152:155], v[184:187], v[40:43]
	v_mfma_f32_16x16x32_f16 v[40:43], v[156:159], v[188:191], v[40:43]
	v_mfma_f32_16x16x32_f16 v[48:51], v[148:151], v[188:191], v[48:51]
	v_mfma_f32_16x16x32_f16 v[48:51], v[144:147], v[184:187], v[48:51]
	v_mfma_f32_16x16x32_f16 v[32:35], v[144:147], v[196:199], v[32:35]
	v_mfma_f32_16x16x32_f16 v[32:35], v[148:151], v[200:203], v[32:35]
	v_mfma_f32_16x16x32_f16 v[24:27], v[156:159], v[200:203], v[24:27]
	v_mfma_f32_16x16x32_f16 v[24:27], v[152:155], v[196:199], v[24:27]
	v_mfma_f32_16x16x32_f16 v[8:11], v[152:155], v[204:207], v[8:11]
	v_mfma_f32_16x16x32_f16 v[8:11], v[156:159], v[208:211], v[8:11]
	v_mfma_f32_16x16x32_f16 v[16:19], v[148:151], v[208:211], v[16:19]
	v_mfma_f32_16x16x32_f16 v[16:19], v[144:147], v[204:207], v[16:19]
	s_setprio 0
	s_setprio 1
	v_mfma_f32_16x16x32_f16 v[60:63], v[160:163], v[176:179], v[60:63]
	v_mfma_f32_16x16x32_f16 v[60:63], v[164:167], v[180:183], v[60:63]
	v_mfma_f32_16x16x32_f16 v[52:55], v[172:175], v[180:183], v[52:55]
	v_mfma_f32_16x16x32_f16 v[52:55], v[168:171], v[176:179], v[52:55]
	v_mfma_f32_16x16x32_f16 v[36:39], v[168:171], v[184:187], v[36:39]
	v_mfma_f32_16x16x32_f16 v[36:39], v[172:175], v[188:191], v[36:39]
	v_mfma_f32_16x16x32_f16 v[44:47], v[164:167], v[188:191], v[44:47]
	v_mfma_f32_16x16x32_f16 v[44:47], v[160:163], v[184:187], v[44:47]
	v_mfma_f32_16x16x32_f16 v[28:31], v[160:163], v[196:199], v[28:31]
	v_mfma_f32_16x16x32_f16 v[28:31], v[164:167], v[200:203], v[28:31]
	v_mfma_f32_16x16x32_f16 v[20:23], v[172:175], v[200:203], v[20:23]
	v_mfma_f32_16x16x32_f16 v[20:23], v[168:171], v[196:199], v[20:23]
	v_mfma_f32_16x16x32_f16 v[4:7], v[168:171], v[204:207], v[4:7]
	v_mfma_f32_16x16x32_f16 v[4:7], v[172:175], v[208:211], v[4:7]
	s_setprio 2
	s_barrier
	v_mfma_f32_16x16x32_f16 v[12:15], v[164:167], v[208:211], v[12:15]
	v_mfma_f32_16x16x32_f16 v[12:15], v[160:163], v[204:207], v[12:15]
	s_setprio 0
	s_add_i32 s11, s11, 2
	s_add_u32 s40, s40, 0x100
	s_addc_u32 s41, s41, 0
	s_cmp_gt_u32 s11, 29
	s_cbranch_scc0 .LBB0_2161
	s_andn2_b64 vcc, exec, s[26:27]
	s_cbranch_vccnz .LBB0_2164
	s_add_u32 s6, s28, 0x80080
	s_addc_u32 s7, s29, 0
	s_mov_b32 m0, s61
	v_lshl_add_u64 v[144:145], s[6:7], 0, v[2:3]
	v_lshl_add_u64 v[136:137], s[6:7], 0, v[132:133]
	global_load_lds_dwordx4 v[144:145], off
	s_mov_b32 m0, s62
	s_mov_b32 s47, s65
	global_load_lds_dwordx4 v[136:137], off
	s_mov_b32 s64, s10
	s_mov_b64 s[8:9], s[14:15]
	s_mov_b64 s[6:7], s[12:13]
	s_mov_b32 s63, s66

.LBB0_2269:
	s_add_i32 s51, 0, 0x10000
	s_add_i32 s71, 0, 0x14000
	v_add_u32_e32 v16, s51, v232
	v_add_u32_e32 v32, s71, v232
	ds_read_b128 v[4:7], v16
	ds_read_b128 v[8:11], v16 offset:1024
	ds_read_b128 v[12:15], v16 offset:2048
	ds_read_b128 v[16:19], v16 offset:3072
	ds_read_b128 v[20:23], v32
	ds_read_b128 v[24:27], v32 offset:1024
	ds_read_b128 v[28:31], v32 offset:2048
	ds_read_b128 v[32:35], v32 offset:3072
	v_add_u32_e32 v233, 0, v231
	ds_read_b128 v[36:39], v233
	ds_read_b128 v[40:43], v233 offset:1024
	ds_read_b128 v[44:47], v233 offset:2048
	ds_read_b128 v[48:51], v233 offset:3072
	ds_read_b128 v[52:55], v233 offset:4096
	ds_read_b128 v[56:59], v233 offset:5120
	ds_read_b128 v[60:63], v233 offset:6144
	ds_read_b128 v[64:67], v233 offset:7168
	s_waitcnt vmcnt(8)
	s_waitcnt lgkmcnt(0)
	s_barrier
	s_setprio 1
	s_waitcnt lgkmcnt(0)
	v_mfma_f32_16x16x32_bf16 v[68:71], v[4:7], v[36:39], 0
	v_mfma_f32_16x16x32_bf16 v[68:71], v[8:11], v[40:43], v[68:71]
	v_mfma_f32_16x16x32_bf16 v[72:75], v[12:15], v[36:39], 0
	v_mfma_f32_16x16x32_bf16 v[72:75], v[16:19], v[40:43], v[72:75]
	v_mfma_f32_16x16x32_bf16 v[80:83], v[12:15], v[44:47], 0
	v_mfma_f32_16x16x32_bf16 v[80:83], v[16:19], v[48:51], v[80:83]
	v_mfma_f32_16x16x32_bf16 v[76:79], v[4:7], v[44:47], 0
	v_mfma_f32_16x16x32_bf16 v[76:79], v[8:11], v[48:51], v[76:79]
	v_mfma_f32_16x16x32_bf16 v[84:87], v[4:7], v[52:55], 0
	v_mfma_f32_16x16x32_bf16 v[84:87], v[8:11], v[56:59], v[84:87]
	v_mfma_f32_16x16x32_bf16 v[88:91], v[12:15], v[52:55], 0
	v_mfma_f32_16x16x32_bf16 v[88:91], v[16:19], v[56:59], v[88:91]
	v_mfma_f32_16x16x32_bf16 v[96:99], v[12:15], v[60:63], 0
	v_mfma_f32_16x16x32_bf16 v[96:99], v[16:19], v[64:67], v[96:99]
	v_mfma_f32_16x16x32_bf16 v[92:95], v[4:7], v[60:63], 0
	v_mfma_f32_16x16x32_bf16 v[92:95], v[8:11], v[64:67], v[92:95]
	s_setprio 0
	s_setprio 1
	v_mfma_f32_16x16x32_bf16 v[100:103], v[20:23], v[36:39], 0
	v_mfma_f32_16x16x32_bf16 v[36:39], v[28:31], v[36:39], 0
	v_mfma_f32_16x16x32_bf16 v[104:107], v[20:23], v[44:47], 0
	v_mfma_f32_16x16x32_bf16 v[44:47], v[28:31], v[44:47], 0
	v_mfma_f32_16x16x32_bf16 v[108:111], v[20:23], v[52:55], 0
	v_mfma_f32_16x16x32_bf16 v[52:55], v[28:31], v[52:55], 0
	v_mfma_f32_16x16x32_bf16 v[112:115], v[20:23], v[60:63], 0
	v_mfma_f32_16x16x32_bf16 v[60:63], v[28:31], v[60:63], 0
	v_mfma_f32_16x16x32_bf16 v[100:103], v[24:27], v[40:43], v[100:103]
	v_mfma_f32_16x16x32_bf16 v[40:43], v[32:35], v[40:43], v[36:39]
	v_mfma_f32_16x16x32_bf16 v[104:107], v[24:27], v[48:51], v[104:107]
	v_mfma_f32_16x16x32_bf16 v[48:51], v[32:35], v[48:51], v[44:47]
	v_mfma_f32_16x16x32_bf16 v[108:111], v[24:27], v[56:59], v[108:111]
	v_mfma_f32_16x16x32_bf16 v[56:59], v[32:35], v[56:59], v[52:55]
	s_setprio 2
	s_barrier
	v_mfma_f32_16x16x32_bf16 v[112:115], v[24:27], v[64:67], v[112:115]
	v_mfma_f32_16x16x32_bf16 v[64:67], v[32:35], v[64:67], v[60:63]
	v_lshl_add_u64 v[186:187], s[12:13], 0, v[2:3]
	s_add_i32 s51, s51, s38
	v_mov_b32_e32 v191, v3
	v_lshl_add_u64 v[134:135], v[186:187], 0, s[74:75]
	s_mov_b32 m0, s51
	v_lshl_add_u64 v[246:247], s[12:13], 0, v[190:191]
	ds_read_b128 v[36:39], v233 offset:16384
	ds_read_b128 v[44:47], v233 offset:17408
	ds_read_b128 v[52:55], v233 offset:18432
	ds_read_b128 v[60:63], v233 offset:19456
	ds_read_b128 v[116:119], v233 offset:20480
	ds_read_b128 v[120:123], v233 offset:21504
	ds_read_b128 v[124:127], v233 offset:22528
	ds_read_b128 v[128:131], v233 offset:23552
	global_load_lds_dwordx4 v[134:135], off
	v_lshl_add_u64 v[134:135], v[246:247], 0, s[74:75]
	s_add_i32 m0, s51, 0x2000
	s_add_i32 s51, s71, s38
	global_load_lds_dwordx4 v[134:135], off
	s_mov_b32 m0, s51
	v_mov_b32_e32 v133, v3
	global_load_lds_dwordx4 v2, s[16:17]
	s_add_i32 m0, s51, 0x2000
	v_lshl_add_u64 v[248:249], s[14:15], 0, v[132:133]
	v_mov_b32_e32 v189, v3
	global_load_lds_dwordx4 v190, s[16:17]
	v_lshl_add_u64 v[134:135], v[248:249], 0, s[74:75]
	s_mov_b32 m0, s56
	v_lshl_add_u64 v[250:251], s[14:15], 0, v[188:189]
	global_load_lds_dwordx4 v[134:135], off
	v_lshl_add_u64 v[134:135], v[250:251], 0, s[74:75]
	s_mov_b32 m0, s57
	s_nop 0
	global_load_lds_dwordx4 v[134:135], off
	s_setprio 0
	s_waitcnt vmcnt(8)
	s_waitcnt lgkmcnt(0)
	s_barrier
	s_setprio 1
	s_waitcnt lgkmcnt(0)
	v_mfma_f32_16x16x32_bf16 v[134:137], v[4:7], v[36:39], 0
	v_mfma_f32_16x16x32_bf16 v[138:141], v[12:15], v[36:39], 0
	v_mfma_f32_16x16x32_bf16 v[142:145], v[4:7], v[52:55], 0
	v_mfma_f32_16x16x32_bf16 v[146:149], v[12:15], v[52:55], 0
	v_mfma_f32_16x16x32_bf16 v[150:153], v[4:7], v[116:119], 0
	v_mfma_f32_16x16x32_bf16 v[154:157], v[12:15], v[116:119], 0
	v_mfma_f32_16x16x32_bf16 v[4:7], v[4:7], v[124:127], 0
	v_mfma_f32_16x16x32_bf16 v[12:15], v[12:15], v[124:127], 0
	v_mfma_f32_16x16x32_bf16 v[134:137], v[8:11], v[44:47], v[134:137]
	v_mfma_f32_16x16x32_bf16 v[138:141], v[16:19], v[44:47], v[138:141]
	v_mfma_f32_16x16x32_bf16 v[142:145], v[8:11], v[60:63], v[142:145]
	v_mfma_f32_16x16x32_bf16 v[146:149], v[16:19], v[60:63], v[146:149]
	v_mfma_f32_16x16x32_bf16 v[150:153], v[8:11], v[120:123], v[150:153]
	v_mfma_f32_16x16x32_bf16 v[154:157], v[16:19], v[120:123], v[154:157]
	v_mfma_f32_16x16x32_bf16 v[158:161], v[8:11], v[128:131], v[4:7]
	v_mfma_f32_16x16x32_bf16 v[162:165], v[16:19], v[128:131], v[12:15]
	s_setprio 0
	s_setprio 1
	v_mfma_f32_16x16x32_bf16 v[4:7], v[20:23], v[36:39], 0
	v_mfma_f32_16x16x32_bf16 v[8:11], v[28:31], v[36:39], 0
	v_mfma_f32_16x16x32_bf16 v[12:15], v[20:23], v[52:55], 0
	v_mfma_f32_16x16x32_bf16 v[16:19], v[28:31], v[52:55], 0
	v_mfma_f32_16x16x32_bf16 v[36:39], v[20:23], v[116:119], 0
	v_mfma_f32_16x16x32_bf16 v[52:55], v[28:31], v[116:119], 0
	v_mfma_f32_16x16x32_bf16 v[20:23], v[20:23], v[124:127], 0
	v_mfma_f32_16x16x32_bf16 v[28:31], v[28:31], v[124:127], 0
	v_mfma_f32_16x16x32_bf16 v[116:119], v[24:27], v[44:47], v[4:7]
	v_mfma_f32_16x16x32_bf16 v[124:127], v[32:35], v[44:47], v[8:11]
	v_mfma_f32_16x16x32_bf16 v[174:177], v[24:27], v[120:123], v[36:39]
	v_mfma_f32_16x16x32_bf16 v[120:123], v[32:35], v[120:123], v[52:55]
	v_mfma_f32_16x16x32_bf16 v[178:181], v[24:27], v[128:131], v[20:23]
	v_mfma_f32_16x16x32_bf16 v[128:131], v[32:35], v[128:131], v[28:31]
	s_setprio 2
	s_barrier
	v_mfma_f32_16x16x32_bf16 v[166:169], v[24:27], v[60:63], v[12:15]
	v_mfma_f32_16x16x32_bf16 v[170:173], v[32:35], v[60:63], v[16:19]
	s_add_i32 s51, 0, 0x18000
	v_add_u32_e32 v4, s51, v232
	s_add_i32 s71, 0, 0x1c000
	ds_read_b128 v[182:185], v4
	ds_read_b128 v[192:195], v4 offset:1024
	ds_read_b128 v[196:199], v4 offset:2048
	ds_read_b128 v[200:203], v4 offset:3072
	v_add_u32_e32 v4, s71, v232
	ds_read_b128 v[204:207], v4
	ds_read_b128 v[208:211], v4 offset:1024
	ds_read_b128 v[212:215], v4 offset:2048
	ds_read_b128 v[216:219], v4 offset:3072
	s_mov_b32 m0, s58
	ds_read_b128 v[44:47], v233 offset:32768
	ds_read_b128 v[52:55], v233 offset:33792
	ds_read_b128 v[60:63], v233 offset:34816
	ds_read_b128 v[220:223], v233 offset:35840
	ds_read_b128 v[224:227], v233 offset:36864
	ds_read_b128 v[234:237], v233 offset:37888
	ds_read_b128 v[238:241], v233 offset:38912
	ds_read_b128 v[242:245], v233 offset:39936
	global_load_lds_dwordx4 v132, s[26:27]
	s_mov_b32 m0, s59
	s_nop 0
	global_load_lds_dwordx4 v188, s[26:27]
	s_setprio 0
	s_waitcnt vmcnt(8)
	s_waitcnt lgkmcnt(0)
	s_barrier
	s_setprio 1
	s_waitcnt lgkmcnt(0)
	v_mfma_f32_16x16x32_bf16 v[4:7], v[182:185], v[44:47], v[68:71]
	v_mfma_f32_16x16x32_bf16 v[8:11], v[196:199], v[44:47], v[72:75]
	v_mfma_f32_16x16x32_bf16 v[12:15], v[182:185], v[60:63], v[76:79]
	v_mfma_f32_16x16x32_bf16 v[16:19], v[196:199], v[60:63], v[80:83]
	v_mfma_f32_16x16x32_bf16 v[20:23], v[182:185], v[224:227], v[84:87]
	v_mfma_f32_16x16x32_bf16 v[24:27], v[196:199], v[224:227], v[88:91]
	v_mfma_f32_16x16x32_bf16 v[28:31], v[182:185], v[238:241], v[92:95]
	v_mfma_f32_16x16x32_bf16 v[32:35], v[196:199], v[238:241], v[96:99]
	v_mfma_f32_16x16x32_bf16 v[4:7], v[192:195], v[52:55], v[4:7]
	v_mfma_f32_16x16x32_bf16 v[8:11], v[200:203], v[52:55], v[8:11]
	v_mfma_f32_16x16x32_bf16 v[12:15], v[192:195], v[220:223], v[12:15]
	v_mfma_f32_16x16x32_bf16 v[16:19], v[200:203], v[220:223], v[16:19]
	v_mfma_f32_16x16x32_bf16 v[20:23], v[192:195], v[234:237], v[20:23]
	v_mfma_f32_16x16x32_bf16 v[24:27], v[200:203], v[234:237], v[24:27]
	v_mfma_f32_16x16x32_bf16 v[28:31], v[192:195], v[242:245], v[28:31]
	v_mfma_f32_16x16x32_bf16 v[32:35], v[200:203], v[242:245], v[32:35]
	s_setprio 0
	s_setprio 1
	v_mfma_f32_16x16x32_bf16 v[36:39], v[204:207], v[44:47], v[100:103]
	v_mfma_f32_16x16x32_bf16 v[40:43], v[212:215], v[44:47], v[40:43]
	v_mfma_f32_16x16x32_bf16 v[36:39], v[208:211], v[52:55], v[36:39]
	v_mfma_f32_16x16x32_bf16 v[40:43], v[216:219], v[52:55], v[40:43]
	v_mfma_f32_16x16x32_bf16 v[44:47], v[204:207], v[60:63], v[104:107]
	v_mfma_f32_16x16x32_bf16 v[48:51], v[212:215], v[60:63], v[48:51]
	v_mfma_f32_16x16x32_bf16 v[52:55], v[204:207], v[224:227], v[108:111]
	v_mfma_f32_16x16x32_bf16 v[56:59], v[212:215], v[224:227], v[56:59]
	v_mfma_f32_16x16x32_bf16 v[60:63], v[204:207], v[238:241], v[112:115]
	v_mfma_f32_16x16x32_bf16 v[64:67], v[212:215], v[238:241], v[64:67]
	v_mfma_f32_16x16x32_bf16 v[44:47], v[208:211], v[220:223], v[44:47]
	v_mfma_f32_16x16x32_bf16 v[48:51], v[216:219], v[220:223], v[48:51]
	v_mfma_f32_16x16x32_bf16 v[52:55], v[208:211], v[234:237], v[52:55]
	v_mfma_f32_16x16x32_bf16 v[56:59], v[216:219], v[234:237], v[56:59]
	s_setprio 2
	s_barrier
	v_mfma_f32_16x16x32_bf16 v[60:63], v[208:211], v[242:245], v[60:63]
	v_mfma_f32_16x16x32_bf16 v[64:67], v[216:219], v[242:245], v[64:67]
	s_add_i32 s51, s51, s38
	v_lshl_add_u64 v[68:69], v[186:187], 0, s[24:25]
	s_mov_b32 m0, s51
	ds_read_b128 v[104:107], v233 offset:49152
	ds_read_b128 v[108:111], v233 offset:50176
	ds_read_b128 v[112:115], v233 offset:51200
	ds_read_b128 v[220:223], v233 offset:52224
	ds_read_b128 v[224:227], v233 offset:53248
	ds_read_b128 v[234:237], v233 offset:54272
	ds_read_b128 v[238:241], v233 offset:55296
	ds_read_b128 v[242:245], v233 offset:56320
	global_load_lds_dwordx4 v[68:69], off
	v_lshl_add_u64 v[68:69], v[246:247], 0, s[24:25]
	s_add_i32 m0, s51, 0x2000
	s_add_i32 s51, s71, s38
	global_load_lds_dwordx4 v[68:69], off
	s_mov_b32 m0, s51
	v_lshl_add_u64 v[68:69], v[248:249], 0, s[24:25]
	global_load_lds_dwordx4 v2, s[28:29]
	s_add_i32 m0, s51, 0x2000
	s_nop 0
	global_load_lds_dwordx4 v190, s[28:29]
	s_mov_b32 m0, s63
	s_nop 0
	global_load_lds_dwordx4 v[68:69], off
	v_lshl_add_u64 v[68:69], v[250:251], 0, s[24:25]
	s_mov_b32 m0, s64
	s_nop 0
	global_load_lds_dwordx4 v[68:69], off
	s_setprio 0
	s_waitcnt vmcnt(8)
	s_waitcnt lgkmcnt(0)
	s_barrier
	s_setprio 1
	s_waitcnt lgkmcnt(0)
	v_mfma_f32_16x16x32_bf16 v[68:71], v[182:185], v[104:107], v[134:137]
	v_mfma_f32_16x16x32_bf16 v[72:75], v[196:199], v[104:107], v[138:141]
	v_mfma_f32_16x16x32_bf16 v[76:79], v[182:185], v[112:115], v[142:145]
	v_mfma_f32_16x16x32_bf16 v[80:83], v[196:199], v[112:115], v[146:149]
	v_mfma_f32_16x16x32_bf16 v[84:87], v[182:185], v[224:227], v[150:153]
	v_mfma_f32_16x16x32_bf16 v[88:91], v[196:199], v[224:227], v[154:157]
	v_mfma_f32_16x16x32_bf16 v[92:95], v[182:185], v[238:241], v[158:161]
	v_mfma_f32_16x16x32_bf16 v[96:99], v[196:199], v[238:241], v[162:165]
	v_mfma_f32_16x16x32_bf16 v[68:71], v[192:195], v[108:111], v[68:71]
	v_mfma_f32_16x16x32_bf16 v[72:75], v[200:203], v[108:111], v[72:75]
	v_mfma_f32_16x16x32_bf16 v[76:79], v[192:195], v[220:223], v[76:79]
	v_mfma_f32_16x16x32_bf16 v[80:83], v[200:203], v[220:223], v[80:83]
	v_mfma_f32_16x16x32_bf16 v[84:87], v[192:195], v[234:237], v[84:87]
	v_mfma_f32_16x16x32_bf16 v[88:91], v[200:203], v[234:237], v[88:91]
	v_mfma_f32_16x16x32_bf16 v[92:95], v[192:195], v[242:245], v[92:95]
	v_mfma_f32_16x16x32_bf16 v[96:99], v[200:203], v[242:245], v[96:99]
	s_setprio 0
	s_setprio 1
	v_mfma_f32_16x16x32_bf16 v[100:103], v[204:207], v[104:107], v[116:119]
	v_mfma_f32_16x16x32_bf16 v[104:107], v[212:215], v[104:107], v[124:127]
	v_mfma_f32_16x16x32_bf16 v[100:103], v[208:211], v[108:111], v[100:103]
	v_mfma_f32_16x16x32_bf16 v[104:107], v[216:219], v[108:111], v[104:107]
	v_mfma_f32_16x16x32_bf16 v[108:111], v[204:207], v[112:115], v[166:169]
	v_mfma_f32_16x16x32_bf16 v[112:115], v[212:215], v[112:115], v[170:173]
	v_mfma_f32_16x16x32_bf16 v[116:119], v[204:207], v[224:227], v[174:177]
	v_mfma_f32_16x16x32_bf16 v[120:123], v[212:215], v[224:227], v[120:123]
	v_mfma_f32_16x16x32_bf16 v[124:127], v[204:207], v[238:241], v[178:181]
	v_mfma_f32_16x16x32_bf16 v[128:131], v[212:215], v[238:241], v[128:131]
	v_mfma_f32_16x16x32_bf16 v[108:111], v[208:211], v[220:223], v[108:111]
	v_mfma_f32_16x16x32_bf16 v[112:115], v[216:219], v[220:223], v[112:115]
	v_mfma_f32_16x16x32_bf16 v[116:119], v[208:211], v[234:237], v[116:119]
	v_mfma_f32_16x16x32_bf16 v[120:123], v[216:219], v[234:237], v[120:123]
	s_setprio 2
	s_barrier
	v_mfma_f32_16x16x32_bf16 v[124:127], v[208:211], v[242:245], v[124:127]
	v_mfma_f32_16x16x32_bf16 v[128:131], v[216:219], v[242:245], v[128:131]
	s_setprio 0
	s_add_i32 s41, s41, 2
	s_cmp_ge_i32 s41, s40
	s_cbranch_scc0 .LBB0_2269
	v_mov_b32_e32 v192, v2
	s_branch .LBB0_2272

.LBB0_2273:
	s_add_u32 s12, s14, 0xfffc0080
	s_addc_u32 s13, s15, -1
	s_add_i32 s29, 0, 0x10000
	s_cmp_eq_u32 s28, 12
	s_cselect_b32 s17, s9, s13
	s_cselect_b32 s16, s8, s12
	s_cselect_b32 s13, s11, s27
	s_cselect_b32 s12, s10, s26
	s_add_i32 s51, 0, 0x14000
	v_add_u32_e32 v144, s29, v232
	v_add_u32_e32 v160, s51, v232
	s_waitcnt lgkmcnt(0)
	ds_read_b128 v[132:135], v144
	ds_read_b128 v[136:139], v144 offset:1024
	ds_read_b128 v[140:143], v144 offset:2048
	ds_read_b128 v[144:147], v144 offset:3072
	ds_read_b128 v[148:151], v160
	ds_read_b128 v[152:155], v160 offset:1024
	ds_read_b128 v[156:159], v160 offset:2048
	ds_read_b128 v[160:163], v160 offset:3072
	s_mov_b32 m0, s65
	v_add_u32_e32 v210, 0, v231
	ds_read_b128 v[164:167], v210
	ds_read_b128 v[168:171], v210 offset:1024
	ds_read_b128 v[172:175], v210 offset:2048
	ds_read_b128 v[176:179], v210 offset:3072
	ds_read_b128 v[180:183], v210 offset:4096
	ds_read_b128 v[184:187], v210 offset:5120
	ds_read_b128 v[194:197], v210 offset:6144
	ds_read_b128 v[198:201], v210 offset:7168
	global_load_lds_dwordx4 v2, s[14:15]
	s_mov_b32 m0, s66
	v_mov_b32_e32 v189, v3
	global_load_lds_dwordx4 v188, s[14:15]
	s_waitcnt vmcnt(8)
	s_waitcnt lgkmcnt(0)
	s_barrier
	s_setprio 1
	s_waitcnt lgkmcnt(0)
	v_mfma_f32_16x16x32_bf16 v[4:7], v[132:135], v[164:167], v[4:7]
	v_mfma_f32_16x16x32_bf16 v[4:7], v[136:139], v[168:171], v[4:7]
	v_mfma_f32_16x16x32_bf16 v[8:11], v[144:147], v[168:171], v[8:11]
	v_mfma_f32_16x16x32_bf16 v[8:11], v[140:143], v[164:167], v[8:11]
	v_mfma_f32_16x16x32_bf16 v[16:19], v[140:143], v[172:175], v[16:19]
	v_mfma_f32_16x16x32_bf16 v[16:19], v[144:147], v[176:179], v[16:19]
	v_mfma_f32_16x16x32_bf16 v[12:15], v[136:139], v[176:179], v[12:15]
	v_mfma_f32_16x16x32_bf16 v[12:15], v[132:135], v[172:175], v[12:15]
	v_mfma_f32_16x16x32_bf16 v[20:23], v[132:135], v[180:183], v[20:23]
	v_mfma_f32_16x16x32_bf16 v[20:23], v[136:139], v[184:187], v[20:23]
	v_mfma_f32_16x16x32_bf16 v[24:27], v[144:147], v[184:187], v[24:27]
	v_mfma_f32_16x16x32_bf16 v[24:27], v[140:143], v[180:183], v[24:27]
	v_mfma_f32_16x16x32_bf16 v[32:35], v[140:143], v[194:197], v[32:35]
	v_mfma_f32_16x16x32_bf16 v[32:35], v[144:147], v[198:201], v[32:35]
	v_mfma_f32_16x16x32_bf16 v[28:31], v[136:139], v[198:201], v[28:31]
	v_mfma_f32_16x16x32_bf16 v[28:31], v[132:135], v[194:197], v[28:31]
	s_setprio 0
	s_setprio 1
	v_mfma_f32_16x16x32_bf16 v[36:39], v[148:151], v[164:167], v[36:39]
	v_mfma_f32_16x16x32_bf16 v[36:39], v[152:155], v[168:171], v[36:39]
	v_mfma_f32_16x16x32_bf16 v[40:43], v[160:163], v[168:171], v[40:43]
	v_mfma_f32_16x16x32_bf16 v[40:43], v[156:159], v[164:167], v[40:43]
	v_mfma_f32_16x16x32_bf16 v[48:51], v[156:159], v[172:175], v[48:51]
	v_mfma_f32_16x16x32_bf16 v[48:51], v[160:163], v[176:179], v[48:51]
	v_mfma_f32_16x16x32_bf16 v[44:47], v[152:155], v[176:179], v[44:47]
	v_mfma_f32_16x16x32_bf16 v[44:47], v[148:151], v[172:175], v[44:47]
	v_mfma_f32_16x16x32_bf16 v[52:55], v[148:151], v[180:183], v[52:55]
	v_mfma_f32_16x16x32_bf16 v[52:55], v[152:155], v[184:187], v[52:55]
	v_mfma_f32_16x16x32_bf16 v[56:59], v[160:163], v[184:187], v[56:59]
	v_mfma_f32_16x16x32_bf16 v[56:59], v[156:159], v[180:183], v[56:59]
	v_mfma_f32_16x16x32_bf16 v[64:67], v[156:159], v[194:197], v[64:67]
	v_mfma_f32_16x16x32_bf16 v[64:67], v[160:163], v[198:201], v[64:67]
	s_setprio 2
	s_barrier
	v_mfma_f32_16x16x32_bf16 v[60:63], v[152:155], v[198:201], v[60:63]
	v_mfma_f32_16x16x32_bf16 v[60:63], v[148:151], v[194:197], v[60:63]
	s_add_i32 s29, s29, s38
	s_mov_b32 m0, s29
	ds_read_b128 v[164:167], v210 offset:16384
	ds_read_b128 v[168:171], v210 offset:17408
	ds_read_b128 v[172:175], v210 offset:18432
	ds_read_b128 v[176:179], v210 offset:19456
	ds_read_b128 v[180:183], v210 offset:20480
	ds_read_b128 v[184:187], v210 offset:21504
	ds_read_b128 v[194:197], v210 offset:22528
	ds_read_b128 v[198:201], v210 offset:23552
	global_load_lds_dwordx4 v192, s[12:13]
	s_add_i32 m0, s29, 0x2000
	s_add_u32 s40, s12, 0x100000
	s_addc_u32 s41, s13, 0
	s_add_i32 s29, s51, s38
	global_load_lds_dwordx4 v190, s[12:13]
	s_mov_b32 m0, s29
	v_mov_b32_e32 v193, v3
	global_load_lds_dwordx4 v192, s[40:41]
	s_add_i32 m0, s29, 0x2000
	v_mov_b32_e32 v191, v3
	global_load_lds_dwordx4 v190, s[40:41]
	s_mov_b32 m0, s56
	v_lshl_add_u64 v[202:203], s[12:13], 0, v[192:193]
	global_load_lds_dwordx4 v2, s[16:17]
	s_mov_b32 m0, s57
	v_lshl_add_u64 v[204:205], s[12:13], 0, v[190:191]
	global_load_lds_dwordx4 v188, s[16:17]
	s_setprio 0
	s_waitcnt vmcnt(8)
	s_waitcnt lgkmcnt(0)
	v_lshl_add_u64 v[206:207], s[16:17], 0, v[2:3]
	v_lshl_add_u64 v[208:209], s[16:17], 0, v[188:189]
	s_barrier
	s_setprio 1
	s_waitcnt lgkmcnt(0)
	v_mfma_f32_16x16x32_bf16 v[68:71], v[132:135], v[164:167], v[68:71]
	v_mfma_f32_16x16x32_bf16 v[68:71], v[136:139], v[168:171], v[68:71]
	v_mfma_f32_16x16x32_bf16 v[72:75], v[144:147], v[168:171], v[72:75]
	v_mfma_f32_16x16x32_bf16 v[72:75], v[140:143], v[164:167], v[72:75]
	v_mfma_f32_16x16x32_bf16 v[80:83], v[140:143], v[172:175], v[80:83]
	v_mfma_f32_16x16x32_bf16 v[80:83], v[144:147], v[176:179], v[80:83]
	v_mfma_f32_16x16x32_bf16 v[76:79], v[136:139], v[176:179], v[76:79]
	v_mfma_f32_16x16x32_bf16 v[76:79], v[132:135], v[172:175], v[76:79]
	v_mfma_f32_16x16x32_bf16 v[84:87], v[132:135], v[180:183], v[84:87]
	v_mfma_f32_16x16x32_bf16 v[84:87], v[136:139], v[184:187], v[84:87]
	v_mfma_f32_16x16x32_bf16 v[88:91], v[144:147], v[184:187], v[88:91]
	v_mfma_f32_16x16x32_bf16 v[88:91], v[140:143], v[180:183], v[88:91]
	v_mfma_f32_16x16x32_bf16 v[96:99], v[140:143], v[194:197], v[96:99]
	v_mfma_f32_16x16x32_bf16 v[96:99], v[144:147], v[198:201], v[96:99]
	v_mfma_f32_16x16x32_bf16 v[92:95], v[136:139], v[198:201], v[92:95]
	v_mfma_f32_16x16x32_bf16 v[92:95], v[132:135], v[194:197], v[92:95]
	s_setprio 0
	s_setprio 1
	v_mfma_f32_16x16x32_bf16 v[100:103], v[148:151], v[164:167], v[100:103]
	v_mfma_f32_16x16x32_bf16 v[100:103], v[152:155], v[168:171], v[100:103]
	v_mfma_f32_16x16x32_bf16 v[104:107], v[160:163], v[168:171], v[104:107]
	v_mfma_f32_16x16x32_bf16 v[104:107], v[156:159], v[164:167], v[104:107]
	v_mfma_f32_16x16x32_bf16 v[112:115], v[156:159], v[172:175], v[112:115]
	v_mfma_f32_16x16x32_bf16 v[112:115], v[160:163], v[176:179], v[112:115]
	v_mfma_f32_16x16x32_bf16 v[108:111], v[152:155], v[176:179], v[108:111]
	v_mfma_f32_16x16x32_bf16 v[108:111], v[148:151], v[172:175], v[108:111]
	v_mfma_f32_16x16x32_bf16 v[116:119], v[148:151], v[180:183], v[116:119]
	v_mfma_f32_16x16x32_bf16 v[116:119], v[152:155], v[184:187], v[116:119]
	v_mfma_f32_16x16x32_bf16 v[120:123], v[160:163], v[184:187], v[120:123]
	v_mfma_f32_16x16x32_bf16 v[120:123], v[156:159], v[180:183], v[120:123]
	v_mfma_f32_16x16x32_bf16 v[128:131], v[156:159], v[194:197], v[128:131]
	v_mfma_f32_16x16x32_bf16 v[128:131], v[160:163], v[198:201], v[128:131]
	s_setprio 2
	s_barrier
	v_mfma_f32_16x16x32_bf16 v[124:127], v[152:155], v[198:201], v[124:127]
	v_mfma_f32_16x16x32_bf16 v[124:127], v[148:151], v[194:197], v[124:127]
	s_add_i32 s29, 0, 0x18000
	s_add_i32 s40, 0, 0x1c000
	v_add_u32_e32 v144, s29, v232
	v_add_u32_e32 v160, s40, v232
	ds_read_b128 v[132:135], v144
	ds_read_b128 v[136:139], v144 offset:1024
	ds_read_b128 v[140:143], v144 offset:2048
	ds_read_b128 v[144:147], v144 offset:3072
	ds_read_b128 v[148:151], v160
	ds_read_b128 v[152:155], v160 offset:1024
	ds_read_b128 v[156:159], v160 offset:2048
	ds_read_b128 v[160:163], v160 offset:3072
	s_add_u32 s16, s16, 0x40000
	s_addc_u32 s17, s17, 0
	s_mov_b32 m0, s58
	ds_read_b128 v[164:167], v210 offset:32768
	ds_read_b128 v[168:171], v210 offset:33792
	ds_read_b128 v[172:175], v210 offset:34816
	ds_read_b128 v[176:179], v210 offset:35840
	ds_read_b128 v[180:183], v210 offset:36864
	ds_read_b128 v[184:187], v210 offset:37888
	ds_read_b128 v[194:197], v210 offset:38912
	ds_read_b128 v[198:201], v210 offset:39936
	global_load_lds_dwordx4 v2, s[16:17]
	s_mov_b32 m0, s59
	s_nop 0
	global_load_lds_dwordx4 v188, s[16:17]
	s_setprio 0
	s_waitcnt vmcnt(8)
	s_waitcnt lgkmcnt(0)
	s_barrier
	s_setprio 1
	s_waitcnt lgkmcnt(0)
	v_mfma_f32_16x16x32_bf16 v[4:7], v[132:135], v[164:167], v[4:7]
	v_mfma_f32_16x16x32_bf16 v[4:7], v[136:139], v[168:171], v[4:7]
	v_mfma_f32_16x16x32_bf16 v[8:11], v[144:147], v[168:171], v[8:11]
	v_mfma_f32_16x16x32_bf16 v[8:11], v[140:143], v[164:167], v[8:11]
	v_mfma_f32_16x16x32_bf16 v[16:19], v[140:143], v[172:175], v[16:19]
	v_mfma_f32_16x16x32_bf16 v[16:19], v[144:147], v[176:179], v[16:19]
	v_mfma_f32_16x16x32_bf16 v[12:15], v[136:139], v[176:179], v[12:15]
	v_mfma_f32_16x16x32_bf16 v[12:15], v[132:135], v[172:175], v[12:15]
	v_mfma_f32_16x16x32_bf16 v[20:23], v[132:135], v[180:183], v[20:23]
	v_mfma_f32_16x16x32_bf16 v[20:23], v[136:139], v[184:187], v[20:23]
	v_mfma_f32_16x16x32_bf16 v[24:27], v[144:147], v[184:187], v[24:27]
	v_mfma_f32_16x16x32_bf16 v[24:27], v[140:143], v[180:183], v[24:27]
	v_mfma_f32_16x16x32_bf16 v[32:35], v[140:143], v[194:197], v[32:35]
	v_mfma_f32_16x16x32_bf16 v[32:35], v[144:147], v[198:201], v[32:35]
	v_mfma_f32_16x16x32_bf16 v[28:31], v[136:139], v[198:201], v[28:31]
	v_mfma_f32_16x16x32_bf16 v[28:31], v[132:135], v[194:197], v[28:31]
	s_setprio 0
	s_setprio 1
	v_mfma_f32_16x16x32_bf16 v[36:39], v[148:151], v[164:167], v[36:39]
	v_mfma_f32_16x16x32_bf16 v[36:39], v[152:155], v[168:171], v[36:39]
	v_mfma_f32_16x16x32_bf16 v[40:43], v[160:163], v[168:171], v[40:43]
	v_mfma_f32_16x16x32_bf16 v[40:43], v[156:159], v[164:167], v[40:43]
	v_mfma_f32_16x16x32_bf16 v[48:51], v[156:159], v[172:175], v[48:51]
	v_mfma_f32_16x16x32_bf16 v[48:51], v[160:163], v[176:179], v[48:51]
	v_mfma_f32_16x16x32_bf16 v[44:47], v[152:155], v[176:179], v[44:47]
	v_mfma_f32_16x16x32_bf16 v[44:47], v[148:151], v[172:175], v[44:47]
	v_mfma_f32_16x16x32_bf16 v[52:55], v[148:151], v[180:183], v[52:55]
	v_mfma_f32_16x16x32_bf16 v[52:55], v[152:155], v[184:187], v[52:55]
	v_mfma_f32_16x16x32_bf16 v[56:59], v[160:163], v[184:187], v[56:59]
	v_mfma_f32_16x16x32_bf16 v[56:59], v[156:159], v[180:183], v[56:59]
	v_mfma_f32_16x16x32_bf16 v[64:67], v[156:159], v[194:197], v[64:67]
	v_mfma_f32_16x16x32_bf16 v[64:67], v[160:163], v[198:201], v[64:67]
	s_setprio 2
	s_barrier
	v_mfma_f32_16x16x32_bf16 v[60:63], v[152:155], v[198:201], v[60:63]
	v_mfma_f32_16x16x32_bf16 v[60:63], v[148:151], v[194:197], v[60:63]
	s_add_i32 s16, s29, s38
	v_lshl_add_u64 v[202:203], v[202:203], 0, s[86:87]
	s_mov_b32 m0, s16
	ds_read_b128 v[164:167], v210 offset:49152
	ds_read_b128 v[168:171], v210 offset:50176
	ds_read_b128 v[172:175], v210 offset:51200
	ds_read_b128 v[176:179], v210 offset:52224
	ds_read_b128 v[180:183], v210 offset:53248
	ds_read_b128 v[184:187], v210 offset:54272
	ds_read_b128 v[194:197], v210 offset:55296
	ds_read_b128 v[198:201], v210 offset:56320
	global_load_lds_dwordx4 v[202:203], off
	s_add_i32 m0, s16, 0x2000
	s_add_u32 s12, s12, 0x100080
	v_lshl_add_u64 v[202:203], v[204:205], 0, s[86:87]
	s_addc_u32 s13, s13, 0
	s_add_i32 s16, s40, s38
	global_load_lds_dwordx4 v[202:203], off
	s_mov_b32 m0, s16
	v_lshl_add_u64 v[202:203], v[206:207], 0, s[86:87]
	global_load_lds_dwordx4 v192, s[12:13]
	s_add_i32 m0, s16, 0x2000
	s_nop 0
	global_load_lds_dwordx4 v190, s[12:13]
	s_mov_b32 m0, s63
	s_nop 0
	global_load_lds_dwordx4 v[202:203], off
	v_lshl_add_u64 v[202:203], v[208:209], 0, s[86:87]
	s_mov_b32 m0, s64
	s_nop 0
	global_load_lds_dwordx4 v[202:203], off
	s_setprio 0
	s_waitcnt vmcnt(8)
	s_waitcnt lgkmcnt(0)
	s_barrier
	s_setprio 1
	s_waitcnt lgkmcnt(0)
	v_mfma_f32_16x16x32_bf16 v[68:71], v[132:135], v[164:167], v[68:71]
	v_mfma_f32_16x16x32_bf16 v[68:71], v[136:139], v[168:171], v[68:71]
	v_mfma_f32_16x16x32_bf16 v[72:75], v[144:147], v[168:171], v[72:75]
	v_mfma_f32_16x16x32_bf16 v[72:75], v[140:143], v[164:167], v[72:75]
	v_mfma_f32_16x16x32_bf16 v[80:83], v[140:143], v[172:175], v[80:83]
	v_mfma_f32_16x16x32_bf16 v[80:83], v[144:147], v[176:179], v[80:83]
	v_mfma_f32_16x16x32_bf16 v[76:79], v[136:139], v[176:179], v[76:79]
	v_mfma_f32_16x16x32_bf16 v[76:79], v[132:135], v[172:175], v[76:79]
	v_mfma_f32_16x16x32_bf16 v[84:87], v[132:135], v[180:183], v[84:87]
	v_mfma_f32_16x16x32_bf16 v[84:87], v[136:139], v[184:187], v[84:87]
	v_mfma_f32_16x16x32_bf16 v[88:91], v[144:147], v[184:187], v[88:91]
	v_mfma_f32_16x16x32_bf16 v[88:91], v[140:143], v[180:183], v[88:91]
	v_mfma_f32_16x16x32_bf16 v[96:99], v[140:143], v[194:197], v[96:99]
	v_mfma_f32_16x16x32_bf16 v[96:99], v[144:147], v[198:201], v[96:99]
	v_mfma_f32_16x16x32_bf16 v[92:95], v[136:139], v[198:201], v[92:95]
	v_mfma_f32_16x16x32_bf16 v[92:95], v[132:135], v[194:197], v[92:95]
	s_setprio 0
	s_setprio 1
	v_mfma_f32_16x16x32_bf16 v[100:103], v[148:151], v[164:167], v[100:103]
	v_mfma_f32_16x16x32_bf16 v[100:103], v[152:155], v[168:171], v[100:103]
	v_mfma_f32_16x16x32_bf16 v[104:107], v[160:163], v[168:171], v[104:107]
	v_mfma_f32_16x16x32_bf16 v[104:107], v[156:159], v[164:167], v[104:107]
	v_mfma_f32_16x16x32_bf16 v[112:115], v[156:159], v[172:175], v[112:115]
	v_mfma_f32_16x16x32_bf16 v[112:115], v[160:163], v[176:179], v[112:115]
	v_mfma_f32_16x16x32_bf16 v[108:111], v[152:155], v[176:179], v[108:111]
	v_mfma_f32_16x16x32_bf16 v[108:111], v[148:151], v[172:175], v[108:111]
	v_mfma_f32_16x16x32_bf16 v[116:119], v[148:151], v[180:183], v[116:119]
	v_mfma_f32_16x16x32_bf16 v[116:119], v[152:155], v[184:187], v[116:119]
	v_mfma_f32_16x16x32_bf16 v[120:123], v[160:163], v[184:187], v[120:123]
	v_mfma_f32_16x16x32_bf16 v[120:123], v[156:159], v[180:183], v[120:123]
	v_mfma_f32_16x16x32_bf16 v[128:131], v[156:159], v[194:197], v[128:131]
	v_mfma_f32_16x16x32_bf16 v[128:131], v[160:163], v[198:201], v[128:131]
	s_setprio 2
	s_barrier
	v_mfma_f32_16x16x32_bf16 v[124:127], v[152:155], v[198:201], v[124:127]
	v_mfma_f32_16x16x32_bf16 v[124:127], v[148:151], v[194:197], v[124:127]
	s_setprio 0
	s_add_i32 s28, s28, 2
	s_add_u32 s14, s14, 0x100
	s_addc_u32 s15, s15, 0
	s_add_u32 s26, s26, 0x100
	s_addc_u32 s27, s27, 0
	s_cmp_gt_u32 s28, 13
	s_cbranch_scc0 .LBB0_2273
	s_and_b64 vcc, exec, s[48:49]
	s_cbranch_vccz .LBB0_2276
	s_barrier
